# back-edge rotation (7.11): loop-carried SALU moved in front of the loop-back barrier in 12 K-loops and the attention loop
# baseline (speedup 1.0000x reference)
; #define PG8_STAGE(bufoff, gbase, voff) do { _Pragma("unroll") for (int _i = 0; _i < 2; ++_i) \
;         __builtin_amdgcn_global_load_lds((const unsigned*)((const char*)(gbase) + (voff)[_i]), (LAS unsigned*)(lds + (bufoff) + ldsw + _i * 8192), 16, 0, 0); } while (0)
; #define PG8_LDA(dst, b, h) do { _Pragma("unroll") for (int m = 0; m < 4; ++m) _Pragma("unroll") for (int k = 0; k < 2; ++k) dst[m][k] = *(const LAS bf16x8*)(lds + PG8_SA(b, h) + aoff + m * 2048 + k * 1024); } while (0)
; #define PG8_LDB(dst, b, h) do { _Pragma("unroll") for (int n = 0; n < 2; ++n) _Pragma("unroll") for (int k = 0; k < 2; ++k) dst[n][k] = *(const LAS bf16x8*)(lds + PG8_SB(b, h) + boff + n * 2048 + k * 1024); } while (0)
; #define PG8_MMA(ai, bj, At, Bt) do { __builtin_amdgcn_s_setprio(1); _Pragma("unroll") for (int m = 0; m < 4; ++m) _Pragma("unroll") for (int n = 0; n < 2; ++n) _Pragma("unroll") for (int k = 0; k < 2; ++k) \
;         acc[ai][bj][m][n] = __builtin_amdgcn_mfma_f32_16x16x32_bf16(Bt[n][k], At[m][k], acc[ai][bj][m][n], 0, 0, 0); __builtin_amdgcn_s_setprio(0); } while (0)
; #define PG8_WAIT_V(n) asm volatile("s_waitcnt vmcnt(" #n ")" ::: "memory")
; #define PG8_WAIT_L(n) asm volatile("s_waitcnt lgkmcnt(" #n ")" ::: "memory")
; #define PG8_BAR __builtin_amdgcn_s_barrier()
; #define PG8_SCHED __builtin_amdgcn_sched_barrier(0)
; template <class Epi, bool ALIGN_EPI>
; __device__ __forceinline__ void gemm_phase(LAS unsigned char* lds, const Gemm g, const StaticOrder& S, const Epi& E) {
;     ...
;         for (int t = 0; t < nt; t += 2) {
;             const bool last = (t == nt - 2);
;             const char* a1 = cA + (size_t)(t + 1) * kstepA;
;             const char* a2 = last ? nA : cA + (size_t)(t + 2) * kstepA; const char* b2 = last ? nB : cB + (size_t)(t + 2) * kstep;
;             const char* a3 = a2 + kstepA; const char* b3 = b2 + kstep;
;             PG8_LDB(B0, 0, 0); PG8_LDB(B1, 0, 1); PG8_SCHED; PG8_LDA(At, 0, 0); PG8_STAGE(PG8_SA(1, 1), a1 + hsA, voffA);
;             PG8_WAIT_V(8); PG8_WAIT_L(0); PG8_BAR; PG8_MMA(0, 0, At, B0); PG8_MMA(0, 1, At, B1); PG8_BAR; PG8_SCHED;
;             PG8_LDA(At, 0, 1); PG8_STAGE(PG8_SB(0, 0), b2, voffB); PG8_STAGE(PG8_SB(0, 1), b2 + hsB, voffB); PG8_STAGE(PG8_SA(0, 0), a2, voffA);
;             PG8_WAIT_V(8); PG8_WAIT_L(0); PG8_BAR; PG8_MMA(1, 0, At, B0); PG8_MMA(1, 1, At, B1); PG8_BAR; PG8_SCHED;
.LBB0_156:
	ds_read_b128 v[156:159], v151
	ds_read_b128 v[160:163], v151 offset:1024
	ds_read_b128 v[164:167], v151 offset:2048
	ds_read_b128 v[168:171], v151 offset:3072
	ds_read_b128 v[172:175], v152
	ds_read_b128 v[176:179], v152 offset:1024
	ds_read_b128 v[180:183], v152 offset:2048
	ds_read_b128 v[184:187], v152 offset:3072
	s_add_u32 s28, s26, 0xfffc0080
	s_addc_u32 s29, s27, -1
	s_cmp_eq_u32 s54, 12
	s_cselect_b32 s31, s17, s29
	s_cselect_b32 s30, s50, s28
	s_cselect_b32 s29, s19, s53
	s_cselect_b32 s28, s51, s52
	v_lshl_add_u64 v[220:221], s[26:27], 0, v[140:141]
	s_add_i32 m0, s25, 0xc000
	ds_read_b128 v[188:191], v153
	ds_read_b128 v[192:195], v153 offset:1024
	ds_read_b128 v[196:199], v153 offset:2048
	ds_read_b128 v[200:203], v153 offset:3072
	ds_read_b128 v[204:207], v153 offset:4096
	ds_read_b128 v[208:211], v153 offset:5120
	ds_read_b128 v[212:215], v153 offset:6144
	ds_read_b128 v[216:219], v153 offset:7168
	global_load_lds_dwordx4 v[220:221], off
	v_lshl_add_u64 v[220:221], s[26:27], 0, v[142:143]
	s_add_i32 m0, s25, 0xe000
	s_nop 0
	global_load_lds_dwordx4 v[220:221], off
	s_waitcnt vmcnt(8)
	s_waitcnt lgkmcnt(0)
	s_barrier
	s_waitcnt lgkmcnt(0)
	v_mfma_f32_16x16x32_bf16 v[118:121], v[156:159], v[188:191], v[118:121]
	v_mfma_f32_16x16x32_bf16 v[114:117], v[164:167], v[188:191], v[114:117]
	v_mfma_f32_16x16x32_bf16 v[106:109], v[156:159], v[196:199], v[106:109]
	v_mfma_f32_16x16x32_bf16 v[102:105], v[164:167], v[196:199], v[102:105]
	v_mfma_f32_16x16x32_bf16 v[94:97], v[156:159], v[204:207], v[94:97]
	v_mfma_f32_16x16x32_bf16 v[90:93], v[164:167], v[204:207], v[90:93]
	v_mfma_f32_16x16x32_bf16 v[78:81], v[156:159], v[212:215], v[78:81]
	v_mfma_f32_16x16x32_bf16 v[74:77], v[164:167], v[212:215], v[74:77]
	v_mfma_f32_16x16x32_bf16 v[118:121], v[160:163], v[192:195], v[118:121]
	v_mfma_f32_16x16x32_bf16 v[114:117], v[168:171], v[192:195], v[114:117]
	v_mfma_f32_16x16x32_bf16 v[106:109], v[160:163], v[200:203], v[106:109]
	v_mfma_f32_16x16x32_bf16 v[102:105], v[168:171], v[200:203], v[102:105]
	v_mfma_f32_16x16x32_bf16 v[94:97], v[160:163], v[208:211], v[94:97]
	v_mfma_f32_16x16x32_bf16 v[90:93], v[168:171], v[208:211], v[90:93]
	v_mfma_f32_16x16x32_bf16 v[78:81], v[160:163], v[216:219], v[78:81]
	v_mfma_f32_16x16x32_bf16 v[74:77], v[168:171], v[216:219], v[74:77]
	v_mfma_f32_16x16x32_bf16 v[126:129], v[172:175], v[188:191], v[126:129]
	v_mfma_f32_16x16x32_bf16 v[122:125], v[180:183], v[188:191], v[122:125]
	v_mfma_f32_16x16x32_bf16 v[110:113], v[172:175], v[196:199], v[110:113]
	v_mfma_f32_16x16x32_bf16 v[98:101], v[180:183], v[196:199], v[98:101]
	v_mfma_f32_16x16x32_bf16 v[86:89], v[172:175], v[204:207], v[86:89]
	v_mfma_f32_16x16x32_bf16 v[82:85], v[180:183], v[204:207], v[82:85]
	v_mfma_f32_16x16x32_bf16 v[70:73], v[172:175], v[212:215], v[70:73]
	v_mfma_f32_16x16x32_bf16 v[66:69], v[180:183], v[212:215], v[66:69]
	v_mfma_f32_16x16x32_bf16 v[126:129], v[176:179], v[192:195], v[126:129]
	v_mfma_f32_16x16x32_bf16 v[122:125], v[184:187], v[192:195], v[122:125]
	v_mfma_f32_16x16x32_bf16 v[110:113], v[176:179], v[200:203], v[110:113]
	v_mfma_f32_16x16x32_bf16 v[98:101], v[184:187], v[200:203], v[98:101]
	v_mfma_f32_16x16x32_bf16 v[86:89], v[176:179], v[208:211], v[86:89]
	v_mfma_f32_16x16x32_bf16 v[82:85], v[184:187], v[208:211], v[82:85]
	v_mfma_f32_16x16x32_bf16 v[70:73], v[176:179], v[216:219], v[70:73]
	v_mfma_f32_16x16x32_bf16 v[66:69], v[184:187], v[216:219], v[66:69]
	s_barrier
	s_add_i32 s55, s46, s33
	v_lshl_add_u64 v[220:221], s[28:29], 0, v[134:135]
	s_mov_b32 m0, s55
	ds_read_b128 v[188:191], v153 offset:16384
	ds_read_b128 v[192:195], v153 offset:17408
	ds_read_b128 v[196:199], v153 offset:18432
	ds_read_b128 v[200:203], v153 offset:19456
	ds_read_b128 v[204:207], v153 offset:20480
	ds_read_b128 v[208:211], v153 offset:21504
	ds_read_b128 v[212:215], v153 offset:22528
	ds_read_b128 v[216:219], v153 offset:23552
	global_load_lds_dwordx4 v[220:221], off
	s_add_i32 m0, s55, 0x2000
	s_add_u32 s56, s28, 0x40000
	v_lshl_add_u64 v[222:223], s[28:29], 0, v[130:131]
	s_addc_u32 s57, s29, 0
	s_add_i32 s55, s47, s33
	global_load_lds_dwordx4 v[222:223], off
	v_lshl_add_u64 v[224:225], s[56:57], 0, v[134:135]
	s_mov_b32 m0, s55
	v_lshl_add_u64 v[226:227], s[30:31], 0, v[132:133]
	global_load_lds_dwordx4 v[224:225], off
	v_lshl_add_u64 v[224:225], s[56:57], 0, v[130:131]
	s_add_i32 m0, s55, 0x2000
	s_nop 0
	global_load_lds_dwordx4 v[224:225], off
	v_lshl_add_u64 v[224:225], s[30:31], 0, v[136:137]
	s_mov_b32 m0, s25
	s_nop 0
	global_load_lds_dwordx4 v[224:225], off
	s_mov_b32 m0, s36
	s_nop 0
	global_load_lds_dwordx4 v[226:227], off
	s_waitcnt vmcnt(8)
	s_waitcnt lgkmcnt(0)
	s_barrier
; #define PG8_STAGE(bufoff, gbase, voff) do { _Pragma("unroll") for (int _i = 0; _i < 2; ++_i) \
;         __builtin_amdgcn_global_load_lds((const unsigned*)((const char*)(gbase) + (voff)[_i]), (LAS unsigned*)(lds + (bufoff) + ldsw + _i * 8192), 16, 0, 0); } while (0)
; #define PG8_LDA(dst, b, h) do { _Pragma("unroll") for (int m = 0; m < 4; ++m) _Pragma("unroll") for (int k = 0; k < 2; ++k) dst[m][k] = *(const LAS bf16x8*)(lds + PG8_SA(b, h) + aoff + m * 2048 + k * 1024); } while (0)
; #define PG8_LDB(dst, b, h) do { _Pragma("unroll") for (int n = 0; n < 2; ++n) _Pragma("unroll") for (int k = 0; k < 2; ++k) dst[n][k] = *(const LAS bf16x8*)(lds + PG8_SB(b, h) + boff + n * 2048 + k * 1024); } while (0)
; #define PG8_MMA(ai, bj, At, Bt) do { __builtin_amdgcn_s_setprio(1); _Pragma("unroll") for (int m = 0; m < 4; ++m) _Pragma("unroll") for (int n = 0; n < 2; ++n) _Pragma("unroll") for (int k = 0; k < 2; ++k) \
;         acc[ai][bj][m][n] = __builtin_amdgcn_mfma_f32_16x16x32_bf16(Bt[n][k], At[m][k], acc[ai][bj][m][n], 0, 0, 0); __builtin_amdgcn_s_setprio(0); } while (0)
; #define PG8_WAIT_V(n) asm volatile("s_waitcnt vmcnt(" #n ")" ::: "memory")
; #define PG8_WAIT_L(n) asm volatile("s_waitcnt lgkmcnt(" #n ")" ::: "memory")
; #define PG8_BAR __builtin_amdgcn_s_barrier()
; #define PG8_SCHED __builtin_amdgcn_sched_barrier(0)
; template <class Epi, bool ALIGN_EPI>
; __device__ __forceinline__ void gemm_phase(LAS unsigned char* lds, const Gemm g, const StaticOrder& S, const Epi& E) {
;     ...
;             PG8_WAIT_V(8); PG8_WAIT_L(0); PG8_BAR; PG8_MMA(1, 0, At, B0); PG8_MMA(1, 1, At, B1); PG8_BAR; PG8_SCHED;
;             PG8_LDB(B0, 1, 0); PG8_LDB(B1, 1, 1); PG8_SCHED; PG8_LDA(At, 1, 0); PG8_STAGE(PG8_SA(0, 1), a2 + hsA, voffA);
;             PG8_WAIT_V(8); PG8_WAIT_L(0); PG8_BAR; PG8_MMA(0, 0, At, B0); PG8_MMA(0, 1, At, B1); PG8_BAR; PG8_SCHED;
	s_waitcnt lgkmcnt(0)
	v_mfma_f32_16x16x32_bf16 v[62:65], v[156:159], v[188:191], v[62:65]
	v_mfma_f32_16x16x32_bf16 v[58:61], v[164:167], v[188:191], v[58:61]
	v_mfma_f32_16x16x32_bf16 v[46:49], v[156:159], v[196:199], v[46:49]
	v_mfma_f32_16x16x32_bf16 v[42:45], v[164:167], v[196:199], v[42:45]
	v_mfma_f32_16x16x32_bf16 v[30:33], v[156:159], v[204:207], v[30:33]
	v_mfma_f32_16x16x32_bf16 v[26:29], v[164:167], v[204:207], v[26:29]
	v_mfma_f32_16x16x32_bf16 v[14:17], v[156:159], v[212:215], v[14:17]
	v_mfma_f32_16x16x32_bf16 v[10:13], v[164:167], v[212:215], v[10:13]
	v_mfma_f32_16x16x32_bf16 v[62:65], v[160:163], v[192:195], v[62:65]
	v_mfma_f32_16x16x32_bf16 v[58:61], v[168:171], v[192:195], v[58:61]
	v_mfma_f32_16x16x32_bf16 v[46:49], v[160:163], v[200:203], v[46:49]
	v_mfma_f32_16x16x32_bf16 v[42:45], v[168:171], v[200:203], v[42:45]
	v_mfma_f32_16x16x32_bf16 v[30:33], v[160:163], v[208:211], v[30:33]
	v_mfma_f32_16x16x32_bf16 v[26:29], v[168:171], v[208:211], v[26:29]
	v_mfma_f32_16x16x32_bf16 v[14:17], v[160:163], v[216:219], v[14:17]
	v_mfma_f32_16x16x32_bf16 v[10:13], v[168:171], v[216:219], v[10:13]
	v_mfma_f32_16x16x32_bf16 v[54:57], v[172:175], v[188:191], v[54:57]
	v_mfma_f32_16x16x32_bf16 v[50:53], v[180:183], v[188:191], v[50:53]
	v_mfma_f32_16x16x32_bf16 v[38:41], v[172:175], v[196:199], v[38:41]
	v_mfma_f32_16x16x32_bf16 v[34:37], v[180:183], v[196:199], v[34:37]
	v_mfma_f32_16x16x32_bf16 v[22:25], v[172:175], v[204:207], v[22:25]
	v_mfma_f32_16x16x32_bf16 v[18:21], v[180:183], v[204:207], v[18:21]
	v_mfma_f32_16x16x32_bf16 v[6:9], v[172:175], v[212:215], v[6:9]
	v_mfma_f32_16x16x32_bf16 v[2:5], v[180:183], v[212:215], v[2:5]
	v_mfma_f32_16x16x32_bf16 v[54:57], v[176:179], v[192:195], v[54:57]
	v_mfma_f32_16x16x32_bf16 v[50:53], v[184:187], v[192:195], v[50:53]
	v_mfma_f32_16x16x32_bf16 v[38:41], v[176:179], v[200:203], v[38:41]
	v_mfma_f32_16x16x32_bf16 v[34:37], v[184:187], v[200:203], v[34:37]
	v_mfma_f32_16x16x32_bf16 v[22:25], v[176:179], v[208:211], v[22:25]
	v_mfma_f32_16x16x32_bf16 v[18:21], v[184:187], v[208:211], v[18:21]
	v_mfma_f32_16x16x32_bf16 v[6:9], v[176:179], v[216:219], v[6:9]
	v_mfma_f32_16x16x32_bf16 v[2:5], v[184:187], v[216:219], v[2:5]
	s_barrier
	s_add_i32 s55, 0, 0x18000
	v_add_u32_e32 v138, s55, v150
	s_add_i32 s56, 0, 0x1c000
	ds_read_b128 v[156:159], v138
	ds_read_b128 v[160:163], v138 offset:1024
	ds_read_b128 v[164:167], v138 offset:2048
	ds_read_b128 v[168:171], v138 offset:3072
	v_add_u32_e32 v138, s56, v150
	ds_read_b128 v[172:175], v138
	ds_read_b128 v[176:179], v138 offset:1024
	ds_read_b128 v[180:183], v138 offset:2048
	ds_read_b128 v[184:187], v138 offset:3072
	s_add_u32 s30, s30, 0x40000
	s_addc_u32 s31, s31, 0
	s_mov_b32 m0, s37
	v_lshl_add_u64 v[228:229], s[30:31], 0, v[136:137]
	ds_read_b128 v[188:191], v153 offset:32768
	ds_read_b128 v[192:195], v153 offset:33792
	ds_read_b128 v[196:199], v153 offset:34816
	ds_read_b128 v[200:203], v153 offset:35840
	ds_read_b128 v[204:207], v153 offset:36864
	ds_read_b128 v[208:211], v153 offset:37888
	ds_read_b128 v[212:215], v153 offset:38912
	ds_read_b128 v[216:219], v153 offset:39936
	global_load_lds_dwordx4 v[228:229], off
	v_lshl_add_u64 v[228:229], s[30:31], 0, v[132:133]
	s_mov_b32 m0, s38
	s_nop 0
	global_load_lds_dwordx4 v[228:229], off
	s_waitcnt vmcnt(8)
	s_waitcnt lgkmcnt(0)
	s_barrier
	s_waitcnt lgkmcnt(0)
	v_mfma_f32_16x16x32_bf16 v[118:121], v[156:159], v[188:191], v[118:121]
	v_mfma_f32_16x16x32_bf16 v[114:117], v[164:167], v[188:191], v[114:117]
	v_mfma_f32_16x16x32_bf16 v[106:109], v[156:159], v[196:199], v[106:109]
	v_mfma_f32_16x16x32_bf16 v[102:105], v[164:167], v[196:199], v[102:105]
	v_mfma_f32_16x16x32_bf16 v[94:97], v[156:159], v[204:207], v[94:97]
	v_mfma_f32_16x16x32_bf16 v[90:93], v[164:167], v[204:207], v[90:93]
	v_mfma_f32_16x16x32_bf16 v[78:81], v[156:159], v[212:215], v[78:81]
	v_mfma_f32_16x16x32_bf16 v[74:77], v[164:167], v[212:215], v[74:77]
	v_mfma_f32_16x16x32_bf16 v[118:121], v[160:163], v[192:195], v[118:121]
	v_mfma_f32_16x16x32_bf16 v[114:117], v[168:171], v[192:195], v[114:117]
	v_mfma_f32_16x16x32_bf16 v[106:109], v[160:163], v[200:203], v[106:109]
	v_mfma_f32_16x16x32_bf16 v[102:105], v[168:171], v[200:203], v[102:105]
	v_mfma_f32_16x16x32_bf16 v[94:97], v[160:163], v[208:211], v[94:97]
	v_mfma_f32_16x16x32_bf16 v[90:93], v[168:171], v[208:211], v[90:93]
	v_mfma_f32_16x16x32_bf16 v[78:81], v[160:163], v[216:219], v[78:81]
	v_mfma_f32_16x16x32_bf16 v[74:77], v[168:171], v[216:219], v[74:77]
	v_mfma_f32_16x16x32_bf16 v[126:129], v[172:175], v[188:191], v[126:129]
	v_mfma_f32_16x16x32_bf16 v[122:125], v[180:183], v[188:191], v[122:125]
	v_mfma_f32_16x16x32_bf16 v[110:113], v[172:175], v[196:199], v[110:113]
	v_mfma_f32_16x16x32_bf16 v[98:101], v[180:183], v[196:199], v[98:101]
	v_mfma_f32_16x16x32_bf16 v[86:89], v[172:175], v[204:207], v[86:89]
	v_mfma_f32_16x16x32_bf16 v[82:85], v[180:183], v[204:207], v[82:85]
	v_mfma_f32_16x16x32_bf16 v[70:73], v[172:175], v[212:215], v[70:73]
	v_mfma_f32_16x16x32_bf16 v[66:69], v[180:183], v[212:215], v[66:69]
	v_mfma_f32_16x16x32_bf16 v[126:129], v[176:179], v[192:195], v[126:129]
	v_mfma_f32_16x16x32_bf16 v[122:125], v[184:187], v[192:195], v[122:125]
	v_mfma_f32_16x16x32_bf16 v[110:113], v[176:179], v[200:203], v[110:113]
	v_mfma_f32_16x16x32_bf16 v[98:101], v[184:187], v[200:203], v[98:101]
	v_mfma_f32_16x16x32_bf16 v[86:89], v[176:179], v[208:211], v[86:89]
	v_mfma_f32_16x16x32_bf16 v[82:85], v[184:187], v[208:211], v[82:85]
	v_mfma_f32_16x16x32_bf16 v[70:73], v[176:179], v[216:219], v[70:73]
	v_mfma_f32_16x16x32_bf16 v[66:69], v[184:187], v[216:219], v[66:69]
	s_barrier
; #define PG8_STAGE(bufoff, gbase, voff) do { _Pragma("unroll") for (int _i = 0; _i < 2; ++_i) \
;         __builtin_amdgcn_global_load_lds((const unsigned*)((const char*)(gbase) + (voff)[_i]), (LAS unsigned*)(lds + (bufoff) + ldsw + _i * 8192), 16, 0, 0); } while (0)
; #define PG8_LDA(dst, b, h) do { _Pragma("unroll") for (int m = 0; m < 4; ++m) _Pragma("unroll") for (int k = 0; k < 2; ++k) dst[m][k] = *(const LAS bf16x8*)(lds + PG8_SA(b, h) + aoff + m * 2048 + k * 1024); } while (0)
; #define PG8_MMA(ai, bj, At, Bt) do { __builtin_amdgcn_s_setprio(1); _Pragma("unroll") for (int m = 0; m < 4; ++m) _Pragma("unroll") for (int n = 0; n < 2; ++n) _Pragma("unroll") for (int k = 0; k < 2; ++k) \
;         acc[ai][bj][m][n] = __builtin_amdgcn_mfma_f32_16x16x32_bf16(Bt[n][k], At[m][k], acc[ai][bj][m][n], 0, 0, 0); __builtin_amdgcn_s_setprio(0); } while (0)
; #define PG8_WAIT_V(n) asm volatile("s_waitcnt vmcnt(" #n ")" ::: "memory")
; #define PG8_WAIT_L(n) asm volatile("s_waitcnt lgkmcnt(" #n ")" ::: "memory")
; #define PG8_BAR __builtin_amdgcn_s_barrier()
; #define PG8_SCHED __builtin_amdgcn_sched_barrier(0)
; template <class Epi, bool ALIGN_EPI>
; __device__ __forceinline__ void gemm_phase(LAS unsigned char* lds, const Gemm g, const StaticOrder& S, const Epi& E) {
;     ...
;             PG8_LDA(At, 1, 1); PG8_STAGE(PG8_SB(1, 0), b3, voffB); PG8_STAGE(PG8_SB(1, 1), b3 + hsB, voffB); PG8_STAGE(PG8_SA(1, 0), a3, voffA);
;             PG8_WAIT_V(8); PG8_WAIT_L(0); PG8_BAR; PG8_MMA(1, 0, At, B0); PG8_MMA(1, 1, At, B1); PG8_BAR; PG8_SCHED;
;         }
	s_add_i32 s30, s55, s33
	v_lshl_add_u64 v[220:221], v[220:221], 0, s[12:13]
	s_mov_b32 m0, s30
	ds_read_b128 v[188:191], v153 offset:49152
	ds_read_b128 v[192:195], v153 offset:50176
	ds_read_b128 v[196:199], v153 offset:51200
	ds_read_b128 v[200:203], v153 offset:52224
	ds_read_b128 v[204:207], v153 offset:53248
	ds_read_b128 v[208:211], v153 offset:54272
	ds_read_b128 v[212:215], v153 offset:55296
	ds_read_b128 v[216:219], v153 offset:56320
	global_load_lds_dwordx4 v[220:221], off
	s_add_i32 m0, s30, 0x2000
	s_add_u32 s28, s28, 0x40080
	v_lshl_add_u64 v[220:221], v[222:223], 0, s[12:13]
	s_addc_u32 s29, s29, 0
	s_add_i32 s30, s56, s33
	global_load_lds_dwordx4 v[220:221], off
	v_lshl_add_u64 v[220:221], s[28:29], 0, v[134:135]
	s_mov_b32 m0, s30
	s_nop 0
	global_load_lds_dwordx4 v[220:221], off
	v_lshl_add_u64 v[220:221], s[28:29], 0, v[130:131]
	s_add_i32 m0, s30, 0x2000
	s_nop 0
	global_load_lds_dwordx4 v[220:221], off
	v_lshl_add_u64 v[220:221], v[224:225], 0, s[12:13]
	s_mov_b32 m0, s42
	s_nop 0
	global_load_lds_dwordx4 v[220:221], off
	v_lshl_add_u64 v[220:221], v[226:227], 0, s[12:13]
	s_mov_b32 m0, s43
	s_nop 0
	global_load_lds_dwordx4 v[220:221], off
	s_waitcnt vmcnt(8)
	s_waitcnt lgkmcnt(0)
	s_barrier
	s_waitcnt lgkmcnt(0)
	v_mfma_f32_16x16x32_bf16 v[62:65], v[156:159], v[188:191], v[62:65]
	v_mfma_f32_16x16x32_bf16 v[58:61], v[164:167], v[188:191], v[58:61]
	v_mfma_f32_16x16x32_bf16 v[46:49], v[156:159], v[196:199], v[46:49]
	v_mfma_f32_16x16x32_bf16 v[42:45], v[164:167], v[196:199], v[42:45]
	v_mfma_f32_16x16x32_bf16 v[30:33], v[156:159], v[204:207], v[30:33]
	v_mfma_f32_16x16x32_bf16 v[26:29], v[164:167], v[204:207], v[26:29]
	v_mfma_f32_16x16x32_bf16 v[14:17], v[156:159], v[212:215], v[14:17]
	v_mfma_f32_16x16x32_bf16 v[10:13], v[164:167], v[212:215], v[10:13]
	v_mfma_f32_16x16x32_bf16 v[62:65], v[160:163], v[192:195], v[62:65]
	v_mfma_f32_16x16x32_bf16 v[58:61], v[168:171], v[192:195], v[58:61]
	v_mfma_f32_16x16x32_bf16 v[46:49], v[160:163], v[200:203], v[46:49]
	v_mfma_f32_16x16x32_bf16 v[42:45], v[168:171], v[200:203], v[42:45]
	v_mfma_f32_16x16x32_bf16 v[30:33], v[160:163], v[208:211], v[30:33]
	v_mfma_f32_16x16x32_bf16 v[26:29], v[168:171], v[208:211], v[26:29]
	v_mfma_f32_16x16x32_bf16 v[14:17], v[160:163], v[216:219], v[14:17]
	v_mfma_f32_16x16x32_bf16 v[10:13], v[168:171], v[216:219], v[10:13]
	v_mfma_f32_16x16x32_bf16 v[54:57], v[172:175], v[188:191], v[54:57]
	v_mfma_f32_16x16x32_bf16 v[50:53], v[180:183], v[188:191], v[50:53]
	v_mfma_f32_16x16x32_bf16 v[38:41], v[172:175], v[196:199], v[38:41]
	v_mfma_f32_16x16x32_bf16 v[34:37], v[180:183], v[196:199], v[34:37]
	v_mfma_f32_16x16x32_bf16 v[22:25], v[172:175], v[204:207], v[22:25]
	v_mfma_f32_16x16x32_bf16 v[18:21], v[180:183], v[204:207], v[18:21]
	v_mfma_f32_16x16x32_bf16 v[6:9], v[172:175], v[212:215], v[6:9]
	v_mfma_f32_16x16x32_bf16 v[2:5], v[180:183], v[212:215], v[2:5]
	v_mfma_f32_16x16x32_bf16 v[54:57], v[176:179], v[192:195], v[54:57]
	v_mfma_f32_16x16x32_bf16 v[50:53], v[184:187], v[192:195], v[50:53]
	v_mfma_f32_16x16x32_bf16 v[38:41], v[176:179], v[200:203], v[38:41]
	v_mfma_f32_16x16x32_bf16 v[34:37], v[184:187], v[200:203], v[34:37]
	v_mfma_f32_16x16x32_bf16 v[22:25], v[176:179], v[208:211], v[22:25]
	v_mfma_f32_16x16x32_bf16 v[18:21], v[184:187], v[208:211], v[18:21]
	v_mfma_f32_16x16x32_bf16 v[6:9], v[176:179], v[216:219], v[6:9]
	v_mfma_f32_16x16x32_bf16 v[2:5], v[184:187], v[216:219], v[2:5]
	s_add_i32 s54, s54, 2
	s_add_u32 s26, s26, 0x100
	s_addc_u32 s27, s27, 0
	s_add_u32 s52, s52, 0x100
	s_addc_u32 s53, s53, 0
	s_cmp_gt_u32 s54, 13
	s_barrier
	s_cbranch_scc0 .LBB0_156
	s_and_b64 vcc, exec, s[14:15]
	s_cbranch_vccz .LBB0_159
	s_barrier

; #define PG8_STAGE(bufoff, gbase, voff) do { _Pragma("unroll") for (int _i = 0; _i < 2; ++_i) \
;         __builtin_amdgcn_global_load_lds((const unsigned*)((const char*)(gbase) + (voff)[_i]), (LAS unsigned*)(lds + (bufoff) + ldsw + _i * 8192), 16, 0, 0); } while (0)
; #define PG8_LDA(dst, b, h) do { _Pragma("unroll") for (int m = 0; m < 4; ++m) _Pragma("unroll") for (int k = 0; k < 2; ++k) dst[m][k] = *(const LAS bf16x8*)(lds + PG8_SA(b, h) + aoff + m * 2048 + k * 1024); } while (0)
; #define PG8_LDB(dst, b, h) do { _Pragma("unroll") for (int n = 0; n < 2; ++n) _Pragma("unroll") for (int k = 0; k < 2; ++k) dst[n][k] = *(const LAS bf16x8*)(lds + PG8_SB(b, h) + boff + n * 2048 + k * 1024); } while (0)
; #define PG8_MMA(ai, bj, At, Bt) do { __builtin_amdgcn_s_setprio(1); _Pragma("unroll") for (int m = 0; m < 4; ++m) _Pragma("unroll") for (int n = 0; n < 2; ++n) _Pragma("unroll") for (int k = 0; k < 2; ++k) \
;         acc[ai][bj][m][n] = __builtin_amdgcn_mfma_f32_16x16x32_bf16(Bt[n][k], At[m][k], acc[ai][bj][m][n], 0, 0, 0); __builtin_amdgcn_s_setprio(0); } while (0)
; #define PG8_WAIT_V(n) asm volatile("s_waitcnt vmcnt(" #n ")" ::: "memory")
; #define PG8_WAIT_L(n) asm volatile("s_waitcnt lgkmcnt(" #n ")" ::: "memory")
; #define PG8_BAR __builtin_amdgcn_s_barrier()
; #define PG8_SCHED __builtin_amdgcn_sched_barrier(0)
; template <class Epi, bool ALIGN_EPI>
; __device__ __forceinline__ void gemm_phase(LAS unsigned char* lds, const Gemm g, const StaticOrder& S, const Epi& E) {
;     ...
;         for (int t = 0; t < nt; t += 2) {
;             const bool last = (t == nt - 2);
;             const char* a1 = cA + (size_t)(t + 1) * kstepA;
;             const char* a2 = last ? nA : cA + (size_t)(t + 2) * kstepA; const char* b2 = last ? nB : cB + (size_t)(t + 2) * kstep;
;             const char* a3 = a2 + kstepA; const char* b3 = b2 + kstep;
;             PG8_LDB(B0, 0, 0); PG8_LDB(B1, 0, 1); PG8_SCHED; PG8_LDA(At, 0, 0); PG8_STAGE(PG8_SA(1, 1), a1 + hsA, voffA);
;             PG8_WAIT_V(8); PG8_WAIT_L(0); PG8_BAR; PG8_MMA(0, 0, At, B0); PG8_MMA(0, 1, At, B1); PG8_BAR; PG8_SCHED;
;             PG8_LDA(At, 0, 1); PG8_STAGE(PG8_SB(0, 0), b2, voffB); PG8_STAGE(PG8_SB(0, 1), b2 + hsB, voffB); PG8_STAGE(PG8_SA(0, 0), a2, voffA);
;             PG8_WAIT_V(8); PG8_WAIT_L(0); PG8_BAR; PG8_MMA(1, 0, At, B0); PG8_MMA(1, 1, At, B1); PG8_BAR; PG8_SCHED;
.LBB0_330:
	ds_read_b128 v[118:121], v190
	ds_read_b128 v[126:129], v190 offset:1024
	ds_read_b128 v[138:141], v190 offset:2048
	ds_read_b128 v[142:145], v190 offset:3072
	ds_read_b128 v[146:149], v191
	ds_read_b128 v[150:153], v191 offset:1024
	ds_read_b128 v[170:173], v191 offset:2048
	ds_read_b128 v[174:177], v191 offset:3072
	s_add_u32 s14, s12, 0x4000
	s_addc_u32 s15, s13, 0
	s_cmp_eq_u32 s48, 40
	s_cselect_b32 s18, s6, s14
	s_cselect_b32 s19, s7, s15
	s_cselect_b32 s16, s42, s46
	s_cselect_b32 s17, s43, s47
	s_add_u32 s14, s18, 0x8000
	s_addc_u32 s15, s19, 0
	v_lshl_add_u64 v[186:187], s[12:13], 0, v[162:163]
	s_add_i32 m0, s21, 0xc000
	ds_read_b128 v[178:181], v192
	ds_read_b128 v[182:185], v192 offset:1024
	ds_read_b128 v[194:197], v192 offset:2048
	ds_read_b128 v[198:201], v192 offset:3072
	ds_read_b128 v[202:205], v192 offset:4096
	ds_read_b128 v[206:209], v192 offset:5120
	ds_read_b128 v[210:213], v192 offset:6144
	ds_read_b128 v[214:217], v192 offset:7168
	global_load_lds_dwordx4 v[186:187], off
	v_lshl_add_u64 v[186:187], s[12:13], 0, v[164:165]
	s_add_i32 m0, s21, 0xe000
	s_nop 0
	global_load_lds_dwordx4 v[186:187], off
	s_waitcnt vmcnt(8)
	s_waitcnt lgkmcnt(0)
	s_barrier
	s_waitcnt lgkmcnt(0)
	v_mfma_f32_16x16x32_bf16 v[134:137], v[118:121], v[178:181], v[134:137]
	v_mfma_f32_16x16x32_bf16 v[130:133], v[138:141], v[178:181], v[130:133]
	v_mfma_f32_16x16x32_bf16 v[110:113], v[118:121], v[194:197], v[110:113]
	v_mfma_f32_16x16x32_bf16 v[106:109], v[138:141], v[194:197], v[106:109]
	v_mfma_f32_16x16x32_bf16 v[94:97], v[118:121], v[202:205], v[94:97]
	v_mfma_f32_16x16x32_bf16 v[90:93], v[138:141], v[202:205], v[90:93]
	v_mfma_f32_16x16x32_bf16 v[78:81], v[118:121], v[210:213], v[78:81]
	v_mfma_f32_16x16x32_bf16 v[74:77], v[138:141], v[210:213], v[74:77]
	v_mfma_f32_16x16x32_bf16 v[134:137], v[126:129], v[182:185], v[134:137]
	v_mfma_f32_16x16x32_bf16 v[130:133], v[142:145], v[182:185], v[130:133]
	v_mfma_f32_16x16x32_bf16 v[110:113], v[126:129], v[198:201], v[110:113]
	v_mfma_f32_16x16x32_bf16 v[106:109], v[142:145], v[198:201], v[106:109]
	v_mfma_f32_16x16x32_bf16 v[94:97], v[126:129], v[206:209], v[94:97]
	v_mfma_f32_16x16x32_bf16 v[90:93], v[142:145], v[206:209], v[90:93]
	v_mfma_f32_16x16x32_bf16 v[78:81], v[126:129], v[214:217], v[78:81]
	v_mfma_f32_16x16x32_bf16 v[74:77], v[142:145], v[214:217], v[74:77]
	v_mfma_f32_16x16x32_bf16 v[122:125], v[146:149], v[178:181], v[122:125]
	v_mfma_f32_16x16x32_bf16 v[114:117], v[170:173], v[178:181], v[114:117]
	v_mfma_f32_16x16x32_bf16 v[102:105], v[146:149], v[194:197], v[102:105]
	v_mfma_f32_16x16x32_bf16 v[98:101], v[170:173], v[194:197], v[98:101]
	v_mfma_f32_16x16x32_bf16 v[86:89], v[146:149], v[202:205], v[86:89]
	v_mfma_f32_16x16x32_bf16 v[82:85], v[170:173], v[202:205], v[82:85]
	v_mfma_f32_16x16x32_bf16 v[70:73], v[146:149], v[210:213], v[70:73]
	v_mfma_f32_16x16x32_bf16 v[66:69], v[170:173], v[210:213], v[66:69]
	v_mfma_f32_16x16x32_bf16 v[122:125], v[150:153], v[182:185], v[122:125]
	v_mfma_f32_16x16x32_bf16 v[114:117], v[174:177], v[182:185], v[114:117]
	v_mfma_f32_16x16x32_bf16 v[102:105], v[150:153], v[198:201], v[102:105]
	v_mfma_f32_16x16x32_bf16 v[98:101], v[174:177], v[198:201], v[98:101]
	v_mfma_f32_16x16x32_bf16 v[86:89], v[150:153], v[206:209], v[86:89]
	v_mfma_f32_16x16x32_bf16 v[82:85], v[174:177], v[206:209], v[82:85]
	v_mfma_f32_16x16x32_bf16 v[70:73], v[150:153], v[214:217], v[70:73]
	v_mfma_f32_16x16x32_bf16 v[66:69], v[174:177], v[214:217], v[66:69]
	s_barrier
	s_add_i32 s49, s31, s20
	v_lshl_add_u64 v[186:187], s[16:17], 0, v[156:157]
	s_mov_b32 m0, s49
	ds_read_b128 v[178:181], v192 offset:16384
	ds_read_b128 v[182:185], v192 offset:17408
	ds_read_b128 v[194:197], v192 offset:18432
	ds_read_b128 v[198:201], v192 offset:19456
	ds_read_b128 v[202:205], v192 offset:20480
	ds_read_b128 v[206:209], v192 offset:21504
	ds_read_b128 v[210:213], v192 offset:22528
	ds_read_b128 v[214:217], v192 offset:23552
	global_load_lds_dwordx4 v[186:187], off
	s_add_i32 m0, s49, 0x2000
	s_add_u32 s50, s16, 0xb0000
	v_lshl_add_u64 v[218:219], s[16:17], 0, v[160:161]
	s_addc_u32 s51, s17, 0
	s_add_i32 s49, s33, s20
	global_load_lds_dwordx4 v[218:219], off
	v_lshl_add_u64 v[220:221], s[50:51], 0, v[156:157]
	s_mov_b32 m0, s49
	s_nop 0
	global_load_lds_dwordx4 v[220:221], off
	v_lshl_add_u64 v[220:221], s[50:51], 0, v[160:161]
	s_add_i32 m0, s49, 0x2000
	s_nop 0
	global_load_lds_dwordx4 v[220:221], off
	v_lshl_add_u64 v[220:221], s[18:19], 0, v[154:155]
	s_mov_b32 m0, s21
	s_nop 0
	global_load_lds_dwordx4 v[220:221], off
	v_lshl_add_u64 v[220:221], s[18:19], 0, v[158:159]
	s_mov_b32 m0, s22
	s_nop 0
	global_load_lds_dwordx4 v[220:221], off
	s_waitcnt vmcnt(8)
	s_waitcnt lgkmcnt(0)
	s_barrier
; #define PG8_STAGE(bufoff, gbase, voff) do { _Pragma("unroll") for (int _i = 0; _i < 2; ++_i) \
;         __builtin_amdgcn_global_load_lds((const unsigned*)((const char*)(gbase) + (voff)[_i]), (LAS unsigned*)(lds + (bufoff) + ldsw + _i * 8192), 16, 0, 0); } while (0)
; #define PG8_LDA(dst, b, h) do { _Pragma("unroll") for (int m = 0; m < 4; ++m) _Pragma("unroll") for (int k = 0; k < 2; ++k) dst[m][k] = *(const LAS bf16x8*)(lds + PG8_SA(b, h) + aoff + m * 2048 + k * 1024); } while (0)
; #define PG8_LDB(dst, b, h) do { _Pragma("unroll") for (int n = 0; n < 2; ++n) _Pragma("unroll") for (int k = 0; k < 2; ++k) dst[n][k] = *(const LAS bf16x8*)(lds + PG8_SB(b, h) + boff + n * 2048 + k * 1024); } while (0)
; #define PG8_MMA(ai, bj, At, Bt) do { __builtin_amdgcn_s_setprio(1); _Pragma("unroll") for (int m = 0; m < 4; ++m) _Pragma("unroll") for (int n = 0; n < 2; ++n) _Pragma("unroll") for (int k = 0; k < 2; ++k) \
;         acc[ai][bj][m][n] = __builtin_amdgcn_mfma_f32_16x16x32_bf16(Bt[n][k], At[m][k], acc[ai][bj][m][n], 0, 0, 0); __builtin_amdgcn_s_setprio(0); } while (0)
; #define PG8_WAIT_V(n) asm volatile("s_waitcnt vmcnt(" #n ")" ::: "memory")
; #define PG8_WAIT_L(n) asm volatile("s_waitcnt lgkmcnt(" #n ")" ::: "memory")
; #define PG8_BAR __builtin_amdgcn_s_barrier()
; #define PG8_SCHED __builtin_amdgcn_sched_barrier(0)
; template <class Epi, bool ALIGN_EPI>
; __device__ __forceinline__ void gemm_phase(LAS unsigned char* lds, const Gemm g, const StaticOrder& S, const Epi& E) {
;     ...
;             PG8_WAIT_V(8); PG8_WAIT_L(0); PG8_BAR; PG8_MMA(1, 0, At, B0); PG8_MMA(1, 1, At, B1); PG8_BAR; PG8_SCHED;
;             PG8_LDB(B0, 1, 0); PG8_LDB(B1, 1, 1); PG8_SCHED; PG8_LDA(At, 1, 0); PG8_STAGE(PG8_SA(0, 1), a2 + hsA, voffA);
;             PG8_WAIT_V(8); PG8_WAIT_L(0); PG8_BAR; PG8_MMA(0, 0, At, B0); PG8_MMA(0, 1, At, B1); PG8_BAR; PG8_SCHED;
;             PG8_LDA(At, 1, 1); PG8_STAGE(PG8_SB(1, 0), b3, voffB); PG8_STAGE(PG8_SB(1, 1), b3 + hsB, voffB); PG8_STAGE(PG8_SA(1, 0), a3, voffA);
;             PG8_WAIT_V(8); PG8_WAIT_L(0); PG8_BAR; PG8_MMA(1, 0, At, B0); PG8_MMA(1, 1, At, B1); PG8_BAR; PG8_SCHED;
	s_waitcnt lgkmcnt(0)
	v_mfma_f32_16x16x32_bf16 v[62:65], v[118:121], v[178:181], v[62:65]
	v_mfma_f32_16x16x32_bf16 v[58:61], v[138:141], v[178:181], v[58:61]
	v_mfma_f32_16x16x32_bf16 v[46:49], v[118:121], v[194:197], v[46:49]
	v_mfma_f32_16x16x32_bf16 v[42:45], v[138:141], v[194:197], v[42:45]
	v_mfma_f32_16x16x32_bf16 v[30:33], v[118:121], v[202:205], v[30:33]
	v_mfma_f32_16x16x32_bf16 v[26:29], v[138:141], v[202:205], v[26:29]
	v_mfma_f32_16x16x32_bf16 v[14:17], v[118:121], v[210:213], v[14:17]
	v_mfma_f32_16x16x32_bf16 v[10:13], v[138:141], v[210:213], v[10:13]
	v_mfma_f32_16x16x32_bf16 v[62:65], v[126:129], v[182:185], v[62:65]
	v_mfma_f32_16x16x32_bf16 v[58:61], v[142:145], v[182:185], v[58:61]
	v_mfma_f32_16x16x32_bf16 v[46:49], v[126:129], v[198:201], v[46:49]
	v_mfma_f32_16x16x32_bf16 v[42:45], v[142:145], v[198:201], v[42:45]
	v_mfma_f32_16x16x32_bf16 v[30:33], v[126:129], v[206:209], v[30:33]
	v_mfma_f32_16x16x32_bf16 v[26:29], v[142:145], v[206:209], v[26:29]
	v_mfma_f32_16x16x32_bf16 v[14:17], v[126:129], v[214:217], v[14:17]
	v_mfma_f32_16x16x32_bf16 v[10:13], v[142:145], v[214:217], v[10:13]
	v_mfma_f32_16x16x32_bf16 v[54:57], v[146:149], v[178:181], v[54:57]
	v_mfma_f32_16x16x32_bf16 v[50:53], v[170:173], v[178:181], v[50:53]
	v_mfma_f32_16x16x32_bf16 v[38:41], v[146:149], v[194:197], v[38:41]
	v_mfma_f32_16x16x32_bf16 v[34:37], v[170:173], v[194:197], v[34:37]
	v_mfma_f32_16x16x32_bf16 v[22:25], v[146:149], v[202:205], v[22:25]
	v_mfma_f32_16x16x32_bf16 v[18:21], v[170:173], v[202:205], v[18:21]
	v_mfma_f32_16x16x32_bf16 v[6:9], v[146:149], v[210:213], v[6:9]
	v_mfma_f32_16x16x32_bf16 v[2:5], v[170:173], v[210:213], v[2:5]
	v_mfma_f32_16x16x32_bf16 v[54:57], v[150:153], v[182:185], v[54:57]
	v_mfma_f32_16x16x32_bf16 v[50:53], v[174:177], v[182:185], v[50:53]
	v_mfma_f32_16x16x32_bf16 v[38:41], v[150:153], v[198:201], v[38:41]
	v_mfma_f32_16x16x32_bf16 v[34:37], v[174:177], v[198:201], v[34:37]
	v_mfma_f32_16x16x32_bf16 v[22:25], v[150:153], v[206:209], v[22:25]
	v_mfma_f32_16x16x32_bf16 v[18:21], v[174:177], v[206:209], v[18:21]
	v_mfma_f32_16x16x32_bf16 v[6:9], v[150:153], v[214:217], v[6:9]
	v_mfma_f32_16x16x32_bf16 v[2:5], v[174:177], v[214:217], v[2:5]
	s_barrier
	s_add_i32 s49, 0, 0x18000
	s_add_i32 s50, 0, 0x1c000
	v_add_u32_e32 v142, s49, v188
	v_add_u32_e32 v174, s50, v188
	ds_read_b128 v[118:121], v142
	ds_read_b128 v[126:129], v142 offset:1024
	ds_read_b128 v[138:141], v142 offset:2048
	ds_read_b128 v[142:145], v142 offset:3072
	ds_read_b128 v[146:149], v174
	ds_read_b128 v[150:153], v174 offset:1024
	ds_read_b128 v[170:173], v174 offset:2048
	ds_read_b128 v[174:177], v174 offset:3072
	s_add_u32 s18, s18, 0x4000
	s_addc_u32 s19, s19, 0
	s_mov_b32 m0, s23
	v_lshl_add_u64 v[220:221], s[18:19], 0, v[154:155]
	ds_read_b128 v[178:181], v192 offset:32768
	ds_read_b128 v[182:185], v192 offset:33792
	ds_read_b128 v[194:197], v192 offset:34816
	ds_read_b128 v[198:201], v192 offset:35840
	ds_read_b128 v[202:205], v192 offset:36864
	ds_read_b128 v[206:209], v192 offset:37888
	ds_read_b128 v[210:213], v192 offset:38912
	ds_read_b128 v[214:217], v192 offset:39936
	global_load_lds_dwordx4 v[220:221], off
	v_lshl_add_u64 v[220:221], s[18:19], 0, v[158:159]
	s_mov_b32 m0, s24
	s_nop 0
	global_load_lds_dwordx4 v[220:221], off
	s_waitcnt vmcnt(8)
	s_waitcnt lgkmcnt(0)
	s_barrier
	s_waitcnt lgkmcnt(0)
	v_mfma_f32_16x16x32_bf16 v[134:137], v[118:121], v[178:181], v[134:137]
	v_mfma_f32_16x16x32_bf16 v[130:133], v[138:141], v[178:181], v[130:133]
	v_mfma_f32_16x16x32_bf16 v[110:113], v[118:121], v[194:197], v[110:113]
	v_mfma_f32_16x16x32_bf16 v[106:109], v[138:141], v[194:197], v[106:109]
	v_mfma_f32_16x16x32_bf16 v[94:97], v[118:121], v[202:205], v[94:97]
	v_mfma_f32_16x16x32_bf16 v[90:93], v[138:141], v[202:205], v[90:93]
	v_mfma_f32_16x16x32_bf16 v[78:81], v[118:121], v[210:213], v[78:81]
	v_mfma_f32_16x16x32_bf16 v[74:77], v[138:141], v[210:213], v[74:77]
	v_mfma_f32_16x16x32_bf16 v[134:137], v[126:129], v[182:185], v[134:137]
	v_mfma_f32_16x16x32_bf16 v[130:133], v[142:145], v[182:185], v[130:133]
	v_mfma_f32_16x16x32_bf16 v[110:113], v[126:129], v[198:201], v[110:113]
	v_mfma_f32_16x16x32_bf16 v[106:109], v[142:145], v[198:201], v[106:109]
	v_mfma_f32_16x16x32_bf16 v[94:97], v[126:129], v[206:209], v[94:97]
	v_mfma_f32_16x16x32_bf16 v[90:93], v[142:145], v[206:209], v[90:93]
	v_mfma_f32_16x16x32_bf16 v[78:81], v[126:129], v[214:217], v[78:81]
	v_mfma_f32_16x16x32_bf16 v[74:77], v[142:145], v[214:217], v[74:77]
	v_mfma_f32_16x16x32_bf16 v[122:125], v[146:149], v[178:181], v[122:125]
	v_mfma_f32_16x16x32_bf16 v[114:117], v[170:173], v[178:181], v[114:117]
	v_mfma_f32_16x16x32_bf16 v[102:105], v[146:149], v[194:197], v[102:105]
	v_mfma_f32_16x16x32_bf16 v[98:101], v[170:173], v[194:197], v[98:101]
	v_mfma_f32_16x16x32_bf16 v[86:89], v[146:149], v[202:205], v[86:89]
	v_mfma_f32_16x16x32_bf16 v[82:85], v[170:173], v[202:205], v[82:85]
	v_mfma_f32_16x16x32_bf16 v[70:73], v[146:149], v[210:213], v[70:73]
	v_mfma_f32_16x16x32_bf16 v[66:69], v[170:173], v[210:213], v[66:69]
	v_mfma_f32_16x16x32_bf16 v[122:125], v[150:153], v[182:185], v[122:125]
	v_mfma_f32_16x16x32_bf16 v[114:117], v[174:177], v[182:185], v[114:117]
	v_mfma_f32_16x16x32_bf16 v[102:105], v[150:153], v[198:201], v[102:105]
	v_mfma_f32_16x16x32_bf16 v[98:101], v[174:177], v[198:201], v[98:101]
	v_mfma_f32_16x16x32_bf16 v[86:89], v[150:153], v[206:209], v[86:89]
	v_mfma_f32_16x16x32_bf16 v[82:85], v[174:177], v[206:209], v[82:85]
	v_mfma_f32_16x16x32_bf16 v[70:73], v[150:153], v[214:217], v[70:73]
	v_mfma_f32_16x16x32_bf16 v[66:69], v[174:177], v[214:217], v[66:69]
	s_barrier
; #define PG8_STAGE(bufoff, gbase, voff) do { _Pragma("unroll") for (int _i = 0; _i < 2; ++_i) \
;         __builtin_amdgcn_global_load_lds((const unsigned*)((const char*)(gbase) + (voff)[_i]), (LAS unsigned*)(lds + (bufoff) + ldsw + _i * 8192), 16, 0, 0); } while (0)
; #define PG8_LDA(dst, b, h) do { _Pragma("unroll") for (int m = 0; m < 4; ++m) _Pragma("unroll") for (int k = 0; k < 2; ++k) dst[m][k] = *(const LAS bf16x8*)(lds + PG8_SA(b, h) + aoff + m * 2048 + k * 1024); } while (0)
; #define PG8_MMA(ai, bj, At, Bt) do { __builtin_amdgcn_s_setprio(1); _Pragma("unroll") for (int m = 0; m < 4; ++m) _Pragma("unroll") for (int n = 0; n < 2; ++n) _Pragma("unroll") for (int k = 0; k < 2; ++k) \
;         acc[ai][bj][m][n] = __builtin_amdgcn_mfma_f32_16x16x32_bf16(Bt[n][k], At[m][k], acc[ai][bj][m][n], 0, 0, 0); __builtin_amdgcn_s_setprio(0); } while (0)
; #define PG8_WAIT_V(n) asm volatile("s_waitcnt vmcnt(" #n ")" ::: "memory")
; #define PG8_WAIT_L(n) asm volatile("s_waitcnt lgkmcnt(" #n ")" ::: "memory")
; #define PG8_BAR __builtin_amdgcn_s_barrier()
; #define PG8_SCHED __builtin_amdgcn_sched_barrier(0)
; template <class Epi, bool ALIGN_EPI>
; __device__ __forceinline__ void gemm_phase(LAS unsigned char* lds, const Gemm g, const StaticOrder& S, const Epi& E) {
;     ...
;             PG8_LDA(At, 1, 1); PG8_STAGE(PG8_SB(1, 0), b3, voffB); PG8_STAGE(PG8_SB(1, 1), b3 + hsB, voffB); PG8_STAGE(PG8_SA(1, 0), a3, voffA);
;             PG8_WAIT_V(8); PG8_WAIT_L(0); PG8_BAR; PG8_MMA(1, 0, At, B0); PG8_MMA(1, 1, At, B1); PG8_BAR; PG8_SCHED;
;         }
;         if constexpr (ALIGN_EPI) { if (wr == 0) PG8_BAR; }
	s_add_i32 s18, s49, s20
	v_lshl_add_u64 v[186:187], v[186:187], 0, s[38:39]
	s_mov_b32 m0, s18
	ds_read_b128 v[178:181], v192 offset:49152
	ds_read_b128 v[182:185], v192 offset:50176
	ds_read_b128 v[194:197], v192 offset:51200
	ds_read_b128 v[198:201], v192 offset:52224
	ds_read_b128 v[202:205], v192 offset:53248
	ds_read_b128 v[206:209], v192 offset:54272
	ds_read_b128 v[210:213], v192 offset:55296
	ds_read_b128 v[214:217], v192 offset:56320
	global_load_lds_dwordx4 v[186:187], off
	s_add_i32 m0, s18, 0x2000
	s_add_u32 s16, s16, 0xb0080
	v_lshl_add_u64 v[186:187], v[218:219], 0, s[38:39]
	s_addc_u32 s17, s17, 0
	s_add_i32 s18, s50, s20
	global_load_lds_dwordx4 v[186:187], off
	v_lshl_add_u64 v[186:187], s[16:17], 0, v[156:157]
	s_mov_b32 m0, s18
	s_nop 0
	global_load_lds_dwordx4 v[186:187], off
	v_lshl_add_u64 v[186:187], s[16:17], 0, v[160:161]
	s_add_i32 m0, s18, 0x2000
	s_nop 0
	global_load_lds_dwordx4 v[186:187], off
	v_lshl_add_u64 v[186:187], s[14:15], 0, v[154:155]
	s_mov_b32 m0, s26
	s_nop 0
	global_load_lds_dwordx4 v[186:187], off
	v_lshl_add_u64 v[186:187], s[14:15], 0, v[158:159]
	s_mov_b32 m0, s27
	s_nop 0
	global_load_lds_dwordx4 v[186:187], off
	s_waitcnt vmcnt(8)
	s_waitcnt lgkmcnt(0)
	s_barrier
	s_waitcnt lgkmcnt(0)
	v_mfma_f32_16x16x32_bf16 v[62:65], v[118:121], v[178:181], v[62:65]
	v_mfma_f32_16x16x32_bf16 v[58:61], v[138:141], v[178:181], v[58:61]
	v_mfma_f32_16x16x32_bf16 v[46:49], v[118:121], v[194:197], v[46:49]
	v_mfma_f32_16x16x32_bf16 v[42:45], v[138:141], v[194:197], v[42:45]
	v_mfma_f32_16x16x32_bf16 v[30:33], v[118:121], v[202:205], v[30:33]
	v_mfma_f32_16x16x32_bf16 v[26:29], v[138:141], v[202:205], v[26:29]
	v_mfma_f32_16x16x32_bf16 v[14:17], v[118:121], v[210:213], v[14:17]
	v_mfma_f32_16x16x32_bf16 v[10:13], v[138:141], v[210:213], v[10:13]
	v_mfma_f32_16x16x32_bf16 v[62:65], v[126:129], v[182:185], v[62:65]
	v_mfma_f32_16x16x32_bf16 v[58:61], v[142:145], v[182:185], v[58:61]
	v_mfma_f32_16x16x32_bf16 v[46:49], v[126:129], v[198:201], v[46:49]
	v_mfma_f32_16x16x32_bf16 v[42:45], v[142:145], v[198:201], v[42:45]
	v_mfma_f32_16x16x32_bf16 v[30:33], v[126:129], v[206:209], v[30:33]
	v_mfma_f32_16x16x32_bf16 v[26:29], v[142:145], v[206:209], v[26:29]
	v_mfma_f32_16x16x32_bf16 v[14:17], v[126:129], v[214:217], v[14:17]
	v_mfma_f32_16x16x32_bf16 v[10:13], v[142:145], v[214:217], v[10:13]
	v_mfma_f32_16x16x32_bf16 v[54:57], v[146:149], v[178:181], v[54:57]
	v_mfma_f32_16x16x32_bf16 v[50:53], v[170:173], v[178:181], v[50:53]
	v_mfma_f32_16x16x32_bf16 v[38:41], v[146:149], v[194:197], v[38:41]
	v_mfma_f32_16x16x32_bf16 v[34:37], v[170:173], v[194:197], v[34:37]
	v_mfma_f32_16x16x32_bf16 v[22:25], v[146:149], v[202:205], v[22:25]
	v_mfma_f32_16x16x32_bf16 v[18:21], v[170:173], v[202:205], v[18:21]
	v_mfma_f32_16x16x32_bf16 v[6:9], v[146:149], v[210:213], v[6:9]
	v_mfma_f32_16x16x32_bf16 v[2:5], v[170:173], v[210:213], v[2:5]
	v_mfma_f32_16x16x32_bf16 v[54:57], v[150:153], v[182:185], v[54:57]
	v_mfma_f32_16x16x32_bf16 v[50:53], v[174:177], v[182:185], v[50:53]
	v_mfma_f32_16x16x32_bf16 v[38:41], v[150:153], v[198:201], v[38:41]
	v_mfma_f32_16x16x32_bf16 v[34:37], v[174:177], v[198:201], v[34:37]
	v_mfma_f32_16x16x32_bf16 v[22:25], v[150:153], v[206:209], v[22:25]
	v_mfma_f32_16x16x32_bf16 v[18:21], v[174:177], v[206:209], v[18:21]
	v_mfma_f32_16x16x32_bf16 v[6:9], v[150:153], v[214:217], v[6:9]
	v_mfma_f32_16x16x32_bf16 v[2:5], v[174:177], v[214:217], v[2:5]
	s_add_i32 s48, s48, 2
	s_add_u32 s12, s12, 0x10000
	s_addc_u32 s13, s13, 0
	s_add_u32 s46, s46, 0x100
	s_addc_u32 s47, s47, 0
	s_cmp_gt_u32 s48, 41
	s_barrier
	s_cbranch_scc0 .LBB0_330
	s_and_b64 vcc, exec, s[40:41]
	s_cbranch_vccz .LBB0_333
	s_barrier

; #define PG8_STAGE(bufoff, gbase, voff) do { _Pragma("unroll") for (int _i = 0; _i < 2; ++_i) \
;         __builtin_amdgcn_global_load_lds((const unsigned*)((const char*)(gbase) + (voff)[_i]), (LAS unsigned*)(lds + (bufoff) + ldsw + _i * 8192), 16, 0, 0); } while (0)
; #define PG8_LDA(dst, b, h) do { _Pragma("unroll") for (int m = 0; m < 4; ++m) _Pragma("unroll") for (int k = 0; k < 2; ++k) dst[m][k] = *(const LAS bf16x8*)(lds + PG8_SA(b, h) + aoff + m * 2048 + k * 1024); } while (0)
; #define PG8_LDB(dst, b, h) do { _Pragma("unroll") for (int n = 0; n < 2; ++n) _Pragma("unroll") for (int k = 0; k < 2; ++k) dst[n][k] = *(const LAS bf16x8*)(lds + PG8_SB(b, h) + boff + n * 2048 + k * 1024); } while (0)
; #define PG8_MMA(ai, bj, At, Bt) do { __builtin_amdgcn_s_setprio(1); _Pragma("unroll") for (int m = 0; m < 4; ++m) _Pragma("unroll") for (int n = 0; n < 2; ++n) _Pragma("unroll") for (int k = 0; k < 2; ++k) \
;         acc[ai][bj][m][n] = __builtin_amdgcn_mfma_f32_16x16x32_bf16(Bt[n][k], At[m][k], acc[ai][bj][m][n], 0, 0, 0); __builtin_amdgcn_s_setprio(0); } while (0)
; #define PG8_WAIT_V(n) asm volatile("s_waitcnt vmcnt(" #n ")" ::: "memory")
; #define PG8_WAIT_L(n) asm volatile("s_waitcnt lgkmcnt(" #n ")" ::: "memory")
; #define PG8_BAR __builtin_amdgcn_s_barrier()
; #define PG8_SCHED __builtin_amdgcn_sched_barrier(0)
; template <class Epi, bool ALIGN_EPI>
; __device__ __forceinline__ void gemm_phase(LAS unsigned char* lds, const Gemm g, const StaticOrder& S, const Epi& E) {
;     ...
;         for (int t = 0; t < nt; t += 2) {
;             const bool last = (t == nt - 2);
;             const char* a1 = cA + (size_t)(t + 1) * kstepA;
;             const char* a2 = last ? nA : cA + (size_t)(t + 2) * kstepA; const char* b2 = last ? nB : cB + (size_t)(t + 2) * kstep;
;             const char* a3 = a2 + kstepA; const char* b3 = b2 + kstep;
;             PG8_LDB(B0, 0, 0); PG8_LDB(B1, 0, 1); PG8_SCHED; PG8_LDA(At, 0, 0); PG8_STAGE(PG8_SA(1, 1), a1 + hsA, voffA);
;             PG8_WAIT_V(8); PG8_WAIT_L(0); PG8_BAR; PG8_MMA(0, 0, At, B0); PG8_MMA(0, 1, At, B1); PG8_BAR; PG8_SCHED;
;             PG8_LDA(At, 0, 1); PG8_STAGE(PG8_SB(0, 0), b2, voffB); PG8_STAGE(PG8_SB(0, 1), b2 + hsB, voffB); PG8_STAGE(PG8_SA(0, 0), a2, voffA);
;             PG8_WAIT_V(8); PG8_WAIT_L(0); PG8_BAR; PG8_MMA(1, 0, At, B0); PG8_MMA(1, 1, At, B1); PG8_BAR; PG8_SCHED;
.LBB0_419:
	ds_read_b128 v[130:133], v194
	ds_read_b128 v[160:163], v194 offset:1024
	ds_read_b128 v[164:167], v194 offset:2048
	ds_read_b128 v[168:171], v194 offset:3072
	ds_read_b128 v[172:175], v195
	ds_read_b128 v[176:179], v195 offset:1024
	s_waitcnt vmcnt(0)
	ds_read_b128 v[200:203], v195 offset:2048
	ds_read_b128 v[204:207], v195 offset:3072
	s_add_u32 s12, s8, 0xfffc0080
	s_addc_u32 s13, s9, -1
	s_cmp_eq_u32 s43, 12
	s_cselect_b32 s15, s7, s13
	s_cselect_b32 s14, s33, s12
	s_cselect_b32 s13, s39, s42
	s_cselect_b32 s12, s40, s41
	v_lshl_add_u64 v[180:181], s[8:9], 0, v[152:153]
	s_add_i32 m0, s17, 0xc000
	ds_read_b128 v[208:211], v196
	ds_read_b128 v[212:215], v196 offset:1024
	ds_read_b128 v[216:219], v196 offset:2048
	ds_read_b128 v[220:223], v196 offset:3072
	ds_read_b128 v[224:227], v196 offset:4096
	ds_read_b128 v[228:231], v196 offset:5120
	ds_read_b128 v[232:235], v196 offset:6144
	ds_read_b128 v[236:239], v196 offset:7168
	global_load_lds_dwordx4 v[180:181], off
	v_lshl_add_u64 v[180:181], s[8:9], 0, v[154:155]
	s_add_i32 m0, s17, 0xe000
	s_nop 0
	global_load_lds_dwordx4 v[180:181], off
	s_waitcnt vmcnt(8)
	s_waitcnt lgkmcnt(0)
	s_barrier
	s_waitcnt lgkmcnt(0)
	v_mfma_f32_16x16x32_bf16 v[118:121], v[130:133], v[208:211], v[118:121]
	v_mfma_f32_16x16x32_bf16 v[126:129], v[164:167], v[208:211], v[126:129]
	v_mfma_f32_16x16x32_bf16 v[106:109], v[130:133], v[216:219], v[106:109]
	v_mfma_f32_16x16x32_bf16 v[110:113], v[164:167], v[216:219], v[110:113]
	v_mfma_f32_16x16x32_bf16 v[90:93], v[130:133], v[224:227], v[90:93]
	v_mfma_f32_16x16x32_bf16 v[94:97], v[164:167], v[224:227], v[94:97]
	v_mfma_f32_16x16x32_bf16 v[74:77], v[130:133], v[232:235], v[74:77]
	v_mfma_f32_16x16x32_bf16 v[78:81], v[164:167], v[232:235], v[78:81]
	v_mfma_f32_16x16x32_bf16 v[118:121], v[160:163], v[212:215], v[118:121]
	v_mfma_f32_16x16x32_bf16 v[126:129], v[168:171], v[212:215], v[126:129]
	v_mfma_f32_16x16x32_bf16 v[106:109], v[160:163], v[220:223], v[106:109]
	v_mfma_f32_16x16x32_bf16 v[110:113], v[168:171], v[220:223], v[110:113]
	v_mfma_f32_16x16x32_bf16 v[90:93], v[160:163], v[228:231], v[90:93]
	v_mfma_f32_16x16x32_bf16 v[94:97], v[168:171], v[228:231], v[94:97]
	v_mfma_f32_16x16x32_bf16 v[74:77], v[160:163], v[236:239], v[74:77]
	v_mfma_f32_16x16x32_bf16 v[78:81], v[168:171], v[236:239], v[78:81]
	v_mfma_f32_16x16x32_bf16 v[114:117], v[172:175], v[208:211], v[114:117]
	v_mfma_f32_16x16x32_bf16 v[122:125], v[200:203], v[208:211], v[122:125]
	v_mfma_f32_16x16x32_bf16 v[98:101], v[172:175], v[216:219], v[98:101]
	v_mfma_f32_16x16x32_bf16 v[102:105], v[200:203], v[216:219], v[102:105]
	v_mfma_f32_16x16x32_bf16 v[82:85], v[172:175], v[224:227], v[82:85]
	v_mfma_f32_16x16x32_bf16 v[86:89], v[200:203], v[224:227], v[86:89]
	v_mfma_f32_16x16x32_bf16 v[66:69], v[172:175], v[232:235], v[66:69]
	v_mfma_f32_16x16x32_bf16 v[70:73], v[200:203], v[232:235], v[70:73]
	v_mfma_f32_16x16x32_bf16 v[114:117], v[176:179], v[212:215], v[114:117]
	v_mfma_f32_16x16x32_bf16 v[122:125], v[204:207], v[212:215], v[122:125]
	v_mfma_f32_16x16x32_bf16 v[98:101], v[176:179], v[220:223], v[98:101]
	v_mfma_f32_16x16x32_bf16 v[102:105], v[204:207], v[220:223], v[102:105]
	v_mfma_f32_16x16x32_bf16 v[82:85], v[176:179], v[228:231], v[82:85]
	v_mfma_f32_16x16x32_bf16 v[86:89], v[204:207], v[228:231], v[86:89]
	v_mfma_f32_16x16x32_bf16 v[66:69], v[176:179], v[236:239], v[66:69]
	v_mfma_f32_16x16x32_bf16 v[70:73], v[204:207], v[236:239], v[70:73]
	s_barrier
	s_add_i32 s44, s31, s16
	v_lshl_add_u64 v[180:181], s[12:13], 0, v[136:137]
	s_mov_b32 m0, s44
	ds_read_b128 v[208:211], v196 offset:16384
	ds_read_b128 v[212:215], v196 offset:17408
	ds_read_b128 v[216:219], v196 offset:18432
	ds_read_b128 v[220:223], v196 offset:19456
	ds_read_b128 v[224:227], v196 offset:20480
	ds_read_b128 v[228:231], v196 offset:21504
	ds_read_b128 v[232:235], v196 offset:22528
	ds_read_b128 v[236:239], v196 offset:23552
	global_load_lds_dwordx4 v[180:181], off
	s_add_i32 m0, s44, 0x2000
	s_add_u32 s44, s12, 0x40000
	v_lshl_add_u64 v[240:241], s[12:13], 0, v[140:141]
	s_addc_u32 s45, s13, 0
	s_add_i32 s46, s34, s16
	global_load_lds_dwordx4 v[240:241], off
	v_lshl_add_u64 v[242:243], s[44:45], 0, v[136:137]
	s_mov_b32 m0, s46
	v_lshl_add_u64 v[244:245], s[14:15], 0, v[138:139]
	global_load_lds_dwordx4 v[242:243], off
	v_lshl_add_u64 v[242:243], s[44:45], 0, v[140:141]
	s_add_i32 m0, s46, 0x2000
	s_nop 0
	global_load_lds_dwordx4 v[242:243], off
	v_lshl_add_u64 v[242:243], s[14:15], 0, v[134:135]
	s_mov_b32 m0, s17
	s_nop 0
	global_load_lds_dwordx4 v[242:243], off
	s_mov_b32 m0, s18
	s_nop 0
	global_load_lds_dwordx4 v[244:245], off
	s_waitcnt vmcnt(8)
	s_waitcnt lgkmcnt(0)
	s_barrier
; #define PG8_STAGE(bufoff, gbase, voff) do { _Pragma("unroll") for (int _i = 0; _i < 2; ++_i) \
;         __builtin_amdgcn_global_load_lds((const unsigned*)((const char*)(gbase) + (voff)[_i]), (LAS unsigned*)(lds + (bufoff) + ldsw + _i * 8192), 16, 0, 0); } while (0)
; #define PG8_LDA(dst, b, h) do { _Pragma("unroll") for (int m = 0; m < 4; ++m) _Pragma("unroll") for (int k = 0; k < 2; ++k) dst[m][k] = *(const LAS bf16x8*)(lds + PG8_SA(b, h) + aoff + m * 2048 + k * 1024); } while (0)
; #define PG8_LDB(dst, b, h) do { _Pragma("unroll") for (int n = 0; n < 2; ++n) _Pragma("unroll") for (int k = 0; k < 2; ++k) dst[n][k] = *(const LAS bf16x8*)(lds + PG8_SB(b, h) + boff + n * 2048 + k * 1024); } while (0)
; #define PG8_MMA(ai, bj, At, Bt) do { __builtin_amdgcn_s_setprio(1); _Pragma("unroll") for (int m = 0; m < 4; ++m) _Pragma("unroll") for (int n = 0; n < 2; ++n) _Pragma("unroll") for (int k = 0; k < 2; ++k) \
;         acc[ai][bj][m][n] = __builtin_amdgcn_mfma_f32_16x16x32_bf16(Bt[n][k], At[m][k], acc[ai][bj][m][n], 0, 0, 0); __builtin_amdgcn_s_setprio(0); } while (0)
; #define PG8_WAIT_V(n) asm volatile("s_waitcnt vmcnt(" #n ")" ::: "memory")
; #define PG8_WAIT_L(n) asm volatile("s_waitcnt lgkmcnt(" #n ")" ::: "memory")
; #define PG8_BAR __builtin_amdgcn_s_barrier()
; #define PG8_SCHED __builtin_amdgcn_sched_barrier(0)
; template <class Epi, bool ALIGN_EPI>
; __device__ __forceinline__ void gemm_phase(LAS unsigned char* lds, const Gemm g, const StaticOrder& S, const Epi& E) {
;     ...
;             PG8_WAIT_V(8); PG8_WAIT_L(0); PG8_BAR; PG8_MMA(1, 0, At, B0); PG8_MMA(1, 1, At, B1); PG8_BAR; PG8_SCHED;
;             PG8_LDB(B0, 1, 0); PG8_LDB(B1, 1, 1); PG8_SCHED; PG8_LDA(At, 1, 0); PG8_STAGE(PG8_SA(0, 1), a2 + hsA, voffA);
;             PG8_WAIT_V(8); PG8_WAIT_L(0); PG8_BAR; PG8_MMA(0, 0, At, B0); PG8_MMA(0, 1, At, B1); PG8_BAR; PG8_SCHED;
	s_waitcnt lgkmcnt(0)
	v_mfma_f32_16x16x32_bf16 v[58:61], v[130:133], v[208:211], v[58:61]
	v_mfma_f32_16x16x32_bf16 v[62:65], v[164:167], v[208:211], v[62:65]
	v_mfma_f32_16x16x32_bf16 v[42:45], v[130:133], v[216:219], v[42:45]
	v_mfma_f32_16x16x32_bf16 v[46:49], v[164:167], v[216:219], v[46:49]
	v_mfma_f32_16x16x32_bf16 v[26:29], v[130:133], v[224:227], v[26:29]
	v_mfma_f32_16x16x32_bf16 v[30:33], v[164:167], v[224:227], v[30:33]
	v_mfma_f32_16x16x32_bf16 v[10:13], v[130:133], v[232:235], v[10:13]
	v_mfma_f32_16x16x32_bf16 v[14:17], v[164:167], v[232:235], v[14:17]
	v_mfma_f32_16x16x32_bf16 v[58:61], v[160:163], v[212:215], v[58:61]
	v_mfma_f32_16x16x32_bf16 v[62:65], v[168:171], v[212:215], v[62:65]
	v_mfma_f32_16x16x32_bf16 v[42:45], v[160:163], v[220:223], v[42:45]
	v_mfma_f32_16x16x32_bf16 v[46:49], v[168:171], v[220:223], v[46:49]
	v_mfma_f32_16x16x32_bf16 v[26:29], v[160:163], v[228:231], v[26:29]
	v_mfma_f32_16x16x32_bf16 v[30:33], v[168:171], v[228:231], v[30:33]
	v_mfma_f32_16x16x32_bf16 v[10:13], v[160:163], v[236:239], v[10:13]
	v_mfma_f32_16x16x32_bf16 v[14:17], v[168:171], v[236:239], v[14:17]
	v_mfma_f32_16x16x32_bf16 v[50:53], v[172:175], v[208:211], v[50:53]
	v_mfma_f32_16x16x32_bf16 v[54:57], v[200:203], v[208:211], v[54:57]
	v_mfma_f32_16x16x32_bf16 v[34:37], v[172:175], v[216:219], v[34:37]
	v_mfma_f32_16x16x32_bf16 v[38:41], v[200:203], v[216:219], v[38:41]
	v_mfma_f32_16x16x32_bf16 v[18:21], v[172:175], v[224:227], v[18:21]
	v_mfma_f32_16x16x32_bf16 v[22:25], v[200:203], v[224:227], v[22:25]
	v_mfma_f32_16x16x32_bf16 v[2:5], v[172:175], v[232:235], v[2:5]
	v_mfma_f32_16x16x32_bf16 v[6:9], v[200:203], v[232:235], v[6:9]
	v_mfma_f32_16x16x32_bf16 v[50:53], v[176:179], v[212:215], v[50:53]
	v_mfma_f32_16x16x32_bf16 v[54:57], v[204:207], v[212:215], v[54:57]
	v_mfma_f32_16x16x32_bf16 v[34:37], v[176:179], v[220:223], v[34:37]
	v_mfma_f32_16x16x32_bf16 v[38:41], v[204:207], v[220:223], v[38:41]
	v_mfma_f32_16x16x32_bf16 v[18:21], v[176:179], v[228:231], v[18:21]
	v_mfma_f32_16x16x32_bf16 v[22:25], v[204:207], v[228:231], v[22:25]
	v_mfma_f32_16x16x32_bf16 v[2:5], v[176:179], v[236:239], v[2:5]
	v_mfma_f32_16x16x32_bf16 v[6:9], v[204:207], v[236:239], v[6:9]
	s_barrier
	s_add_i32 s44, 0, 0x18000
	v_add_u32_e32 v142, s44, v145
	s_add_i32 s45, 0, 0x1c000
	ds_read_b128 v[130:133], v142
	ds_read_b128 v[160:163], v142 offset:1024
	ds_read_b128 v[164:167], v142 offset:2048
	ds_read_b128 v[168:171], v142 offset:3072
	v_add_u32_e32 v142, s45, v145
	ds_read_b128 v[172:175], v142
	ds_read_b128 v[176:179], v142 offset:1024
	ds_read_b128 v[200:203], v142 offset:2048
	ds_read_b128 v[204:207], v142 offset:3072
	s_add_u32 s14, s14, 0x40000
	s_addc_u32 s15, s15, 0
	s_mov_b32 m0, s19
	v_lshl_add_u64 v[246:247], s[14:15], 0, v[134:135]
	ds_read_b128 v[208:211], v196 offset:32768
	ds_read_b128 v[212:215], v196 offset:33792
	ds_read_b128 v[216:219], v196 offset:34816
	ds_read_b128 v[220:223], v196 offset:35840
	ds_read_b128 v[224:227], v196 offset:36864
	ds_read_b128 v[228:231], v196 offset:37888
	ds_read_b128 v[232:235], v196 offset:38912
	ds_read_b128 v[236:239], v196 offset:39936
	global_load_lds_dwordx4 v[246:247], off
	v_lshl_add_u64 v[246:247], s[14:15], 0, v[138:139]
	s_mov_b32 m0, s20
	s_nop 0
	global_load_lds_dwordx4 v[246:247], off
	s_waitcnt vmcnt(8)
	s_waitcnt lgkmcnt(0)
	s_barrier
	s_waitcnt lgkmcnt(0)
	v_mfma_f32_16x16x32_bf16 v[118:121], v[130:133], v[208:211], v[118:121]
	v_mfma_f32_16x16x32_bf16 v[126:129], v[164:167], v[208:211], v[126:129]
	v_mfma_f32_16x16x32_bf16 v[106:109], v[130:133], v[216:219], v[106:109]
	v_mfma_f32_16x16x32_bf16 v[110:113], v[164:167], v[216:219], v[110:113]
	v_mfma_f32_16x16x32_bf16 v[90:93], v[130:133], v[224:227], v[90:93]
	v_mfma_f32_16x16x32_bf16 v[94:97], v[164:167], v[224:227], v[94:97]
	v_mfma_f32_16x16x32_bf16 v[74:77], v[130:133], v[232:235], v[74:77]
	v_mfma_f32_16x16x32_bf16 v[78:81], v[164:167], v[232:235], v[78:81]
	v_mfma_f32_16x16x32_bf16 v[118:121], v[160:163], v[212:215], v[118:121]
	v_mfma_f32_16x16x32_bf16 v[126:129], v[168:171], v[212:215], v[126:129]
	v_mfma_f32_16x16x32_bf16 v[106:109], v[160:163], v[220:223], v[106:109]
	v_mfma_f32_16x16x32_bf16 v[110:113], v[168:171], v[220:223], v[110:113]
	v_mfma_f32_16x16x32_bf16 v[90:93], v[160:163], v[228:231], v[90:93]
	v_mfma_f32_16x16x32_bf16 v[94:97], v[168:171], v[228:231], v[94:97]
	v_mfma_f32_16x16x32_bf16 v[74:77], v[160:163], v[236:239], v[74:77]
	v_mfma_f32_16x16x32_bf16 v[78:81], v[168:171], v[236:239], v[78:81]
	v_mfma_f32_16x16x32_bf16 v[114:117], v[172:175], v[208:211], v[114:117]
	v_mfma_f32_16x16x32_bf16 v[122:125], v[200:203], v[208:211], v[122:125]
	v_mfma_f32_16x16x32_bf16 v[98:101], v[172:175], v[216:219], v[98:101]
	v_mfma_f32_16x16x32_bf16 v[102:105], v[200:203], v[216:219], v[102:105]
	v_mfma_f32_16x16x32_bf16 v[82:85], v[172:175], v[224:227], v[82:85]
	v_mfma_f32_16x16x32_bf16 v[86:89], v[200:203], v[224:227], v[86:89]
	v_mfma_f32_16x16x32_bf16 v[66:69], v[172:175], v[232:235], v[66:69]
	v_mfma_f32_16x16x32_bf16 v[70:73], v[200:203], v[232:235], v[70:73]
	v_mfma_f32_16x16x32_bf16 v[114:117], v[176:179], v[212:215], v[114:117]
	v_mfma_f32_16x16x32_bf16 v[122:125], v[204:207], v[212:215], v[122:125]
	v_mfma_f32_16x16x32_bf16 v[98:101], v[176:179], v[220:223], v[98:101]
	v_mfma_f32_16x16x32_bf16 v[102:105], v[204:207], v[220:223], v[102:105]
	v_mfma_f32_16x16x32_bf16 v[82:85], v[176:179], v[228:231], v[82:85]
	v_mfma_f32_16x16x32_bf16 v[86:89], v[204:207], v[228:231], v[86:89]
	v_mfma_f32_16x16x32_bf16 v[66:69], v[176:179], v[236:239], v[66:69]
	v_mfma_f32_16x16x32_bf16 v[70:73], v[204:207], v[236:239], v[70:73]
	s_barrier
; #define PG8_STAGE(bufoff, gbase, voff) do { _Pragma("unroll") for (int _i = 0; _i < 2; ++_i) \
;         __builtin_amdgcn_global_load_lds((const unsigned*)((const char*)(gbase) + (voff)[_i]), (LAS unsigned*)(lds + (bufoff) + ldsw + _i * 8192), 16, 0, 0); } while (0)
; #define PG8_LDA(dst, b, h) do { _Pragma("unroll") for (int m = 0; m < 4; ++m) _Pragma("unroll") for (int k = 0; k < 2; ++k) dst[m][k] = *(const LAS bf16x8*)(lds + PG8_SA(b, h) + aoff + m * 2048 + k * 1024); } while (0)
; #define PG8_MMA(ai, bj, At, Bt) do { __builtin_amdgcn_s_setprio(1); _Pragma("unroll") for (int m = 0; m < 4; ++m) _Pragma("unroll") for (int n = 0; n < 2; ++n) _Pragma("unroll") for (int k = 0; k < 2; ++k) \
;         acc[ai][bj][m][n] = __builtin_amdgcn_mfma_f32_16x16x32_bf16(Bt[n][k], At[m][k], acc[ai][bj][m][n], 0, 0, 0); __builtin_amdgcn_s_setprio(0); } while (0)
; #define PG8_WAIT_V(n) asm volatile("s_waitcnt vmcnt(" #n ")" ::: "memory")
; #define PG8_WAIT_L(n) asm volatile("s_waitcnt lgkmcnt(" #n ")" ::: "memory")
; #define PG8_BAR __builtin_amdgcn_s_barrier()
; #define PG8_SCHED __builtin_amdgcn_sched_barrier(0)
; template <class Epi, bool ALIGN_EPI>
; __device__ __forceinline__ void gemm_phase(LAS unsigned char* lds, const Gemm g, const StaticOrder& S, const Epi& E) {
;     ...
;         for (int t = 0; t < nt; t += 2) {
;             const bool last = (t == nt - 2);
;             const char* a1 = cA + (size_t)(t + 1) * kstepA;
;             const char* a2 = last ? nA : cA + (size_t)(t + 2) * kstepA; const char* b2 = last ? nB : cB + (size_t)(t + 2) * kstep;
;     ...
;             PG8_LDA(At, 1, 1); PG8_STAGE(PG8_SB(1, 0), b3, voffB); PG8_STAGE(PG8_SB(1, 1), b3 + hsB, voffB); PG8_STAGE(PG8_SA(1, 0), a3, voffA);
;             PG8_WAIT_V(8); PG8_WAIT_L(0); PG8_BAR; PG8_MMA(1, 0, At, B0); PG8_MMA(1, 1, At, B1); PG8_BAR; PG8_SCHED;
;         }
	s_add_i32 s14, s44, s16
	v_lshl_add_u64 v[180:181], v[180:181], 0, s[96:97]
	s_mov_b32 m0, s14
	ds_read_b128 v[208:211], v196 offset:49152
	ds_read_b128 v[212:215], v196 offset:50176
	ds_read_b128 v[216:219], v196 offset:51200
	ds_read_b128 v[220:223], v196 offset:52224
	ds_read_b128 v[224:227], v196 offset:53248
	ds_read_b128 v[228:231], v196 offset:54272
	ds_read_b128 v[232:235], v196 offset:55296
	ds_read_b128 v[236:239], v196 offset:56320
	global_load_lds_dwordx4 v[180:181], off
	s_add_i32 m0, s14, 0x2000
	s_add_u32 s12, s12, 0x40080
	v_lshl_add_u64 v[180:181], v[240:241], 0, s[96:97]
	s_addc_u32 s13, s13, 0
	s_add_i32 s14, s45, s16
	global_load_lds_dwordx4 v[180:181], off
	v_lshl_add_u64 v[180:181], s[12:13], 0, v[136:137]
	s_mov_b32 m0, s14
	s_nop 0
	global_load_lds_dwordx4 v[180:181], off
	v_lshl_add_u64 v[180:181], s[12:13], 0, v[140:141]
	s_add_i32 m0, s14, 0x2000
	s_nop 0
	global_load_lds_dwordx4 v[180:181], off
	v_lshl_add_u64 v[180:181], v[242:243], 0, s[96:97]
	s_mov_b32 m0, s23
	s_nop 0
	global_load_lds_dwordx4 v[180:181], off
	v_lshl_add_u64 v[180:181], v[244:245], 0, s[96:97]
	s_mov_b32 m0, s24
	s_nop 0
	global_load_lds_dwordx4 v[180:181], off
	s_waitcnt vmcnt(8)
	s_waitcnt lgkmcnt(0)
	s_barrier
	s_waitcnt lgkmcnt(0)
	v_mfma_f32_16x16x32_bf16 v[58:61], v[130:133], v[208:211], v[58:61]
	v_mfma_f32_16x16x32_bf16 v[62:65], v[164:167], v[208:211], v[62:65]
	v_mfma_f32_16x16x32_bf16 v[42:45], v[130:133], v[216:219], v[42:45]
	v_mfma_f32_16x16x32_bf16 v[46:49], v[164:167], v[216:219], v[46:49]
	v_mfma_f32_16x16x32_bf16 v[26:29], v[130:133], v[224:227], v[26:29]
	v_mfma_f32_16x16x32_bf16 v[30:33], v[164:167], v[224:227], v[30:33]
	v_mfma_f32_16x16x32_bf16 v[10:13], v[130:133], v[232:235], v[10:13]
	v_mfma_f32_16x16x32_bf16 v[14:17], v[164:167], v[232:235], v[14:17]
	v_mfma_f32_16x16x32_bf16 v[58:61], v[160:163], v[212:215], v[58:61]
	v_mfma_f32_16x16x32_bf16 v[62:65], v[168:171], v[212:215], v[62:65]
	v_mfma_f32_16x16x32_bf16 v[42:45], v[160:163], v[220:223], v[42:45]
	v_mfma_f32_16x16x32_bf16 v[46:49], v[168:171], v[220:223], v[46:49]
	v_mfma_f32_16x16x32_bf16 v[26:29], v[160:163], v[228:231], v[26:29]
	v_mfma_f32_16x16x32_bf16 v[30:33], v[168:171], v[228:231], v[30:33]
	v_mfma_f32_16x16x32_bf16 v[10:13], v[160:163], v[236:239], v[10:13]
	v_mfma_f32_16x16x32_bf16 v[14:17], v[168:171], v[236:239], v[14:17]
	v_mfma_f32_16x16x32_bf16 v[50:53], v[172:175], v[208:211], v[50:53]
	v_mfma_f32_16x16x32_bf16 v[54:57], v[200:203], v[208:211], v[54:57]
	v_mfma_f32_16x16x32_bf16 v[34:37], v[172:175], v[216:219], v[34:37]
	v_mfma_f32_16x16x32_bf16 v[38:41], v[200:203], v[216:219], v[38:41]
	v_mfma_f32_16x16x32_bf16 v[18:21], v[172:175], v[224:227], v[18:21]
	v_mfma_f32_16x16x32_bf16 v[22:25], v[200:203], v[224:227], v[22:25]
	v_mfma_f32_16x16x32_bf16 v[2:5], v[172:175], v[232:235], v[2:5]
	v_mfma_f32_16x16x32_bf16 v[6:9], v[200:203], v[232:235], v[6:9]
	v_mfma_f32_16x16x32_bf16 v[50:53], v[176:179], v[212:215], v[50:53]
	v_mfma_f32_16x16x32_bf16 v[54:57], v[204:207], v[212:215], v[54:57]
	v_mfma_f32_16x16x32_bf16 v[34:37], v[176:179], v[220:223], v[34:37]
	v_mfma_f32_16x16x32_bf16 v[38:41], v[204:207], v[220:223], v[38:41]
	v_mfma_f32_16x16x32_bf16 v[18:21], v[176:179], v[228:231], v[18:21]
	v_mfma_f32_16x16x32_bf16 v[22:25], v[204:207], v[228:231], v[22:25]
	v_mfma_f32_16x16x32_bf16 v[2:5], v[176:179], v[236:239], v[2:5]
	v_mfma_f32_16x16x32_bf16 v[6:9], v[204:207], v[236:239], v[6:9]
	s_add_i32 s43, s43, 2
	s_add_u32 s8, s8, 0x100
	s_addc_u32 s9, s9, 0
	s_add_u32 s41, s41, 0x100
	s_addc_u32 s42, s42, 0
	s_cmp_gt_u32 s43, 13
	s_barrier
	s_cbranch_scc0 .LBB0_419
	s_and_b64 vcc, exec, s[86:87]
	s_cbranch_vccz .LBB0_422
	s_barrier

; #define PG8_STAGE(bufoff, gbase, voff) do { _Pragma("unroll") for (int _i = 0; _i < 2; ++_i) \
;         __builtin_amdgcn_global_load_lds((const unsigned*)((const char*)(gbase) + (voff)[_i]), (LAS unsigned*)(lds + (bufoff) + ldsw + _i * 8192), 16, 0, 0); } while (0)
; #define PG8_LDA(dst, b, h) do { _Pragma("unroll") for (int m = 0; m < 4; ++m) _Pragma("unroll") for (int k = 0; k < 2; ++k) dst[m][k] = *(const LAS bf16x8*)(lds + PG8_SA(b, h) + aoff + m * 2048 + k * 1024); } while (0)
; #define PG8_LDB(dst, b, h) do { _Pragma("unroll") for (int n = 0; n < 2; ++n) _Pragma("unroll") for (int k = 0; k < 2; ++k) dst[n][k] = *(const LAS bf16x8*)(lds + PG8_SB(b, h) + boff + n * 2048 + k * 1024); } while (0)
; #define PG8_MMA(ai, bj, At, Bt) do { __builtin_amdgcn_s_setprio(1); _Pragma("unroll") for (int m = 0; m < 4; ++m) _Pragma("unroll") for (int n = 0; n < 2; ++n) _Pragma("unroll") for (int k = 0; k < 2; ++k) \
;         acc[ai][bj][m][n] = __builtin_amdgcn_mfma_f32_16x16x32_bf16(Bt[n][k], At[m][k], acc[ai][bj][m][n], 0, 0, 0); __builtin_amdgcn_s_setprio(0); } while (0)
; #define PG8_WAIT_V(n) asm volatile("s_waitcnt vmcnt(" #n ")" ::: "memory")
; #define PG8_WAIT_L(n) asm volatile("s_waitcnt lgkmcnt(" #n ")" ::: "memory")
; #define PG8_BAR __builtin_amdgcn_s_barrier()
; #define PG8_SCHED __builtin_amdgcn_sched_barrier(0)
; template <class Epi, bool ALIGN_EPI>
; __device__ __forceinline__ void gemm_phase(LAS unsigned char* lds, const Gemm g, const StaticOrder& S, const Epi& E) {
;     ...
;         for (int t = 0; t < nt; t += 2) {
;             const bool last = (t == nt - 2);
;             const char* a1 = cA + (size_t)(t + 1) * kstepA;
;             const char* a2 = last ? nA : cA + (size_t)(t + 2) * kstepA; const char* b2 = last ? nB : cB + (size_t)(t + 2) * kstep;
;             const char* a3 = a2 + kstepA; const char* b3 = b2 + kstep;
;             PG8_LDB(B0, 0, 0); PG8_LDB(B1, 0, 1); PG8_SCHED; PG8_LDA(At, 0, 0); PG8_STAGE(PG8_SA(1, 1), a1 + hsA, voffA);
;             PG8_WAIT_V(8); PG8_WAIT_L(0); PG8_BAR; PG8_MMA(0, 0, At, B0); PG8_MMA(0, 1, At, B1); PG8_BAR; PG8_SCHED;
;             PG8_LDA(At, 0, 1); PG8_STAGE(PG8_SB(0, 0), b2, voffB); PG8_STAGE(PG8_SB(0, 1), b2 + hsB, voffB); PG8_STAGE(PG8_SA(0, 0), a2, voffA);
;             PG8_WAIT_V(8); PG8_WAIT_L(0); PG8_BAR; PG8_MMA(1, 0, At, B0); PG8_MMA(1, 1, At, B1); PG8_BAR; PG8_SCHED;
.LBB0_670:
	ds_read_b128 v[148:151], v145
	ds_read_b128 v[152:155], v145 offset:1024
	ds_read_b128 v[156:159], v145 offset:2048
	ds_read_b128 v[160:163], v145 offset:3072
	ds_read_b128 v[164:167], v146
	ds_read_b128 v[168:171], v146 offset:1024
	ds_read_b128 v[172:175], v146 offset:2048
	ds_read_b128 v[176:179], v146 offset:3072
	s_add_i32 s55, s28, 2
	s_add_u32 s29, s26, 0xfffe0080
	s_addc_u32 s30, s27, -1
	s_cmp_eq_u32 s46, s28
	s_cselect_b32 s28, s52, s53
	s_cselect_b32 s31, s17, s30
	s_cselect_b32 s30, s19, s29
	s_cselect_b32 s29, s51, s54
	v_lshl_add_u64 v[212:213], s[26:27], 0, v[140:141]
	s_add_i32 m0, s38, 0xc000
	ds_read_b128 v[180:183], v147
	ds_read_b128 v[184:187], v147 offset:1024
	ds_read_b128 v[188:191], v147 offset:2048
	ds_read_b128 v[192:195], v147 offset:3072
	ds_read_b128 v[196:199], v147 offset:4096
	ds_read_b128 v[200:203], v147 offset:5120
	ds_read_b128 v[204:207], v147 offset:6144
	ds_read_b128 v[208:211], v147 offset:7168
	global_load_lds_dwordx4 v[212:213], off
	v_lshl_add_u64 v[212:213], s[26:27], 0, v[142:143]
	s_add_i32 m0, s38, 0xe000
	s_nop 0
	global_load_lds_dwordx4 v[212:213], off
	s_waitcnt vmcnt(8)
	s_waitcnt lgkmcnt(0)
	s_barrier
	s_waitcnt lgkmcnt(0)
	v_mfma_f32_16x16x32_bf16 v[126:129], v[148:151], v[180:183], v[126:129]
	v_mfma_f32_16x16x32_bf16 v[122:125], v[156:159], v[180:183], v[122:125]
	v_mfma_f32_16x16x32_bf16 v[110:113], v[148:151], v[188:191], v[110:113]
	v_mfma_f32_16x16x32_bf16 v[106:109], v[156:159], v[188:191], v[106:109]
	v_mfma_f32_16x16x32_bf16 v[94:97], v[148:151], v[196:199], v[94:97]
	v_mfma_f32_16x16x32_bf16 v[90:93], v[156:159], v[196:199], v[90:93]
	v_mfma_f32_16x16x32_bf16 v[78:81], v[148:151], v[204:207], v[78:81]
	v_mfma_f32_16x16x32_bf16 v[74:77], v[156:159], v[204:207], v[74:77]
	v_mfma_f32_16x16x32_bf16 v[126:129], v[152:155], v[184:187], v[126:129]
	v_mfma_f32_16x16x32_bf16 v[122:125], v[160:163], v[184:187], v[122:125]
	v_mfma_f32_16x16x32_bf16 v[110:113], v[152:155], v[192:195], v[110:113]
	v_mfma_f32_16x16x32_bf16 v[106:109], v[160:163], v[192:195], v[106:109]
	v_mfma_f32_16x16x32_bf16 v[94:97], v[152:155], v[200:203], v[94:97]
	v_mfma_f32_16x16x32_bf16 v[90:93], v[160:163], v[200:203], v[90:93]
	v_mfma_f32_16x16x32_bf16 v[78:81], v[152:155], v[208:211], v[78:81]
	v_mfma_f32_16x16x32_bf16 v[74:77], v[160:163], v[208:211], v[74:77]
	v_mfma_f32_16x16x32_bf16 v[118:121], v[164:167], v[180:183], v[118:121]
	v_mfma_f32_16x16x32_bf16 v[114:117], v[172:175], v[180:183], v[114:117]
	v_mfma_f32_16x16x32_bf16 v[102:105], v[164:167], v[188:191], v[102:105]
	v_mfma_f32_16x16x32_bf16 v[98:101], v[172:175], v[188:191], v[98:101]
	v_mfma_f32_16x16x32_bf16 v[86:89], v[164:167], v[196:199], v[86:89]
	v_mfma_f32_16x16x32_bf16 v[82:85], v[172:175], v[196:199], v[82:85]
	v_mfma_f32_16x16x32_bf16 v[70:73], v[164:167], v[204:207], v[70:73]
	v_mfma_f32_16x16x32_bf16 v[66:69], v[172:175], v[204:207], v[66:69]
	v_mfma_f32_16x16x32_bf16 v[118:121], v[168:171], v[184:187], v[118:121]
	v_mfma_f32_16x16x32_bf16 v[114:117], v[176:179], v[184:187], v[114:117]
	v_mfma_f32_16x16x32_bf16 v[102:105], v[168:171], v[192:195], v[102:105]
	v_mfma_f32_16x16x32_bf16 v[98:101], v[176:179], v[192:195], v[98:101]
	v_mfma_f32_16x16x32_bf16 v[86:89], v[168:171], v[200:203], v[86:89]
	v_mfma_f32_16x16x32_bf16 v[82:85], v[176:179], v[200:203], v[82:85]
	v_mfma_f32_16x16x32_bf16 v[70:73], v[168:171], v[208:211], v[70:73]
	v_mfma_f32_16x16x32_bf16 v[66:69], v[176:179], v[208:211], v[66:69]
	s_barrier
	s_add_i32 s56, s48, s36
	v_lshl_add_u64 v[212:213], s[28:29], 0, v[134:135]
	s_mov_b32 m0, s56
	ds_read_b128 v[180:183], v147 offset:16384
	ds_read_b128 v[184:187], v147 offset:17408
	ds_read_b128 v[188:191], v147 offset:18432
	ds_read_b128 v[192:195], v147 offset:19456
	ds_read_b128 v[196:199], v147 offset:20480
	ds_read_b128 v[200:203], v147 offset:21504
	ds_read_b128 v[204:207], v147 offset:22528
	ds_read_b128 v[208:211], v147 offset:23552
	global_load_lds_dwordx4 v[212:213], off
	s_add_i32 m0, s56, 0x2000
	s_add_u32 s56, s28, 0x10000
	v_lshl_add_u64 v[214:215], s[28:29], 0, v[130:131]
	s_addc_u32 s57, s29, 0
	s_add_i32 s58, s49, s36
	global_load_lds_dwordx4 v[214:215], off
	v_lshl_add_u64 v[216:217], s[56:57], 0, v[134:135]
	s_mov_b32 m0, s58
	v_lshl_add_u64 v[218:219], s[30:31], 0, v[132:133]
	global_load_lds_dwordx4 v[216:217], off
	v_lshl_add_u64 v[216:217], s[56:57], 0, v[130:131]
	s_add_i32 m0, s58, 0x2000
	s_nop 0
	global_load_lds_dwordx4 v[216:217], off
	v_lshl_add_u64 v[216:217], s[30:31], 0, v[136:137]
	s_mov_b32 m0, s38
	s_nop 0
	global_load_lds_dwordx4 v[216:217], off
	s_mov_b32 m0, s39
	s_nop 0
	global_load_lds_dwordx4 v[218:219], off
	s_waitcnt vmcnt(8)
	s_waitcnt lgkmcnt(0)
	s_barrier
; #define PG8_STAGE(bufoff, gbase, voff) do { _Pragma("unroll") for (int _i = 0; _i < 2; ++_i) \
;         __builtin_amdgcn_global_load_lds((const unsigned*)((const char*)(gbase) + (voff)[_i]), (LAS unsigned*)(lds + (bufoff) + ldsw + _i * 8192), 16, 0, 0); } while (0)
; #define PG8_LDA(dst, b, h) do { _Pragma("unroll") for (int m = 0; m < 4; ++m) _Pragma("unroll") for (int k = 0; k < 2; ++k) dst[m][k] = *(const LAS bf16x8*)(lds + PG8_SA(b, h) + aoff + m * 2048 + k * 1024); } while (0)
; #define PG8_LDB(dst, b, h) do { _Pragma("unroll") for (int n = 0; n < 2; ++n) _Pragma("unroll") for (int k = 0; k < 2; ++k) dst[n][k] = *(const LAS bf16x8*)(lds + PG8_SB(b, h) + boff + n * 2048 + k * 1024); } while (0)
; #define PG8_MMA(ai, bj, At, Bt) do { __builtin_amdgcn_s_setprio(1); _Pragma("unroll") for (int m = 0; m < 4; ++m) _Pragma("unroll") for (int n = 0; n < 2; ++n) _Pragma("unroll") for (int k = 0; k < 2; ++k) \
;         acc[ai][bj][m][n] = __builtin_amdgcn_mfma_f32_16x16x32_bf16(Bt[n][k], At[m][k], acc[ai][bj][m][n], 0, 0, 0); __builtin_amdgcn_s_setprio(0); } while (0)
; #define PG8_WAIT_V(n) asm volatile("s_waitcnt vmcnt(" #n ")" ::: "memory")
; #define PG8_WAIT_L(n) asm volatile("s_waitcnt lgkmcnt(" #n ")" ::: "memory")
; #define PG8_BAR __builtin_amdgcn_s_barrier()
; #define PG8_SCHED __builtin_amdgcn_sched_barrier(0)
; template <class Epi, bool ALIGN_EPI>
; __device__ __forceinline__ void gemm_phase(LAS unsigned char* lds, const Gemm g, const StaticOrder& S, const Epi& E) {
;     ...
;             PG8_WAIT_V(8); PG8_WAIT_L(0); PG8_BAR; PG8_MMA(1, 0, At, B0); PG8_MMA(1, 1, At, B1); PG8_BAR; PG8_SCHED;
;             PG8_LDB(B0, 1, 0); PG8_LDB(B1, 1, 1); PG8_SCHED; PG8_LDA(At, 1, 0); PG8_STAGE(PG8_SA(0, 1), a2 + hsA, voffA);
;             PG8_WAIT_V(8); PG8_WAIT_L(0); PG8_BAR; PG8_MMA(0, 0, At, B0); PG8_MMA(0, 1, At, B1); PG8_BAR; PG8_SCHED;
	s_waitcnt lgkmcnt(0)
	v_mfma_f32_16x16x32_bf16 v[62:65], v[148:151], v[180:183], v[62:65]
	v_mfma_f32_16x16x32_bf16 v[58:61], v[156:159], v[180:183], v[58:61]
	v_mfma_f32_16x16x32_bf16 v[46:49], v[148:151], v[188:191], v[46:49]
	v_mfma_f32_16x16x32_bf16 v[42:45], v[156:159], v[188:191], v[42:45]
	v_mfma_f32_16x16x32_bf16 v[30:33], v[148:151], v[196:199], v[30:33]
	v_mfma_f32_16x16x32_bf16 v[26:29], v[156:159], v[196:199], v[26:29]
	v_mfma_f32_16x16x32_bf16 v[14:17], v[148:151], v[204:207], v[14:17]
	v_mfma_f32_16x16x32_bf16 v[10:13], v[156:159], v[204:207], v[10:13]
	v_mfma_f32_16x16x32_bf16 v[62:65], v[152:155], v[184:187], v[62:65]
	v_mfma_f32_16x16x32_bf16 v[58:61], v[160:163], v[184:187], v[58:61]
	v_mfma_f32_16x16x32_bf16 v[46:49], v[152:155], v[192:195], v[46:49]
	v_mfma_f32_16x16x32_bf16 v[42:45], v[160:163], v[192:195], v[42:45]
	v_mfma_f32_16x16x32_bf16 v[30:33], v[152:155], v[200:203], v[30:33]
	v_mfma_f32_16x16x32_bf16 v[26:29], v[160:163], v[200:203], v[26:29]
	v_mfma_f32_16x16x32_bf16 v[14:17], v[152:155], v[208:211], v[14:17]
	v_mfma_f32_16x16x32_bf16 v[10:13], v[160:163], v[208:211], v[10:13]
	v_mfma_f32_16x16x32_bf16 v[54:57], v[164:167], v[180:183], v[54:57]
	v_mfma_f32_16x16x32_bf16 v[50:53], v[172:175], v[180:183], v[50:53]
	v_mfma_f32_16x16x32_bf16 v[38:41], v[164:167], v[188:191], v[38:41]
	v_mfma_f32_16x16x32_bf16 v[34:37], v[172:175], v[188:191], v[34:37]
	v_mfma_f32_16x16x32_bf16 v[22:25], v[164:167], v[196:199], v[22:25]
	v_mfma_f32_16x16x32_bf16 v[18:21], v[172:175], v[196:199], v[18:21]
	v_mfma_f32_16x16x32_bf16 v[6:9], v[164:167], v[204:207], v[6:9]
	v_mfma_f32_16x16x32_bf16 v[2:5], v[172:175], v[204:207], v[2:5]
	v_mfma_f32_16x16x32_bf16 v[54:57], v[168:171], v[184:187], v[54:57]
	v_mfma_f32_16x16x32_bf16 v[50:53], v[176:179], v[184:187], v[50:53]
	v_mfma_f32_16x16x32_bf16 v[38:41], v[168:171], v[192:195], v[38:41]
	v_mfma_f32_16x16x32_bf16 v[34:37], v[176:179], v[192:195], v[34:37]
	v_mfma_f32_16x16x32_bf16 v[22:25], v[168:171], v[200:203], v[22:25]
	v_mfma_f32_16x16x32_bf16 v[18:21], v[176:179], v[200:203], v[18:21]
	v_mfma_f32_16x16x32_bf16 v[6:9], v[168:171], v[208:211], v[6:9]
	v_mfma_f32_16x16x32_bf16 v[2:5], v[176:179], v[208:211], v[2:5]
	s_barrier
	s_add_i32 s56, 0, 0x18000
	s_add_i32 s57, 0, 0x1c000
	v_add_u32_e32 v160, s56, v144
	v_add_u32_e32 v176, s57, v144
	ds_read_b128 v[148:151], v160
	ds_read_b128 v[152:155], v160 offset:1024
	ds_read_b128 v[156:159], v160 offset:2048
	ds_read_b128 v[160:163], v160 offset:3072
	ds_read_b128 v[164:167], v176
	ds_read_b128 v[168:171], v176 offset:1024
	ds_read_b128 v[172:175], v176 offset:2048
	ds_read_b128 v[176:179], v176 offset:3072
	s_add_u32 s30, s30, 0x20000
	s_addc_u32 s31, s31, 0
	s_mov_b32 m0, s40
	v_lshl_add_u64 v[220:221], s[30:31], 0, v[136:137]
	ds_read_b128 v[180:183], v147 offset:32768
	ds_read_b128 v[184:187], v147 offset:33792
	ds_read_b128 v[188:191], v147 offset:34816
	ds_read_b128 v[192:195], v147 offset:35840
	ds_read_b128 v[196:199], v147 offset:36864
	ds_read_b128 v[200:203], v147 offset:37888
	ds_read_b128 v[204:207], v147 offset:38912
	ds_read_b128 v[208:211], v147 offset:39936
	global_load_lds_dwordx4 v[220:221], off
	v_lshl_add_u64 v[220:221], s[30:31], 0, v[132:133]
	s_mov_b32 m0, s41
	s_nop 0
	global_load_lds_dwordx4 v[220:221], off
	s_waitcnt vmcnt(8)
	s_waitcnt lgkmcnt(0)
	s_barrier
	s_waitcnt lgkmcnt(0)
	v_mfma_f32_16x16x32_bf16 v[126:129], v[148:151], v[180:183], v[126:129]
	v_mfma_f32_16x16x32_bf16 v[122:125], v[156:159], v[180:183], v[122:125]
	v_mfma_f32_16x16x32_bf16 v[110:113], v[148:151], v[188:191], v[110:113]
	v_mfma_f32_16x16x32_bf16 v[106:109], v[156:159], v[188:191], v[106:109]
	v_mfma_f32_16x16x32_bf16 v[94:97], v[148:151], v[196:199], v[94:97]
	v_mfma_f32_16x16x32_bf16 v[90:93], v[156:159], v[196:199], v[90:93]
	v_mfma_f32_16x16x32_bf16 v[78:81], v[148:151], v[204:207], v[78:81]
	v_mfma_f32_16x16x32_bf16 v[74:77], v[156:159], v[204:207], v[74:77]
	v_mfma_f32_16x16x32_bf16 v[126:129], v[152:155], v[184:187], v[126:129]
	v_mfma_f32_16x16x32_bf16 v[122:125], v[160:163], v[184:187], v[122:125]
	v_mfma_f32_16x16x32_bf16 v[110:113], v[152:155], v[192:195], v[110:113]
	v_mfma_f32_16x16x32_bf16 v[106:109], v[160:163], v[192:195], v[106:109]
	v_mfma_f32_16x16x32_bf16 v[94:97], v[152:155], v[200:203], v[94:97]
	v_mfma_f32_16x16x32_bf16 v[90:93], v[160:163], v[200:203], v[90:93]
	v_mfma_f32_16x16x32_bf16 v[78:81], v[152:155], v[208:211], v[78:81]
	v_mfma_f32_16x16x32_bf16 v[74:77], v[160:163], v[208:211], v[74:77]
	v_mfma_f32_16x16x32_bf16 v[118:121], v[164:167], v[180:183], v[118:121]
	v_mfma_f32_16x16x32_bf16 v[114:117], v[172:175], v[180:183], v[114:117]
	v_mfma_f32_16x16x32_bf16 v[102:105], v[164:167], v[188:191], v[102:105]
	v_mfma_f32_16x16x32_bf16 v[98:101], v[172:175], v[188:191], v[98:101]
	v_mfma_f32_16x16x32_bf16 v[86:89], v[164:167], v[196:199], v[86:89]
	v_mfma_f32_16x16x32_bf16 v[82:85], v[172:175], v[196:199], v[82:85]
	v_mfma_f32_16x16x32_bf16 v[70:73], v[164:167], v[204:207], v[70:73]
	v_mfma_f32_16x16x32_bf16 v[66:69], v[172:175], v[204:207], v[66:69]
	v_mfma_f32_16x16x32_bf16 v[118:121], v[168:171], v[184:187], v[118:121]
	v_mfma_f32_16x16x32_bf16 v[114:117], v[176:179], v[184:187], v[114:117]
	v_mfma_f32_16x16x32_bf16 v[102:105], v[168:171], v[192:195], v[102:105]
	v_mfma_f32_16x16x32_bf16 v[98:101], v[176:179], v[192:195], v[98:101]
	v_mfma_f32_16x16x32_bf16 v[86:89], v[168:171], v[200:203], v[86:89]
	v_mfma_f32_16x16x32_bf16 v[82:85], v[176:179], v[200:203], v[82:85]
	v_mfma_f32_16x16x32_bf16 v[70:73], v[168:171], v[208:211], v[70:73]
	v_mfma_f32_16x16x32_bf16 v[66:69], v[176:179], v[208:211], v[66:69]
	s_barrier
; #define PG8_STAGE(bufoff, gbase, voff) do { _Pragma("unroll") for (int _i = 0; _i < 2; ++_i) \
;         __builtin_amdgcn_global_load_lds((const unsigned*)((const char*)(gbase) + (voff)[_i]), (LAS unsigned*)(lds + (bufoff) + ldsw + _i * 8192), 16, 0, 0); } while (0)
; #define PG8_LDA(dst, b, h) do { _Pragma("unroll") for (int m = 0; m < 4; ++m) _Pragma("unroll") for (int k = 0; k < 2; ++k) dst[m][k] = *(const LAS bf16x8*)(lds + PG8_SA(b, h) + aoff + m * 2048 + k * 1024); } while (0)
; #define PG8_MMA(ai, bj, At, Bt) do { __builtin_amdgcn_s_setprio(1); _Pragma("unroll") for (int m = 0; m < 4; ++m) _Pragma("unroll") for (int n = 0; n < 2; ++n) _Pragma("unroll") for (int k = 0; k < 2; ++k) \
;         acc[ai][bj][m][n] = __builtin_amdgcn_mfma_f32_16x16x32_bf16(Bt[n][k], At[m][k], acc[ai][bj][m][n], 0, 0, 0); __builtin_amdgcn_s_setprio(0); } while (0)
; #define PG8_WAIT_V(n) asm volatile("s_waitcnt vmcnt(" #n ")" ::: "memory")
; #define PG8_WAIT_L(n) asm volatile("s_waitcnt lgkmcnt(" #n ")" ::: "memory")
; #define PG8_BAR __builtin_amdgcn_s_barrier()
; #define PG8_SCHED __builtin_amdgcn_sched_barrier(0)
; template <class Epi, bool ALIGN_EPI>
; __device__ __forceinline__ void gemm_phase(LAS unsigned char* lds, const Gemm g, const StaticOrder& S, const Epi& E) {
;     ...
;         for (int t = 0; t < nt; t += 2) {
;             const bool last = (t == nt - 2);
;             const char* a1 = cA + (size_t)(t + 1) * kstepA;
;             const char* a2 = last ? nA : cA + (size_t)(t + 2) * kstepA; const char* b2 = last ? nB : cB + (size_t)(t + 2) * kstep;
;     ...
;             PG8_LDA(At, 1, 1); PG8_STAGE(PG8_SB(1, 0), b3, voffB); PG8_STAGE(PG8_SB(1, 1), b3 + hsB, voffB); PG8_STAGE(PG8_SA(1, 0), a3, voffA);
;             PG8_WAIT_V(8); PG8_WAIT_L(0); PG8_BAR; PG8_MMA(1, 0, At, B0); PG8_MMA(1, 1, At, B1); PG8_BAR; PG8_SCHED;
;         }
	s_add_i32 s30, s56, s36
	v_lshl_add_u64 v[212:213], v[212:213], 0, s[8:9]
	s_mov_b32 m0, s30
	ds_read_b128 v[180:183], v147 offset:49152
	ds_read_b128 v[184:187], v147 offset:50176
	ds_read_b128 v[188:191], v147 offset:51200
	ds_read_b128 v[192:195], v147 offset:52224
	ds_read_b128 v[196:199], v147 offset:53248
	ds_read_b128 v[200:203], v147 offset:54272
	ds_read_b128 v[204:207], v147 offset:55296
	ds_read_b128 v[208:211], v147 offset:56320
	global_load_lds_dwordx4 v[212:213], off
	s_add_i32 m0, s30, 0x2000
	s_add_u32 s28, s28, 0x10080
	v_lshl_add_u64 v[212:213], v[214:215], 0, s[8:9]
	s_addc_u32 s29, s29, 0
	s_add_i32 s30, s57, s36
	global_load_lds_dwordx4 v[212:213], off
	v_lshl_add_u64 v[212:213], s[28:29], 0, v[134:135]
	s_mov_b32 m0, s30
	s_nop 0
	global_load_lds_dwordx4 v[212:213], off
	v_lshl_add_u64 v[212:213], s[28:29], 0, v[130:131]
	s_add_i32 m0, s30, 0x2000
	s_nop 0
	global_load_lds_dwordx4 v[212:213], off
	v_lshl_add_u64 v[212:213], v[216:217], 0, s[8:9]
	s_mov_b32 m0, s44
	s_nop 0
	global_load_lds_dwordx4 v[212:213], off
	v_lshl_add_u64 v[212:213], v[218:219], 0, s[8:9]
	s_mov_b32 m0, s45
	s_nop 0
	global_load_lds_dwordx4 v[212:213], off
	s_waitcnt vmcnt(8)
	s_waitcnt lgkmcnt(0)
	s_barrier
	s_waitcnt lgkmcnt(0)
	v_mfma_f32_16x16x32_bf16 v[62:65], v[148:151], v[180:183], v[62:65]
	v_mfma_f32_16x16x32_bf16 v[58:61], v[156:159], v[180:183], v[58:61]
	v_mfma_f32_16x16x32_bf16 v[46:49], v[148:151], v[188:191], v[46:49]
	v_mfma_f32_16x16x32_bf16 v[42:45], v[156:159], v[188:191], v[42:45]
	v_mfma_f32_16x16x32_bf16 v[30:33], v[148:151], v[196:199], v[30:33]
	v_mfma_f32_16x16x32_bf16 v[26:29], v[156:159], v[196:199], v[26:29]
	v_mfma_f32_16x16x32_bf16 v[14:17], v[148:151], v[204:207], v[14:17]
	v_mfma_f32_16x16x32_bf16 v[10:13], v[156:159], v[204:207], v[10:13]
	v_mfma_f32_16x16x32_bf16 v[62:65], v[152:155], v[184:187], v[62:65]
	v_mfma_f32_16x16x32_bf16 v[58:61], v[160:163], v[184:187], v[58:61]
	v_mfma_f32_16x16x32_bf16 v[46:49], v[152:155], v[192:195], v[46:49]
	v_mfma_f32_16x16x32_bf16 v[42:45], v[160:163], v[192:195], v[42:45]
	v_mfma_f32_16x16x32_bf16 v[30:33], v[152:155], v[200:203], v[30:33]
	v_mfma_f32_16x16x32_bf16 v[26:29], v[160:163], v[200:203], v[26:29]
	v_mfma_f32_16x16x32_bf16 v[14:17], v[152:155], v[208:211], v[14:17]
	v_mfma_f32_16x16x32_bf16 v[10:13], v[160:163], v[208:211], v[10:13]
	v_mfma_f32_16x16x32_bf16 v[54:57], v[164:167], v[180:183], v[54:57]
	v_mfma_f32_16x16x32_bf16 v[50:53], v[172:175], v[180:183], v[50:53]
	v_mfma_f32_16x16x32_bf16 v[38:41], v[164:167], v[188:191], v[38:41]
	v_mfma_f32_16x16x32_bf16 v[34:37], v[172:175], v[188:191], v[34:37]
	v_mfma_f32_16x16x32_bf16 v[22:25], v[164:167], v[196:199], v[22:25]
	v_mfma_f32_16x16x32_bf16 v[18:21], v[172:175], v[196:199], v[18:21]
	v_mfma_f32_16x16x32_bf16 v[6:9], v[164:167], v[204:207], v[6:9]
	v_mfma_f32_16x16x32_bf16 v[2:5], v[172:175], v[204:207], v[2:5]
	v_mfma_f32_16x16x32_bf16 v[54:57], v[168:171], v[184:187], v[54:57]
	v_mfma_f32_16x16x32_bf16 v[50:53], v[176:179], v[184:187], v[50:53]
	v_mfma_f32_16x16x32_bf16 v[38:41], v[168:171], v[192:195], v[38:41]
	v_mfma_f32_16x16x32_bf16 v[34:37], v[176:179], v[192:195], v[34:37]
	v_mfma_f32_16x16x32_bf16 v[22:25], v[168:171], v[200:203], v[22:25]
	v_mfma_f32_16x16x32_bf16 v[18:21], v[176:179], v[200:203], v[18:21]
	v_mfma_f32_16x16x32_bf16 v[6:9], v[168:171], v[208:211], v[6:9]
	v_mfma_f32_16x16x32_bf16 v[2:5], v[176:179], v[208:211], v[2:5]
	s_add_u32 s26, s26, 0x100
	s_addc_u32 s27, s27, 0
	s_add_u32 s53, s53, 0x100
	s_addc_u32 s54, s54, 0
	s_cmp_ge_i32 s55, s43
	s_mov_b32 s28, s55
	s_barrier
	s_cbranch_scc0 .LBB0_670

; #define WAIT_BAR(N) asm volatile("s_waitcnt vmcnt(" #N ") lgkmcnt(0)\n\ts_barrier":::"memory")
;   #define RESC() do{}while(0)
;   #define ROT() do{sl_prev=sl_cur;sl_cur=sl_next;sl_next=(sl_next==(NSLOT-1)*SLOTB)?0:sl_next+SLOTB;}while(0)
; template<int THRL> __device__ __forceinline__ void attn_unit(int b,int h,int qb,const bf16*Q,const bf16*__restrict__ K,const bf16*__restrict__ V,bf16*O,char*shm,float m2){
;     ...
;   int t=1;
;   for(;t+5<NT;t+=2){
;     STEP(pB0,pB1,pA0,pA1,t,true,true,true);     WAIT_BAR(2); RESC(); ROT();
;     STEP(pA0,pA1,pB0,pB1,t+1,true,true,true);   WAIT_BAR(2); RESC(); ROT();
.LBB0_829:
	v_add_u32_e32 v190, s17, v220
	ds_read_b64_tr_b16 v[230:231], v190 offset:24576
	ds_read_b64_tr_b16 v[232:233], v190 offset:25088
	s_waitcnt lgkmcnt(9)
	v_mfma_f32_32x32x16_bf16 v[114:129], v[98:101], v[174:177], v[50:65]
	v_exp_f32_e32 v78, v78
	v_add_f32_e32 v102, v82, v83
	v_add_f32_e32 v102, v84, v102
	v_add_f32_e32 v102, v85, v102
	v_add_f32_e32 v102, v86, v102
	v_add_f32_e32 v102, v87, v102
	v_cvt_pk_bf16_f32 v166, v82, v83
	v_cvt_pk_bf16_f32 v167, v84, v85
	ds_read_b64_tr_b16 v[82:83], v190 offset:28672
	ds_read_b64_tr_b16 v[84:85], v190 offset:29184
	v_add_f32_e32 v98, v88, v102
	v_add_f32_e32 v98, v89, v98
	v_add_f32_e32 v98, v90, v98
	v_add_f32_e32 v146, v91, v98
	s_waitcnt lgkmcnt(10)
	v_mfma_f32_32x32x16_bf16 v[98:113], v[182:185], v[174:177], v[50:65]
	v_exp_f32_e32 v79, v79
	v_cvt_pk_bf16_f32 v168, v86, v87
	v_cvt_pk_bf16_f32 v169, v88, v89
	ds_read_b64_tr_b16 v[86:87], v190 offset:25600
	ds_read_b64_tr_b16 v[88:89], v190 offset:26112
	v_add_f32_e32 v146, v92, v146
	v_add_f32_e32 v146, v93, v146
	v_add_f32_e32 v146, v94, v146
	v_add_f32_e32 v146, v95, v146
	v_cvt_pk_bf16_f32 v158, v90, v91
	v_cvt_pk_bf16_f32 v159, v92, v93
	s_waitcnt lgkmcnt(11)
	v_mfma_f32_32x32x16_bf16 v[114:129], v[186:189], v[170:173], v[114:129]
	v_exp_f32_e32 v80, v80
	ds_read_b64_tr_b16 v[90:91], v190 offset:29696
	ds_read_b64_tr_b16 v[92:93], v190 offset:30208
	s_waitcnt lgkmcnt(12)
	v_mfma_f32_32x32x16_bf16 v[98:113], v[178:181], v[170:173], v[98:113]
	v_exp_f32_e32 v81, v81
	v_add_f32_e32 v146, v96, v146
	v_add_f32_e32 v146, v97, v146
	v_add_f32_e32 v146, v66, v146
	v_add_f32_e32 v146, v67, v146
	v_cvt_pk_bf16_f32 v160, v94, v95
	v_cvt_pk_bf16_f32 v161, v96, v97
	ds_read_b64_tr_b16 v[94:95], v190 offset:26624
	ds_read_b64_tr_b16 v[96:97], v190 offset:27136
	s_waitcnt lgkmcnt(13)
	v_mfma_f32_32x32x16_bf16 v[114:129], v[142:145], v[162:165], v[114:129]
	v_add_f32_e32 v142, v68, v146
	v_add_f32_e32 v142, v69, v142
	v_add_f32_e32 v142, v70, v142
	v_add_f32_e32 v142, v71, v142
	v_cvt_pk_bf16_f32 v150, v66, v67
	v_cvt_pk_bf16_f32 v151, v68, v69
	ds_read_b64_tr_b16 v[66:67], v190 offset:30720
	ds_read_b64_tr_b16 v[68:69], v190 offset:31232
	s_waitcnt lgkmcnt(14)
	v_mfma_f32_32x32x16_bf16 v[98:113], v[138:141], v[162:165], v[98:113]
	v_add_f32_e32 v138, v72, v142
	v_add_f32_e32 v138, v73, v138
	v_add_f32_e32 v138, v74, v138
	v_add_f32_e32 v138, v75, v138
	v_cvt_pk_bf16_f32 v152, v70, v71
	v_cvt_pk_bf16_f32 v153, v72, v73
	ds_read_b64_tr_b16 v[70:71], v190 offset:27648
	ds_read_b64_tr_b16 v[72:73], v190 offset:28160
	s_waitcnt lgkmcnt(14)
	v_mfma_f32_32x32x16_bf16 v[114:129], v[134:137], v[154:157], v[114:129]
	v_add_f32_e32 v134, v76, v138
	v_add_f32_e32 v134, v77, v134
	v_add_f32_e32 v134, v78, v134
	v_add_f32_e32 v134, v79, v134
	v_cvt_pk_bf16_f32 v146, v74, v75
	v_cvt_pk_bf16_f32 v147, v76, v77
	ds_read_b64_tr_b16 v[74:75], v190 offset:31744
	ds_read_b64_tr_b16 v[76:77], v190 offset:32256
	v_mfma_f32_32x32x16_bf16 v[98:113], v[130:133], v[154:157], v[98:113]
	v_add_f32_e32 v130, v80, v134
	v_add_f32_e32 v130, v81, v130
	v_add_f32_e32 v130, 0, v130
	v_cvt_pk_bf16_f32 v148, v78, v79
	v_cvt_pk_bf16_f32 v149, v80, v81
	v_lshl_add_u64 v[78:79], v[214:215], 0, s[48:49]
	s_add_i32 s0, s16, s12
	s_mov_b32 s17, m0
	s_mov_b32 m0, s0
	s_nop 0
	global_load_lds_dwordx4 v[78:79], off
	s_mov_b32 m0, s17
	v_lshl_add_u64 v[78:79], v[216:217], 0, s[42:43]
	s_add_i32 s0, s15, s4
	s_mov_b32 s17, m0
	s_mov_b32 m0, s0
	s_nop 0
	global_load_lds_dwordx4 v[78:79], off
	s_mov_b32 m0, s17
	v_add_f32_e32 v190, v199, v130
	s_waitcnt lgkmcnt(14)
	v_mfma_f32_32x32x16_bf16 v[18:33], v[166:169], v[230:233], v[18:33]
	v_exp_f32_e32 v114, v114
	v_exp_f32_e32 v115, v115
	v_exp_f32_e32 v116, v116
	v_exp_f32_e32 v117, v117
	s_waitcnt lgkmcnt(12)
	v_mfma_f32_32x32x16_bf16 v[34:49], v[166:169], v[82:85], v[34:49]
	v_exp_f32_e32 v118, v118
	v_exp_f32_e32 v119, v119
	v_exp_f32_e32 v120, v120
	v_exp_f32_e32 v121, v121
	v_add_u32_e32 v82, s15, v219
	ds_read_b128 v[78:81], v82
	ds_read_b128 v[134:137], v82 offset:512
	s_waitcnt lgkmcnt(12)
	v_mfma_f32_32x32x16_bf16 v[18:33], v[158:161], v[86:89], v[18:33]
	v_exp_f32_e32 v122, v122
	v_exp_f32_e32 v123, v123
	v_exp_f32_e32 v124, v124
	v_exp_f32_e32 v125, v125
	ds_read_b128 v[138:141], v82 offset:2048
	ds_read_b128 v[142:145], v82 offset:2560
	s_waitcnt lgkmcnt(12)
	v_mfma_f32_32x32x16_bf16 v[34:49], v[158:161], v[90:93], v[34:49]
	v_exp_f32_e32 v126, v126
	v_exp_f32_e32 v127, v127
	v_exp_f32_e32 v128, v128
	v_exp_f32_e32 v129, v129
	ds_read_b128 v[178:181], v82 offset:4096
	ds_read_b128 v[182:185], v82 offset:4608
	s_waitcnt lgkmcnt(12)
	v_mfma_f32_32x32x16_bf16 v[18:33], v[150:153], v[94:97], v[18:33]
	v_exp_f32_e32 v98, v98
	v_exp_f32_e32 v99, v99
	v_exp_f32_e32 v100, v100
	v_exp_f32_e32 v101, v101
	ds_read_b128 v[186:189], v82 offset:6144
	ds_read_b128 v[130:133], v82 offset:6656
	s_waitcnt lgkmcnt(12)
	v_mfma_f32_32x32x16_bf16 v[34:49], v[150:153], v[66:69], v[34:49]
	v_exp_f32_e32 v102, v102
	v_exp_f32_e32 v103, v103
	v_exp_f32_e32 v104, v104
	v_exp_f32_e32 v105, v105
	s_waitcnt lgkmcnt(10)
	v_mfma_f32_32x32x16_bf16 v[18:33], v[146:149], v[70:73], v[18:33]
	v_exp_f32_e32 v106, v106
	v_exp_f32_e32 v107, v107
	v_exp_f32_e32 v108, v108
	v_exp_f32_e32 v109, v109
	s_waitcnt lgkmcnt(8)
	v_mfma_f32_32x32x16_bf16 v[34:49], v[146:149], v[74:77], v[34:49]
	s_add_i32 s0, s15, 0x2000
	s_cmpk_lg_i32 s15, 0x4000
	s_cselect_b32 s0, s0, 0
	s_waitcnt vmcnt(2) lgkmcnt(0)
	s_barrier
; #define WAIT_BAR(N) asm volatile("s_waitcnt vmcnt(" #N ") lgkmcnt(0)\n\ts_barrier":::"memory")
;   #define RESC() do{}while(0)
;   #define ROT() do{sl_prev=sl_cur;sl_cur=sl_next;sl_next=(sl_next==(NSLOT-1)*SLOTB)?0:sl_next+SLOTB;}while(0)
; template<int THRL> __device__ __forceinline__ void attn_unit(int b,int h,int qb,const bf16*Q,const bf16*__restrict__ K,const bf16*__restrict__ V,bf16*O,char*shm,float m2){
;     ...
;   int t=1;
;   for(;t+5<NT;t+=2){
;     STEP(pB0,pB1,pA0,pA1,t,true,true,true);     WAIT_BAR(2); RESC(); ROT();
;     STEP(pA0,pA1,pB0,pB1,t+1,true,true,true);   WAIT_BAR(2); RESC(); ROT();
	v_add_u32_e32 v199, s16, v220
	ds_read_b64_tr_b16 v[230:231], v199 offset:24576
	ds_read_b64_tr_b16 v[232:233], v199 offset:25088
	s_waitcnt lgkmcnt(9)
	v_mfma_f32_32x32x16_bf16 v[82:97], v[78:81], v[174:177], v[50:65]
	v_exp_f32_e32 v110, v110
	v_add_f32_e32 v66, v114, v115
	v_add_f32_e32 v66, v116, v66
	v_add_f32_e32 v66, v117, v66
	v_add_f32_e32 v66, v118, v66
	v_add_f32_e32 v66, v119, v66
	v_cvt_pk_bf16_f32 v166, v114, v115
	v_cvt_pk_bf16_f32 v167, v116, v117
	ds_read_b64_tr_b16 v[114:115], v199 offset:28672
	ds_read_b64_tr_b16 v[116:117], v199 offset:29184
	v_add_f32_e32 v66, v120, v66
	v_add_f32_e32 v66, v121, v66
	v_add_f32_e32 v66, v122, v66
	v_add_f32_e32 v146, v123, v66
	s_waitcnt lgkmcnt(10)
	v_mfma_f32_32x32x16_bf16 v[66:81], v[134:137], v[174:177], v[50:65]
	v_exp_f32_e32 v111, v111
	v_cvt_pk_bf16_f32 v168, v118, v119
	v_cvt_pk_bf16_f32 v169, v120, v121
	ds_read_b64_tr_b16 v[118:119], v199 offset:25600
	ds_read_b64_tr_b16 v[120:121], v199 offset:26112
	s_waitcnt lgkmcnt(11)
	v_mfma_f32_32x32x16_bf16 v[82:97], v[138:141], v[170:173], v[82:97]
	v_exp_f32_e32 v112, v112
	v_add_f32_e32 v134, v124, v146
	v_add_f32_e32 v134, v125, v134
	v_add_f32_e32 v134, v126, v134
	v_add_f32_e32 v134, v127, v134
	v_cvt_pk_bf16_f32 v158, v122, v123
	v_cvt_pk_bf16_f32 v159, v124, v125
	ds_read_b64_tr_b16 v[122:123], v199 offset:29696
	ds_read_b64_tr_b16 v[124:125], v199 offset:30208
	s_waitcnt lgkmcnt(12)
	v_mfma_f32_32x32x16_bf16 v[66:81], v[142:145], v[170:173], v[66:81]
	v_exp_f32_e32 v113, v113
	v_add_f32_e32 v134, v128, v134
	v_add_f32_e32 v134, v129, v134
	v_add_f32_e32 v134, v98, v134
	v_add_f32_e32 v134, v99, v134
	v_cvt_pk_bf16_f32 v160, v126, v127
	v_cvt_pk_bf16_f32 v161, v128, v129
	ds_read_b64_tr_b16 v[126:127], v199 offset:26624
	ds_read_b64_tr_b16 v[128:129], v199 offset:27136
	s_waitcnt lgkmcnt(13)
	v_mfma_f32_32x32x16_bf16 v[82:97], v[178:181], v[162:165], v[82:97]
	v_add_f32_e32 v134, v100, v134
	v_add_f32_e32 v134, v101, v134
	v_add_f32_e32 v134, v102, v134
	v_add_f32_e32 v134, v103, v134
	v_cvt_pk_bf16_f32 v150, v98, v99
	v_cvt_pk_bf16_f32 v151, v100, v101
	ds_read_b64_tr_b16 v[234:235], v199 offset:30720
	ds_read_b64_tr_b16 v[236:237], v199 offset:31232
	s_waitcnt lgkmcnt(14)
	v_mfma_f32_32x32x16_bf16 v[66:81], v[182:185], v[162:165], v[66:81]
	v_add_f32_e32 v98, v104, v134
	v_add_f32_e32 v98, v105, v98
	v_add_f32_e32 v98, v106, v98
	v_add_f32_e32 v98, v107, v98
	v_cvt_pk_bf16_f32 v152, v102, v103
	v_cvt_pk_bf16_f32 v153, v104, v105
	ds_read_b64_tr_b16 v[102:103], v199 offset:27648
	ds_read_b64_tr_b16 v[104:105], v199 offset:28160
	s_waitcnt lgkmcnt(14)
	v_mfma_f32_32x32x16_bf16 v[82:97], v[186:189], v[154:157], v[82:97]
	v_add_f32_e32 v98, v108, v98
	v_add_f32_e32 v98, v109, v98
	v_add_f32_e32 v98, v110, v98
	v_add_f32_e32 v98, v111, v98
	v_cvt_pk_bf16_f32 v146, v106, v107
	v_cvt_pk_bf16_f32 v147, v108, v109
	ds_read_b64_tr_b16 v[106:107], v199 offset:31744
	ds_read_b64_tr_b16 v[108:109], v199 offset:32256
	v_mfma_f32_32x32x16_bf16 v[66:81], v[130:133], v[154:157], v[66:81]
	v_add_f32_e32 v98, v112, v98
	v_add_f32_e32 v98, v113, v98
	v_add_f32_e32 v98, 0, v98
	v_cvt_pk_bf16_f32 v148, v110, v111
	v_cvt_pk_bf16_f32 v149, v112, v113
	s_mov_b64 s[16:17], 0x10000
	v_add_f32_e32 v199, v190, v98
	v_lshl_add_u64 v[98:99], v[214:215], 0, s[16:17]
	s_add_i32 s16, s15, s12
	s_mov_b32 s17, m0
	s_mov_b32 m0, s16
	s_nop 0
	global_load_lds_dwordx4 v[98:99], off
	s_mov_b32 m0, s17
	v_lshl_add_u64 v[216:217], v[216:217], 0, s[46:47]
	s_add_i32 s16, s0, s4
	s_mov_b32 s17, m0
	s_mov_b32 m0, s16
	s_nop 0
	global_load_lds_dwordx4 v[216:217], off
	s_mov_b32 m0, s17
	s_waitcnt lgkmcnt(14)
	v_mfma_f32_32x32x16_bf16 v[18:33], v[166:169], v[230:233], v[18:33]
	v_exp_f32_e32 v82, v82
	v_exp_f32_e32 v83, v83
	v_exp_f32_e32 v84, v84
	v_exp_f32_e32 v85, v85
	s_waitcnt lgkmcnt(12)
	v_mfma_f32_32x32x16_bf16 v[34:49], v[166:169], v[114:117], v[34:49]
	v_exp_f32_e32 v86, v86
	v_exp_f32_e32 v87, v87
	v_exp_f32_e32 v88, v88
	v_exp_f32_e32 v89, v89
	v_add_u32_e32 v110, s0, v219
	ds_read_b128 v[98:101], v110
	ds_read_b128 v[182:185], v110 offset:512
	s_waitcnt lgkmcnt(12)
	v_mfma_f32_32x32x16_bf16 v[18:33], v[158:161], v[118:121], v[18:33]
	v_exp_f32_e32 v90, v90
	v_exp_f32_e32 v91, v91
	v_exp_f32_e32 v92, v92
	v_exp_f32_e32 v93, v93
	ds_read_b128 v[186:189], v110 offset:2048
	ds_read_b128 v[178:181], v110 offset:2560
	s_waitcnt lgkmcnt(12)
	v_mfma_f32_32x32x16_bf16 v[34:49], v[158:161], v[122:125], v[34:49]
	v_exp_f32_e32 v94, v94
	v_exp_f32_e32 v95, v95
	v_exp_f32_e32 v96, v96
	v_exp_f32_e32 v97, v97
	ds_read_b128 v[142:145], v110 offset:4096
	ds_read_b128 v[138:141], v110 offset:4608
	s_waitcnt lgkmcnt(12)
	v_mfma_f32_32x32x16_bf16 v[18:33], v[150:153], v[126:129], v[18:33]
	v_exp_f32_e32 v66, v66
	v_exp_f32_e32 v67, v67
	v_exp_f32_e32 v68, v68
	v_exp_f32_e32 v69, v69
	ds_read_b128 v[134:137], v110 offset:6144
	ds_read_b128 v[130:133], v110 offset:6656
	s_waitcnt lgkmcnt(12)
	v_mfma_f32_32x32x16_bf16 v[34:49], v[150:153], v[234:237], v[34:49]
	v_exp_f32_e32 v70, v70
	v_exp_f32_e32 v71, v71
	v_exp_f32_e32 v72, v72
	v_exp_f32_e32 v73, v73
	s_waitcnt lgkmcnt(10)
	v_mfma_f32_32x32x16_bf16 v[18:33], v[146:149], v[102:105], v[18:33]
	v_exp_f32_e32 v74, v74
	v_exp_f32_e32 v75, v75
	v_exp_f32_e32 v76, v76
	v_exp_f32_e32 v77, v77
	s_waitcnt lgkmcnt(8)
	v_mfma_f32_32x32x16_bf16 v[34:49], v[146:149], v[106:109], v[34:49]
	s_add_i32 s18, s0, 0x2000
	s_cmpk_lg_i32 s0, 0x4000
	s_mov_b32 s17, s15
	s_cselect_b32 s15, s18, 0
	s_add_i32 s14, s14, 2
	v_lshl_add_u64 v[214:215], v[214:215], 0, s[46:47]
	s_mov_b32 s16, s0
	s_cmpk_gt_u32 s14, 0x78
	s_waitcnt vmcnt(2) lgkmcnt(0)
	s_barrier
;   #define RESC() do{}while(0)
;   #define ROT() do{sl_prev=sl_cur;sl_cur=sl_next;sl_next=(sl_next==(NSLOT-1)*SLOTB)?0:sl_next+SLOTB;}while(0)
;   #define ENDW(tt) do{ if((tt)+3<NT){WAIT_BAR(2);} else if((tt)+2<NT){WAIT_BAR(1);} else {WAIT_BAR(0);} }while(0)
; template<int THRL> __device__ __forceinline__ void attn_unit(int b,int h,int qb,const bf16*Q,const bf16*__restrict__ K,const bf16*__restrict__ V,bf16*O,char*shm,float m2){
;     ...
;   for(;t+1<NT;t+=2){
;     STEP(pB0,pB1,pA0,pA1,t,(t+3<NT),(t+1<NT),(t+1<NT));       ENDW(t);   RESC(); ROT();
	s_cbranch_scc0 .LBB0_829
	v_exp_f32_e32 v78, v78
	v_exp_f32_e32 v79, v79
	v_exp_f32_e32 v80, v80
	v_exp_f32_e32 v81, v81
	s_and_b32 s0, s13, 0x3fffffc0
	s_lshl_b32 s0, s0, 2
	s_add_i32 s0, s0, 0
	ds_read_b64_tr_b16 v[214:215], v220 offset:40960
	ds_read_b64_tr_b16 v[216:217], v220 offset:41472
	v_add_f32_e32 v102, v82, v83
	v_add_f32_e32 v102, v84, v102
	v_add_f32_e32 v102, v85, v102
	v_add_f32_e32 v102, v86, v102
	v_add_f32_e32 v102, v87, v102
	v_cvt_pk_bf16_f32 v166, v82, v83
	v_cvt_pk_bf16_f32 v167, v84, v85
	s_waitcnt lgkmcnt(9)
	v_mfma_f32_32x32x16_bf16 v[114:129], v[98:101], v[174:177], v[50:65]
	ds_read_b64_tr_b16 v[82:83], v220 offset:45056
	ds_read_b64_tr_b16 v[84:85], v220 offset:45568
	v_add_f32_e32 v98, v88, v102
	v_add_f32_e32 v98, v89, v98
	v_add_f32_e32 v98, v90, v98
	v_add_f32_e32 v146, v91, v98
	v_cvt_pk_bf16_f32 v168, v86, v87
	v_cvt_pk_bf16_f32 v169, v88, v89
	s_waitcnt lgkmcnt(10)
	v_mfma_f32_32x32x16_bf16 v[98:113], v[182:185], v[174:177], v[50:65]
	ds_read_b64_tr_b16 v[86:87], v220 offset:41984
	ds_read_b64_tr_b16 v[88:89], v220 offset:42496
	v_add_f32_e32 v146, v92, v146
	v_add_f32_e32 v146, v93, v146
	v_add_f32_e32 v146, v94, v146
	v_add_f32_e32 v146, v95, v146
	v_cvt_pk_bf16_f32 v158, v90, v91
	v_cvt_pk_bf16_f32 v159, v92, v93
	s_waitcnt lgkmcnt(11)
	v_mfma_f32_32x32x16_bf16 v[114:129], v[186:189], v[170:173], v[114:129]
	ds_read_b64_tr_b16 v[90:91], v220 offset:46080
	ds_read_b64_tr_b16 v[92:93], v220 offset:46592
	v_add_f32_e32 v146, v96, v146
	v_add_f32_e32 v146, v97, v146
	v_add_f32_e32 v146, v66, v146
	v_add_f32_e32 v146, v67, v146
	v_cvt_pk_bf16_f32 v160, v94, v95
	v_cvt_pk_bf16_f32 v161, v96, v97
	s_waitcnt lgkmcnt(12)
	v_mfma_f32_32x32x16_bf16 v[98:113], v[178:181], v[170:173], v[98:113]
	ds_read_b64_tr_b16 v[94:95], v220 offset:43008
	ds_read_b64_tr_b16 v[96:97], v220 offset:43520
	s_waitcnt lgkmcnt(13)
	v_mfma_f32_32x32x16_bf16 v[114:129], v[142:145], v[162:165], v[114:129]
	v_add_f32_e32 v142, v68, v146
	v_add_f32_e32 v142, v69, v142
	v_add_f32_e32 v142, v70, v142
	v_add_f32_e32 v142, v71, v142
	v_cvt_pk_bf16_f32 v150, v66, v67
	v_cvt_pk_bf16_f32 v151, v68, v69
	ds_read_b64_tr_b16 v[66:67], v220 offset:47104
	ds_read_b64_tr_b16 v[68:69], v220 offset:47616
	s_waitcnt lgkmcnt(14)
	v_mfma_f32_32x32x16_bf16 v[98:113], v[138:141], v[162:165], v[98:113]
	v_add_f32_e32 v138, v72, v142
	v_add_f32_e32 v138, v73, v138
	v_add_f32_e32 v138, v74, v138
	v_add_f32_e32 v138, v75, v138
	v_cvt_pk_bf16_f32 v152, v70, v71
	v_cvt_pk_bf16_f32 v153, v72, v73
	ds_read_b64_tr_b16 v[70:71], v220 offset:44032
	ds_read_b64_tr_b16 v[72:73], v220 offset:44544
	s_waitcnt lgkmcnt(14)
	v_mfma_f32_32x32x16_bf16 v[114:129], v[134:137], v[154:157], v[114:129]
	v_add_f32_e32 v134, v76, v138
	v_add_f32_e32 v134, v77, v134
	v_add_f32_e32 v134, v78, v134
	v_add_f32_e32 v134, v79, v134
	v_cvt_pk_bf16_f32 v146, v74, v75
	v_cvt_pk_bf16_f32 v147, v76, v77
	ds_read_b64_tr_b16 v[74:75], v220 offset:48128
	ds_read_b64_tr_b16 v[76:77], v220 offset:48640
	v_mfma_f32_32x32x16_bf16 v[98:113], v[130:133], v[154:157], v[98:113]
	v_add_f32_e32 v130, v80, v134
	v_add_f32_e32 v130, v81, v130
	v_add_f32_e32 v130, 0, v130
	v_cvt_pk_bf16_f32 v148, v78, v79
	v_cvt_pk_bf16_f32 v149, v80, v81
	v_lshl_add_u64 v[78:79], v[212:213], 0, s[50:51]
	s_mov_b32 s13, m0
	s_mov_b32 m0, s12
	s_nop 0
	global_load_lds_dwordx4 v[78:79], off
	s_mov_b32 m0, s13
	s_mov_b64 s[12:13], 0x1f0000
	s_cmp_lg_u32 0, -1
	v_lshl_add_u64 v[78:79], v[210:211], 0, s[12:13]
	s_cselect_b32 s12, 0, 0
	s_add_i32 s12, s12, s5
	s_add_i32 s5, s12, 0x8000
	s_mov_b32 s13, m0
	s_mov_b32 m0, s5
	s_nop 0
	global_load_lds_dwordx4 v[78:79], off
	s_mov_b32 m0, s13
	v_add_f32_e32 v190, v199, v130
	s_waitcnt lgkmcnt(14)
	v_mfma_f32_32x32x16_bf16 v[18:33], v[166:169], v[214:217], v[18:33]
	v_exp_f32_e32 v114, v114
	v_exp_f32_e32 v115, v115
	v_exp_f32_e32 v116, v116
	v_exp_f32_e32 v117, v117
	s_waitcnt lgkmcnt(12)
	v_mfma_f32_32x32x16_bf16 v[34:49], v[166:169], v[82:85], v[34:49]
	v_exp_f32_e32 v118, v118
	v_exp_f32_e32 v119, v119
	v_exp_f32_e32 v120, v120
	v_exp_f32_e32 v121, v121
	ds_read_b128 v[78:81], v219 offset:8192
	ds_read_b128 v[178:181], v219 offset:8704
	s_waitcnt lgkmcnt(12)
	v_mfma_f32_32x32x16_bf16 v[18:33], v[158:161], v[86:89], v[18:33]
	v_exp_f32_e32 v122, v122
	v_exp_f32_e32 v123, v123
	v_exp_f32_e32 v124, v124
	v_exp_f32_e32 v125, v125
	ds_read_b128 v[86:89], v219 offset:10240
	ds_read_b128 v[182:185], v219 offset:10752
	s_waitcnt lgkmcnt(12)
	v_mfma_f32_32x32x16_bf16 v[34:49], v[158:161], v[90:93], v[34:49]
	v_exp_f32_e32 v126, v126
	v_exp_f32_e32 v127, v127
	v_exp_f32_e32 v128, v128
	v_exp_f32_e32 v129, v129
	ds_read_b128 v[90:93], v219 offset:12288
	ds_read_b128 v[186:189], v219 offset:12800
	s_waitcnt lgkmcnt(12)
	v_mfma_f32_32x32x16_bf16 v[18:33], v[150:153], v[94:97], v[18:33]
	v_exp_f32_e32 v98, v98
	v_exp_f32_e32 v99, v99
	v_exp_f32_e32 v100, v100
	v_exp_f32_e32 v101, v101
	ds_read_b128 v[94:97], v219 offset:14336
	ds_read_b128 v[82:85], v219 offset:14848
	s_waitcnt lgkmcnt(12)
	v_mfma_f32_32x32x16_bf16 v[34:49], v[150:153], v[66:69], v[34:49]
	v_exp_f32_e32 v102, v102
	v_exp_f32_e32 v103, v103
	v_exp_f32_e32 v104, v104
	v_exp_f32_e32 v105, v105
	s_waitcnt lgkmcnt(10)
	v_mfma_f32_32x32x16_bf16 v[18:33], v[146:149], v[70:73], v[18:33]
	v_exp_f32_e32 v106, v106
	v_exp_f32_e32 v107, v107
	v_exp_f32_e32 v108, v108
	v_exp_f32_e32 v109, v109
	s_waitcnt lgkmcnt(8)
	v_mfma_f32_32x32x16_bf16 v[34:49], v[146:149], v[74:77], v[34:49]
	v_exp_f32_e32 v110, v110
	v_exp_f32_e32 v111, v111
	v_exp_f32_e32 v112, v112
	v_exp_f32_e32 v113, v113
	s_waitcnt vmcnt(2) lgkmcnt(0)
	s_barrier
;   #define RESC() do{}while(0)
;   #define ROT() do{sl_prev=sl_cur;sl_cur=sl_next;sl_next=(sl_next==(NSLOT-1)*SLOTB)?0:sl_next+SLOTB;}while(0)
;   #define ENDW(tt) do{ if((tt)+3<NT){WAIT_BAR(2);} else if((tt)+2<NT){WAIT_BAR(1);} else {WAIT_BAR(0);} }while(0)
; template<int THRL> __device__ __forceinline__ void attn_unit(int b,int h,int qb,const bf16*Q,const bf16*__restrict__ K,const bf16*__restrict__ V,bf16*O,char*shm,float m2){
;     ...
;   for(;t+1<NT;t+=2){
;     STEP(pB0,pB1,pA0,pA1,t,(t+3<NT),(t+1<NT),(t+1<NT));       ENDW(t);   RESC(); ROT();
;     STEP(pA0,pA1,pB0,pB1,t+1,(t+4<NT),(t+2<NT),(t+2<NT));     ENDW(t+1); RESC(); ROT();
	ds_read_b64_tr_b16 v[214:215], v220 offset:24576
	ds_read_b64_tr_b16 v[216:217], v220 offset:25088
	v_add_f32_e32 v66, v114, v115
	v_add_f32_e32 v66, v116, v66
	v_add_f32_e32 v66, v117, v66
	v_add_f32_e32 v66, v118, v66
	v_add_f32_e32 v66, v119, v66
	v_cvt_pk_bf16_f32 v166, v114, v115
	v_cvt_pk_bf16_f32 v167, v116, v117
	s_waitcnt lgkmcnt(9)
	v_mfma_f32_32x32x16_bf16 v[130:145], v[78:81], v[174:177], v[50:65]
	ds_read_b64_tr_b16 v[114:115], v220 offset:28672
	ds_read_b64_tr_b16 v[116:117], v220 offset:29184
	v_add_f32_e32 v66, v120, v66
	v_add_f32_e32 v66, v121, v66
	v_add_f32_e32 v66, v122, v66
	v_add_f32_e32 v146, v123, v66
	s_waitcnt lgkmcnt(10)
	v_mfma_f32_32x32x16_bf16 v[66:81], v[178:181], v[174:177], v[50:65]
	v_cvt_pk_bf16_f32 v168, v118, v119
	v_cvt_pk_bf16_f32 v169, v120, v121
	ds_read_b64_tr_b16 v[118:119], v220 offset:25600
	ds_read_b64_tr_b16 v[120:121], v220 offset:26112
	s_waitcnt lgkmcnt(11)
	v_mfma_f32_32x32x16_bf16 v[130:145], v[86:89], v[170:173], v[130:145]
	v_add_f32_e32 v86, v124, v146
	v_add_f32_e32 v86, v125, v86
	v_add_f32_e32 v86, v126, v86
	v_add_f32_e32 v146, v127, v86
	v_cvt_pk_bf16_f32 v158, v122, v123
	v_cvt_pk_bf16_f32 v159, v124, v125
	ds_read_b64_tr_b16 v[86:87], v220 offset:29696
	ds_read_b64_tr_b16 v[88:89], v220 offset:30208
	s_waitcnt lgkmcnt(12)
	v_mfma_f32_32x32x16_bf16 v[66:81], v[182:185], v[170:173], v[66:81]
	v_add_f32_e32 v122, v128, v146
	v_add_f32_e32 v122, v129, v122
	v_add_f32_e32 v122, v98, v122
	v_add_f32_e32 v146, v99, v122
	v_cvt_pk_bf16_f32 v160, v126, v127
	v_cvt_pk_bf16_f32 v161, v128, v129
	ds_read_b64_tr_b16 v[122:123], v220 offset:26624
	ds_read_b64_tr_b16 v[124:125], v220 offset:27136
	s_waitcnt lgkmcnt(13)
	v_mfma_f32_32x32x16_bf16 v[130:145], v[90:93], v[162:165], v[130:145]
	v_add_f32_e32 v90, v100, v146
	v_add_f32_e32 v90, v101, v90
	v_add_f32_e32 v90, v102, v90
	v_add_f32_e32 v126, v103, v90
	v_cvt_pk_bf16_f32 v150, v98, v99
	v_cvt_pk_bf16_f32 v151, v100, v101
	ds_read_b64_tr_b16 v[90:91], v220 offset:30720
	ds_read_b64_tr_b16 v[92:93], v220 offset:31232
	s_waitcnt lgkmcnt(14)
	v_mfma_f32_32x32x16_bf16 v[66:81], v[186:189], v[162:165], v[66:81]
	v_add_f32_e32 v98, v104, v126
	v_add_f32_e32 v98, v105, v98
	v_add_f32_e32 v98, v106, v98
	v_add_f32_e32 v98, v107, v98
	v_cvt_pk_bf16_f32 v152, v102, v103
	v_cvt_pk_bf16_f32 v153, v104, v105
	ds_read_b64_tr_b16 v[102:103], v220 offset:27648
	ds_read_b64_tr_b16 v[104:105], v220 offset:28160
	s_waitcnt lgkmcnt(14)
	v_mfma_f32_32x32x16_bf16 v[130:145], v[94:97], v[154:157], v[130:145]
	v_add_f32_e32 v94, v108, v98
	v_add_f32_e32 v94, v109, v94
	v_add_f32_e32 v94, v110, v94
	v_add_f32_e32 v98, v111, v94
	v_cvt_pk_bf16_f32 v146, v106, v107
	v_cvt_pk_bf16_f32 v147, v108, v109
	ds_read_b64_tr_b16 v[94:95], v220 offset:31744
	ds_read_b64_tr_b16 v[96:97], v220 offset:32256
	v_mfma_f32_32x32x16_bf16 v[66:81], v[82:85], v[154:157], v[66:81]
	v_add_f32_e32 v82, v112, v98
	v_add_f32_e32 v82, v113, v82
	v_add_f32_e32 v82, 0, v82
	v_cvt_pk_bf16_f32 v148, v110, v111
	v_cvt_pk_bf16_f32 v149, v112, v113
	s_nop 0
	v_add_f32_e32 v190, v190, v82
	v_lshl_add_u64 v[82:83], v[212:213], 0, s[52:53]
	s_add_i32 s13, s12, 0x2000
	s_mov_b32 s14, m0
	s_mov_b32 m0, s13
	s_nop 0
	global_load_lds_dwordx4 v[82:83], off
	s_mov_b32 m0, s14
	s_mov_b64 s[14:15], 0x1f4000
	v_lshl_add_u64 v[82:83], v[210:211], 0, s[14:15]
	s_add_i32 s12, s12, 0xa000
	s_mov_b32 s13, m0
	s_mov_b32 m0, s12
	s_nop 0
	global_load_lds_dwordx4 v[82:83], off
	s_mov_b32 m0, s13
	s_waitcnt lgkmcnt(14)
	v_mfma_f32_32x32x16_bf16 v[18:33], v[166:169], v[214:217], v[18:33]
	v_exp_f32_e32 v130, v130
	v_exp_f32_e32 v131, v131
	v_exp_f32_e32 v132, v132
	v_exp_f32_e32 v133, v133
	s_waitcnt lgkmcnt(12)
	v_mfma_f32_32x32x16_bf16 v[34:49], v[166:169], v[114:117], v[34:49]
	v_exp_f32_e32 v134, v134
	v_exp_f32_e32 v135, v135
	v_exp_f32_e32 v136, v136
	v_exp_f32_e32 v137, v137
	ds_read_b128 v[82:85], v219 offset:16384
	ds_read_b128 v[106:109], v219 offset:16896
	s_waitcnt lgkmcnt(12)
	v_mfma_f32_32x32x16_bf16 v[18:33], v[158:161], v[118:121], v[18:33]
	v_exp_f32_e32 v138, v138
	v_exp_f32_e32 v139, v139
	v_exp_f32_e32 v140, v140
	v_exp_f32_e32 v141, v141
	ds_read_b128 v[110:113], v219 offset:18432
	ds_read_b128 v[178:181], v219 offset:18944
	s_waitcnt lgkmcnt(12)
	v_mfma_f32_32x32x16_bf16 v[34:49], v[158:161], v[86:89], v[34:49]
	v_exp_f32_e32 v142, v142
	v_exp_f32_e32 v143, v143
	v_exp_f32_e32 v144, v144
	v_exp_f32_e32 v145, v145
	ds_read_b128 v[182:185], v219 offset:20480
	ds_read_b128 v[186:189], v219 offset:20992
	s_waitcnt lgkmcnt(12)
	v_mfma_f32_32x32x16_bf16 v[18:33], v[150:153], v[122:125], v[18:33]
	v_exp_f32_e32 v66, v66
	v_exp_f32_e32 v67, v67
	v_exp_f32_e32 v68, v68
	v_exp_f32_e32 v69, v69
	ds_read_b128 v[212:215], v219 offset:22528
	ds_read_b128 v[98:101], v219 offset:23040
	s_waitcnt lgkmcnt(12)
	v_mfma_f32_32x32x16_bf16 v[34:49], v[150:153], v[90:93], v[34:49]
	v_exp_f32_e32 v70, v70
	v_exp_f32_e32 v71, v71
	v_exp_f32_e32 v72, v72
	v_exp_f32_e32 v73, v73
	s_waitcnt lgkmcnt(10)
	v_mfma_f32_32x32x16_bf16 v[18:33], v[146:149], v[102:105], v[18:33]
	v_exp_f32_e32 v74, v74
	v_exp_f32_e32 v75, v75
	v_exp_f32_e32 v76, v76
	v_exp_f32_e32 v77, v77
	s_waitcnt lgkmcnt(8)
	v_mfma_f32_32x32x16_bf16 v[34:49], v[146:149], v[94:97], v[34:49]
	v_exp_f32_e32 v78, v78
	v_exp_f32_e32 v79, v79
	v_exp_f32_e32 v80, v80
	v_exp_f32_e32 v81, v81
	s_waitcnt vmcnt(2) lgkmcnt(0)
	s_barrier
;   #define RESC() do{}while(0)
;   #define ROT() do{sl_prev=sl_cur;sl_cur=sl_next;sl_next=(sl_next==(NSLOT-1)*SLOTB)?0:sl_next+SLOTB;}while(0)
;   #define ENDW(tt) do{ if((tt)+3<NT){WAIT_BAR(2);} else if((tt)+2<NT){WAIT_BAR(1);} else {WAIT_BAR(0);} }while(0)
; template<int THRL> __device__ __forceinline__ void attn_unit(int b,int h,int qb,const bf16*Q,const bf16*__restrict__ K,const bf16*__restrict__ V,bf16*O,char*shm,float m2){
;     ...
;   for(;t+1<NT;t+=2){
;     STEP(pB0,pB1,pA0,pA1,t,(t+3<NT),(t+1<NT),(t+1<NT));       ENDW(t);   RESC(); ROT();
	ds_read_b64_tr_b16 v[102:103], v220 offset:32768
	ds_read_b64_tr_b16 v[104:105], v220 offset:33280
	v_add_f32_e32 v86, v130, v131
	v_add_f32_e32 v86, v132, v86
	v_add_f32_e32 v86, v133, v86
	v_add_f32_e32 v86, v134, v86
	v_add_f32_e32 v86, v135, v86
	v_cvt_pk_bf16_f32 v166, v130, v131
	v_cvt_pk_bf16_f32 v167, v132, v133
	s_waitcnt lgkmcnt(9)
	v_mfma_f32_32x32x16_bf16 v[114:129], v[82:85], v[174:177], v[50:65]
	ds_read_b64_tr_b16 v[130:131], v220 offset:36864
	ds_read_b64_tr_b16 v[132:133], v220 offset:37376
	v_add_f32_e32 v82, v136, v86
	v_add_f32_e32 v82, v137, v82
	v_add_f32_e32 v82, v138, v82
	v_add_f32_e32 v146, v139, v82
	v_cvt_pk_bf16_f32 v168, v134, v135
	v_cvt_pk_bf16_f32 v169, v136, v137
	s_waitcnt lgkmcnt(10)
	v_mfma_f32_32x32x16_bf16 v[82:97], v[106:109], v[174:177], v[50:65]
	ds_read_b64_tr_b16 v[106:107], v220 offset:33792
	ds_read_b64_tr_b16 v[108:109], v220 offset:34304
	s_waitcnt lgkmcnt(11)
	v_mfma_f32_32x32x16_bf16 v[114:129], v[110:113], v[170:173], v[114:129]
	v_add_f32_e32 v110, v140, v146
	v_add_f32_e32 v110, v141, v110
	v_add_f32_e32 v110, v142, v110
	v_add_f32_e32 v134, v143, v110
	v_cvt_pk_bf16_f32 v158, v138, v139
	v_cvt_pk_bf16_f32 v159, v140, v141
	ds_read_b64_tr_b16 v[110:111], v220 offset:37888
	ds_read_b64_tr_b16 v[112:113], v220 offset:38400
	v_add_f32_e32 v134, v144, v134
	v_add_f32_e32 v134, v145, v134
	v_add_f32_e32 v134, v66, v134
	v_add_f32_e32 v138, v67, v134
	v_cvt_pk_bf16_f32 v160, v142, v143
	v_cvt_pk_bf16_f32 v161, v144, v145
	s_waitcnt lgkmcnt(12)
	v_mfma_f32_32x32x16_bf16 v[82:97], v[178:181], v[170:173], v[82:97]
	ds_read_b64_tr_b16 v[134:135], v220 offset:34816
	ds_read_b64_tr_b16 v[136:137], v220 offset:35328
	v_add_f32_e32 v138, v68, v138
	v_add_f32_e32 v138, v69, v138
	v_add_f32_e32 v138, v70, v138
	v_add_f32_e32 v138, v71, v138
	v_cvt_pk_bf16_f32 v150, v66, v67
	v_cvt_pk_bf16_f32 v151, v68, v69
	s_waitcnt lgkmcnt(13)
	v_mfma_f32_32x32x16_bf16 v[114:129], v[182:185], v[162:165], v[114:129]
	ds_read_b64_tr_b16 v[66:67], v220 offset:38912
	ds_read_b64_tr_b16 v[68:69], v220 offset:39424
	v_add_f32_e32 v138, v72, v138
	v_add_f32_e32 v138, v73, v138
	v_add_f32_e32 v138, v74, v138
	v_add_f32_e32 v138, v75, v138
	v_cvt_pk_bf16_f32 v152, v70, v71
	v_cvt_pk_bf16_f32 v153, v72, v73
	s_waitcnt lgkmcnt(14)
	v_mfma_f32_32x32x16_bf16 v[82:97], v[186:189], v[162:165], v[82:97]
	ds_read_b64_tr_b16 v[70:71], v220 offset:35840
	ds_read_b64_tr_b16 v[72:73], v220 offset:36352
	v_add_f32_e32 v138, v76, v138
	v_add_f32_e32 v138, v77, v138
	v_add_f32_e32 v138, v78, v138
	v_add_f32_e32 v138, v79, v138
	v_cvt_pk_bf16_f32 v146, v74, v75
	v_cvt_pk_bf16_f32 v147, v76, v77
	s_waitcnt lgkmcnt(14)
	v_mfma_f32_32x32x16_bf16 v[114:129], v[212:215], v[154:157], v[114:129]
	ds_read_b64_tr_b16 v[74:75], v220 offset:39936
	ds_read_b64_tr_b16 v[76:77], v220 offset:40448
	v_mfma_f32_32x32x16_bf16 v[82:97], v[98:101], v[154:157], v[82:97]
	v_add_f32_e32 v98, v80, v138
	v_add_f32_e32 v98, v81, v98
	v_add_f32_e32 v98, 0, v98
	v_cvt_pk_bf16_f32 v148, v78, v79
	v_cvt_pk_bf16_f32 v149, v80, v81
	v_lshl_add_u64 v[78:79], v[210:211], 0, s[50:51]
	s_mov_b32 s12, m0
	s_mov_b32 m0, s4
	s_nop 0
	global_load_lds_dwordx4 v[78:79], off
	s_mov_b32 m0, s12
	v_add_f32_e32 v190, v190, v98
	s_waitcnt lgkmcnt(14)
	v_mfma_f32_32x32x16_bf16 v[18:33], v[166:169], v[102:105], v[18:33]
	v_exp_f32_e32 v114, v114
	v_exp_f32_e32 v115, v115
	v_exp_f32_e32 v116, v116
	v_exp_f32_e32 v117, v117
	s_waitcnt lgkmcnt(12)
	v_mfma_f32_32x32x16_bf16 v[34:49], v[166:169], v[130:133], v[34:49]
	v_exp_f32_e32 v118, v118
	v_exp_f32_e32 v119, v119
	v_exp_f32_e32 v120, v120
	v_exp_f32_e32 v121, v121
	ds_read_b128 v[78:81], v219
	ds_read_b128 v[138:141], v219 offset:512
	s_waitcnt lgkmcnt(12)
	v_mfma_f32_32x32x16_bf16 v[18:33], v[158:161], v[106:109], v[18:33]
	v_exp_f32_e32 v122, v122
	v_exp_f32_e32 v123, v123
	v_exp_f32_e32 v124, v124
	v_exp_f32_e32 v125, v125
	ds_read_b128 v[142:145], v219 offset:2048
	ds_read_b128 v[178:181], v219 offset:2560
	s_waitcnt lgkmcnt(12)
	v_mfma_f32_32x32x16_bf16 v[34:49], v[158:161], v[110:113], v[34:49]
	v_exp_f32_e32 v126, v126
	v_exp_f32_e32 v127, v127
	v_exp_f32_e32 v128, v128
	v_exp_f32_e32 v129, v129
	ds_read_b128 v[182:185], v219 offset:4096
	ds_read_b128 v[186:189], v219 offset:4608
	s_waitcnt lgkmcnt(12)
	v_mfma_f32_32x32x16_bf16 v[18:33], v[150:153], v[134:137], v[18:33]
	v_exp_f32_e32 v82, v82
	v_exp_f32_e32 v83, v83
	v_exp_f32_e32 v84, v84
	v_exp_f32_e32 v85, v85
	ds_read_b128 v[134:137], v219 offset:6144
	ds_read_b128 v[130:133], v219 offset:6656
	s_waitcnt lgkmcnt(12)
	v_mfma_f32_32x32x16_bf16 v[34:49], v[150:153], v[66:69], v[34:49]
	v_exp_f32_e32 v86, v86
	v_exp_f32_e32 v87, v87
	v_exp_f32_e32 v88, v88
	v_exp_f32_e32 v89, v89
	s_waitcnt lgkmcnt(10)
	v_mfma_f32_32x32x16_bf16 v[18:33], v[146:149], v[70:73], v[18:33]
	v_exp_f32_e32 v90, v90
	v_exp_f32_e32 v91, v91
	v_exp_f32_e32 v92, v92
	v_exp_f32_e32 v93, v93
	s_waitcnt lgkmcnt(8)
	v_mfma_f32_32x32x16_bf16 v[34:49], v[146:149], v[74:77], v[34:49]
	v_exp_f32_e32 v94, v94
	v_exp_f32_e32 v95, v95
	v_exp_f32_e32 v96, v96
	v_exp_f32_e32 v97, v97
	s_waitcnt vmcnt(1) lgkmcnt(0)
	s_barrier
;   #define RESC() do{}while(0)
;   #define ROT() do{sl_prev=sl_cur;sl_cur=sl_next;sl_next=(sl_next==(NSLOT-1)*SLOTB)?0:sl_next+SLOTB;}while(0)
;   #define ENDW(tt) do{ if((tt)+3<NT){WAIT_BAR(2);} else if((tt)+2<NT){WAIT_BAR(1);} else {WAIT_BAR(0);} }while(0)
; template<int THRL> __device__ __forceinline__ void attn_unit(int b,int h,int qb,const bf16*Q,const bf16*__restrict__ K,const bf16*__restrict__ V,bf16*O,char*shm,float m2){
;     ...
;   for(;t+1<NT;t+=2){
;     STEP(pB0,pB1,pA0,pA1,t,(t+3<NT),(t+1<NT),(t+1<NT));       ENDW(t);   RESC(); ROT();
;     STEP(pA0,pA1,pB0,pB1,t+1,(t+4<NT),(t+2<NT),(t+2<NT));     ENDW(t+1); RESC(); ROT();
	ds_read_b64_tr_b16 v[212:213], v220 offset:40960
	ds_read_b64_tr_b16 v[214:215], v220 offset:41472
	v_add_f32_e32 v66, v114, v115
	v_add_f32_e32 v66, v116, v66
	v_add_f32_e32 v66, v117, v66
	v_add_f32_e32 v66, v118, v66
	v_add_f32_e32 v66, v119, v66
	v_cvt_pk_bf16_f32 v166, v114, v115
	v_cvt_pk_bf16_f32 v167, v116, v117
	s_waitcnt lgkmcnt(9)
	v_mfma_f32_32x32x16_bf16 v[98:113], v[78:81], v[174:177], v[50:65]
	ds_read_b64_tr_b16 v[114:115], v220 offset:45056
	ds_read_b64_tr_b16 v[116:117], v220 offset:45568
	v_add_f32_e32 v66, v120, v66
	v_add_f32_e32 v66, v121, v66
	v_add_f32_e32 v66, v122, v66
	v_add_f32_e32 v146, v123, v66
	s_waitcnt lgkmcnt(10)
	v_mfma_f32_32x32x16_bf16 v[66:81], v[138:141], v[174:177], v[50:65]
	v_cvt_pk_bf16_f32 v168, v118, v119
	v_cvt_pk_bf16_f32 v169, v120, v121
	ds_read_b64_tr_b16 v[138:139], v220 offset:41984
	ds_read_b64_tr_b16 v[140:141], v220 offset:42496
	v_add_f32_e32 v118, v124, v146
	v_add_f32_e32 v118, v125, v118
	v_add_f32_e32 v118, v126, v118
	v_add_f32_e32 v118, v127, v118
	v_cvt_pk_bf16_f32 v158, v122, v123
	v_cvt_pk_bf16_f32 v159, v124, v125
	s_waitcnt lgkmcnt(11)
	v_mfma_f32_32x32x16_bf16 v[98:113], v[142:145], v[170:173], v[98:113]
	ds_read_b64_tr_b16 v[120:121], v220 offset:46080
	ds_read_b64_tr_b16 v[122:123], v220 offset:46592
	s_waitcnt lgkmcnt(12)
	v_mfma_f32_32x32x16_bf16 v[66:81], v[178:181], v[170:173], v[66:81]
	v_add_f32_e32 v118, v128, v118
	v_add_f32_e32 v118, v129, v118
	v_add_f32_e32 v118, v82, v118
	v_add_f32_e32 v118, v83, v118
	v_cvt_pk_bf16_f32 v160, v126, v127
	v_cvt_pk_bf16_f32 v161, v128, v129
	ds_read_b64_tr_b16 v[124:125], v220 offset:43008
	ds_read_b64_tr_b16 v[126:127], v220 offset:43520
	v_add_f32_e32 v118, v84, v118
	v_add_f32_e32 v118, v85, v118
	v_add_f32_e32 v118, v86, v118
	v_add_f32_e32 v118, v87, v118
	v_cvt_pk_bf16_f32 v150, v82, v83
	v_cvt_pk_bf16_f32 v151, v84, v85
	s_waitcnt lgkmcnt(13)
	v_mfma_f32_32x32x16_bf16 v[98:113], v[182:185], v[162:165], v[98:113]
	ds_read_b64_tr_b16 v[82:83], v220 offset:47104
	ds_read_b64_tr_b16 v[84:85], v220 offset:47616
	s_waitcnt lgkmcnt(14)
	v_mfma_f32_32x32x16_bf16 v[66:81], v[186:189], v[162:165], v[66:81]
	v_add_f32_e32 v118, v88, v118
	v_add_f32_e32 v118, v89, v118
	v_add_f32_e32 v118, v90, v118
	v_add_f32_e32 v118, v91, v118
	v_cvt_pk_bf16_f32 v152, v86, v87
	v_cvt_pk_bf16_f32 v153, v88, v89
	ds_read_b64_tr_b16 v[86:87], v220 offset:44032
	ds_read_b64_tr_b16 v[88:89], v220 offset:44544
	v_add_f32_e32 v118, v92, v118
	v_add_f32_e32 v118, v93, v118
	v_add_f32_e32 v118, v94, v118
	v_add_f32_e32 v118, v95, v118
	v_cvt_pk_bf16_f32 v146, v90, v91
	v_cvt_pk_bf16_f32 v147, v92, v93
	s_waitcnt lgkmcnt(14)
	v_mfma_f32_32x32x16_bf16 v[98:113], v[134:137], v[154:157], v[98:113]
	ds_read_b64_tr_b16 v[90:91], v220 offset:48128
	ds_read_b64_tr_b16 v[92:93], v220 offset:48640
	v_mfma_f32_32x32x16_bf16 v[66:81], v[130:133], v[154:157], v[66:81]
	v_add_f32_e32 v118, v96, v118
	v_add_f32_e32 v118, v97, v118
	v_add_f32_e32 v118, 0, v118
	v_cvt_pk_bf16_f32 v148, v94, v95
	v_cvt_pk_bf16_f32 v149, v96, v97
	v_lshl_add_u64 v[94:95], v[210:211], 0, s[52:53]
	s_mov_b32 s4, m0
	s_mov_b32 m0, s5
	s_nop 0
	global_load_lds_dwordx4 v[94:95], off
	s_mov_b32 m0, s4
	v_add_f32_e32 v118, v190, v118
	s_waitcnt lgkmcnt(14)
	v_mfma_f32_32x32x16_bf16 v[18:33], v[166:169], v[212:215], v[18:33]
	v_exp_f32_e32 v98, v98
	v_exp_f32_e32 v99, v99
	v_exp_f32_e32 v100, v100
	v_exp_f32_e32 v101, v101
	s_waitcnt lgkmcnt(12)
	v_mfma_f32_32x32x16_bf16 v[34:49], v[166:169], v[114:117], v[34:49]
	v_exp_f32_e32 v102, v102
	v_exp_f32_e32 v103, v103
	v_exp_f32_e32 v104, v104
	v_exp_f32_e32 v105, v105
	ds_read_b128 v[128:131], v219 offset:8192
	ds_read_b128 v[132:135], v219 offset:8704
	s_waitcnt lgkmcnt(12)
	v_mfma_f32_32x32x16_bf16 v[18:33], v[158:161], v[138:141], v[18:33]
	v_exp_f32_e32 v106, v106
	v_exp_f32_e32 v107, v107
	v_exp_f32_e32 v108, v108
	v_exp_f32_e32 v109, v109
	ds_read_b128 v[136:139], v219 offset:10240
	ds_read_b128 v[140:143], v219 offset:10752
	s_waitcnt lgkmcnt(12)
	v_mfma_f32_32x32x16_bf16 v[34:49], v[158:161], v[120:123], v[34:49]
	v_exp_f32_e32 v110, v110
	v_exp_f32_e32 v111, v111
	v_exp_f32_e32 v112, v112
	v_exp_f32_e32 v113, v113
	ds_read_b128 v[120:123], v219 offset:12288
	ds_read_b128 v[178:181], v219 offset:12800
	s_waitcnt lgkmcnt(12)
	v_mfma_f32_32x32x16_bf16 v[18:33], v[150:153], v[124:127], v[18:33]
	v_exp_f32_e32 v66, v66
	v_exp_f32_e32 v67, v67
	v_exp_f32_e32 v68, v68
	v_exp_f32_e32 v69, v69
	ds_read_b128 v[124:127], v219 offset:14336
	ds_read_b128 v[114:117], v219 offset:14848
	s_waitcnt lgkmcnt(12)
	v_mfma_f32_32x32x16_bf16 v[34:49], v[150:153], v[82:85], v[34:49]
	v_exp_f32_e32 v70, v70
	v_exp_f32_e32 v71, v71
	v_exp_f32_e32 v72, v72
	v_exp_f32_e32 v73, v73
	s_waitcnt lgkmcnt(10)
	v_mfma_f32_32x32x16_bf16 v[18:33], v[146:149], v[86:89], v[18:33]
	v_exp_f32_e32 v74, v74
	v_exp_f32_e32 v75, v75
	v_exp_f32_e32 v76, v76
	v_exp_f32_e32 v77, v77
	s_waitcnt lgkmcnt(8)
	v_mfma_f32_32x32x16_bf16 v[34:49], v[146:149], v[90:93], v[34:49]
	v_exp_f32_e32 v78, v78
	v_exp_f32_e32 v79, v79
	v_exp_f32_e32 v80, v80
	v_exp_f32_e32 v81, v81
	s_waitcnt vmcnt(0) lgkmcnt(0)
	s_barrier
;   #define RESC() do{}while(0)
; template<int THRL> __device__ __forceinline__ void attn_unit(int b,int h,int qb,const bf16*Q,const bf16*__restrict__ K,const bf16*__restrict__ V,bf16*O,char*shm,float m2){
;     ...
;   STEP(pB0,pB1,pA0,pA1,NT-1,false,false,false); RESC();
	ds_read_b64_tr_b16 v[182:183], v220 offset:24576
	ds_read_b64_tr_b16 v[184:185], v220 offset:25088
	v_add_f32_e32 v82, v98, v99
	v_add_f32_e32 v82, v100, v82
	v_add_f32_e32 v82, v101, v82
	v_add_f32_e32 v82, v102, v82
	v_add_f32_e32 v119, v103, v82
	v_cvt_pk_bf16_f32 v166, v98, v99
	v_cvt_pk_bf16_f32 v167, v100, v101
	s_waitcnt lgkmcnt(9)
	v_mfma_f32_32x32x16_bf16 v[82:97], v[128:131], v[174:177], v[50:65]
	ds_read_b64_tr_b16 v[98:99], v220 offset:28672
	ds_read_b64_tr_b16 v[100:101], v220 offset:29184
	s_waitcnt lgkmcnt(10)
	v_mfma_f32_32x32x16_bf16 v[50:65], v[132:135], v[174:177], v[50:65]
	v_add_f32_e32 v119, v104, v119
	v_add_f32_e32 v119, v105, v119
	v_add_f32_e32 v119, v106, v119
	v_add_f32_e32 v119, v107, v119
	v_cvt_pk_bf16_f32 v168, v102, v103
	v_cvt_pk_bf16_f32 v169, v104, v105
	ds_read_b64_tr_b16 v[102:103], v220 offset:25600
	ds_read_b64_tr_b16 v[104:105], v220 offset:26112
	v_add_f32_e32 v119, v108, v119
	v_add_f32_e32 v119, v109, v119
	v_add_f32_e32 v119, v110, v119
	v_add_f32_e32 v119, v111, v119
	v_cvt_pk_bf16_f32 v158, v106, v107
	v_cvt_pk_bf16_f32 v159, v108, v109
	s_waitcnt lgkmcnt(11)
	v_mfma_f32_32x32x16_bf16 v[82:97], v[136:139], v[170:173], v[82:97]
	ds_read_b64_tr_b16 v[106:107], v220 offset:29696
	ds_read_b64_tr_b16 v[108:109], v220 offset:30208
	s_waitcnt lgkmcnt(12)
	v_mfma_f32_32x32x16_bf16 v[50:65], v[140:143], v[170:173], v[50:65]
	v_add_f32_e32 v119, v112, v119
	v_add_f32_e32 v119, v113, v119
	v_add_f32_e32 v119, v66, v119
	v_add_f32_e32 v119, v67, v119
	v_cvt_pk_bf16_f32 v160, v110, v111
	v_cvt_pk_bf16_f32 v161, v112, v113
	ds_read_b64_tr_b16 v[110:111], v220 offset:26624
	ds_read_b64_tr_b16 v[112:113], v220 offset:27136
	v_add_f32_e32 v119, v68, v119
	v_add_f32_e32 v119, v69, v119
	v_add_f32_e32 v119, v70, v119
	v_add_f32_e32 v119, v71, v119
	v_cvt_pk_bf16_f32 v150, v66, v67
	v_cvt_pk_bf16_f32 v151, v68, v69
	s_waitcnt lgkmcnt(13)
	v_mfma_f32_32x32x16_bf16 v[82:97], v[120:123], v[162:165], v[82:97]
	ds_read_b64_tr_b16 v[66:67], v220 offset:30720
	ds_read_b64_tr_b16 v[68:69], v220 offset:31232
	s_waitcnt lgkmcnt(14)
	v_mfma_f32_32x32x16_bf16 v[50:65], v[178:181], v[162:165], v[50:65]
	v_add_f32_e32 v119, v72, v119
	v_add_f32_e32 v119, v73, v119
	v_add_f32_e32 v119, v74, v119
	v_add_f32_e32 v119, v75, v119
	v_cvt_pk_bf16_f32 v152, v70, v71
	v_cvt_pk_bf16_f32 v153, v72, v73
	ds_read_b64_tr_b16 v[70:71], v220 offset:27648
	ds_read_b64_tr_b16 v[72:73], v220 offset:28160
	v_add_f32_e32 v119, v76, v119
	v_add_f32_e32 v119, v77, v119
	v_add_f32_e32 v119, v78, v119
	v_add_f32_e32 v119, v79, v119
	v_cvt_pk_bf16_f32 v146, v74, v75
	v_cvt_pk_bf16_f32 v147, v76, v77
	s_waitcnt lgkmcnt(14)
	v_mfma_f32_32x32x16_bf16 v[82:97], v[124:127], v[154:157], v[82:97]
	ds_read_b64_tr_b16 v[74:75], v220 offset:31744
	ds_read_b64_tr_b16 v[76:77], v220 offset:32256
	v_mfma_f32_32x32x16_bf16 v[50:65], v[114:117], v[154:157], v[50:65]
	v_add_f32_e32 v114, v80, v119
	v_add_f32_e32 v114, v81, v114
	v_add_f32_e32 v114, 0, v114
	v_cvt_pk_bf16_f32 v148, v78, v79
	v_cvt_pk_bf16_f32 v149, v80, v81
	s_waitcnt lgkmcnt(14)
	v_mfma_f32_32x32x16_bf16 v[18:33], v[166:169], v[182:185], v[18:33]
	s_nop 1
	v_exp_f32_e32 v82, v82
	v_exp_f32_e32 v83, v83
	v_exp_f32_e32 v84, v84
	v_exp_f32_e32 v85, v85
	s_waitcnt lgkmcnt(12)
	v_mfma_f32_32x32x16_bf16 v[34:49], v[166:169], v[98:101], v[34:49]
	v_exp_f32_e32 v86, v86
	v_exp_f32_e32 v87, v87
	v_exp_f32_e32 v88, v88
	v_exp_f32_e32 v89, v89
	s_waitcnt lgkmcnt(10)
	v_mfma_f32_32x32x16_bf16 v[18:33], v[158:161], v[102:105], v[18:33]
	v_exp_f32_e32 v90, v90
	v_exp_f32_e32 v91, v91
	v_exp_f32_e32 v92, v92
	v_exp_f32_e32 v93, v93
	s_waitcnt lgkmcnt(8)
	v_mfma_f32_32x32x16_bf16 v[34:49], v[158:161], v[106:109], v[34:49]
	v_exp_f32_e32 v94, v94
	v_exp_f32_e32 v95, v95
	v_exp_f32_e32 v96, v96
	v_exp_f32_e32 v97, v97
	s_waitcnt lgkmcnt(6)
; #define SBAR() __builtin_amdgcn_sched_barrier(0)
;   #define RESC() do{}while(0)
;   #define PKW(P,B) cvtpk_s(P[B],P[B+1])
; __device__ __forceinline__ void pv(f32x16*o,int vb,bf16x8 pa0,bf16x8 pa1,bf16x8 pa2,bf16x8 pa3){
;   #pragma unroll
;   for(int d0=0;d0<2;++d0){s16x4 lo[4],hi[4];
;     #pragma unroll
;     for(int ks=0;ks<4;++ks){
;       asm volatile("ds_read_b64_tr_b16 %0,%1 offset:%c2":"=&v"(lo[ks]):"v"(vb),"i"(d0*4096+ks*1024):"memory");
;       asm volatile("ds_read_b64_tr_b16 %0,%1 offset:%c2":"=&v"(hi[ks]):"v"(vb),"i"(d0*4096+ks*1024+512):"memory");}
;     asm volatile("s_waitcnt lgkmcnt(0)":::"memory");SBAR();
;     ...
;     o[d0]=__builtin_amdgcn_mfma_f32_32x32x16_bf16(pa0,PK(0),o[d0],0,0,0);
;     o[d0]=__builtin_amdgcn_mfma_f32_32x32x16_bf16(pa1,PK(1),o[d0],0,0,0);
;     o[d0]=__builtin_amdgcn_mfma_f32_32x32x16_bf16(pa2,PK(2),o[d0],0,0,0);
;     o[d0]=__builtin_amdgcn_mfma_f32_32x32x16_bf16(pa3,PK(3),o[d0],0,0,0);
;     ...
;   }
; }
; template<int THRL> __device__ __forceinline__ void attn_unit(int b,int h,int qb,const bf16*Q,const bf16*__restrict__ K,const bf16*__restrict__ V,bf16*O,char*shm,float m2){
;     ...
;   STEP(pB0,pB1,pA0,pA1,NT-1,false,false,false); RESC();
;   { float sacc=pB0[0]+pB0[1]; _Pragma("unroll") for(int r=2;r<16;++r)sacc+=pB0[r]; _Pragma("unroll") for(int r=0;r<16;++r)sacc+=pB1[r]; l_reg+=sacc;
;     pw0=(u32x4){PKW(pB0,0),PKW(pB0,2),PKW(pB0,4),PKW(pB0,6)};pw1=(u32x4){PKW(pB0,8),PKW(pB0,10),PKW(pB0,12),PKW(pB0,14)};pw2=(u32x4){PKW(pB1,0),PKW(pB1,2),PKW(pB1,4),PKW(pB1,6)};pw3=(u32x4){PKW(pB1,8),PKW(pB1,10),PKW(pB1,12),PKW(pB1,14)};
;     SBAR(); pv(o,vb0+sl_cur,PAF(0),PAF(1),PAF(2),PAF(3)); }
;     ...
;   {auto rr=__builtin_amdgcn_permlane32_swap(__float_as_uint(l_reg),__float_as_uint(l_reg),false,false);l_reg=__uint_as_float(rr[0])+__uint_as_float(rr[1]);}
;   if(hi==0)wsf[32+r32]=l_reg;asm volatile("s_waitcnt lgkmcnt(0)":::"memory");
	v_mfma_f32_32x32x16_bf16 v[18:33], v[150:153], v[110:113], v[18:33]
	v_exp_f32_e32 v50, v50
	v_exp_f32_e32 v51, v51
	v_exp_f32_e32 v52, v52
	v_exp_f32_e32 v53, v53
	s_waitcnt lgkmcnt(4)
	v_mfma_f32_32x32x16_bf16 v[34:49], v[150:153], v[66:69], v[34:49]
	v_exp_f32_e32 v54, v54
	v_exp_f32_e32 v55, v55
	v_exp_f32_e32 v56, v56
	v_exp_f32_e32 v57, v57
	s_waitcnt lgkmcnt(2)
	v_mfma_f32_32x32x16_bf16 v[18:33], v[146:149], v[70:73], v[18:33]
	v_exp_f32_e32 v58, v58
	v_exp_f32_e32 v59, v59
	v_exp_f32_e32 v60, v60
	v_exp_f32_e32 v61, v61
	s_waitcnt lgkmcnt(0)
	v_mfma_f32_32x32x16_bf16 v[34:49], v[146:149], v[74:77], v[34:49]
	v_exp_f32_e32 v62, v62
	v_exp_f32_e32 v63, v63
	v_exp_f32_e32 v64, v64
	v_exp_f32_e32 v65, v65
	v_add_f32_e32 v66, v82, v83
	v_add_f32_e32 v66, v84, v66
	v_add_f32_e32 v66, v85, v66
	v_add_f32_e32 v66, v86, v66
	v_add_f32_e32 v66, v87, v66
	v_add_f32_e32 v66, v88, v66
	v_add_f32_e32 v66, v89, v66
	v_add_f32_e32 v66, v90, v66
	v_add_f32_e32 v66, v91, v66
	v_add_f32_e32 v66, v92, v66
	v_add_f32_e32 v66, v93, v66
	v_add_f32_e32 v66, v94, v66
	v_add_f32_e32 v66, v95, v66
	v_add_f32_e32 v66, v96, v66
	v_add_f32_e32 v66, v97, v66
	v_add_f32_e32 v66, v50, v66
	v_add_f32_e32 v66, v51, v66
	v_add_f32_e32 v66, v52, v66
	v_add_f32_e32 v66, v53, v66
	v_add_f32_e32 v66, v54, v66
	v_add_f32_e32 v66, v55, v66
	v_add_f32_e32 v66, v56, v66
	v_add_f32_e32 v66, v57, v66
	v_add_f32_e32 v66, v58, v66
	v_add_f32_e32 v66, v59, v66
	v_add_f32_e32 v66, v60, v66
	v_add_f32_e32 v66, v61, v66
	v_add_f32_e32 v66, v62, v66
	v_add_f32_e32 v66, v63, v66
	v_add_f32_e32 v66, v64, v66
	v_add_f32_e32 v66, v65, v66
	v_add_f32_e32 v67, v118, v114
	v_add_f32_e32 v66, v67, v66
	v_cvt_pk_bf16_f32 v50, v50, v51
	v_cvt_pk_bf16_f32 v68, v82, v83
	v_cvt_pk_bf16_f32 v69, v84, v85
	v_cvt_pk_bf16_f32 v70, v86, v87
	v_cvt_pk_bf16_f32 v71, v88, v89
	v_cvt_pk_bf16_f32 v72, v90, v91
	v_cvt_pk_bf16_f32 v73, v92, v93
	v_cvt_pk_bf16_f32 v74, v94, v95
	v_cvt_pk_bf16_f32 v75, v96, v97
	v_cvt_pk_bf16_f32 v51, v52, v53
	v_cvt_pk_bf16_f32 v52, v54, v55
	v_cvt_pk_bf16_f32 v53, v56, v57
	v_cvt_pk_bf16_f32 v54, v58, v59
	v_cvt_pk_bf16_f32 v55, v60, v61
	v_cvt_pk_bf16_f32 v56, v62, v63
	v_cvt_pk_bf16_f32 v57, v64, v65
	ds_read_b64_tr_b16 v[58:59],v221 offset:0
	ds_read_b64_tr_b16 v[60:61],v221 offset:512
	ds_read_b64_tr_b16 v[62:63],v221 offset:1024
	ds_read_b64_tr_b16 v[64:65],v221 offset:1536
	ds_read_b64_tr_b16 v[76:77],v221 offset:2048
	ds_read_b64_tr_b16 v[78:79],v221 offset:2560
	ds_read_b64_tr_b16 v[80:81],v221 offset:3072
	ds_read_b64_tr_b16 v[82:83],v221 offset:3584
	s_waitcnt lgkmcnt(0)
	s_nop 0
	v_mfma_f32_32x32x16_bf16 v[18:33], v[68:71], v[58:61], v[18:33]
	ds_read_b64_tr_b16 v[58:59],v221 offset:4096
	ds_read_b64_tr_b16 v[60:61],v221 offset:4608
	v_mfma_f32_32x32x16_bf16 v[18:33], v[72:75], v[62:65], v[18:33]
	ds_read_b64_tr_b16 v[62:63],v221 offset:5120
	ds_read_b64_tr_b16 v[64:65],v221 offset:5632
	v_mfma_f32_32x32x16_bf16 v[18:33], v[50:53], v[76:79], v[18:33]
	ds_read_b64_tr_b16 v[76:77],v221 offset:6144
	ds_read_b64_tr_b16 v[78:79],v221 offset:6656
	v_mfma_f32_32x32x16_bf16 v[18:33], v[54:57], v[80:83], v[18:33]
	ds_read_b64_tr_b16 v[80:81],v221 offset:7168
	ds_read_b64_tr_b16 v[82:83],v221 offset:7680
	s_waitcnt lgkmcnt(0)
	v_mfma_f32_32x32x16_bf16 v[34:49], v[68:71], v[58:61], v[34:49]
	v_mfma_f32_32x32x16_bf16 v[34:49], v[72:75], v[62:65], v[34:49]
	v_mfma_f32_32x32x16_bf16 v[34:49], v[50:53], v[76:79], v[34:49]
	v_mov_b32_e32 v50, v66
	s_nop 1
	v_permlane32_swap_b32_e32 v66, v50
	v_mfma_f32_32x32x16_bf16 v[34:49], v[54:57], v[80:83], v[34:49]
	s_and_saveexec_b64 s[4:5], s[2:3]
	s_cbranch_execz .LBB0_823
	v_add_f32_e32 v50, v66, v50
	v_lshl_add_u32 v51, v1, 2, s0
	ds_write_b32 v51, v50 offset:49280
	s_branch .LBB0_823

; #define PG8_STAGE(bufoff, gbase, voff) do { _Pragma("unroll") for (int _i = 0; _i < 2; ++_i) \
;         __builtin_amdgcn_global_load_lds((const unsigned*)((const char*)(gbase) + (voff)[_i]), (LAS unsigned*)(lds + (bufoff) + ldsw + _i * 8192), 16, 0, 0); } while (0)
; #define PG8_LDA(dst, b, h) do { _Pragma("unroll") for (int m = 0; m < 4; ++m) _Pragma("unroll") for (int k = 0; k < 2; ++k) dst[m][k] = *(const LAS bf16x8*)(lds + PG8_SA(b, h) + aoff + m * 2048 + k * 1024); } while (0)
; #define PG8_LDB(dst, b, h) do { _Pragma("unroll") for (int n = 0; n < 2; ++n) _Pragma("unroll") for (int k = 0; k < 2; ++k) dst[n][k] = *(const LAS bf16x8*)(lds + PG8_SB(b, h) + boff + n * 2048 + k * 1024); } while (0)
; #define PG8_MMA(ai, bj, At, Bt) do { __builtin_amdgcn_s_setprio(1); _Pragma("unroll") for (int m = 0; m < 4; ++m) _Pragma("unroll") for (int n = 0; n < 2; ++n) _Pragma("unroll") for (int k = 0; k < 2; ++k) \
;         acc[ai][bj][m][n] = __builtin_amdgcn_mfma_f32_16x16x32_bf16(Bt[n][k], At[m][k], acc[ai][bj][m][n], 0, 0, 0); __builtin_amdgcn_s_setprio(0); } while (0)
; #define PG8_WAIT_V(n) asm volatile("s_waitcnt vmcnt(" #n ")" ::: "memory")
; #define PG8_WAIT_L(n) asm volatile("s_waitcnt lgkmcnt(" #n ")" ::: "memory")
; #define PG8_BAR __builtin_amdgcn_s_barrier()
; #define PG8_SCHED __builtin_amdgcn_sched_barrier(0)
; template <class Epi, bool ALIGN_EPI>
; __device__ __forceinline__ void gemm_phase(LAS unsigned char* lds, const Gemm g, const StaticOrder& S, const Epi& E) {
;     ...
;         for (int t = 0; t < nt; t += 2) {
;             const bool last = (t == nt - 2);
;             const char* a1 = cA + (size_t)(t + 1) * kstepA;
;             const char* a2 = last ? nA : cA + (size_t)(t + 2) * kstepA; const char* b2 = last ? nB : cB + (size_t)(t + 2) * kstep;
;             const char* a3 = a2 + kstepA; const char* b3 = b2 + kstep;
;             PG8_LDB(B0, 0, 0); PG8_LDB(B1, 0, 1); PG8_SCHED; PG8_LDA(At, 0, 0); PG8_STAGE(PG8_SA(1, 1), a1 + hsA, voffA);
;             PG8_WAIT_V(8); PG8_WAIT_L(0); PG8_BAR; PG8_MMA(0, 0, At, B0); PG8_MMA(0, 1, At, B1); PG8_BAR; PG8_SCHED;
;             PG8_LDA(At, 0, 1); PG8_STAGE(PG8_SB(0, 0), b2, voffB); PG8_STAGE(PG8_SB(0, 1), b2 + hsB, voffB); PG8_STAGE(PG8_SA(0, 0), a2, voffA);
;             PG8_WAIT_V(8); PG8_WAIT_L(0); PG8_BAR; PG8_MMA(1, 0, At, B0); PG8_MMA(1, 1, At, B1); PG8_BAR; PG8_SCHED;
.LBB0_948:
	ds_read_b128 v[154:157], v151
	ds_read_b128 v[158:161], v151 offset:1024
	ds_read_b128 v[162:165], v151 offset:2048
	ds_read_b128 v[166:169], v151 offset:3072
	ds_read_b128 v[170:173], v152
	ds_read_b128 v[174:177], v152 offset:1024
	ds_read_b128 v[178:181], v152 offset:2048
	ds_read_b128 v[182:185], v152 offset:3072
	s_add_u32 s26, s24, 0xfffe0080
	s_addc_u32 s27, s25, -1
	s_cmp_eq_u32 s21, 4
	s_cselect_b32 s29, s5, s27
	s_cselect_b32 s28, s4, s26
	s_cselect_b32 s27, s23, s19
	s_cselect_b32 s26, s22, s17
	v_lshl_add_u64 v[218:219], s[24:25], 0, v[140:141]
	s_add_i32 m0, s30, 0xc000
	ds_read_b128 v[186:189], v153
	ds_read_b128 v[190:193], v153 offset:1024
	ds_read_b128 v[194:197], v153 offset:2048
	ds_read_b128 v[198:201], v153 offset:3072
	ds_read_b128 v[202:205], v153 offset:4096
	ds_read_b128 v[206:209], v153 offset:5120
	ds_read_b128 v[210:213], v153 offset:6144
	ds_read_b128 v[214:217], v153 offset:7168
	global_load_lds_dwordx4 v[218:219], off
	v_lshl_add_u64 v[218:219], s[24:25], 0, v[142:143]
	s_add_i32 m0, s30, 0xe000
	s_nop 0
	global_load_lds_dwordx4 v[218:219], off
	s_waitcnt vmcnt(8)
	s_waitcnt lgkmcnt(0)
	s_barrier
	s_waitcnt lgkmcnt(0)
	v_mfma_f32_16x16x32_bf16 v[126:129], v[154:157], v[186:189], v[126:129]
	v_mfma_f32_16x16x32_bf16 v[122:125], v[162:165], v[186:189], v[122:125]
	v_mfma_f32_16x16x32_bf16 v[110:113], v[154:157], v[194:197], v[110:113]
	v_mfma_f32_16x16x32_bf16 v[106:109], v[162:165], v[194:197], v[106:109]
	v_mfma_f32_16x16x32_bf16 v[94:97], v[154:157], v[202:205], v[94:97]
	v_mfma_f32_16x16x32_bf16 v[90:93], v[162:165], v[202:205], v[90:93]
	v_mfma_f32_16x16x32_bf16 v[78:81], v[154:157], v[210:213], v[78:81]
	v_mfma_f32_16x16x32_bf16 v[74:77], v[162:165], v[210:213], v[74:77]
	v_mfma_f32_16x16x32_bf16 v[126:129], v[158:161], v[190:193], v[126:129]
	v_mfma_f32_16x16x32_bf16 v[122:125], v[166:169], v[190:193], v[122:125]
	v_mfma_f32_16x16x32_bf16 v[110:113], v[158:161], v[198:201], v[110:113]
	v_mfma_f32_16x16x32_bf16 v[106:109], v[166:169], v[198:201], v[106:109]
	v_mfma_f32_16x16x32_bf16 v[94:97], v[158:161], v[206:209], v[94:97]
	v_mfma_f32_16x16x32_bf16 v[90:93], v[166:169], v[206:209], v[90:93]
	v_mfma_f32_16x16x32_bf16 v[78:81], v[158:161], v[214:217], v[78:81]
	v_mfma_f32_16x16x32_bf16 v[74:77], v[166:169], v[214:217], v[74:77]
	v_mfma_f32_16x16x32_bf16 v[118:121], v[170:173], v[186:189], v[118:121]
	v_mfma_f32_16x16x32_bf16 v[114:117], v[178:181], v[186:189], v[114:117]
	v_mfma_f32_16x16x32_bf16 v[102:105], v[170:173], v[194:197], v[102:105]
	v_mfma_f32_16x16x32_bf16 v[98:101], v[178:181], v[194:197], v[98:101]
	v_mfma_f32_16x16x32_bf16 v[86:89], v[170:173], v[202:205], v[86:89]
	v_mfma_f32_16x16x32_bf16 v[82:85], v[178:181], v[202:205], v[82:85]
	v_mfma_f32_16x16x32_bf16 v[70:73], v[170:173], v[210:213], v[70:73]
	v_mfma_f32_16x16x32_bf16 v[66:69], v[178:181], v[210:213], v[66:69]
	v_mfma_f32_16x16x32_bf16 v[118:121], v[174:177], v[190:193], v[118:121]
	v_mfma_f32_16x16x32_bf16 v[114:117], v[182:185], v[190:193], v[114:117]
	v_mfma_f32_16x16x32_bf16 v[102:105], v[174:177], v[198:201], v[102:105]
	v_mfma_f32_16x16x32_bf16 v[98:101], v[182:185], v[198:201], v[98:101]
	v_mfma_f32_16x16x32_bf16 v[86:89], v[174:177], v[206:209], v[86:89]
	v_mfma_f32_16x16x32_bf16 v[82:85], v[182:185], v[206:209], v[82:85]
	v_mfma_f32_16x16x32_bf16 v[70:73], v[174:177], v[214:217], v[70:73]
	v_mfma_f32_16x16x32_bf16 v[66:69], v[182:185], v[214:217], v[66:69]
	s_barrier
	s_add_i32 s42, s39, s15
	v_lshl_add_u64 v[218:219], s[26:27], 0, v[134:135]
	s_mov_b32 m0, s42
	ds_read_b128 v[186:189], v153 offset:16384
	ds_read_b128 v[190:193], v153 offset:17408
	ds_read_b128 v[194:197], v153 offset:18432
	ds_read_b128 v[198:201], v153 offset:19456
	ds_read_b128 v[202:205], v153 offset:20480
	ds_read_b128 v[206:209], v153 offset:21504
	ds_read_b128 v[210:213], v153 offset:22528
	ds_read_b128 v[214:217], v153 offset:23552
	global_load_lds_dwordx4 v[218:219], off
	s_add_i32 m0, s42, 0x2000
	s_add_u32 s42, s26, 0x20000
	v_lshl_add_u64 v[220:221], s[26:27], 0, v[130:131]
	s_addc_u32 s43, s27, 0
	s_add_i32 s44, s40, s15
	global_load_lds_dwordx4 v[220:221], off
	v_lshl_add_u64 v[222:223], s[42:43], 0, v[134:135]
	s_mov_b32 m0, s44
	v_lshl_add_u64 v[224:225], s[28:29], 0, v[132:133]
	global_load_lds_dwordx4 v[222:223], off
	v_lshl_add_u64 v[222:223], s[42:43], 0, v[130:131]
	s_add_i32 m0, s44, 0x2000
	s_nop 0
	global_load_lds_dwordx4 v[222:223], off
	v_lshl_add_u64 v[222:223], s[28:29], 0, v[136:137]
	s_mov_b32 m0, s30
	s_nop 0
	global_load_lds_dwordx4 v[222:223], off
	s_mov_b32 m0, s31
	s_nop 0
	global_load_lds_dwordx4 v[224:225], off
	s_waitcnt vmcnt(8)
	s_waitcnt lgkmcnt(0)
	s_barrier
; #define PG8_STAGE(bufoff, gbase, voff) do { _Pragma("unroll") for (int _i = 0; _i < 2; ++_i) \
;         __builtin_amdgcn_global_load_lds((const unsigned*)((const char*)(gbase) + (voff)[_i]), (LAS unsigned*)(lds + (bufoff) + ldsw + _i * 8192), 16, 0, 0); } while (0)
; #define PG8_LDA(dst, b, h) do { _Pragma("unroll") for (int m = 0; m < 4; ++m) _Pragma("unroll") for (int k = 0; k < 2; ++k) dst[m][k] = *(const LAS bf16x8*)(lds + PG8_SA(b, h) + aoff + m * 2048 + k * 1024); } while (0)
; #define PG8_LDB(dst, b, h) do { _Pragma("unroll") for (int n = 0; n < 2; ++n) _Pragma("unroll") for (int k = 0; k < 2; ++k) dst[n][k] = *(const LAS bf16x8*)(lds + PG8_SB(b, h) + boff + n * 2048 + k * 1024); } while (0)
; #define PG8_MMA(ai, bj, At, Bt) do { __builtin_amdgcn_s_setprio(1); _Pragma("unroll") for (int m = 0; m < 4; ++m) _Pragma("unroll") for (int n = 0; n < 2; ++n) _Pragma("unroll") for (int k = 0; k < 2; ++k) \
;         acc[ai][bj][m][n] = __builtin_amdgcn_mfma_f32_16x16x32_bf16(Bt[n][k], At[m][k], acc[ai][bj][m][n], 0, 0, 0); __builtin_amdgcn_s_setprio(0); } while (0)
; #define PG8_WAIT_V(n) asm volatile("s_waitcnt vmcnt(" #n ")" ::: "memory")
; #define PG8_WAIT_L(n) asm volatile("s_waitcnt lgkmcnt(" #n ")" ::: "memory")
; #define PG8_BAR __builtin_amdgcn_s_barrier()
; #define PG8_SCHED __builtin_amdgcn_sched_barrier(0)
; template <class Epi, bool ALIGN_EPI>
; __device__ __forceinline__ void gemm_phase(LAS unsigned char* lds, const Gemm g, const StaticOrder& S, const Epi& E) {
;     ...
;             PG8_WAIT_V(8); PG8_WAIT_L(0); PG8_BAR; PG8_MMA(1, 0, At, B0); PG8_MMA(1, 1, At, B1); PG8_BAR; PG8_SCHED;
;             PG8_LDB(B0, 1, 0); PG8_LDB(B1, 1, 1); PG8_SCHED; PG8_LDA(At, 1, 0); PG8_STAGE(PG8_SA(0, 1), a2 + hsA, voffA);
;             PG8_WAIT_V(8); PG8_WAIT_L(0); PG8_BAR; PG8_MMA(0, 0, At, B0); PG8_MMA(0, 1, At, B1); PG8_BAR; PG8_SCHED;
	s_waitcnt lgkmcnt(0)
	v_mfma_f32_16x16x32_bf16 v[62:65], v[154:157], v[186:189], v[62:65]
	v_mfma_f32_16x16x32_bf16 v[58:61], v[162:165], v[186:189], v[58:61]
	v_mfma_f32_16x16x32_bf16 v[46:49], v[154:157], v[194:197], v[46:49]
	v_mfma_f32_16x16x32_bf16 v[42:45], v[162:165], v[194:197], v[42:45]
	v_mfma_f32_16x16x32_bf16 v[30:33], v[154:157], v[202:205], v[30:33]
	v_mfma_f32_16x16x32_bf16 v[26:29], v[162:165], v[202:205], v[26:29]
	v_mfma_f32_16x16x32_bf16 v[14:17], v[154:157], v[210:213], v[14:17]
	v_mfma_f32_16x16x32_bf16 v[10:13], v[162:165], v[210:213], v[10:13]
	v_mfma_f32_16x16x32_bf16 v[62:65], v[158:161], v[190:193], v[62:65]
	v_mfma_f32_16x16x32_bf16 v[58:61], v[166:169], v[190:193], v[58:61]
	v_mfma_f32_16x16x32_bf16 v[46:49], v[158:161], v[198:201], v[46:49]
	v_mfma_f32_16x16x32_bf16 v[42:45], v[166:169], v[198:201], v[42:45]
	v_mfma_f32_16x16x32_bf16 v[30:33], v[158:161], v[206:209], v[30:33]
	v_mfma_f32_16x16x32_bf16 v[26:29], v[166:169], v[206:209], v[26:29]
	v_mfma_f32_16x16x32_bf16 v[14:17], v[158:161], v[214:217], v[14:17]
	v_mfma_f32_16x16x32_bf16 v[10:13], v[166:169], v[214:217], v[10:13]
	v_mfma_f32_16x16x32_bf16 v[54:57], v[170:173], v[186:189], v[54:57]
	v_mfma_f32_16x16x32_bf16 v[50:53], v[178:181], v[186:189], v[50:53]
	v_mfma_f32_16x16x32_bf16 v[38:41], v[170:173], v[194:197], v[38:41]
	v_mfma_f32_16x16x32_bf16 v[34:37], v[178:181], v[194:197], v[34:37]
	v_mfma_f32_16x16x32_bf16 v[22:25], v[170:173], v[202:205], v[22:25]
	v_mfma_f32_16x16x32_bf16 v[18:21], v[178:181], v[202:205], v[18:21]
	v_mfma_f32_16x16x32_bf16 v[6:9], v[170:173], v[210:213], v[6:9]
	v_mfma_f32_16x16x32_bf16 v[2:5], v[178:181], v[210:213], v[2:5]
	v_mfma_f32_16x16x32_bf16 v[54:57], v[174:177], v[190:193], v[54:57]
	v_mfma_f32_16x16x32_bf16 v[50:53], v[182:185], v[190:193], v[50:53]
	v_mfma_f32_16x16x32_bf16 v[38:41], v[174:177], v[198:201], v[38:41]
	v_mfma_f32_16x16x32_bf16 v[34:37], v[182:185], v[198:201], v[34:37]
	v_mfma_f32_16x16x32_bf16 v[22:25], v[174:177], v[206:209], v[22:25]
	v_mfma_f32_16x16x32_bf16 v[18:21], v[182:185], v[206:209], v[18:21]
	v_mfma_f32_16x16x32_bf16 v[6:9], v[174:177], v[214:217], v[6:9]
	v_mfma_f32_16x16x32_bf16 v[2:5], v[182:185], v[214:217], v[2:5]
	s_barrier
	s_add_i32 s42, 0, 0x18000
	s_add_i32 s43, 0, 0x1c000
	v_add_u32_e32 v166, s42, v1
	v_add_u32_e32 v182, s43, v1
	ds_read_b128 v[154:157], v166
	ds_read_b128 v[158:161], v166 offset:1024
	ds_read_b128 v[162:165], v166 offset:2048
	ds_read_b128 v[166:169], v166 offset:3072
	ds_read_b128 v[170:173], v182
	ds_read_b128 v[174:177], v182 offset:1024
	ds_read_b128 v[178:181], v182 offset:2048
	ds_read_b128 v[182:185], v182 offset:3072
	s_add_u32 s28, s28, 0x20000
	s_addc_u32 s29, s29, 0
	s_mov_b32 m0, s33
	v_lshl_add_u64 v[226:227], s[28:29], 0, v[136:137]
	ds_read_b128 v[186:189], v153 offset:32768
	ds_read_b128 v[190:193], v153 offset:33792
	ds_read_b128 v[194:197], v153 offset:34816
	ds_read_b128 v[198:201], v153 offset:35840
	ds_read_b128 v[202:205], v153 offset:36864
	ds_read_b128 v[206:209], v153 offset:37888
	ds_read_b128 v[210:213], v153 offset:38912
	ds_read_b128 v[214:217], v153 offset:39936
	global_load_lds_dwordx4 v[226:227], off
	v_lshl_add_u64 v[226:227], s[28:29], 0, v[132:133]
	s_mov_b32 m0, s34
	s_nop 0
	global_load_lds_dwordx4 v[226:227], off
	s_waitcnt vmcnt(8)
	s_waitcnt lgkmcnt(0)
	s_barrier
	s_waitcnt lgkmcnt(0)
	v_mfma_f32_16x16x32_bf16 v[126:129], v[154:157], v[186:189], v[126:129]
	v_mfma_f32_16x16x32_bf16 v[122:125], v[162:165], v[186:189], v[122:125]
	v_mfma_f32_16x16x32_bf16 v[110:113], v[154:157], v[194:197], v[110:113]
	v_mfma_f32_16x16x32_bf16 v[106:109], v[162:165], v[194:197], v[106:109]
	v_mfma_f32_16x16x32_bf16 v[94:97], v[154:157], v[202:205], v[94:97]
	v_mfma_f32_16x16x32_bf16 v[90:93], v[162:165], v[202:205], v[90:93]
	v_mfma_f32_16x16x32_bf16 v[78:81], v[154:157], v[210:213], v[78:81]
	v_mfma_f32_16x16x32_bf16 v[74:77], v[162:165], v[210:213], v[74:77]
	v_mfma_f32_16x16x32_bf16 v[126:129], v[158:161], v[190:193], v[126:129]
	v_mfma_f32_16x16x32_bf16 v[122:125], v[166:169], v[190:193], v[122:125]
	v_mfma_f32_16x16x32_bf16 v[110:113], v[158:161], v[198:201], v[110:113]
	v_mfma_f32_16x16x32_bf16 v[106:109], v[166:169], v[198:201], v[106:109]
	v_mfma_f32_16x16x32_bf16 v[94:97], v[158:161], v[206:209], v[94:97]
	v_mfma_f32_16x16x32_bf16 v[90:93], v[166:169], v[206:209], v[90:93]
	v_mfma_f32_16x16x32_bf16 v[78:81], v[158:161], v[214:217], v[78:81]
	v_mfma_f32_16x16x32_bf16 v[74:77], v[166:169], v[214:217], v[74:77]
	v_mfma_f32_16x16x32_bf16 v[118:121], v[170:173], v[186:189], v[118:121]
	v_mfma_f32_16x16x32_bf16 v[114:117], v[178:181], v[186:189], v[114:117]
	v_mfma_f32_16x16x32_bf16 v[102:105], v[170:173], v[194:197], v[102:105]
	v_mfma_f32_16x16x32_bf16 v[98:101], v[178:181], v[194:197], v[98:101]
	v_mfma_f32_16x16x32_bf16 v[86:89], v[170:173], v[202:205], v[86:89]
	v_mfma_f32_16x16x32_bf16 v[82:85], v[178:181], v[202:205], v[82:85]
	v_mfma_f32_16x16x32_bf16 v[70:73], v[170:173], v[210:213], v[70:73]
	v_mfma_f32_16x16x32_bf16 v[66:69], v[178:181], v[210:213], v[66:69]
	v_mfma_f32_16x16x32_bf16 v[118:121], v[174:177], v[190:193], v[118:121]
	v_mfma_f32_16x16x32_bf16 v[114:117], v[182:185], v[190:193], v[114:117]
	v_mfma_f32_16x16x32_bf16 v[102:105], v[174:177], v[198:201], v[102:105]
	v_mfma_f32_16x16x32_bf16 v[98:101], v[182:185], v[198:201], v[98:101]
	v_mfma_f32_16x16x32_bf16 v[86:89], v[174:177], v[206:209], v[86:89]
	v_mfma_f32_16x16x32_bf16 v[82:85], v[182:185], v[206:209], v[82:85]
	v_mfma_f32_16x16x32_bf16 v[70:73], v[174:177], v[214:217], v[70:73]
	v_mfma_f32_16x16x32_bf16 v[66:69], v[182:185], v[214:217], v[66:69]
	s_barrier
; #define PG8_STAGE(bufoff, gbase, voff) do { _Pragma("unroll") for (int _i = 0; _i < 2; ++_i) \
;         __builtin_amdgcn_global_load_lds((const unsigned*)((const char*)(gbase) + (voff)[_i]), (LAS unsigned*)(lds + (bufoff) + ldsw + _i * 8192), 16, 0, 0); } while (0)
; #define PG8_LDA(dst, b, h) do { _Pragma("unroll") for (int m = 0; m < 4; ++m) _Pragma("unroll") for (int k = 0; k < 2; ++k) dst[m][k] = *(const LAS bf16x8*)(lds + PG8_SA(b, h) + aoff + m * 2048 + k * 1024); } while (0)
; #define PG8_MMA(ai, bj, At, Bt) do { __builtin_amdgcn_s_setprio(1); _Pragma("unroll") for (int m = 0; m < 4; ++m) _Pragma("unroll") for (int n = 0; n < 2; ++n) _Pragma("unroll") for (int k = 0; k < 2; ++k) \
;         acc[ai][bj][m][n] = __builtin_amdgcn_mfma_f32_16x16x32_bf16(Bt[n][k], At[m][k], acc[ai][bj][m][n], 0, 0, 0); __builtin_amdgcn_s_setprio(0); } while (0)
; #define PG8_WAIT_V(n) asm volatile("s_waitcnt vmcnt(" #n ")" ::: "memory")
; #define PG8_WAIT_L(n) asm volatile("s_waitcnt lgkmcnt(" #n ")" ::: "memory")
; #define PG8_BAR __builtin_amdgcn_s_barrier()
; #define PG8_SCHED __builtin_amdgcn_sched_barrier(0)
; template <class Epi, bool ALIGN_EPI>
; __device__ __forceinline__ void gemm_phase(LAS unsigned char* lds, const Gemm g, const StaticOrder& S, const Epi& E) {
;     ...
;         for (int t = 0; t < nt; t += 2) {
;             const bool last = (t == nt - 2);
;             const char* a1 = cA + (size_t)(t + 1) * kstepA;
;             const char* a2 = last ? nA : cA + (size_t)(t + 2) * kstepA; const char* b2 = last ? nB : cB + (size_t)(t + 2) * kstep;
;     ...
;             PG8_LDA(At, 1, 1); PG8_STAGE(PG8_SB(1, 0), b3, voffB); PG8_STAGE(PG8_SB(1, 1), b3 + hsB, voffB); PG8_STAGE(PG8_SA(1, 0), a3, voffA);
;             PG8_WAIT_V(8); PG8_WAIT_L(0); PG8_BAR; PG8_MMA(1, 0, At, B0); PG8_MMA(1, 1, At, B1); PG8_BAR; PG8_SCHED;
;         }
	s_add_i32 s28, s42, s15
	v_lshl_add_u64 v[218:219], v[218:219], 0, s[8:9]
	s_mov_b32 m0, s28
	ds_read_b128 v[186:189], v153 offset:49152
	ds_read_b128 v[190:193], v153 offset:50176
	ds_read_b128 v[194:197], v153 offset:51200
	ds_read_b128 v[198:201], v153 offset:52224
	ds_read_b128 v[202:205], v153 offset:53248
	ds_read_b128 v[206:209], v153 offset:54272
	ds_read_b128 v[210:213], v153 offset:55296
	ds_read_b128 v[214:217], v153 offset:56320
	global_load_lds_dwordx4 v[218:219], off
	s_add_i32 m0, s28, 0x2000
	s_add_u32 s26, s26, 0x20080
	v_lshl_add_u64 v[218:219], v[220:221], 0, s[8:9]
	s_addc_u32 s27, s27, 0
	s_add_i32 s28, s43, s15
	global_load_lds_dwordx4 v[218:219], off
	v_lshl_add_u64 v[218:219], s[26:27], 0, v[134:135]
	s_mov_b32 m0, s28
	s_nop 0
	global_load_lds_dwordx4 v[218:219], off
	v_lshl_add_u64 v[218:219], s[26:27], 0, v[130:131]
	s_add_i32 m0, s28, 0x2000
	s_nop 0
	global_load_lds_dwordx4 v[218:219], off
	v_lshl_add_u64 v[218:219], v[222:223], 0, s[8:9]
	s_mov_b32 m0, s36
	s_nop 0
	global_load_lds_dwordx4 v[218:219], off
	v_lshl_add_u64 v[218:219], v[224:225], 0, s[8:9]
	s_mov_b32 m0, s37
	s_nop 0
	global_load_lds_dwordx4 v[218:219], off
	s_waitcnt vmcnt(8)
	s_waitcnt lgkmcnt(0)
	s_barrier
	s_waitcnt lgkmcnt(0)
	v_mfma_f32_16x16x32_bf16 v[62:65], v[154:157], v[186:189], v[62:65]
	v_mfma_f32_16x16x32_bf16 v[58:61], v[162:165], v[186:189], v[58:61]
	v_mfma_f32_16x16x32_bf16 v[46:49], v[154:157], v[194:197], v[46:49]
	v_mfma_f32_16x16x32_bf16 v[42:45], v[162:165], v[194:197], v[42:45]
	v_mfma_f32_16x16x32_bf16 v[30:33], v[154:157], v[202:205], v[30:33]
	v_mfma_f32_16x16x32_bf16 v[26:29], v[162:165], v[202:205], v[26:29]
	v_mfma_f32_16x16x32_bf16 v[14:17], v[154:157], v[210:213], v[14:17]
	v_mfma_f32_16x16x32_bf16 v[10:13], v[162:165], v[210:213], v[10:13]
	v_mfma_f32_16x16x32_bf16 v[62:65], v[158:161], v[190:193], v[62:65]
	v_mfma_f32_16x16x32_bf16 v[58:61], v[166:169], v[190:193], v[58:61]
	v_mfma_f32_16x16x32_bf16 v[46:49], v[158:161], v[198:201], v[46:49]
	v_mfma_f32_16x16x32_bf16 v[42:45], v[166:169], v[198:201], v[42:45]
	v_mfma_f32_16x16x32_bf16 v[30:33], v[158:161], v[206:209], v[30:33]
	v_mfma_f32_16x16x32_bf16 v[26:29], v[166:169], v[206:209], v[26:29]
	v_mfma_f32_16x16x32_bf16 v[14:17], v[158:161], v[214:217], v[14:17]
	v_mfma_f32_16x16x32_bf16 v[10:13], v[166:169], v[214:217], v[10:13]
	v_mfma_f32_16x16x32_bf16 v[54:57], v[170:173], v[186:189], v[54:57]
	v_mfma_f32_16x16x32_bf16 v[50:53], v[178:181], v[186:189], v[50:53]
	v_mfma_f32_16x16x32_bf16 v[38:41], v[170:173], v[194:197], v[38:41]
	v_mfma_f32_16x16x32_bf16 v[34:37], v[178:181], v[194:197], v[34:37]
	v_mfma_f32_16x16x32_bf16 v[22:25], v[170:173], v[202:205], v[22:25]
	v_mfma_f32_16x16x32_bf16 v[18:21], v[178:181], v[202:205], v[18:21]
	v_mfma_f32_16x16x32_bf16 v[6:9], v[170:173], v[210:213], v[6:9]
	v_mfma_f32_16x16x32_bf16 v[2:5], v[178:181], v[210:213], v[2:5]
	v_mfma_f32_16x16x32_bf16 v[54:57], v[174:177], v[190:193], v[54:57]
	v_mfma_f32_16x16x32_bf16 v[50:53], v[182:185], v[190:193], v[50:53]
	v_mfma_f32_16x16x32_bf16 v[38:41], v[174:177], v[198:201], v[38:41]
	v_mfma_f32_16x16x32_bf16 v[34:37], v[182:185], v[198:201], v[34:37]
	v_mfma_f32_16x16x32_bf16 v[22:25], v[174:177], v[206:209], v[22:25]
	v_mfma_f32_16x16x32_bf16 v[18:21], v[182:185], v[206:209], v[18:21]
	v_mfma_f32_16x16x32_bf16 v[6:9], v[174:177], v[214:217], v[6:9]
	v_mfma_f32_16x16x32_bf16 v[2:5], v[182:185], v[214:217], v[2:5]
	s_add_i32 s21, s21, 2
	s_add_u32 s24, s24, 0x100
	s_addc_u32 s25, s25, 0
	s_add_u32 s17, s17, 0x100
	s_addc_u32 s19, s19, 0
	s_cmp_gt_u32 s21, 5
	s_barrier
	s_cbranch_scc0 .LBB0_948
	s_and_b64 vcc, exec, s[10:11]
	s_cbranch_vccz .LBB0_951
	s_barrier

; #define PG8_STAGE(bufoff, gbase, voff) do { _Pragma("unroll") for (int _i = 0; _i < 2; ++_i) \
;         __builtin_amdgcn_global_load_lds((const unsigned*)((const char*)(gbase) + (voff)[_i]), (LAS unsigned*)(lds + (bufoff) + ldsw + _i * 8192), 16, 0, 0); } while (0)
; #define PG8_LDA(dst, b, h) do { _Pragma("unroll") for (int m = 0; m < 4; ++m) _Pragma("unroll") for (int k = 0; k < 2; ++k) dst[m][k] = *(const LAS bf16x8*)(lds + PG8_SA(b, h) + aoff + m * 2048 + k * 1024); } while (0)
; #define PG8_LDB(dst, b, h) do { _Pragma("unroll") for (int n = 0; n < 2; ++n) _Pragma("unroll") for (int k = 0; k < 2; ++k) dst[n][k] = *(const LAS bf16x8*)(lds + PG8_SB(b, h) + boff + n * 2048 + k * 1024); } while (0)
; #define PG8_MMA(ai, bj, At, Bt) do { __builtin_amdgcn_s_setprio(1); _Pragma("unroll") for (int m = 0; m < 4; ++m) _Pragma("unroll") for (int n = 0; n < 2; ++n) _Pragma("unroll") for (int k = 0; k < 2; ++k) \
;         acc[ai][bj][m][n] = __builtin_amdgcn_mfma_f32_16x16x32_bf16(Bt[n][k], At[m][k], acc[ai][bj][m][n], 0, 0, 0); __builtin_amdgcn_s_setprio(0); } while (0)
; #define PG8_WAIT_V(n) asm volatile("s_waitcnt vmcnt(" #n ")" ::: "memory")
; #define PG8_WAIT_L(n) asm volatile("s_waitcnt lgkmcnt(" #n ")" ::: "memory")
; #define PG8_BAR __builtin_amdgcn_s_barrier()
; #define PG8_SCHED __builtin_amdgcn_sched_barrier(0)
; template <class Epi, bool ALIGN_EPI>
; __device__ __forceinline__ void gemm_phase(LAS unsigned char* lds, const Gemm g, const StaticOrder& S, const Epi& E) {
;     ...
;         for (int t = 0; t < nt; t += 2) {
;             const bool last = (t == nt - 2);
;             const char* a1 = cA + (size_t)(t + 1) * kstepA;
;             const char* a2 = last ? nA : cA + (size_t)(t + 2) * kstepA; const char* b2 = last ? nB : cB + (size_t)(t + 2) * kstep;
;             const char* a3 = a2 + kstepA; const char* b3 = b2 + kstep;
;             PG8_LDB(B0, 0, 0); PG8_LDB(B1, 0, 1); PG8_SCHED; PG8_LDA(At, 0, 0); PG8_STAGE(PG8_SA(1, 1), a1 + hsA, voffA);
;             PG8_WAIT_V(8); PG8_WAIT_L(0); PG8_BAR; PG8_MMA(0, 0, At, B0); PG8_MMA(0, 1, At, B1); PG8_BAR; PG8_SCHED;
;             PG8_LDA(At, 0, 1); PG8_STAGE(PG8_SB(0, 0), b2, voffB); PG8_STAGE(PG8_SB(0, 1), b2 + hsB, voffB); PG8_STAGE(PG8_SA(0, 0), a2, voffA);
;             PG8_WAIT_V(8); PG8_WAIT_L(0); PG8_BAR; PG8_MMA(1, 0, At, B0); PG8_MMA(1, 1, At, B1); PG8_BAR; PG8_SCHED;
.LBB0_1027:
	ds_read_b128 v[74:77], v232
	ds_read_b128 v[82:85], v232 offset:1024
	ds_read_b128 v[90:93], v232 offset:2048
	ds_read_b128 v[98:101], v232 offset:3072
	ds_read_b128 v[106:109], v233
	ds_read_b128 v[114:117], v233 offset:1024
	ds_read_b128 v[130:133], v233 offset:2048
	ds_read_b128 v[138:141], v233 offset:3072
	s_add_u32 s30, s26, 0xfffe0080
	s_addc_u32 s31, s27, -1
	s_cmp_eq_u32 s51, 4
	s_cselect_b32 s35, s9, s31
	s_cselect_b32 s34, s47, s30
	s_cselect_b32 s31, s21, s50
	s_cselect_b32 s30, s48, s49
	v_lshl_add_u64 v[194:195], s[26:27], 0, v[206:207]
	s_add_i32 m0, s25, 0xc000
	ds_read_b128 v[154:157], v234
	ds_read_b128 v[166:169], v234 offset:1024
	ds_read_b128 v[170:173], v234 offset:2048
	ds_read_b128 v[174:177], v234 offset:3072
	ds_read_b128 v[178:181], v234 offset:4096
	ds_read_b128 v[182:185], v234 offset:5120
	ds_read_b128 v[186:189], v234 offset:6144
	ds_read_b128 v[190:193], v234 offset:7168
	global_load_lds_dwordx4 v[194:195], off
	v_lshl_add_u64 v[194:195], s[26:27], 0, v[208:209]
	s_add_i32 m0, s25, 0xe000
	s_nop 0
	global_load_lds_dwordx4 v[194:195], off
	s_waitcnt vmcnt(8)
	s_waitcnt lgkmcnt(0)
	s_barrier
	s_waitcnt lgkmcnt(0)
	v_mfma_f32_16x16x32_bf16 v[162:165], v[74:77], v[154:157], v[162:165]
	v_mfma_f32_16x16x32_bf16 v[158:161], v[90:93], v[154:157], v[158:161]
	v_mfma_f32_16x16x32_bf16 v[142:145], v[74:77], v[170:173], v[142:145]
	v_mfma_f32_16x16x32_bf16 v[134:137], v[90:93], v[170:173], v[134:137]
	v_mfma_f32_16x16x32_bf16 v[118:121], v[74:77], v[178:181], v[118:121]
	v_mfma_f32_16x16x32_bf16 v[110:113], v[90:93], v[178:181], v[110:113]
	v_mfma_f32_16x16x32_bf16 v[86:89], v[74:77], v[186:189], v[86:89]
	v_mfma_f32_16x16x32_bf16 v[78:81], v[90:93], v[186:189], v[78:81]
	v_mfma_f32_16x16x32_bf16 v[162:165], v[82:85], v[166:169], v[162:165]
	v_mfma_f32_16x16x32_bf16 v[158:161], v[98:101], v[166:169], v[158:161]
	v_mfma_f32_16x16x32_bf16 v[142:145], v[82:85], v[174:177], v[142:145]
	v_mfma_f32_16x16x32_bf16 v[134:137], v[98:101], v[174:177], v[134:137]
	v_mfma_f32_16x16x32_bf16 v[118:121], v[82:85], v[182:185], v[118:121]
	v_mfma_f32_16x16x32_bf16 v[110:113], v[98:101], v[182:185], v[110:113]
	v_mfma_f32_16x16x32_bf16 v[86:89], v[82:85], v[190:193], v[86:89]
	v_mfma_f32_16x16x32_bf16 v[78:81], v[98:101], v[190:193], v[78:81]
	v_mfma_f32_16x16x32_bf16 v[150:153], v[106:109], v[154:157], v[150:153]
	v_mfma_f32_16x16x32_bf16 v[146:149], v[130:133], v[154:157], v[146:149]
	v_mfma_f32_16x16x32_bf16 v[126:129], v[106:109], v[170:173], v[126:129]
	v_mfma_f32_16x16x32_bf16 v[122:125], v[130:133], v[170:173], v[122:125]
	v_mfma_f32_16x16x32_bf16 v[102:105], v[106:109], v[178:181], v[102:105]
	v_mfma_f32_16x16x32_bf16 v[94:97], v[130:133], v[178:181], v[94:97]
	v_mfma_f32_16x16x32_bf16 v[70:73], v[106:109], v[186:189], v[70:73]
	v_mfma_f32_16x16x32_bf16 v[66:69], v[130:133], v[186:189], v[66:69]
	v_mfma_f32_16x16x32_bf16 v[150:153], v[114:117], v[166:169], v[150:153]
	v_mfma_f32_16x16x32_bf16 v[146:149], v[138:141], v[166:169], v[146:149]
	v_mfma_f32_16x16x32_bf16 v[126:129], v[114:117], v[174:177], v[126:129]
	v_mfma_f32_16x16x32_bf16 v[122:125], v[138:141], v[174:177], v[122:125]
	v_mfma_f32_16x16x32_bf16 v[102:105], v[114:117], v[182:185], v[102:105]
	v_mfma_f32_16x16x32_bf16 v[94:97], v[138:141], v[182:185], v[94:97]
	v_mfma_f32_16x16x32_bf16 v[70:73], v[114:117], v[190:193], v[70:73]
	v_mfma_f32_16x16x32_bf16 v[66:69], v[138:141], v[190:193], v[66:69]
	s_barrier
	s_add_i32 s52, s44, s33
	v_lshl_add_u64 v[194:195], s[30:31], 0, v[200:201]
	s_mov_b32 m0, s52
	ds_read_b128 v[154:157], v234 offset:16384
	ds_read_b128 v[166:169], v234 offset:17408
	ds_read_b128 v[170:173], v234 offset:18432
	ds_read_b128 v[174:177], v234 offset:19456
	ds_read_b128 v[178:181], v234 offset:20480
	ds_read_b128 v[182:185], v234 offset:21504
	ds_read_b128 v[186:189], v234 offset:22528
	ds_read_b128 v[190:193], v234 offset:23552
	global_load_lds_dwordx4 v[194:195], off
	s_add_i32 m0, s52, 0x2000
	s_add_u32 s52, s30, 0x20000
	v_lshl_add_u64 v[196:197], s[30:31], 0, v[204:205]
	s_addc_u32 s53, s31, 0
	s_add_i32 s54, s45, s33
	global_load_lds_dwordx4 v[196:197], off
	v_lshl_add_u64 v[214:215], s[52:53], 0, v[200:201]
	s_mov_b32 m0, s54
	v_lshl_add_u64 v[216:217], s[34:35], 0, v[202:203]
	global_load_lds_dwordx4 v[214:215], off
	v_lshl_add_u64 v[214:215], s[52:53], 0, v[204:205]
	s_add_i32 m0, s54, 0x2000
	s_nop 0
	global_load_lds_dwordx4 v[214:215], off
	v_lshl_add_u64 v[214:215], s[34:35], 0, v[198:199]
	s_mov_b32 m0, s25
	s_nop 0
	global_load_lds_dwordx4 v[214:215], off
	s_mov_b32 m0, s36
	s_nop 0
	global_load_lds_dwordx4 v[216:217], off
	s_waitcnt vmcnt(8)
	s_waitcnt lgkmcnt(0)
	s_barrier
; #define PG8_STAGE(bufoff, gbase, voff) do { _Pragma("unroll") for (int _i = 0; _i < 2; ++_i) \
;         __builtin_amdgcn_global_load_lds((const unsigned*)((const char*)(gbase) + (voff)[_i]), (LAS unsigned*)(lds + (bufoff) + ldsw + _i * 8192), 16, 0, 0); } while (0)
; #define PG8_LDA(dst, b, h) do { _Pragma("unroll") for (int m = 0; m < 4; ++m) _Pragma("unroll") for (int k = 0; k < 2; ++k) dst[m][k] = *(const LAS bf16x8*)(lds + PG8_SA(b, h) + aoff + m * 2048 + k * 1024); } while (0)
; #define PG8_LDB(dst, b, h) do { _Pragma("unroll") for (int n = 0; n < 2; ++n) _Pragma("unroll") for (int k = 0; k < 2; ++k) dst[n][k] = *(const LAS bf16x8*)(lds + PG8_SB(b, h) + boff + n * 2048 + k * 1024); } while (0)
; #define PG8_MMA(ai, bj, At, Bt) do { __builtin_amdgcn_s_setprio(1); _Pragma("unroll") for (int m = 0; m < 4; ++m) _Pragma("unroll") for (int n = 0; n < 2; ++n) _Pragma("unroll") for (int k = 0; k < 2; ++k) \
;         acc[ai][bj][m][n] = __builtin_amdgcn_mfma_f32_16x16x32_bf16(Bt[n][k], At[m][k], acc[ai][bj][m][n], 0, 0, 0); __builtin_amdgcn_s_setprio(0); } while (0)
; #define PG8_WAIT_V(n) asm volatile("s_waitcnt vmcnt(" #n ")" ::: "memory")
; #define PG8_WAIT_L(n) asm volatile("s_waitcnt lgkmcnt(" #n ")" ::: "memory")
; #define PG8_BAR __builtin_amdgcn_s_barrier()
; #define PG8_SCHED __builtin_amdgcn_sched_barrier(0)
; template <class Epi, bool ALIGN_EPI>
; __device__ __forceinline__ void gemm_phase(LAS unsigned char* lds, const Gemm g, const StaticOrder& S, const Epi& E) {
;     ...
;             PG8_WAIT_V(8); PG8_WAIT_L(0); PG8_BAR; PG8_MMA(1, 0, At, B0); PG8_MMA(1, 1, At, B1); PG8_BAR; PG8_SCHED;
;             PG8_LDB(B0, 1, 0); PG8_LDB(B1, 1, 1); PG8_SCHED; PG8_LDA(At, 1, 0); PG8_STAGE(PG8_SA(0, 1), a2 + hsA, voffA);
;             PG8_WAIT_V(8); PG8_WAIT_L(0); PG8_BAR; PG8_MMA(0, 0, At, B0); PG8_MMA(0, 1, At, B1); PG8_BAR; PG8_SCHED;
	s_waitcnt lgkmcnt(0)
	v_mfma_f32_16x16x32_bf16 v[62:65], v[74:77], v[154:157], v[62:65]
	v_mfma_f32_16x16x32_bf16 v[58:61], v[90:93], v[154:157], v[58:61]
	v_mfma_f32_16x16x32_bf16 v[46:49], v[74:77], v[170:173], v[46:49]
	v_mfma_f32_16x16x32_bf16 v[42:45], v[90:93], v[170:173], v[42:45]
	v_mfma_f32_16x16x32_bf16 v[30:33], v[74:77], v[178:181], v[30:33]
	v_mfma_f32_16x16x32_bf16 v[26:29], v[90:93], v[178:181], v[26:29]
	v_mfma_f32_16x16x32_bf16 v[14:17], v[74:77], v[186:189], v[14:17]
	v_mfma_f32_16x16x32_bf16 v[10:13], v[90:93], v[186:189], v[10:13]
	v_mfma_f32_16x16x32_bf16 v[62:65], v[82:85], v[166:169], v[62:65]
	v_mfma_f32_16x16x32_bf16 v[58:61], v[98:101], v[166:169], v[58:61]
	v_mfma_f32_16x16x32_bf16 v[46:49], v[82:85], v[174:177], v[46:49]
	v_mfma_f32_16x16x32_bf16 v[42:45], v[98:101], v[174:177], v[42:45]
	v_mfma_f32_16x16x32_bf16 v[30:33], v[82:85], v[182:185], v[30:33]
	v_mfma_f32_16x16x32_bf16 v[26:29], v[98:101], v[182:185], v[26:29]
	v_mfma_f32_16x16x32_bf16 v[14:17], v[82:85], v[190:193], v[14:17]
	v_mfma_f32_16x16x32_bf16 v[10:13], v[98:101], v[190:193], v[10:13]
	v_mfma_f32_16x16x32_bf16 v[54:57], v[106:109], v[154:157], v[54:57]
	v_mfma_f32_16x16x32_bf16 v[50:53], v[130:133], v[154:157], v[50:53]
	v_mfma_f32_16x16x32_bf16 v[38:41], v[106:109], v[170:173], v[38:41]
	v_mfma_f32_16x16x32_bf16 v[34:37], v[130:133], v[170:173], v[34:37]
	v_mfma_f32_16x16x32_bf16 v[22:25], v[106:109], v[178:181], v[22:25]
	v_mfma_f32_16x16x32_bf16 v[18:21], v[130:133], v[178:181], v[18:21]
	v_mfma_f32_16x16x32_bf16 v[6:9], v[106:109], v[186:189], v[6:9]
	v_mfma_f32_16x16x32_bf16 v[2:5], v[130:133], v[186:189], v[2:5]
	v_mfma_f32_16x16x32_bf16 v[54:57], v[114:117], v[166:169], v[54:57]
	v_mfma_f32_16x16x32_bf16 v[50:53], v[138:141], v[166:169], v[50:53]
	v_mfma_f32_16x16x32_bf16 v[38:41], v[114:117], v[174:177], v[38:41]
	v_mfma_f32_16x16x32_bf16 v[34:37], v[138:141], v[174:177], v[34:37]
	v_mfma_f32_16x16x32_bf16 v[22:25], v[114:117], v[182:185], v[22:25]
	v_mfma_f32_16x16x32_bf16 v[18:21], v[138:141], v[182:185], v[18:21]
	v_mfma_f32_16x16x32_bf16 v[6:9], v[114:117], v[190:193], v[6:9]
	v_mfma_f32_16x16x32_bf16 v[2:5], v[138:141], v[190:193], v[2:5]
	s_barrier
	s_add_i32 s52, 0, 0x18000
	s_add_i32 s53, 0, 0x1c000
	v_add_u32_e32 v98, s52, v230
	v_add_u32_e32 v138, s53, v230
	ds_read_b128 v[74:77], v98
	ds_read_b128 v[82:85], v98 offset:1024
	ds_read_b128 v[90:93], v98 offset:2048
	ds_read_b128 v[98:101], v98 offset:3072
	ds_read_b128 v[106:109], v138
	ds_read_b128 v[114:117], v138 offset:1024
	ds_read_b128 v[130:133], v138 offset:2048
	ds_read_b128 v[138:141], v138 offset:3072
	s_add_u32 s34, s34, 0x20000
	s_addc_u32 s35, s35, 0
	s_mov_b32 m0, s37
	v_lshl_add_u64 v[218:219], s[34:35], 0, v[198:199]
	ds_read_b128 v[154:157], v234 offset:32768
	ds_read_b128 v[166:169], v234 offset:33792
	ds_read_b128 v[170:173], v234 offset:34816
	ds_read_b128 v[174:177], v234 offset:35840
	ds_read_b128 v[178:181], v234 offset:36864
	ds_read_b128 v[182:185], v234 offset:37888
	ds_read_b128 v[186:189], v234 offset:38912
	ds_read_b128 v[190:193], v234 offset:39936
	global_load_lds_dwordx4 v[218:219], off
	v_lshl_add_u64 v[218:219], s[34:35], 0, v[202:203]
	s_mov_b32 m0, s38
	s_nop 0
	global_load_lds_dwordx4 v[218:219], off
	s_waitcnt vmcnt(8)
	s_waitcnt lgkmcnt(0)
	s_barrier
	s_waitcnt lgkmcnt(0)
	v_mfma_f32_16x16x32_bf16 v[162:165], v[74:77], v[154:157], v[162:165]
	v_mfma_f32_16x16x32_bf16 v[158:161], v[90:93], v[154:157], v[158:161]
	v_mfma_f32_16x16x32_bf16 v[142:145], v[74:77], v[170:173], v[142:145]
	v_mfma_f32_16x16x32_bf16 v[134:137], v[90:93], v[170:173], v[134:137]
	v_mfma_f32_16x16x32_bf16 v[118:121], v[74:77], v[178:181], v[118:121]
	v_mfma_f32_16x16x32_bf16 v[110:113], v[90:93], v[178:181], v[110:113]
	v_mfma_f32_16x16x32_bf16 v[86:89], v[74:77], v[186:189], v[86:89]
	v_mfma_f32_16x16x32_bf16 v[78:81], v[90:93], v[186:189], v[78:81]
	v_mfma_f32_16x16x32_bf16 v[162:165], v[82:85], v[166:169], v[162:165]
	v_mfma_f32_16x16x32_bf16 v[158:161], v[98:101], v[166:169], v[158:161]
	v_mfma_f32_16x16x32_bf16 v[142:145], v[82:85], v[174:177], v[142:145]
	v_mfma_f32_16x16x32_bf16 v[134:137], v[98:101], v[174:177], v[134:137]
	v_mfma_f32_16x16x32_bf16 v[118:121], v[82:85], v[182:185], v[118:121]
	v_mfma_f32_16x16x32_bf16 v[110:113], v[98:101], v[182:185], v[110:113]
	v_mfma_f32_16x16x32_bf16 v[86:89], v[82:85], v[190:193], v[86:89]
	v_mfma_f32_16x16x32_bf16 v[78:81], v[98:101], v[190:193], v[78:81]
	v_mfma_f32_16x16x32_bf16 v[150:153], v[106:109], v[154:157], v[150:153]
	v_mfma_f32_16x16x32_bf16 v[146:149], v[130:133], v[154:157], v[146:149]
	v_mfma_f32_16x16x32_bf16 v[126:129], v[106:109], v[170:173], v[126:129]
	v_mfma_f32_16x16x32_bf16 v[122:125], v[130:133], v[170:173], v[122:125]
	v_mfma_f32_16x16x32_bf16 v[102:105], v[106:109], v[178:181], v[102:105]
	v_mfma_f32_16x16x32_bf16 v[94:97], v[130:133], v[178:181], v[94:97]
	v_mfma_f32_16x16x32_bf16 v[70:73], v[106:109], v[186:189], v[70:73]
	v_mfma_f32_16x16x32_bf16 v[66:69], v[130:133], v[186:189], v[66:69]
	v_mfma_f32_16x16x32_bf16 v[150:153], v[114:117], v[166:169], v[150:153]
	v_mfma_f32_16x16x32_bf16 v[146:149], v[138:141], v[166:169], v[146:149]
	v_mfma_f32_16x16x32_bf16 v[126:129], v[114:117], v[174:177], v[126:129]
	v_mfma_f32_16x16x32_bf16 v[122:125], v[138:141], v[174:177], v[122:125]
	v_mfma_f32_16x16x32_bf16 v[102:105], v[114:117], v[182:185], v[102:105]
	v_mfma_f32_16x16x32_bf16 v[94:97], v[138:141], v[182:185], v[94:97]
	v_mfma_f32_16x16x32_bf16 v[70:73], v[114:117], v[190:193], v[70:73]
	v_mfma_f32_16x16x32_bf16 v[66:69], v[138:141], v[190:193], v[66:69]
	s_barrier
; #define PG8_STAGE(bufoff, gbase, voff) do { _Pragma("unroll") for (int _i = 0; _i < 2; ++_i) \
;         __builtin_amdgcn_global_load_lds((const unsigned*)((const char*)(gbase) + (voff)[_i]), (LAS unsigned*)(lds + (bufoff) + ldsw + _i * 8192), 16, 0, 0); } while (0)
; #define PG8_LDA(dst, b, h) do { _Pragma("unroll") for (int m = 0; m < 4; ++m) _Pragma("unroll") for (int k = 0; k < 2; ++k) dst[m][k] = *(const LAS bf16x8*)(lds + PG8_SA(b, h) + aoff + m * 2048 + k * 1024); } while (0)
; #define PG8_MMA(ai, bj, At, Bt) do { __builtin_amdgcn_s_setprio(1); _Pragma("unroll") for (int m = 0; m < 4; ++m) _Pragma("unroll") for (int n = 0; n < 2; ++n) _Pragma("unroll") for (int k = 0; k < 2; ++k) \
;         acc[ai][bj][m][n] = __builtin_amdgcn_mfma_f32_16x16x32_bf16(Bt[n][k], At[m][k], acc[ai][bj][m][n], 0, 0, 0); __builtin_amdgcn_s_setprio(0); } while (0)
; #define PG8_WAIT_V(n) asm volatile("s_waitcnt vmcnt(" #n ")" ::: "memory")
; #define PG8_WAIT_L(n) asm volatile("s_waitcnt lgkmcnt(" #n ")" ::: "memory")
; #define PG8_BAR __builtin_amdgcn_s_barrier()
; #define PG8_SCHED __builtin_amdgcn_sched_barrier(0)
; template <class Epi, bool ALIGN_EPI>
; __device__ __forceinline__ void gemm_phase(LAS unsigned char* lds, const Gemm g, const StaticOrder& S, const Epi& E) {
;     ...
;         for (int t = 0; t < nt; t += 2) {
;             const bool last = (t == nt - 2);
;             const char* a1 = cA + (size_t)(t + 1) * kstepA;
;             const char* a2 = last ? nA : cA + (size_t)(t + 2) * kstepA; const char* b2 = last ? nB : cB + (size_t)(t + 2) * kstep;
;     ...
;             PG8_LDA(At, 1, 1); PG8_STAGE(PG8_SB(1, 0), b3, voffB); PG8_STAGE(PG8_SB(1, 1), b3 + hsB, voffB); PG8_STAGE(PG8_SA(1, 0), a3, voffA);
;             PG8_WAIT_V(8); PG8_WAIT_L(0); PG8_BAR; PG8_MMA(1, 0, At, B0); PG8_MMA(1, 1, At, B1); PG8_BAR; PG8_SCHED;
;         }
	s_add_i32 s34, s52, s33
	v_lshl_add_u64 v[194:195], v[194:195], 0, s[12:13]
	s_mov_b32 m0, s34
	ds_read_b128 v[154:157], v234 offset:49152
	ds_read_b128 v[166:169], v234 offset:50176
	ds_read_b128 v[170:173], v234 offset:51200
	ds_read_b128 v[174:177], v234 offset:52224
	ds_read_b128 v[178:181], v234 offset:53248
	ds_read_b128 v[182:185], v234 offset:54272
	ds_read_b128 v[186:189], v234 offset:55296
	ds_read_b128 v[190:193], v234 offset:56320
	global_load_lds_dwordx4 v[194:195], off
	s_add_i32 m0, s34, 0x2000
	s_add_u32 s30, s30, 0x20080
	v_lshl_add_u64 v[194:195], v[196:197], 0, s[12:13]
	s_addc_u32 s31, s31, 0
	s_add_i32 s34, s53, s33
	global_load_lds_dwordx4 v[194:195], off
	v_lshl_add_u64 v[194:195], s[30:31], 0, v[200:201]
	s_mov_b32 m0, s34
	s_nop 0
	global_load_lds_dwordx4 v[194:195], off
	v_lshl_add_u64 v[194:195], s[30:31], 0, v[204:205]
	s_add_i32 m0, s34, 0x2000
	s_nop 0
	global_load_lds_dwordx4 v[194:195], off
	v_lshl_add_u64 v[194:195], v[214:215], 0, s[12:13]
	s_mov_b32 m0, s40
	s_nop 0
	global_load_lds_dwordx4 v[194:195], off
	v_lshl_add_u64 v[194:195], v[216:217], 0, s[12:13]
	s_mov_b32 m0, s41
	s_nop 0
	global_load_lds_dwordx4 v[194:195], off
	s_waitcnt vmcnt(8)
	s_waitcnt lgkmcnt(0)
	s_barrier
	s_waitcnt lgkmcnt(0)
	v_mfma_f32_16x16x32_bf16 v[62:65], v[74:77], v[154:157], v[62:65]
	v_mfma_f32_16x16x32_bf16 v[58:61], v[90:93], v[154:157], v[58:61]
	v_mfma_f32_16x16x32_bf16 v[46:49], v[74:77], v[170:173], v[46:49]
	v_mfma_f32_16x16x32_bf16 v[42:45], v[90:93], v[170:173], v[42:45]
	v_mfma_f32_16x16x32_bf16 v[30:33], v[74:77], v[178:181], v[30:33]
	v_mfma_f32_16x16x32_bf16 v[26:29], v[90:93], v[178:181], v[26:29]
	v_mfma_f32_16x16x32_bf16 v[14:17], v[74:77], v[186:189], v[14:17]
	v_mfma_f32_16x16x32_bf16 v[10:13], v[90:93], v[186:189], v[10:13]
	v_mfma_f32_16x16x32_bf16 v[62:65], v[82:85], v[166:169], v[62:65]
	v_mfma_f32_16x16x32_bf16 v[58:61], v[98:101], v[166:169], v[58:61]
	v_mfma_f32_16x16x32_bf16 v[46:49], v[82:85], v[174:177], v[46:49]
	v_mfma_f32_16x16x32_bf16 v[42:45], v[98:101], v[174:177], v[42:45]
	v_mfma_f32_16x16x32_bf16 v[30:33], v[82:85], v[182:185], v[30:33]
	v_mfma_f32_16x16x32_bf16 v[26:29], v[98:101], v[182:185], v[26:29]
	v_mfma_f32_16x16x32_bf16 v[14:17], v[82:85], v[190:193], v[14:17]
	v_mfma_f32_16x16x32_bf16 v[10:13], v[98:101], v[190:193], v[10:13]
	v_mfma_f32_16x16x32_bf16 v[54:57], v[106:109], v[154:157], v[54:57]
	v_mfma_f32_16x16x32_bf16 v[50:53], v[130:133], v[154:157], v[50:53]
	v_mfma_f32_16x16x32_bf16 v[38:41], v[106:109], v[170:173], v[38:41]
	v_mfma_f32_16x16x32_bf16 v[34:37], v[130:133], v[170:173], v[34:37]
	v_mfma_f32_16x16x32_bf16 v[22:25], v[106:109], v[178:181], v[22:25]
	v_mfma_f32_16x16x32_bf16 v[18:21], v[130:133], v[178:181], v[18:21]
	v_mfma_f32_16x16x32_bf16 v[6:9], v[106:109], v[186:189], v[6:9]
	v_mfma_f32_16x16x32_bf16 v[2:5], v[130:133], v[186:189], v[2:5]
	v_mfma_f32_16x16x32_bf16 v[54:57], v[114:117], v[166:169], v[54:57]
	v_mfma_f32_16x16x32_bf16 v[50:53], v[138:141], v[166:169], v[50:53]
	v_mfma_f32_16x16x32_bf16 v[38:41], v[114:117], v[174:177], v[38:41]
	v_mfma_f32_16x16x32_bf16 v[34:37], v[138:141], v[174:177], v[34:37]
	v_mfma_f32_16x16x32_bf16 v[22:25], v[114:117], v[182:185], v[22:25]
	v_mfma_f32_16x16x32_bf16 v[18:21], v[138:141], v[182:185], v[18:21]
	v_mfma_f32_16x16x32_bf16 v[6:9], v[114:117], v[190:193], v[6:9]
	v_mfma_f32_16x16x32_bf16 v[2:5], v[138:141], v[190:193], v[2:5]
	s_add_i32 s51, s51, 2
	s_add_u32 s26, s26, 0x100
	s_addc_u32 s27, s27, 0
	s_add_u32 s49, s49, 0x100
	s_addc_u32 s50, s50, 0
	s_cmp_gt_u32 s51, 5
	s_barrier
	s_cbranch_scc0 .LBB0_1027
	s_and_b64 vcc, exec, s[14:15]
	s_cbranch_vccz .LBB0_1030
	s_barrier

; #define PG8_STAGE(bufoff, gbase, voff) do { _Pragma("unroll") for (int _i = 0; _i < 2; ++_i) \
;         __builtin_amdgcn_global_load_lds((const unsigned*)((const char*)(gbase) + (voff)[_i]), (LAS unsigned*)(lds + (bufoff) + ldsw + _i * 8192), 16, 0, 0); } while (0)
; #define PG8_LDA(dst, b, h) do { _Pragma("unroll") for (int m = 0; m < 4; ++m) _Pragma("unroll") for (int k = 0; k < 2; ++k) dst[m][k] = *(const LAS bf16x8*)(lds + PG8_SA(b, h) + aoff + m * 2048 + k * 1024); } while (0)
; #define PG8_LDB(dst, b, h) do { _Pragma("unroll") for (int n = 0; n < 2; ++n) _Pragma("unroll") for (int k = 0; k < 2; ++k) dst[n][k] = *(const LAS bf16x8*)(lds + PG8_SB(b, h) + boff + n * 2048 + k * 1024); } while (0)
; #define PG8_MMA(ai, bj, At, Bt) do { __builtin_amdgcn_s_setprio(1); _Pragma("unroll") for (int m = 0; m < 4; ++m) _Pragma("unroll") for (int n = 0; n < 2; ++n) _Pragma("unroll") for (int k = 0; k < 2; ++k) \
;         acc[ai][bj][m][n] = __builtin_amdgcn_mfma_f32_16x16x32_bf16(Bt[n][k], At[m][k], acc[ai][bj][m][n], 0, 0, 0); __builtin_amdgcn_s_setprio(0); } while (0)
; #define PG8_WAIT_V(n) asm volatile("s_waitcnt vmcnt(" #n ")" ::: "memory")
; #define PG8_WAIT_L(n) asm volatile("s_waitcnt lgkmcnt(" #n ")" ::: "memory")
; #define PG8_BAR __builtin_amdgcn_s_barrier()
; #define PG8_SCHED __builtin_amdgcn_sched_barrier(0)
; template <class Epi, bool ALIGN_EPI>
; __device__ __forceinline__ void gemm_phase(LAS unsigned char* lds, const Gemm g, const StaticOrder& S, const Epi& E) {
;     ...
;         for (int t = 0; t < nt; t += 2) {
;             const bool last = (t == nt - 2);
;             const char* a1 = cA + (size_t)(t + 1) * kstepA;
;             const char* a2 = last ? nA : cA + (size_t)(t + 2) * kstepA; const char* b2 = last ? nB : cB + (size_t)(t + 2) * kstep;
;             const char* a3 = a2 + kstepA; const char* b3 = b2 + kstep;
;             PG8_LDB(B0, 0, 0); PG8_LDB(B1, 0, 1); PG8_SCHED; PG8_LDA(At, 0, 0); PG8_STAGE(PG8_SA(1, 1), a1 + hsA, voffA);
;             PG8_WAIT_V(8); PG8_WAIT_L(0); PG8_BAR; PG8_MMA(0, 0, At, B0); PG8_MMA(0, 1, At, B1); PG8_BAR; PG8_SCHED;
;             PG8_LDA(At, 0, 1); PG8_STAGE(PG8_SB(0, 0), b2, voffB); PG8_STAGE(PG8_SB(0, 1), b2 + hsB, voffB); PG8_STAGE(PG8_SA(0, 0), a2, voffA);
;             PG8_WAIT_V(8); PG8_WAIT_L(0); PG8_BAR; PG8_MMA(1, 0, At, B0); PG8_MMA(1, 1, At, B1); PG8_BAR; PG8_SCHED;
.LBB0_1106:
	ds_read_b128 v[146:149], v160
	ds_read_b128 v[150:153], v160 offset:1024
	ds_read_b128 v[154:157], v160 offset:2048
	ds_read_b128 v[164:167], v160 offset:3072
	ds_read_b128 v[168:171], v161
	ds_read_b128 v[172:175], v161 offset:1024
	ds_read_b128 v[176:179], v161 offset:2048
	ds_read_b128 v[180:183], v161 offset:3072
	s_add_u32 s36, s34, 0xfffe0080
	s_addc_u32 s37, s35, -1
	s_cmp_eq_u32 s55, 4
	s_cselect_b32 s39, s23, s37
	s_cselect_b32 s38, s51, s36
	s_cselect_b32 s37, s25, s54
	s_cselect_b32 s36, s52, s53
	v_lshl_add_u64 v[216:217], s[34:35], 0, v[138:139]
	s_add_i32 m0, s31, 0xc000
	ds_read_b128 v[184:187], v162
	ds_read_b128 v[188:191], v162 offset:1024
	ds_read_b128 v[192:195], v162 offset:2048
	ds_read_b128 v[196:199], v162 offset:3072
	ds_read_b128 v[200:203], v162 offset:4096
	ds_read_b128 v[204:207], v162 offset:5120
	ds_read_b128 v[208:211], v162 offset:6144
	ds_read_b128 v[212:215], v162 offset:7168
	global_load_lds_dwordx4 v[216:217], off
	v_lshl_add_u64 v[216:217], s[34:35], 0, v[140:141]
	s_add_i32 m0, s31, 0xe000
	s_nop 0
	global_load_lds_dwordx4 v[216:217], off
	s_waitcnt vmcnt(8)
	s_waitcnt lgkmcnt(0)
	s_barrier
	s_waitcnt lgkmcnt(0)
	v_mfma_f32_16x16x32_bf16 v[126:129], v[146:149], v[184:187], v[126:129]
	v_mfma_f32_16x16x32_bf16 v[122:125], v[154:157], v[184:187], v[122:125]
	v_mfma_f32_16x16x32_bf16 v[118:121], v[146:149], v[192:195], v[118:121]
	v_mfma_f32_16x16x32_bf16 v[106:109], v[154:157], v[192:195], v[106:109]
	v_mfma_f32_16x16x32_bf16 v[94:97], v[146:149], v[200:203], v[94:97]
	v_mfma_f32_16x16x32_bf16 v[90:93], v[154:157], v[200:203], v[90:93]
	v_mfma_f32_16x16x32_bf16 v[78:81], v[146:149], v[208:211], v[78:81]
	v_mfma_f32_16x16x32_bf16 v[74:77], v[154:157], v[208:211], v[74:77]
	v_mfma_f32_16x16x32_bf16 v[126:129], v[150:153], v[188:191], v[126:129]
	v_mfma_f32_16x16x32_bf16 v[122:125], v[164:167], v[188:191], v[122:125]
	v_mfma_f32_16x16x32_bf16 v[118:121], v[150:153], v[196:199], v[118:121]
	v_mfma_f32_16x16x32_bf16 v[106:109], v[164:167], v[196:199], v[106:109]
	v_mfma_f32_16x16x32_bf16 v[94:97], v[150:153], v[204:207], v[94:97]
	v_mfma_f32_16x16x32_bf16 v[90:93], v[164:167], v[204:207], v[90:93]
	v_mfma_f32_16x16x32_bf16 v[78:81], v[150:153], v[212:215], v[78:81]
	v_mfma_f32_16x16x32_bf16 v[74:77], v[164:167], v[212:215], v[74:77]
	v_mfma_f32_16x16x32_bf16 v[114:117], v[168:171], v[184:187], v[114:117]
	v_mfma_f32_16x16x32_bf16 v[110:113], v[176:179], v[184:187], v[110:113]
	v_mfma_f32_16x16x32_bf16 v[102:105], v[168:171], v[192:195], v[102:105]
	v_mfma_f32_16x16x32_bf16 v[98:101], v[176:179], v[192:195], v[98:101]
	v_mfma_f32_16x16x32_bf16 v[86:89], v[168:171], v[200:203], v[86:89]
	v_mfma_f32_16x16x32_bf16 v[82:85], v[176:179], v[200:203], v[82:85]
	v_mfma_f32_16x16x32_bf16 v[70:73], v[168:171], v[208:211], v[70:73]
	v_mfma_f32_16x16x32_bf16 v[66:69], v[176:179], v[208:211], v[66:69]
	v_mfma_f32_16x16x32_bf16 v[114:117], v[172:175], v[188:191], v[114:117]
	v_mfma_f32_16x16x32_bf16 v[110:113], v[180:183], v[188:191], v[110:113]
	v_mfma_f32_16x16x32_bf16 v[102:105], v[172:175], v[196:199], v[102:105]
	v_mfma_f32_16x16x32_bf16 v[98:101], v[180:183], v[196:199], v[98:101]
	v_mfma_f32_16x16x32_bf16 v[86:89], v[172:175], v[204:207], v[86:89]
	v_mfma_f32_16x16x32_bf16 v[82:85], v[180:183], v[204:207], v[82:85]
	v_mfma_f32_16x16x32_bf16 v[70:73], v[172:175], v[212:215], v[70:73]
	v_mfma_f32_16x16x32_bf16 v[66:69], v[180:183], v[212:215], v[66:69]
	s_barrier
	s_add_i32 s56, s48, s33
	v_lshl_add_u64 v[216:217], s[36:37], 0, v[132:133]
	s_mov_b32 m0, s56
	ds_read_b128 v[184:187], v162 offset:16384
	ds_read_b128 v[188:191], v162 offset:17408
	ds_read_b128 v[192:195], v162 offset:18432
	ds_read_b128 v[196:199], v162 offset:19456
	ds_read_b128 v[200:203], v162 offset:20480
	ds_read_b128 v[204:207], v162 offset:21504
	ds_read_b128 v[208:211], v162 offset:22528
	ds_read_b128 v[212:215], v162 offset:23552
	global_load_lds_dwordx4 v[216:217], off
	s_add_i32 m0, s56, 0x2000
	s_add_u32 s56, s36, 0x20000
	v_lshl_add_u64 v[218:219], s[36:37], 0, v[136:137]
	s_addc_u32 s57, s37, 0
	s_add_i32 s58, s49, s33
	global_load_lds_dwordx4 v[218:219], off
	v_lshl_add_u64 v[220:221], s[56:57], 0, v[132:133]
	s_mov_b32 m0, s58
	v_lshl_add_u64 v[222:223], s[38:39], 0, v[134:135]
	global_load_lds_dwordx4 v[220:221], off
	v_lshl_add_u64 v[220:221], s[56:57], 0, v[136:137]
	s_add_i32 m0, s58, 0x2000
	s_nop 0
	global_load_lds_dwordx4 v[220:221], off
	v_lshl_add_u64 v[220:221], s[38:39], 0, v[130:131]
	s_mov_b32 m0, s31
	s_nop 0
	global_load_lds_dwordx4 v[220:221], off
	s_mov_b32 m0, s40
	s_nop 0
	global_load_lds_dwordx4 v[222:223], off
	s_waitcnt vmcnt(8)
	s_waitcnt lgkmcnt(0)
	s_barrier
; #define PG8_STAGE(bufoff, gbase, voff) do { _Pragma("unroll") for (int _i = 0; _i < 2; ++_i) \
;         __builtin_amdgcn_global_load_lds((const unsigned*)((const char*)(gbase) + (voff)[_i]), (LAS unsigned*)(lds + (bufoff) + ldsw + _i * 8192), 16, 0, 0); } while (0)
; #define PG8_LDA(dst, b, h) do { _Pragma("unroll") for (int m = 0; m < 4; ++m) _Pragma("unroll") for (int k = 0; k < 2; ++k) dst[m][k] = *(const LAS bf16x8*)(lds + PG8_SA(b, h) + aoff + m * 2048 + k * 1024); } while (0)
; #define PG8_LDB(dst, b, h) do { _Pragma("unroll") for (int n = 0; n < 2; ++n) _Pragma("unroll") for (int k = 0; k < 2; ++k) dst[n][k] = *(const LAS bf16x8*)(lds + PG8_SB(b, h) + boff + n * 2048 + k * 1024); } while (0)
; #define PG8_MMA(ai, bj, At, Bt) do { __builtin_amdgcn_s_setprio(1); _Pragma("unroll") for (int m = 0; m < 4; ++m) _Pragma("unroll") for (int n = 0; n < 2; ++n) _Pragma("unroll") for (int k = 0; k < 2; ++k) \
;         acc[ai][bj][m][n] = __builtin_amdgcn_mfma_f32_16x16x32_bf16(Bt[n][k], At[m][k], acc[ai][bj][m][n], 0, 0, 0); __builtin_amdgcn_s_setprio(0); } while (0)
; #define PG8_WAIT_V(n) asm volatile("s_waitcnt vmcnt(" #n ")" ::: "memory")
; #define PG8_WAIT_L(n) asm volatile("s_waitcnt lgkmcnt(" #n ")" ::: "memory")
; #define PG8_BAR __builtin_amdgcn_s_barrier()
; #define PG8_SCHED __builtin_amdgcn_sched_barrier(0)
; template <class Epi, bool ALIGN_EPI>
; __device__ __forceinline__ void gemm_phase(LAS unsigned char* lds, const Gemm g, const StaticOrder& S, const Epi& E) {
;     ...
;             PG8_WAIT_V(8); PG8_WAIT_L(0); PG8_BAR; PG8_MMA(1, 0, At, B0); PG8_MMA(1, 1, At, B1); PG8_BAR; PG8_SCHED;
;             PG8_LDB(B0, 1, 0); PG8_LDB(B1, 1, 1); PG8_SCHED; PG8_LDA(At, 1, 0); PG8_STAGE(PG8_SA(0, 1), a2 + hsA, voffA);
;             PG8_WAIT_V(8); PG8_WAIT_L(0); PG8_BAR; PG8_MMA(0, 0, At, B0); PG8_MMA(0, 1, At, B1); PG8_BAR; PG8_SCHED;
	s_waitcnt lgkmcnt(0)
	v_mfma_f32_16x16x32_bf16 v[62:65], v[146:149], v[184:187], v[62:65]
	v_mfma_f32_16x16x32_bf16 v[58:61], v[154:157], v[184:187], v[58:61]
	v_mfma_f32_16x16x32_bf16 v[46:49], v[146:149], v[192:195], v[46:49]
	v_mfma_f32_16x16x32_bf16 v[42:45], v[154:157], v[192:195], v[42:45]
	v_mfma_f32_16x16x32_bf16 v[30:33], v[146:149], v[200:203], v[30:33]
	v_mfma_f32_16x16x32_bf16 v[26:29], v[154:157], v[200:203], v[26:29]
	v_mfma_f32_16x16x32_bf16 v[14:17], v[146:149], v[208:211], v[14:17]
	v_mfma_f32_16x16x32_bf16 v[10:13], v[154:157], v[208:211], v[10:13]
	v_mfma_f32_16x16x32_bf16 v[62:65], v[150:153], v[188:191], v[62:65]
	v_mfma_f32_16x16x32_bf16 v[58:61], v[164:167], v[188:191], v[58:61]
	v_mfma_f32_16x16x32_bf16 v[46:49], v[150:153], v[196:199], v[46:49]
	v_mfma_f32_16x16x32_bf16 v[42:45], v[164:167], v[196:199], v[42:45]
	v_mfma_f32_16x16x32_bf16 v[30:33], v[150:153], v[204:207], v[30:33]
	v_mfma_f32_16x16x32_bf16 v[26:29], v[164:167], v[204:207], v[26:29]
	v_mfma_f32_16x16x32_bf16 v[14:17], v[150:153], v[212:215], v[14:17]
	v_mfma_f32_16x16x32_bf16 v[10:13], v[164:167], v[212:215], v[10:13]
	v_mfma_f32_16x16x32_bf16 v[54:57], v[168:171], v[184:187], v[54:57]
	v_mfma_f32_16x16x32_bf16 v[50:53], v[176:179], v[184:187], v[50:53]
	v_mfma_f32_16x16x32_bf16 v[38:41], v[168:171], v[192:195], v[38:41]
	v_mfma_f32_16x16x32_bf16 v[34:37], v[176:179], v[192:195], v[34:37]
	v_mfma_f32_16x16x32_bf16 v[22:25], v[168:171], v[200:203], v[22:25]
	v_mfma_f32_16x16x32_bf16 v[18:21], v[176:179], v[200:203], v[18:21]
	v_mfma_f32_16x16x32_bf16 v[6:9], v[168:171], v[208:211], v[6:9]
	v_mfma_f32_16x16x32_bf16 v[2:5], v[176:179], v[208:211], v[2:5]
	v_mfma_f32_16x16x32_bf16 v[54:57], v[172:175], v[188:191], v[54:57]
	v_mfma_f32_16x16x32_bf16 v[50:53], v[180:183], v[188:191], v[50:53]
	v_mfma_f32_16x16x32_bf16 v[38:41], v[172:175], v[196:199], v[38:41]
	v_mfma_f32_16x16x32_bf16 v[34:37], v[180:183], v[196:199], v[34:37]
	v_mfma_f32_16x16x32_bf16 v[22:25], v[172:175], v[204:207], v[22:25]
	v_mfma_f32_16x16x32_bf16 v[18:21], v[180:183], v[204:207], v[18:21]
	v_mfma_f32_16x16x32_bf16 v[6:9], v[172:175], v[212:215], v[6:9]
	v_mfma_f32_16x16x32_bf16 v[2:5], v[180:183], v[212:215], v[2:5]
	s_barrier
	s_add_i32 s56, 0, 0x18000
	v_add_u32_e32 v163, s56, v158
	s_add_i32 s57, 0, 0x1c000
	ds_read_b128 v[146:149], v163
	ds_read_b128 v[150:153], v163 offset:1024
	ds_read_b128 v[154:157], v163 offset:2048
	ds_read_b128 v[164:167], v163 offset:3072
	v_add_u32_e32 v163, s57, v158
	ds_read_b128 v[168:171], v163
	ds_read_b128 v[172:175], v163 offset:1024
	ds_read_b128 v[176:179], v163 offset:2048
	ds_read_b128 v[180:183], v163 offset:3072
	s_add_u32 s38, s38, 0x20000
	s_addc_u32 s39, s39, 0
	s_mov_b32 m0, s41
	v_lshl_add_u64 v[224:225], s[38:39], 0, v[130:131]
	ds_read_b128 v[184:187], v162 offset:32768
	ds_read_b128 v[188:191], v162 offset:33792
	ds_read_b128 v[192:195], v162 offset:34816
	ds_read_b128 v[196:199], v162 offset:35840
	ds_read_b128 v[200:203], v162 offset:36864
	ds_read_b128 v[204:207], v162 offset:37888
	ds_read_b128 v[208:211], v162 offset:38912
	ds_read_b128 v[212:215], v162 offset:39936
	global_load_lds_dwordx4 v[224:225], off
	v_lshl_add_u64 v[224:225], s[38:39], 0, v[134:135]
	s_mov_b32 m0, s42
	s_nop 0
	global_load_lds_dwordx4 v[224:225], off
	s_waitcnt vmcnt(8)
	s_waitcnt lgkmcnt(0)
	s_barrier
	s_waitcnt lgkmcnt(0)
	v_mfma_f32_16x16x32_bf16 v[126:129], v[146:149], v[184:187], v[126:129]
	v_mfma_f32_16x16x32_bf16 v[122:125], v[154:157], v[184:187], v[122:125]
	v_mfma_f32_16x16x32_bf16 v[118:121], v[146:149], v[192:195], v[118:121]
	v_mfma_f32_16x16x32_bf16 v[106:109], v[154:157], v[192:195], v[106:109]
	v_mfma_f32_16x16x32_bf16 v[94:97], v[146:149], v[200:203], v[94:97]
	v_mfma_f32_16x16x32_bf16 v[90:93], v[154:157], v[200:203], v[90:93]
	v_mfma_f32_16x16x32_bf16 v[78:81], v[146:149], v[208:211], v[78:81]
	v_mfma_f32_16x16x32_bf16 v[74:77], v[154:157], v[208:211], v[74:77]
	v_mfma_f32_16x16x32_bf16 v[126:129], v[150:153], v[188:191], v[126:129]
	v_mfma_f32_16x16x32_bf16 v[122:125], v[164:167], v[188:191], v[122:125]
	v_mfma_f32_16x16x32_bf16 v[118:121], v[150:153], v[196:199], v[118:121]
	v_mfma_f32_16x16x32_bf16 v[106:109], v[164:167], v[196:199], v[106:109]
	v_mfma_f32_16x16x32_bf16 v[94:97], v[150:153], v[204:207], v[94:97]
	v_mfma_f32_16x16x32_bf16 v[90:93], v[164:167], v[204:207], v[90:93]
	v_mfma_f32_16x16x32_bf16 v[78:81], v[150:153], v[212:215], v[78:81]
	v_mfma_f32_16x16x32_bf16 v[74:77], v[164:167], v[212:215], v[74:77]
	v_mfma_f32_16x16x32_bf16 v[114:117], v[168:171], v[184:187], v[114:117]
	v_mfma_f32_16x16x32_bf16 v[110:113], v[176:179], v[184:187], v[110:113]
	v_mfma_f32_16x16x32_bf16 v[102:105], v[168:171], v[192:195], v[102:105]
	v_mfma_f32_16x16x32_bf16 v[98:101], v[176:179], v[192:195], v[98:101]
	v_mfma_f32_16x16x32_bf16 v[86:89], v[168:171], v[200:203], v[86:89]
	v_mfma_f32_16x16x32_bf16 v[82:85], v[176:179], v[200:203], v[82:85]
	v_mfma_f32_16x16x32_bf16 v[70:73], v[168:171], v[208:211], v[70:73]
	v_mfma_f32_16x16x32_bf16 v[66:69], v[176:179], v[208:211], v[66:69]
	v_mfma_f32_16x16x32_bf16 v[114:117], v[172:175], v[188:191], v[114:117]
	v_mfma_f32_16x16x32_bf16 v[110:113], v[180:183], v[188:191], v[110:113]
	v_mfma_f32_16x16x32_bf16 v[102:105], v[172:175], v[196:199], v[102:105]
	v_mfma_f32_16x16x32_bf16 v[98:101], v[180:183], v[196:199], v[98:101]
	v_mfma_f32_16x16x32_bf16 v[86:89], v[172:175], v[204:207], v[86:89]
	v_mfma_f32_16x16x32_bf16 v[82:85], v[180:183], v[204:207], v[82:85]
	v_mfma_f32_16x16x32_bf16 v[70:73], v[172:175], v[212:215], v[70:73]
	v_mfma_f32_16x16x32_bf16 v[66:69], v[180:183], v[212:215], v[66:69]
	s_barrier
; #define PG8_STAGE(bufoff, gbase, voff) do { _Pragma("unroll") for (int _i = 0; _i < 2; ++_i) \
;         __builtin_amdgcn_global_load_lds((const unsigned*)((const char*)(gbase) + (voff)[_i]), (LAS unsigned*)(lds + (bufoff) + ldsw + _i * 8192), 16, 0, 0); } while (0)
; #define PG8_LDA(dst, b, h) do { _Pragma("unroll") for (int m = 0; m < 4; ++m) _Pragma("unroll") for (int k = 0; k < 2; ++k) dst[m][k] = *(const LAS bf16x8*)(lds + PG8_SA(b, h) + aoff + m * 2048 + k * 1024); } while (0)
; #define PG8_MMA(ai, bj, At, Bt) do { __builtin_amdgcn_s_setprio(1); _Pragma("unroll") for (int m = 0; m < 4; ++m) _Pragma("unroll") for (int n = 0; n < 2; ++n) _Pragma("unroll") for (int k = 0; k < 2; ++k) \
;         acc[ai][bj][m][n] = __builtin_amdgcn_mfma_f32_16x16x32_bf16(Bt[n][k], At[m][k], acc[ai][bj][m][n], 0, 0, 0); __builtin_amdgcn_s_setprio(0); } while (0)
; #define PG8_WAIT_V(n) asm volatile("s_waitcnt vmcnt(" #n ")" ::: "memory")
; #define PG8_WAIT_L(n) asm volatile("s_waitcnt lgkmcnt(" #n ")" ::: "memory")
; #define PG8_BAR __builtin_amdgcn_s_barrier()
; #define PG8_SCHED __builtin_amdgcn_sched_barrier(0)
; template <class Epi, bool ALIGN_EPI>
; __device__ __forceinline__ void gemm_phase(LAS unsigned char* lds, const Gemm g, const StaticOrder& S, const Epi& E) {
;     ...
;         for (int t = 0; t < nt; t += 2) {
;             const bool last = (t == nt - 2);
;             const char* a1 = cA + (size_t)(t + 1) * kstepA;
;             const char* a2 = last ? nA : cA + (size_t)(t + 2) * kstepA; const char* b2 = last ? nB : cB + (size_t)(t + 2) * kstep;
;     ...
;             PG8_LDA(At, 1, 1); PG8_STAGE(PG8_SB(1, 0), b3, voffB); PG8_STAGE(PG8_SB(1, 1), b3 + hsB, voffB); PG8_STAGE(PG8_SA(1, 0), a3, voffA);
;             PG8_WAIT_V(8); PG8_WAIT_L(0); PG8_BAR; PG8_MMA(1, 0, At, B0); PG8_MMA(1, 1, At, B1); PG8_BAR; PG8_SCHED;
;         }
	s_add_i32 s38, s56, s33
	v_lshl_add_u64 v[216:217], v[216:217], 0, s[10:11]
	s_mov_b32 m0, s38
	ds_read_b128 v[184:187], v162 offset:49152
	ds_read_b128 v[188:191], v162 offset:50176
	ds_read_b128 v[192:195], v162 offset:51200
	ds_read_b128 v[196:199], v162 offset:52224
	ds_read_b128 v[200:203], v162 offset:53248
	ds_read_b128 v[204:207], v162 offset:54272
	ds_read_b128 v[208:211], v162 offset:55296
	ds_read_b128 v[212:215], v162 offset:56320
	global_load_lds_dwordx4 v[216:217], off
	s_add_i32 m0, s38, 0x2000
	s_add_u32 s36, s36, 0x20080
	v_lshl_add_u64 v[216:217], v[218:219], 0, s[10:11]
	s_addc_u32 s37, s37, 0
	s_add_i32 s38, s57, s33
	global_load_lds_dwordx4 v[216:217], off
	v_lshl_add_u64 v[216:217], s[36:37], 0, v[132:133]
	s_mov_b32 m0, s38
	s_nop 0
	global_load_lds_dwordx4 v[216:217], off
	v_lshl_add_u64 v[216:217], s[36:37], 0, v[136:137]
	s_add_i32 m0, s38, 0x2000
	s_nop 0
	global_load_lds_dwordx4 v[216:217], off
	v_lshl_add_u64 v[216:217], v[220:221], 0, s[10:11]
	s_mov_b32 m0, s44
	s_nop 0
	global_load_lds_dwordx4 v[216:217], off
	v_lshl_add_u64 v[216:217], v[222:223], 0, s[10:11]
	s_mov_b32 m0, s45
	s_nop 0
	global_load_lds_dwordx4 v[216:217], off
	s_waitcnt vmcnt(8)
	s_waitcnt lgkmcnt(0)
	s_barrier
	s_waitcnt lgkmcnt(0)
	v_mfma_f32_16x16x32_bf16 v[62:65], v[146:149], v[184:187], v[62:65]
	v_mfma_f32_16x16x32_bf16 v[58:61], v[154:157], v[184:187], v[58:61]
	v_mfma_f32_16x16x32_bf16 v[46:49], v[146:149], v[192:195], v[46:49]
	v_mfma_f32_16x16x32_bf16 v[42:45], v[154:157], v[192:195], v[42:45]
	v_mfma_f32_16x16x32_bf16 v[30:33], v[146:149], v[200:203], v[30:33]
	v_mfma_f32_16x16x32_bf16 v[26:29], v[154:157], v[200:203], v[26:29]
	v_mfma_f32_16x16x32_bf16 v[14:17], v[146:149], v[208:211], v[14:17]
	v_mfma_f32_16x16x32_bf16 v[10:13], v[154:157], v[208:211], v[10:13]
	v_mfma_f32_16x16x32_bf16 v[62:65], v[150:153], v[188:191], v[62:65]
	v_mfma_f32_16x16x32_bf16 v[58:61], v[164:167], v[188:191], v[58:61]
	v_mfma_f32_16x16x32_bf16 v[46:49], v[150:153], v[196:199], v[46:49]
	v_mfma_f32_16x16x32_bf16 v[42:45], v[164:167], v[196:199], v[42:45]
	v_mfma_f32_16x16x32_bf16 v[30:33], v[150:153], v[204:207], v[30:33]
	v_mfma_f32_16x16x32_bf16 v[26:29], v[164:167], v[204:207], v[26:29]
	v_mfma_f32_16x16x32_bf16 v[14:17], v[150:153], v[212:215], v[14:17]
	v_mfma_f32_16x16x32_bf16 v[10:13], v[164:167], v[212:215], v[10:13]
	v_mfma_f32_16x16x32_bf16 v[54:57], v[168:171], v[184:187], v[54:57]
	v_mfma_f32_16x16x32_bf16 v[50:53], v[176:179], v[184:187], v[50:53]
	v_mfma_f32_16x16x32_bf16 v[38:41], v[168:171], v[192:195], v[38:41]
	v_mfma_f32_16x16x32_bf16 v[34:37], v[176:179], v[192:195], v[34:37]
	v_mfma_f32_16x16x32_bf16 v[22:25], v[168:171], v[200:203], v[22:25]
	v_mfma_f32_16x16x32_bf16 v[18:21], v[176:179], v[200:203], v[18:21]
	v_mfma_f32_16x16x32_bf16 v[6:9], v[168:171], v[208:211], v[6:9]
	v_mfma_f32_16x16x32_bf16 v[2:5], v[176:179], v[208:211], v[2:5]
	v_mfma_f32_16x16x32_bf16 v[54:57], v[172:175], v[188:191], v[54:57]
	v_mfma_f32_16x16x32_bf16 v[50:53], v[180:183], v[188:191], v[50:53]
	v_mfma_f32_16x16x32_bf16 v[38:41], v[172:175], v[196:199], v[38:41]
	v_mfma_f32_16x16x32_bf16 v[34:37], v[180:183], v[196:199], v[34:37]
	v_mfma_f32_16x16x32_bf16 v[22:25], v[172:175], v[204:207], v[22:25]
	v_mfma_f32_16x16x32_bf16 v[18:21], v[180:183], v[204:207], v[18:21]
	v_mfma_f32_16x16x32_bf16 v[6:9], v[172:175], v[212:215], v[6:9]
	v_mfma_f32_16x16x32_bf16 v[2:5], v[180:183], v[212:215], v[2:5]
	s_add_i32 s55, s55, 2
	s_add_u32 s34, s34, 0x100
	s_addc_u32 s35, s35, 0
	s_add_u32 s53, s53, 0x100
	s_addc_u32 s54, s54, 0
	s_cmp_gt_u32 s55, 5
	s_barrier
	s_cbranch_scc0 .LBB0_1106
	v_readlane_b32 s52, v251, 40
	s_and_b64 vcc, exec, s[12:13]
	v_readlane_b32 s66, v251, 54
	v_readlane_b32 s67, v251, 55
	v_readlane_b32 s53, v251, 41
	v_readlane_b32 s54, v251, 42
	v_readlane_b32 s55, v251, 43
	v_readlane_b32 s56, v251, 44
	v_readlane_b32 s57, v251, 45
	v_readlane_b32 s58, v251, 46
	v_readlane_b32 s59, v251, 47
	v_readlane_b32 s60, v251, 48
	v_readlane_b32 s61, v251, 49
	v_readlane_b32 s62, v251, 50
	v_readlane_b32 s63, v251, 51
	v_readlane_b32 s64, v251, 52
	v_readlane_b32 s65, v251, 53
	s_cbranch_vccz .LBB0_1109
	s_barrier

; #define PG8_STAGE(bufoff, gbase, voff) do { _Pragma("unroll") for (int _i = 0; _i < 2; ++_i) \
;         __builtin_amdgcn_global_load_lds((const unsigned*)((const char*)(gbase) + (voff)[_i]), (LAS unsigned*)(lds + (bufoff) + ldsw + _i * 8192), 16, 0, 0); } while (0)
; #define PG8_LDA(dst, b, h) do { _Pragma("unroll") for (int m = 0; m < 4; ++m) _Pragma("unroll") for (int k = 0; k < 2; ++k) dst[m][k] = *(const LAS bf16x8*)(lds + PG8_SA(b, h) + aoff + m * 2048 + k * 1024); } while (0)
; #define PG8_LDB(dst, b, h) do { _Pragma("unroll") for (int n = 0; n < 2; ++n) _Pragma("unroll") for (int k = 0; k < 2; ++k) dst[n][k] = *(const LAS bf16x8*)(lds + PG8_SB(b, h) + boff + n * 2048 + k * 1024); } while (0)
; #define PG8_MMA(ai, bj, At, Bt) do { __builtin_amdgcn_s_setprio(1); _Pragma("unroll") for (int m = 0; m < 4; ++m) _Pragma("unroll") for (int n = 0; n < 2; ++n) _Pragma("unroll") for (int k = 0; k < 2; ++k) \
;         acc[ai][bj][m][n] = __builtin_amdgcn_mfma_f32_16x16x32_bf16(Bt[n][k], At[m][k], acc[ai][bj][m][n], 0, 0, 0); __builtin_amdgcn_s_setprio(0); } while (0)
; #define PG8_WAIT_V(n) asm volatile("s_waitcnt vmcnt(" #n ")" ::: "memory")
; #define PG8_WAIT_L(n) asm volatile("s_waitcnt lgkmcnt(" #n ")" ::: "memory")
; #define PG8_BAR __builtin_amdgcn_s_barrier()
; #define PG8_SCHED __builtin_amdgcn_sched_barrier(0)
; template <class Epi, bool ALIGN_EPI>
; __device__ __forceinline__ void gemm_phase(LAS unsigned char* lds, const Gemm g, const StaticOrder& S, const Epi& E) {
;     ...
;         for (int t = 0; t < nt; t += 2) {
;             const bool last = (t == nt - 2);
;             const char* a1 = cA + (size_t)(t + 1) * kstepA;
;             const char* a2 = last ? nA : cA + (size_t)(t + 2) * kstepA; const char* b2 = last ? nB : cB + (size_t)(t + 2) * kstep;
;             const char* a3 = a2 + kstepA; const char* b3 = b2 + kstep;
;             PG8_LDB(B0, 0, 0); PG8_LDB(B1, 0, 1); PG8_SCHED; PG8_LDA(At, 0, 0); PG8_STAGE(PG8_SA(1, 1), a1 + hsA, voffA);
;             PG8_WAIT_V(8); PG8_WAIT_L(0); PG8_BAR; PG8_MMA(0, 0, At, B0); PG8_MMA(0, 1, At, B1); PG8_BAR; PG8_SCHED;
;             PG8_LDA(At, 0, 1); PG8_STAGE(PG8_SB(0, 0), b2, voffB); PG8_STAGE(PG8_SB(0, 1), b2 + hsB, voffB); PG8_STAGE(PG8_SA(0, 0), a2, voffA);
;             PG8_WAIT_V(8); PG8_WAIT_L(0); PG8_BAR; PG8_MMA(1, 0, At, B0); PG8_MMA(1, 1, At, B1); PG8_BAR; PG8_SCHED;
.LBB0_1131:
	ds_read_b128 v[130:133], v184
	ds_read_b128 v[134:137], v184 offset:1024
	ds_read_b128 v[138:141], v184 offset:2048
	ds_read_b128 v[142:145], v184 offset:3072
	ds_read_b128 v[162:165], v185
	ds_read_b128 v[166:169], v185 offset:1024
	ds_read_b128 v[170:173], v185 offset:2048
	ds_read_b128 v[174:177], v185 offset:3072
	s_add_u32 s38, s36, 0xfffe0080
	s_addc_u32 s39, s37, -1
	s_cmp_eq_u32 s57, 4
	s_cselect_b32 s41, s25, s39
	s_cselect_b32 s40, s53, s38
	s_cselect_b32 s39, s27, s56
	s_cselect_b32 s38, s54, s55
	v_lshl_add_u64 v[216:217], s[36:37], 0, v[154:155]
	s_add_i32 m0, s35, 0xc000
	ds_read_b128 v[178:181], v186
	ds_read_b128 v[188:191], v186 offset:1024
	ds_read_b128 v[192:195], v186 offset:2048
	ds_read_b128 v[196:199], v186 offset:3072
	ds_read_b128 v[200:203], v186 offset:4096
	ds_read_b128 v[204:207], v186 offset:5120
	ds_read_b128 v[208:211], v186 offset:6144
	ds_read_b128 v[212:215], v186 offset:7168
	global_load_lds_dwordx4 v[216:217], off
	v_lshl_add_u64 v[216:217], s[36:37], 0, v[156:157]
	s_add_i32 m0, s35, 0xe000
	s_nop 0
	global_load_lds_dwordx4 v[216:217], off
	s_waitcnt vmcnt(8)
	s_waitcnt lgkmcnt(0)
	s_barrier
	s_waitcnt lgkmcnt(0)
	v_mfma_f32_16x16x32_bf16 v[126:129], v[130:133], v[178:181], v[126:129]
	v_mfma_f32_16x16x32_bf16 v[122:125], v[138:141], v[178:181], v[122:125]
	v_mfma_f32_16x16x32_bf16 v[110:113], v[130:133], v[192:195], v[110:113]
	v_mfma_f32_16x16x32_bf16 v[106:109], v[138:141], v[192:195], v[106:109]
	v_mfma_f32_16x16x32_bf16 v[94:97], v[130:133], v[200:203], v[94:97]
	v_mfma_f32_16x16x32_bf16 v[90:93], v[138:141], v[200:203], v[90:93]
	v_mfma_f32_16x16x32_bf16 v[78:81], v[130:133], v[208:211], v[78:81]
	v_mfma_f32_16x16x32_bf16 v[74:77], v[138:141], v[208:211], v[74:77]
	v_mfma_f32_16x16x32_bf16 v[126:129], v[134:137], v[188:191], v[126:129]
	v_mfma_f32_16x16x32_bf16 v[122:125], v[142:145], v[188:191], v[122:125]
	v_mfma_f32_16x16x32_bf16 v[110:113], v[134:137], v[196:199], v[110:113]
	v_mfma_f32_16x16x32_bf16 v[106:109], v[142:145], v[196:199], v[106:109]
	v_mfma_f32_16x16x32_bf16 v[94:97], v[134:137], v[204:207], v[94:97]
	v_mfma_f32_16x16x32_bf16 v[90:93], v[142:145], v[204:207], v[90:93]
	v_mfma_f32_16x16x32_bf16 v[78:81], v[134:137], v[212:215], v[78:81]
	v_mfma_f32_16x16x32_bf16 v[74:77], v[142:145], v[212:215], v[74:77]
	v_mfma_f32_16x16x32_bf16 v[118:121], v[162:165], v[178:181], v[118:121]
	v_mfma_f32_16x16x32_bf16 v[114:117], v[170:173], v[178:181], v[114:117]
	v_mfma_f32_16x16x32_bf16 v[102:105], v[162:165], v[192:195], v[102:105]
	v_mfma_f32_16x16x32_bf16 v[98:101], v[170:173], v[192:195], v[98:101]
	v_mfma_f32_16x16x32_bf16 v[86:89], v[162:165], v[200:203], v[86:89]
	v_mfma_f32_16x16x32_bf16 v[82:85], v[170:173], v[200:203], v[82:85]
	v_mfma_f32_16x16x32_bf16 v[70:73], v[162:165], v[208:211], v[70:73]
	v_mfma_f32_16x16x32_bf16 v[66:69], v[170:173], v[208:211], v[66:69]
	v_mfma_f32_16x16x32_bf16 v[118:121], v[166:169], v[188:191], v[118:121]
	v_mfma_f32_16x16x32_bf16 v[114:117], v[174:177], v[188:191], v[114:117]
	v_mfma_f32_16x16x32_bf16 v[102:105], v[166:169], v[196:199], v[102:105]
	v_mfma_f32_16x16x32_bf16 v[98:101], v[174:177], v[196:199], v[98:101]
	v_mfma_f32_16x16x32_bf16 v[86:89], v[166:169], v[204:207], v[86:89]
	v_mfma_f32_16x16x32_bf16 v[82:85], v[174:177], v[204:207], v[82:85]
	v_mfma_f32_16x16x32_bf16 v[70:73], v[166:169], v[212:215], v[70:73]
	v_mfma_f32_16x16x32_bf16 v[66:69], v[174:177], v[212:215], v[66:69]
	s_barrier
	s_add_i32 s58, s50, s33
	v_lshl_add_u64 v[216:217], s[38:39], 0, v[148:149]
	s_mov_b32 m0, s58
	ds_read_b128 v[178:181], v186 offset:16384
	ds_read_b128 v[188:191], v186 offset:17408
	ds_read_b128 v[192:195], v186 offset:18432
	ds_read_b128 v[196:199], v186 offset:19456
	ds_read_b128 v[200:203], v186 offset:20480
	ds_read_b128 v[204:207], v186 offset:21504
	ds_read_b128 v[208:211], v186 offset:22528
	ds_read_b128 v[212:215], v186 offset:23552
	global_load_lds_dwordx4 v[216:217], off
	s_add_i32 m0, s58, 0x2000
	s_add_u32 s58, s38, 0x20000
	v_lshl_add_u64 v[218:219], s[38:39], 0, v[152:153]
	s_addc_u32 s59, s39, 0
	s_add_i32 s60, s51, s33
	global_load_lds_dwordx4 v[218:219], off
	v_lshl_add_u64 v[220:221], s[58:59], 0, v[148:149]
	s_mov_b32 m0, s60
	v_lshl_add_u64 v[222:223], s[40:41], 0, v[150:151]
	global_load_lds_dwordx4 v[220:221], off
	v_lshl_add_u64 v[220:221], s[58:59], 0, v[152:153]
	s_add_i32 m0, s60, 0x2000
	s_nop 0
	global_load_lds_dwordx4 v[220:221], off
	v_lshl_add_u64 v[220:221], s[40:41], 0, v[146:147]
	s_mov_b32 m0, s35
	s_nop 0
	global_load_lds_dwordx4 v[220:221], off
	s_mov_b32 m0, s42
	s_nop 0
	global_load_lds_dwordx4 v[222:223], off
	s_waitcnt vmcnt(8)
	s_waitcnt lgkmcnt(0)
	s_barrier
; #define PG8_STAGE(bufoff, gbase, voff) do { _Pragma("unroll") for (int _i = 0; _i < 2; ++_i) \
;         __builtin_amdgcn_global_load_lds((const unsigned*)((const char*)(gbase) + (voff)[_i]), (LAS unsigned*)(lds + (bufoff) + ldsw + _i * 8192), 16, 0, 0); } while (0)
; #define PG8_LDA(dst, b, h) do { _Pragma("unroll") for (int m = 0; m < 4; ++m) _Pragma("unroll") for (int k = 0; k < 2; ++k) dst[m][k] = *(const LAS bf16x8*)(lds + PG8_SA(b, h) + aoff + m * 2048 + k * 1024); } while (0)
; #define PG8_LDB(dst, b, h) do { _Pragma("unroll") for (int n = 0; n < 2; ++n) _Pragma("unroll") for (int k = 0; k < 2; ++k) dst[n][k] = *(const LAS bf16x8*)(lds + PG8_SB(b, h) + boff + n * 2048 + k * 1024); } while (0)
; #define PG8_MMA(ai, bj, At, Bt) do { __builtin_amdgcn_s_setprio(1); _Pragma("unroll") for (int m = 0; m < 4; ++m) _Pragma("unroll") for (int n = 0; n < 2; ++n) _Pragma("unroll") for (int k = 0; k < 2; ++k) \
;         acc[ai][bj][m][n] = __builtin_amdgcn_mfma_f32_16x16x32_bf16(Bt[n][k], At[m][k], acc[ai][bj][m][n], 0, 0, 0); __builtin_amdgcn_s_setprio(0); } while (0)
; #define PG8_WAIT_V(n) asm volatile("s_waitcnt vmcnt(" #n ")" ::: "memory")
; #define PG8_WAIT_L(n) asm volatile("s_waitcnt lgkmcnt(" #n ")" ::: "memory")
; #define PG8_BAR __builtin_amdgcn_s_barrier()
; #define PG8_SCHED __builtin_amdgcn_sched_barrier(0)
; template <class Epi, bool ALIGN_EPI>
; __device__ __forceinline__ void gemm_phase(LAS unsigned char* lds, const Gemm g, const StaticOrder& S, const Epi& E) {
;     ...
;             PG8_WAIT_V(8); PG8_WAIT_L(0); PG8_BAR; PG8_MMA(1, 0, At, B0); PG8_MMA(1, 1, At, B1); PG8_BAR; PG8_SCHED;
;             PG8_LDB(B0, 1, 0); PG8_LDB(B1, 1, 1); PG8_SCHED; PG8_LDA(At, 1, 0); PG8_STAGE(PG8_SA(0, 1), a2 + hsA, voffA);
;             PG8_WAIT_V(8); PG8_WAIT_L(0); PG8_BAR; PG8_MMA(0, 0, At, B0); PG8_MMA(0, 1, At, B1); PG8_BAR; PG8_SCHED;
	s_waitcnt lgkmcnt(0)
	v_mfma_f32_16x16x32_bf16 v[62:65], v[130:133], v[178:181], v[62:65]
	v_mfma_f32_16x16x32_bf16 v[58:61], v[138:141], v[178:181], v[58:61]
	v_mfma_f32_16x16x32_bf16 v[46:49], v[130:133], v[192:195], v[46:49]
	v_mfma_f32_16x16x32_bf16 v[42:45], v[138:141], v[192:195], v[42:45]
	v_mfma_f32_16x16x32_bf16 v[30:33], v[130:133], v[200:203], v[30:33]
	v_mfma_f32_16x16x32_bf16 v[26:29], v[138:141], v[200:203], v[26:29]
	v_mfma_f32_16x16x32_bf16 v[14:17], v[130:133], v[208:211], v[14:17]
	v_mfma_f32_16x16x32_bf16 v[10:13], v[138:141], v[208:211], v[10:13]
	v_mfma_f32_16x16x32_bf16 v[62:65], v[134:137], v[188:191], v[62:65]
	v_mfma_f32_16x16x32_bf16 v[58:61], v[142:145], v[188:191], v[58:61]
	v_mfma_f32_16x16x32_bf16 v[46:49], v[134:137], v[196:199], v[46:49]
	v_mfma_f32_16x16x32_bf16 v[42:45], v[142:145], v[196:199], v[42:45]
	v_mfma_f32_16x16x32_bf16 v[30:33], v[134:137], v[204:207], v[30:33]
	v_mfma_f32_16x16x32_bf16 v[26:29], v[142:145], v[204:207], v[26:29]
	v_mfma_f32_16x16x32_bf16 v[14:17], v[134:137], v[212:215], v[14:17]
	v_mfma_f32_16x16x32_bf16 v[10:13], v[142:145], v[212:215], v[10:13]
	v_mfma_f32_16x16x32_bf16 v[54:57], v[162:165], v[178:181], v[54:57]
	v_mfma_f32_16x16x32_bf16 v[50:53], v[170:173], v[178:181], v[50:53]
	v_mfma_f32_16x16x32_bf16 v[38:41], v[162:165], v[192:195], v[38:41]
	v_mfma_f32_16x16x32_bf16 v[34:37], v[170:173], v[192:195], v[34:37]
	v_mfma_f32_16x16x32_bf16 v[22:25], v[162:165], v[200:203], v[22:25]
	v_mfma_f32_16x16x32_bf16 v[18:21], v[170:173], v[200:203], v[18:21]
	v_mfma_f32_16x16x32_bf16 v[6:9], v[162:165], v[208:211], v[6:9]
	v_mfma_f32_16x16x32_bf16 v[2:5], v[170:173], v[208:211], v[2:5]
	v_mfma_f32_16x16x32_bf16 v[54:57], v[166:169], v[188:191], v[54:57]
	v_mfma_f32_16x16x32_bf16 v[50:53], v[174:177], v[188:191], v[50:53]
	v_mfma_f32_16x16x32_bf16 v[38:41], v[166:169], v[196:199], v[38:41]
	v_mfma_f32_16x16x32_bf16 v[34:37], v[174:177], v[196:199], v[34:37]
	v_mfma_f32_16x16x32_bf16 v[22:25], v[166:169], v[204:207], v[22:25]
	v_mfma_f32_16x16x32_bf16 v[18:21], v[174:177], v[204:207], v[18:21]
	v_mfma_f32_16x16x32_bf16 v[6:9], v[166:169], v[212:215], v[6:9]
	v_mfma_f32_16x16x32_bf16 v[2:5], v[174:177], v[212:215], v[2:5]
	s_barrier
	s_add_i32 s58, 0, 0x18000
	s_add_i32 s59, 0, 0x1c000
	v_add_u32_e32 v142, s58, v182
	v_add_u32_e32 v174, s59, v182
	ds_read_b128 v[130:133], v142
	ds_read_b128 v[134:137], v142 offset:1024
	ds_read_b128 v[138:141], v142 offset:2048
	ds_read_b128 v[142:145], v142 offset:3072
	ds_read_b128 v[162:165], v174
	ds_read_b128 v[166:169], v174 offset:1024
	ds_read_b128 v[170:173], v174 offset:2048
	ds_read_b128 v[174:177], v174 offset:3072
	s_add_u32 s40, s40, 0x20000
	s_addc_u32 s41, s41, 0
	s_mov_b32 m0, s43
	v_lshl_add_u64 v[224:225], s[40:41], 0, v[146:147]
	ds_read_b128 v[178:181], v186 offset:32768
	ds_read_b128 v[188:191], v186 offset:33792
	ds_read_b128 v[192:195], v186 offset:34816
	ds_read_b128 v[196:199], v186 offset:35840
	ds_read_b128 v[200:203], v186 offset:36864
	ds_read_b128 v[204:207], v186 offset:37888
	ds_read_b128 v[208:211], v186 offset:38912
	ds_read_b128 v[212:215], v186 offset:39936
	global_load_lds_dwordx4 v[224:225], off
	v_lshl_add_u64 v[224:225], s[40:41], 0, v[150:151]
	s_mov_b32 m0, s44
	s_nop 0
	global_load_lds_dwordx4 v[224:225], off
	s_waitcnt vmcnt(8)
	s_waitcnt lgkmcnt(0)
	s_barrier
	s_waitcnt lgkmcnt(0)
	v_mfma_f32_16x16x32_bf16 v[126:129], v[130:133], v[178:181], v[126:129]
	v_mfma_f32_16x16x32_bf16 v[122:125], v[138:141], v[178:181], v[122:125]
	v_mfma_f32_16x16x32_bf16 v[110:113], v[130:133], v[192:195], v[110:113]
	v_mfma_f32_16x16x32_bf16 v[106:109], v[138:141], v[192:195], v[106:109]
	v_mfma_f32_16x16x32_bf16 v[94:97], v[130:133], v[200:203], v[94:97]
	v_mfma_f32_16x16x32_bf16 v[90:93], v[138:141], v[200:203], v[90:93]
	v_mfma_f32_16x16x32_bf16 v[78:81], v[130:133], v[208:211], v[78:81]
	v_mfma_f32_16x16x32_bf16 v[74:77], v[138:141], v[208:211], v[74:77]
	v_mfma_f32_16x16x32_bf16 v[126:129], v[134:137], v[188:191], v[126:129]
	v_mfma_f32_16x16x32_bf16 v[122:125], v[142:145], v[188:191], v[122:125]
	v_mfma_f32_16x16x32_bf16 v[110:113], v[134:137], v[196:199], v[110:113]
	v_mfma_f32_16x16x32_bf16 v[106:109], v[142:145], v[196:199], v[106:109]
	v_mfma_f32_16x16x32_bf16 v[94:97], v[134:137], v[204:207], v[94:97]
	v_mfma_f32_16x16x32_bf16 v[90:93], v[142:145], v[204:207], v[90:93]
	v_mfma_f32_16x16x32_bf16 v[78:81], v[134:137], v[212:215], v[78:81]
	v_mfma_f32_16x16x32_bf16 v[74:77], v[142:145], v[212:215], v[74:77]
	v_mfma_f32_16x16x32_bf16 v[118:121], v[162:165], v[178:181], v[118:121]
	v_mfma_f32_16x16x32_bf16 v[114:117], v[170:173], v[178:181], v[114:117]
	v_mfma_f32_16x16x32_bf16 v[102:105], v[162:165], v[192:195], v[102:105]
	v_mfma_f32_16x16x32_bf16 v[98:101], v[170:173], v[192:195], v[98:101]
	v_mfma_f32_16x16x32_bf16 v[86:89], v[162:165], v[200:203], v[86:89]
	v_mfma_f32_16x16x32_bf16 v[82:85], v[170:173], v[200:203], v[82:85]
	v_mfma_f32_16x16x32_bf16 v[70:73], v[162:165], v[208:211], v[70:73]
	v_mfma_f32_16x16x32_bf16 v[66:69], v[170:173], v[208:211], v[66:69]
	v_mfma_f32_16x16x32_bf16 v[118:121], v[166:169], v[188:191], v[118:121]
	v_mfma_f32_16x16x32_bf16 v[114:117], v[174:177], v[188:191], v[114:117]
	v_mfma_f32_16x16x32_bf16 v[102:105], v[166:169], v[196:199], v[102:105]
	v_mfma_f32_16x16x32_bf16 v[98:101], v[174:177], v[196:199], v[98:101]
	v_mfma_f32_16x16x32_bf16 v[86:89], v[166:169], v[204:207], v[86:89]
	v_mfma_f32_16x16x32_bf16 v[82:85], v[174:177], v[204:207], v[82:85]
	v_mfma_f32_16x16x32_bf16 v[70:73], v[166:169], v[212:215], v[70:73]
	v_mfma_f32_16x16x32_bf16 v[66:69], v[174:177], v[212:215], v[66:69]
	s_barrier
; #define PG8_STAGE(bufoff, gbase, voff) do { _Pragma("unroll") for (int _i = 0; _i < 2; ++_i) \
;         __builtin_amdgcn_global_load_lds((const unsigned*)((const char*)(gbase) + (voff)[_i]), (LAS unsigned*)(lds + (bufoff) + ldsw + _i * 8192), 16, 0, 0); } while (0)
; #define PG8_LDA(dst, b, h) do { _Pragma("unroll") for (int m = 0; m < 4; ++m) _Pragma("unroll") for (int k = 0; k < 2; ++k) dst[m][k] = *(const LAS bf16x8*)(lds + PG8_SA(b, h) + aoff + m * 2048 + k * 1024); } while (0)
; #define PG8_MMA(ai, bj, At, Bt) do { __builtin_amdgcn_s_setprio(1); _Pragma("unroll") for (int m = 0; m < 4; ++m) _Pragma("unroll") for (int n = 0; n < 2; ++n) _Pragma("unroll") for (int k = 0; k < 2; ++k) \
;         acc[ai][bj][m][n] = __builtin_amdgcn_mfma_f32_16x16x32_bf16(Bt[n][k], At[m][k], acc[ai][bj][m][n], 0, 0, 0); __builtin_amdgcn_s_setprio(0); } while (0)
; #define PG8_WAIT_V(n) asm volatile("s_waitcnt vmcnt(" #n ")" ::: "memory")
; #define PG8_WAIT_L(n) asm volatile("s_waitcnt lgkmcnt(" #n ")" ::: "memory")
; #define PG8_BAR __builtin_amdgcn_s_barrier()
; #define PG8_SCHED __builtin_amdgcn_sched_barrier(0)
; template <class Epi, bool ALIGN_EPI>
; __device__ __forceinline__ void gemm_phase(LAS unsigned char* lds, const Gemm g, const StaticOrder& S, const Epi& E) {
;     ...
;             PG8_LDA(At, 1, 1); PG8_STAGE(PG8_SB(1, 0), b3, voffB); PG8_STAGE(PG8_SB(1, 1), b3 + hsB, voffB); PG8_STAGE(PG8_SA(1, 0), a3, voffA);
;             PG8_WAIT_V(8); PG8_WAIT_L(0); PG8_BAR; PG8_MMA(1, 0, At, B0); PG8_MMA(1, 1, At, B1); PG8_BAR; PG8_SCHED;
;         }
	s_add_i32 s40, s58, s33
	v_lshl_add_u64 v[216:217], v[216:217], 0, s[8:9]
	s_mov_b32 m0, s40
	ds_read_b128 v[178:181], v186 offset:49152
	ds_read_b128 v[188:191], v186 offset:50176
	ds_read_b128 v[192:195], v186 offset:51200
	ds_read_b128 v[196:199], v186 offset:52224
	ds_read_b128 v[200:203], v186 offset:53248
	ds_read_b128 v[204:207], v186 offset:54272
	ds_read_b128 v[208:211], v186 offset:55296
	ds_read_b128 v[212:215], v186 offset:56320
	global_load_lds_dwordx4 v[216:217], off
	s_add_i32 m0, s40, 0x2000
	s_add_u32 s38, s38, 0x20080
	v_lshl_add_u64 v[216:217], v[218:219], 0, s[8:9]
	s_addc_u32 s39, s39, 0
	s_add_i32 s40, s59, s33
	global_load_lds_dwordx4 v[216:217], off
	v_lshl_add_u64 v[216:217], s[38:39], 0, v[148:149]
	s_mov_b32 m0, s40
	s_nop 0
	global_load_lds_dwordx4 v[216:217], off
	v_lshl_add_u64 v[216:217], s[38:39], 0, v[152:153]
	s_add_i32 m0, s40, 0x2000
	s_nop 0
	global_load_lds_dwordx4 v[216:217], off
	v_lshl_add_u64 v[216:217], v[220:221], 0, s[8:9]
	s_mov_b32 m0, s46
	s_nop 0
	global_load_lds_dwordx4 v[216:217], off
	v_lshl_add_u64 v[216:217], v[222:223], 0, s[8:9]
	s_mov_b32 m0, s47
	s_nop 0
	global_load_lds_dwordx4 v[216:217], off
	s_waitcnt vmcnt(8)
	s_waitcnt lgkmcnt(0)
	s_barrier
	s_waitcnt lgkmcnt(0)
	v_mfma_f32_16x16x32_bf16 v[62:65], v[130:133], v[178:181], v[62:65]
	v_mfma_f32_16x16x32_bf16 v[58:61], v[138:141], v[178:181], v[58:61]
	v_mfma_f32_16x16x32_bf16 v[46:49], v[130:133], v[192:195], v[46:49]
	v_mfma_f32_16x16x32_bf16 v[42:45], v[138:141], v[192:195], v[42:45]
	v_mfma_f32_16x16x32_bf16 v[30:33], v[130:133], v[200:203], v[30:33]
	v_mfma_f32_16x16x32_bf16 v[26:29], v[138:141], v[200:203], v[26:29]
	v_mfma_f32_16x16x32_bf16 v[14:17], v[130:133], v[208:211], v[14:17]
	v_mfma_f32_16x16x32_bf16 v[10:13], v[138:141], v[208:211], v[10:13]
	v_mfma_f32_16x16x32_bf16 v[62:65], v[134:137], v[188:191], v[62:65]
	v_mfma_f32_16x16x32_bf16 v[58:61], v[142:145], v[188:191], v[58:61]
	v_mfma_f32_16x16x32_bf16 v[46:49], v[134:137], v[196:199], v[46:49]
	v_mfma_f32_16x16x32_bf16 v[42:45], v[142:145], v[196:199], v[42:45]
	v_mfma_f32_16x16x32_bf16 v[30:33], v[134:137], v[204:207], v[30:33]
	v_mfma_f32_16x16x32_bf16 v[26:29], v[142:145], v[204:207], v[26:29]
	v_mfma_f32_16x16x32_bf16 v[14:17], v[134:137], v[212:215], v[14:17]
	v_mfma_f32_16x16x32_bf16 v[10:13], v[142:145], v[212:215], v[10:13]
	v_mfma_f32_16x16x32_bf16 v[54:57], v[162:165], v[178:181], v[54:57]
	v_mfma_f32_16x16x32_bf16 v[50:53], v[170:173], v[178:181], v[50:53]
	v_mfma_f32_16x16x32_bf16 v[38:41], v[162:165], v[192:195], v[38:41]
	v_mfma_f32_16x16x32_bf16 v[34:37], v[170:173], v[192:195], v[34:37]
	v_mfma_f32_16x16x32_bf16 v[22:25], v[162:165], v[200:203], v[22:25]
	v_mfma_f32_16x16x32_bf16 v[18:21], v[170:173], v[200:203], v[18:21]
	v_mfma_f32_16x16x32_bf16 v[6:9], v[162:165], v[208:211], v[6:9]
	v_mfma_f32_16x16x32_bf16 v[2:5], v[170:173], v[208:211], v[2:5]
	v_mfma_f32_16x16x32_bf16 v[54:57], v[166:169], v[188:191], v[54:57]
	v_mfma_f32_16x16x32_bf16 v[50:53], v[174:177], v[188:191], v[50:53]
	v_mfma_f32_16x16x32_bf16 v[38:41], v[166:169], v[196:199], v[38:41]
	v_mfma_f32_16x16x32_bf16 v[34:37], v[174:177], v[196:199], v[34:37]
	v_mfma_f32_16x16x32_bf16 v[22:25], v[166:169], v[204:207], v[22:25]
	v_mfma_f32_16x16x32_bf16 v[18:21], v[174:177], v[204:207], v[18:21]
	v_mfma_f32_16x16x32_bf16 v[6:9], v[166:169], v[212:215], v[6:9]
	v_mfma_f32_16x16x32_bf16 v[2:5], v[174:177], v[212:215], v[2:5]
	s_add_i32 s57, s57, 2
	s_add_u32 s36, s36, 0x100
	s_addc_u32 s37, s37, 0
	s_add_u32 s55, s55, 0x100
	s_addc_u32 s56, s56, 0
	s_cmp_gt_u32 s57, 5
	s_barrier
	s_cbranch_scc0 .LBB0_1131
	s_and_b64 vcc, exec, s[10:11]
	s_cbranch_vccz .LBB0_1134
	s_barrier

; #define PG8_STAGE(bufoff, gbase, voff) do { _Pragma("unroll") for (int _i = 0; _i < 2; ++_i) \
;         __builtin_amdgcn_global_load_lds((const unsigned*)((const char*)(gbase) + (voff)[_i]), (LAS unsigned*)(lds + (bufoff) + ldsw + _i * 8192), 16, 0, 0); } while (0)
; #define PG8_LDA(dst, b, h) do { _Pragma("unroll") for (int m = 0; m < 4; ++m) _Pragma("unroll") for (int k = 0; k < 2; ++k) dst[m][k] = *(const LAS bf16x8*)(lds + PG8_SA(b, h) + aoff + m * 2048 + k * 1024); } while (0)
; #define PG8_LDB(dst, b, h) do { _Pragma("unroll") for (int n = 0; n < 2; ++n) _Pragma("unroll") for (int k = 0; k < 2; ++k) dst[n][k] = *(const LAS bf16x8*)(lds + PG8_SB(b, h) + boff + n * 2048 + k * 1024); } while (0)
; #define PG8_MMA(ai, bj, At, Bt) do { __builtin_amdgcn_s_setprio(1); _Pragma("unroll") for (int m = 0; m < 4; ++m) _Pragma("unroll") for (int n = 0; n < 2; ++n) _Pragma("unroll") for (int k = 0; k < 2; ++k) \
;         acc[ai][bj][m][n] = __builtin_amdgcn_mfma_f32_16x16x32_bf16(Bt[n][k], At[m][k], acc[ai][bj][m][n], 0, 0, 0); __builtin_amdgcn_s_setprio(0); } while (0)
; #define PG8_WAIT_V(n) asm volatile("s_waitcnt vmcnt(" #n ")" ::: "memory")
; #define PG8_WAIT_L(n) asm volatile("s_waitcnt lgkmcnt(" #n ")" ::: "memory")
; #define PG8_BAR __builtin_amdgcn_s_barrier()
; #define PG8_SCHED __builtin_amdgcn_sched_barrier(0)
; template <class Epi, bool ALIGN_EPI>
; __device__ __forceinline__ void gemm_phase(LAS unsigned char* lds, const Gemm g, const StaticOrder& S, const Epi& E) {
;     ...
;             const bool last = (t == nt - 2);
;             const char* a1 = cA + (size_t)(t + 1) * kstepA;
;             const char* a2 = last ? nA : cA + (size_t)(t + 2) * kstepA; const char* b2 = last ? nB : cB + (size_t)(t + 2) * kstep;
;             const char* a3 = a2 + kstepA; const char* b3 = b2 + kstep;
;             PG8_LDB(B0, 0, 0); PG8_LDB(B1, 0, 1); PG8_SCHED; PG8_LDA(At, 0, 0); PG8_STAGE(PG8_SA(1, 1), a1 + hsA, voffA);
;             PG8_WAIT_V(8); PG8_WAIT_L(0); PG8_BAR; PG8_MMA(0, 0, At, B0); PG8_MMA(0, 1, At, B1); PG8_BAR; PG8_SCHED;
;             PG8_LDA(At, 0, 1); PG8_STAGE(PG8_SB(0, 0), b2, voffB); PG8_STAGE(PG8_SB(0, 1), b2 + hsB, voffB); PG8_STAGE(PG8_SA(0, 0), a2, voffA);
;             PG8_WAIT_V(8); PG8_WAIT_L(0); PG8_BAR; PG8_MMA(1, 0, At, B0); PG8_MMA(1, 1, At, B1); PG8_BAR; PG8_SCHED;
.LBB0_1212:
	ds_read_b128 v[130:133], v190
	ds_read_b128 v[134:137], v190 offset:1024
	ds_read_b128 v[138:141], v190 offset:2048
	ds_read_b128 v[142:145], v190 offset:3072
	ds_read_b128 v[146:149], v191
	ds_read_b128 v[150:153], v191 offset:1024
	ds_read_b128 v[170:173], v191 offset:2048
	ds_read_b128 v[174:177], v191 offset:3072
	s_add_u32 s26, s24, 0xfffc0080
	s_addc_u32 s27, s25, -1
	s_cmp_eq_u32 s46, 12
	s_cselect_b32 s29, s13, s27
	s_cselect_b32 s28, s21, s26
	s_cselect_b32 s27, s15, s45
	s_cselect_b32 s26, s43, s44
	v_lshl_add_u64 v[186:187], s[24:25], 0, v[162:163]
	s_add_i32 m0, s23, 0xc000
	ds_read_b128 v[178:181], v192
	ds_read_b128 v[182:185], v192 offset:1024
	ds_read_b128 v[194:197], v192 offset:2048
	ds_read_b128 v[198:201], v192 offset:3072
	ds_read_b128 v[202:205], v192 offset:4096
	ds_read_b128 v[206:209], v192 offset:5120
	ds_read_b128 v[210:213], v192 offset:6144
	ds_read_b128 v[214:217], v192 offset:7168
	global_load_lds_dwordx4 v[186:187], off
	v_lshl_add_u64 v[186:187], s[24:25], 0, v[164:165]
	s_add_i32 m0, s23, 0xe000
	s_nop 0
	global_load_lds_dwordx4 v[186:187], off
	s_waitcnt vmcnt(8)
	s_waitcnt lgkmcnt(0)
	s_barrier
	s_waitcnt lgkmcnt(0)
	v_mfma_f32_16x16x32_bf16 v[126:129], v[130:133], v[178:181], v[126:129]
	v_mfma_f32_16x16x32_bf16 v[122:125], v[138:141], v[178:181], v[122:125]
	v_mfma_f32_16x16x32_bf16 v[110:113], v[130:133], v[194:197], v[110:113]
	v_mfma_f32_16x16x32_bf16 v[106:109], v[138:141], v[194:197], v[106:109]
	v_mfma_f32_16x16x32_bf16 v[94:97], v[130:133], v[202:205], v[94:97]
	v_mfma_f32_16x16x32_bf16 v[90:93], v[138:141], v[202:205], v[90:93]
	v_mfma_f32_16x16x32_bf16 v[78:81], v[130:133], v[210:213], v[78:81]
	v_mfma_f32_16x16x32_bf16 v[74:77], v[138:141], v[210:213], v[74:77]
	v_mfma_f32_16x16x32_bf16 v[126:129], v[134:137], v[182:185], v[126:129]
	v_mfma_f32_16x16x32_bf16 v[122:125], v[142:145], v[182:185], v[122:125]
	v_mfma_f32_16x16x32_bf16 v[110:113], v[134:137], v[198:201], v[110:113]
	v_mfma_f32_16x16x32_bf16 v[106:109], v[142:145], v[198:201], v[106:109]
	v_mfma_f32_16x16x32_bf16 v[94:97], v[134:137], v[206:209], v[94:97]
	v_mfma_f32_16x16x32_bf16 v[90:93], v[142:145], v[206:209], v[90:93]
	v_mfma_f32_16x16x32_bf16 v[78:81], v[134:137], v[214:217], v[78:81]
	v_mfma_f32_16x16x32_bf16 v[74:77], v[142:145], v[214:217], v[74:77]
	v_mfma_f32_16x16x32_bf16 v[118:121], v[146:149], v[178:181], v[118:121]
	v_mfma_f32_16x16x32_bf16 v[114:117], v[170:173], v[178:181], v[114:117]
	v_mfma_f32_16x16x32_bf16 v[102:105], v[146:149], v[194:197], v[102:105]
	v_mfma_f32_16x16x32_bf16 v[98:101], v[170:173], v[194:197], v[98:101]
	v_mfma_f32_16x16x32_bf16 v[86:89], v[146:149], v[202:205], v[86:89]
	v_mfma_f32_16x16x32_bf16 v[82:85], v[170:173], v[202:205], v[82:85]
	v_mfma_f32_16x16x32_bf16 v[70:73], v[146:149], v[210:213], v[70:73]
	v_mfma_f32_16x16x32_bf16 v[66:69], v[170:173], v[210:213], v[66:69]
	v_mfma_f32_16x16x32_bf16 v[118:121], v[150:153], v[182:185], v[118:121]
	v_mfma_f32_16x16x32_bf16 v[114:117], v[174:177], v[182:185], v[114:117]
	v_mfma_f32_16x16x32_bf16 v[102:105], v[150:153], v[198:201], v[102:105]
	v_mfma_f32_16x16x32_bf16 v[98:101], v[174:177], v[198:201], v[98:101]
	v_mfma_f32_16x16x32_bf16 v[86:89], v[150:153], v[206:209], v[86:89]
	v_mfma_f32_16x16x32_bf16 v[82:85], v[174:177], v[206:209], v[82:85]
	v_mfma_f32_16x16x32_bf16 v[70:73], v[150:153], v[214:217], v[70:73]
	v_mfma_f32_16x16x32_bf16 v[66:69], v[174:177], v[214:217], v[66:69]
	s_barrier
	s_add_i32 s47, s41, s30
	v_lshl_add_u64 v[186:187], s[26:27], 0, v[156:157]
	s_mov_b32 m0, s47
	ds_read_b128 v[178:181], v192 offset:16384
	ds_read_b128 v[182:185], v192 offset:17408
	ds_read_b128 v[194:197], v192 offset:18432
	ds_read_b128 v[198:201], v192 offset:19456
	ds_read_b128 v[202:205], v192 offset:20480
	ds_read_b128 v[206:209], v192 offset:21504
	ds_read_b128 v[210:213], v192 offset:22528
	ds_read_b128 v[214:217], v192 offset:23552
	global_load_lds_dwordx4 v[186:187], off
	s_add_i32 m0, s47, 0x2000
	s_add_u32 s48, s26, 0x40000
	v_lshl_add_u64 v[218:219], s[26:27], 0, v[160:161]
	s_addc_u32 s49, s27, 0
	s_add_i32 s47, s42, s30
	global_load_lds_dwordx4 v[218:219], off
	v_lshl_add_u64 v[220:221], s[48:49], 0, v[156:157]
	s_mov_b32 m0, s47
	v_lshl_add_u64 v[222:223], s[28:29], 0, v[158:159]
	global_load_lds_dwordx4 v[220:221], off
	v_lshl_add_u64 v[220:221], s[48:49], 0, v[160:161]
	s_add_i32 m0, s47, 0x2000
	s_nop 0
	global_load_lds_dwordx4 v[220:221], off
	v_lshl_add_u64 v[220:221], s[28:29], 0, v[154:155]
	s_mov_b32 m0, s23
	s_nop 0
	global_load_lds_dwordx4 v[220:221], off
	s_mov_b32 m0, s31
	s_nop 0
	global_load_lds_dwordx4 v[222:223], off
	s_waitcnt vmcnt(8)
	s_waitcnt lgkmcnt(0)
	s_barrier
; #define PG8_STAGE(bufoff, gbase, voff) do { _Pragma("unroll") for (int _i = 0; _i < 2; ++_i) \
;         __builtin_amdgcn_global_load_lds((const unsigned*)((const char*)(gbase) + (voff)[_i]), (LAS unsigned*)(lds + (bufoff) + ldsw + _i * 8192), 16, 0, 0); } while (0)
; #define PG8_LDA(dst, b, h) do { _Pragma("unroll") for (int m = 0; m < 4; ++m) _Pragma("unroll") for (int k = 0; k < 2; ++k) dst[m][k] = *(const LAS bf16x8*)(lds + PG8_SA(b, h) + aoff + m * 2048 + k * 1024); } while (0)
; #define PG8_LDB(dst, b, h) do { _Pragma("unroll") for (int n = 0; n < 2; ++n) _Pragma("unroll") for (int k = 0; k < 2; ++k) dst[n][k] = *(const LAS bf16x8*)(lds + PG8_SB(b, h) + boff + n * 2048 + k * 1024); } while (0)
; #define PG8_MMA(ai, bj, At, Bt) do { __builtin_amdgcn_s_setprio(1); _Pragma("unroll") for (int m = 0; m < 4; ++m) _Pragma("unroll") for (int n = 0; n < 2; ++n) _Pragma("unroll") for (int k = 0; k < 2; ++k) \
;         acc[ai][bj][m][n] = __builtin_amdgcn_mfma_f32_16x16x32_bf16(Bt[n][k], At[m][k], acc[ai][bj][m][n], 0, 0, 0); __builtin_amdgcn_s_setprio(0); } while (0)
; #define PG8_WAIT_V(n) asm volatile("s_waitcnt vmcnt(" #n ")" ::: "memory")
; #define PG8_WAIT_L(n) asm volatile("s_waitcnt lgkmcnt(" #n ")" ::: "memory")
; #define PG8_BAR __builtin_amdgcn_s_barrier()
; #define PG8_SCHED __builtin_amdgcn_sched_barrier(0)
; template <class Epi, bool ALIGN_EPI>
; __device__ __forceinline__ void gemm_phase(LAS unsigned char* lds, const Gemm g, const StaticOrder& S, const Epi& E) {
;     ...
;             PG8_WAIT_V(8); PG8_WAIT_L(0); PG8_BAR; PG8_MMA(1, 0, At, B0); PG8_MMA(1, 1, At, B1); PG8_BAR; PG8_SCHED;
;             PG8_LDB(B0, 1, 0); PG8_LDB(B1, 1, 1); PG8_SCHED; PG8_LDA(At, 1, 0); PG8_STAGE(PG8_SA(0, 1), a2 + hsA, voffA);
;             PG8_WAIT_V(8); PG8_WAIT_L(0); PG8_BAR; PG8_MMA(0, 0, At, B0); PG8_MMA(0, 1, At, B1); PG8_BAR; PG8_SCHED;
	s_waitcnt lgkmcnt(0)
	v_mfma_f32_16x16x32_bf16 v[62:65], v[130:133], v[178:181], v[62:65]
	v_mfma_f32_16x16x32_bf16 v[58:61], v[138:141], v[178:181], v[58:61]
	v_mfma_f32_16x16x32_bf16 v[46:49], v[130:133], v[194:197], v[46:49]
	v_mfma_f32_16x16x32_bf16 v[42:45], v[138:141], v[194:197], v[42:45]
	v_mfma_f32_16x16x32_bf16 v[30:33], v[130:133], v[202:205], v[30:33]
	v_mfma_f32_16x16x32_bf16 v[26:29], v[138:141], v[202:205], v[26:29]
	v_mfma_f32_16x16x32_bf16 v[14:17], v[130:133], v[210:213], v[14:17]
	v_mfma_f32_16x16x32_bf16 v[10:13], v[138:141], v[210:213], v[10:13]
	v_mfma_f32_16x16x32_bf16 v[62:65], v[134:137], v[182:185], v[62:65]
	v_mfma_f32_16x16x32_bf16 v[58:61], v[142:145], v[182:185], v[58:61]
	v_mfma_f32_16x16x32_bf16 v[46:49], v[134:137], v[198:201], v[46:49]
	v_mfma_f32_16x16x32_bf16 v[42:45], v[142:145], v[198:201], v[42:45]
	v_mfma_f32_16x16x32_bf16 v[30:33], v[134:137], v[206:209], v[30:33]
	v_mfma_f32_16x16x32_bf16 v[26:29], v[142:145], v[206:209], v[26:29]
	v_mfma_f32_16x16x32_bf16 v[14:17], v[134:137], v[214:217], v[14:17]
	v_mfma_f32_16x16x32_bf16 v[10:13], v[142:145], v[214:217], v[10:13]
	v_mfma_f32_16x16x32_bf16 v[54:57], v[146:149], v[178:181], v[54:57]
	v_mfma_f32_16x16x32_bf16 v[50:53], v[170:173], v[178:181], v[50:53]
	v_mfma_f32_16x16x32_bf16 v[38:41], v[146:149], v[194:197], v[38:41]
	v_mfma_f32_16x16x32_bf16 v[34:37], v[170:173], v[194:197], v[34:37]
	v_mfma_f32_16x16x32_bf16 v[22:25], v[146:149], v[202:205], v[22:25]
	v_mfma_f32_16x16x32_bf16 v[18:21], v[170:173], v[202:205], v[18:21]
	v_mfma_f32_16x16x32_bf16 v[6:9], v[146:149], v[210:213], v[6:9]
	v_mfma_f32_16x16x32_bf16 v[2:5], v[170:173], v[210:213], v[2:5]
	v_mfma_f32_16x16x32_bf16 v[54:57], v[150:153], v[182:185], v[54:57]
	v_mfma_f32_16x16x32_bf16 v[50:53], v[174:177], v[182:185], v[50:53]
	v_mfma_f32_16x16x32_bf16 v[38:41], v[150:153], v[198:201], v[38:41]
	v_mfma_f32_16x16x32_bf16 v[34:37], v[174:177], v[198:201], v[34:37]
	v_mfma_f32_16x16x32_bf16 v[22:25], v[150:153], v[206:209], v[22:25]
	v_mfma_f32_16x16x32_bf16 v[18:21], v[174:177], v[206:209], v[18:21]
	v_mfma_f32_16x16x32_bf16 v[6:9], v[150:153], v[214:217], v[6:9]
	v_mfma_f32_16x16x32_bf16 v[2:5], v[174:177], v[214:217], v[2:5]
	s_barrier
	s_add_i32 s47, 0, 0x18000
	s_add_i32 s48, 0, 0x1c000
	v_add_u32_e32 v142, s47, v188
	v_add_u32_e32 v174, s48, v188
	ds_read_b128 v[130:133], v142
	ds_read_b128 v[134:137], v142 offset:1024
	ds_read_b128 v[138:141], v142 offset:2048
	ds_read_b128 v[142:145], v142 offset:3072
	ds_read_b128 v[146:149], v174
	ds_read_b128 v[150:153], v174 offset:1024
	ds_read_b128 v[170:173], v174 offset:2048
	ds_read_b128 v[174:177], v174 offset:3072
	s_add_u32 s28, s28, 0x40000
	s_addc_u32 s29, s29, 0
	s_mov_b32 m0, s33
	v_lshl_add_u64 v[224:225], s[28:29], 0, v[154:155]
	ds_read_b128 v[178:181], v192 offset:32768
	ds_read_b128 v[182:185], v192 offset:33792
	ds_read_b128 v[194:197], v192 offset:34816
	ds_read_b128 v[198:201], v192 offset:35840
	ds_read_b128 v[202:205], v192 offset:36864
	ds_read_b128 v[206:209], v192 offset:37888
	ds_read_b128 v[210:213], v192 offset:38912
	ds_read_b128 v[214:217], v192 offset:39936
	global_load_lds_dwordx4 v[224:225], off
	v_lshl_add_u64 v[224:225], s[28:29], 0, v[158:159]
	s_mov_b32 m0, s34
	s_nop 0
	global_load_lds_dwordx4 v[224:225], off
	s_waitcnt vmcnt(8)
	s_waitcnt lgkmcnt(0)
	s_barrier
	s_waitcnt lgkmcnt(0)
	v_mfma_f32_16x16x32_bf16 v[126:129], v[130:133], v[178:181], v[126:129]
	v_mfma_f32_16x16x32_bf16 v[122:125], v[138:141], v[178:181], v[122:125]
	v_mfma_f32_16x16x32_bf16 v[110:113], v[130:133], v[194:197], v[110:113]
	v_mfma_f32_16x16x32_bf16 v[106:109], v[138:141], v[194:197], v[106:109]
	v_mfma_f32_16x16x32_bf16 v[94:97], v[130:133], v[202:205], v[94:97]
	v_mfma_f32_16x16x32_bf16 v[90:93], v[138:141], v[202:205], v[90:93]
	v_mfma_f32_16x16x32_bf16 v[78:81], v[130:133], v[210:213], v[78:81]
	v_mfma_f32_16x16x32_bf16 v[74:77], v[138:141], v[210:213], v[74:77]
	v_mfma_f32_16x16x32_bf16 v[126:129], v[134:137], v[182:185], v[126:129]
	v_mfma_f32_16x16x32_bf16 v[122:125], v[142:145], v[182:185], v[122:125]
	v_mfma_f32_16x16x32_bf16 v[110:113], v[134:137], v[198:201], v[110:113]
	v_mfma_f32_16x16x32_bf16 v[106:109], v[142:145], v[198:201], v[106:109]
	v_mfma_f32_16x16x32_bf16 v[94:97], v[134:137], v[206:209], v[94:97]
	v_mfma_f32_16x16x32_bf16 v[90:93], v[142:145], v[206:209], v[90:93]
	v_mfma_f32_16x16x32_bf16 v[78:81], v[134:137], v[214:217], v[78:81]
	v_mfma_f32_16x16x32_bf16 v[74:77], v[142:145], v[214:217], v[74:77]
	v_mfma_f32_16x16x32_bf16 v[118:121], v[146:149], v[178:181], v[118:121]
	v_mfma_f32_16x16x32_bf16 v[114:117], v[170:173], v[178:181], v[114:117]
	v_mfma_f32_16x16x32_bf16 v[102:105], v[146:149], v[194:197], v[102:105]
	v_mfma_f32_16x16x32_bf16 v[98:101], v[170:173], v[194:197], v[98:101]
	v_mfma_f32_16x16x32_bf16 v[86:89], v[146:149], v[202:205], v[86:89]
	v_mfma_f32_16x16x32_bf16 v[82:85], v[170:173], v[202:205], v[82:85]
	v_mfma_f32_16x16x32_bf16 v[70:73], v[146:149], v[210:213], v[70:73]
	v_mfma_f32_16x16x32_bf16 v[66:69], v[170:173], v[210:213], v[66:69]
	v_mfma_f32_16x16x32_bf16 v[118:121], v[150:153], v[182:185], v[118:121]
	v_mfma_f32_16x16x32_bf16 v[114:117], v[174:177], v[182:185], v[114:117]
	v_mfma_f32_16x16x32_bf16 v[102:105], v[150:153], v[198:201], v[102:105]
	v_mfma_f32_16x16x32_bf16 v[98:101], v[174:177], v[198:201], v[98:101]
	v_mfma_f32_16x16x32_bf16 v[86:89], v[150:153], v[206:209], v[86:89]
	v_mfma_f32_16x16x32_bf16 v[82:85], v[174:177], v[206:209], v[82:85]
	v_mfma_f32_16x16x32_bf16 v[70:73], v[150:153], v[214:217], v[70:73]
	v_mfma_f32_16x16x32_bf16 v[66:69], v[174:177], v[214:217], v[66:69]
	s_barrier
; #define PG8_STAGE(bufoff, gbase, voff) do { _Pragma("unroll") for (int _i = 0; _i < 2; ++_i) \
;         __builtin_amdgcn_global_load_lds((const unsigned*)((const char*)(gbase) + (voff)[_i]), (LAS unsigned*)(lds + (bufoff) + ldsw + _i * 8192), 16, 0, 0); } while (0)
; #define PG8_LDA(dst, b, h) do { _Pragma("unroll") for (int m = 0; m < 4; ++m) _Pragma("unroll") for (int k = 0; k < 2; ++k) dst[m][k] = *(const LAS bf16x8*)(lds + PG8_SA(b, h) + aoff + m * 2048 + k * 1024); } while (0)
; #define PG8_MMA(ai, bj, At, Bt) do { __builtin_amdgcn_s_setprio(1); _Pragma("unroll") for (int m = 0; m < 4; ++m) _Pragma("unroll") for (int n = 0; n < 2; ++n) _Pragma("unroll") for (int k = 0; k < 2; ++k) \
;         acc[ai][bj][m][n] = __builtin_amdgcn_mfma_f32_16x16x32_bf16(Bt[n][k], At[m][k], acc[ai][bj][m][n], 0, 0, 0); __builtin_amdgcn_s_setprio(0); } while (0)
; #define PG8_WAIT_V(n) asm volatile("s_waitcnt vmcnt(" #n ")" ::: "memory")
; #define PG8_WAIT_L(n) asm volatile("s_waitcnt lgkmcnt(" #n ")" ::: "memory")
; #define PG8_BAR __builtin_amdgcn_s_barrier()
; #define PG8_SCHED __builtin_amdgcn_sched_barrier(0)
; template <class Epi, bool ALIGN_EPI>
; __device__ __forceinline__ void gemm_phase(LAS unsigned char* lds, const Gemm g, const StaticOrder& S, const Epi& E) {
;     ...
;             PG8_LDA(At, 1, 1); PG8_STAGE(PG8_SB(1, 0), b3, voffB); PG8_STAGE(PG8_SB(1, 1), b3 + hsB, voffB); PG8_STAGE(PG8_SA(1, 0), a3, voffA);
;             PG8_WAIT_V(8); PG8_WAIT_L(0); PG8_BAR; PG8_MMA(1, 0, At, B0); PG8_MMA(1, 1, At, B1); PG8_BAR; PG8_SCHED;
;         }
	s_add_i32 s28, s47, s30
	v_lshl_add_u64 v[186:187], v[186:187], 0, s[8:9]
	s_mov_b32 m0, s28
	ds_read_b128 v[178:181], v192 offset:49152
	ds_read_b128 v[182:185], v192 offset:50176
	ds_read_b128 v[194:197], v192 offset:51200
	ds_read_b128 v[198:201], v192 offset:52224
	ds_read_b128 v[202:205], v192 offset:53248
	ds_read_b128 v[206:209], v192 offset:54272
	ds_read_b128 v[210:213], v192 offset:55296
	ds_read_b128 v[214:217], v192 offset:56320
	global_load_lds_dwordx4 v[186:187], off
	s_add_i32 m0, s28, 0x2000
	s_add_u32 s26, s26, 0x40080
	v_lshl_add_u64 v[186:187], v[218:219], 0, s[8:9]
	s_addc_u32 s27, s27, 0
	s_add_i32 s28, s48, s30
	global_load_lds_dwordx4 v[186:187], off
	v_lshl_add_u64 v[186:187], s[26:27], 0, v[156:157]
	s_mov_b32 m0, s28
	s_nop 0
	global_load_lds_dwordx4 v[186:187], off
	v_lshl_add_u64 v[186:187], s[26:27], 0, v[160:161]
	s_add_i32 m0, s28, 0x2000
	s_nop 0
	global_load_lds_dwordx4 v[186:187], off
	v_lshl_add_u64 v[186:187], v[220:221], 0, s[8:9]
	s_mov_b32 m0, s36
	s_nop 0
	global_load_lds_dwordx4 v[186:187], off
	v_lshl_add_u64 v[186:187], v[222:223], 0, s[8:9]
	s_mov_b32 m0, s37
	s_nop 0
	global_load_lds_dwordx4 v[186:187], off
	s_waitcnt vmcnt(8)
	s_waitcnt lgkmcnt(0)
	s_barrier
	s_waitcnt lgkmcnt(0)
	v_mfma_f32_16x16x32_bf16 v[62:65], v[130:133], v[178:181], v[62:65]
	v_mfma_f32_16x16x32_bf16 v[58:61], v[138:141], v[178:181], v[58:61]
	v_mfma_f32_16x16x32_bf16 v[46:49], v[130:133], v[194:197], v[46:49]
	v_mfma_f32_16x16x32_bf16 v[42:45], v[138:141], v[194:197], v[42:45]
	v_mfma_f32_16x16x32_bf16 v[30:33], v[130:133], v[202:205], v[30:33]
	v_mfma_f32_16x16x32_bf16 v[26:29], v[138:141], v[202:205], v[26:29]
	v_mfma_f32_16x16x32_bf16 v[14:17], v[130:133], v[210:213], v[14:17]
	v_mfma_f32_16x16x32_bf16 v[10:13], v[138:141], v[210:213], v[10:13]
	v_mfma_f32_16x16x32_bf16 v[62:65], v[134:137], v[182:185], v[62:65]
	v_mfma_f32_16x16x32_bf16 v[58:61], v[142:145], v[182:185], v[58:61]
	v_mfma_f32_16x16x32_bf16 v[46:49], v[134:137], v[198:201], v[46:49]
	v_mfma_f32_16x16x32_bf16 v[42:45], v[142:145], v[198:201], v[42:45]
	v_mfma_f32_16x16x32_bf16 v[30:33], v[134:137], v[206:209], v[30:33]
	v_mfma_f32_16x16x32_bf16 v[26:29], v[142:145], v[206:209], v[26:29]
	v_mfma_f32_16x16x32_bf16 v[14:17], v[134:137], v[214:217], v[14:17]
	v_mfma_f32_16x16x32_bf16 v[10:13], v[142:145], v[214:217], v[10:13]
	v_mfma_f32_16x16x32_bf16 v[54:57], v[146:149], v[178:181], v[54:57]
	v_mfma_f32_16x16x32_bf16 v[50:53], v[170:173], v[178:181], v[50:53]
	v_mfma_f32_16x16x32_bf16 v[38:41], v[146:149], v[194:197], v[38:41]
	v_mfma_f32_16x16x32_bf16 v[34:37], v[170:173], v[194:197], v[34:37]
	v_mfma_f32_16x16x32_bf16 v[22:25], v[146:149], v[202:205], v[22:25]
	v_mfma_f32_16x16x32_bf16 v[18:21], v[170:173], v[202:205], v[18:21]
	v_mfma_f32_16x16x32_bf16 v[6:9], v[146:149], v[210:213], v[6:9]
	v_mfma_f32_16x16x32_bf16 v[2:5], v[170:173], v[210:213], v[2:5]
	v_mfma_f32_16x16x32_bf16 v[54:57], v[150:153], v[182:185], v[54:57]
	v_mfma_f32_16x16x32_bf16 v[50:53], v[174:177], v[182:185], v[50:53]
	v_mfma_f32_16x16x32_bf16 v[38:41], v[150:153], v[198:201], v[38:41]
	v_mfma_f32_16x16x32_bf16 v[34:37], v[174:177], v[198:201], v[34:37]
	v_mfma_f32_16x16x32_bf16 v[22:25], v[150:153], v[206:209], v[22:25]
	v_mfma_f32_16x16x32_bf16 v[18:21], v[174:177], v[206:209], v[18:21]
	v_mfma_f32_16x16x32_bf16 v[6:9], v[150:153], v[214:217], v[6:9]
	v_mfma_f32_16x16x32_bf16 v[2:5], v[174:177], v[214:217], v[2:5]
	s_add_i32 s46, s46, 2
	s_add_u32 s24, s24, 0x100
	s_addc_u32 s25, s25, 0
	s_add_u32 s44, s44, 0x100
	s_addc_u32 s45, s45, 0
	s_cmp_gt_u32 s46, 13
	s_barrier
	s_cbranch_scc0 .LBB0_1212
	s_and_b64 vcc, exec, s[10:11]
	s_cbranch_vccz .LBB0_1215
	s_barrier

; #define PG8_STAGE(bufoff, gbase, voff) do { _Pragma("unroll") for (int _i = 0; _i < 2; ++_i) \
;         __builtin_amdgcn_global_load_lds((const unsigned*)((const char*)(gbase) + (voff)[_i]), (LAS unsigned*)(lds + (bufoff) + ldsw + _i * 8192), 16, 0, 0); } while (0)
; #define PG8_LDA(dst, b, h) do { _Pragma("unroll") for (int m = 0; m < 4; ++m) _Pragma("unroll") for (int k = 0; k < 2; ++k) dst[m][k] = *(const LAS bf16x8*)(lds + PG8_SA(b, h) + aoff + m * 2048 + k * 1024); } while (0)
; #define PG8_LDB(dst, b, h) do { _Pragma("unroll") for (int n = 0; n < 2; ++n) _Pragma("unroll") for (int k = 0; k < 2; ++k) dst[n][k] = *(const LAS bf16x8*)(lds + PG8_SB(b, h) + boff + n * 2048 + k * 1024); } while (0)
; #define PG8_MMA(ai, bj, At, Bt) do { __builtin_amdgcn_s_setprio(1); _Pragma("unroll") for (int m = 0; m < 4; ++m) _Pragma("unroll") for (int n = 0; n < 2; ++n) _Pragma("unroll") for (int k = 0; k < 2; ++k) \
;         acc[ai][bj][m][n] = __builtin_amdgcn_mfma_f32_16x16x32_bf16(Bt[n][k], At[m][k], acc[ai][bj][m][n], 0, 0, 0); __builtin_amdgcn_s_setprio(0); } while (0)
; #define PG8_WAIT_V(n) asm volatile("s_waitcnt vmcnt(" #n ")" ::: "memory")
; #define PG8_WAIT_L(n) asm volatile("s_waitcnt lgkmcnt(" #n ")" ::: "memory")
; #define PG8_BAR __builtin_amdgcn_s_barrier()
; #define PG8_SCHED __builtin_amdgcn_sched_barrier(0)
; template <class Epi, bool ALIGN_EPI>
; __device__ __forceinline__ void gemm_phase(LAS unsigned char* lds, const Gemm g, const StaticOrder& S, const Epi& E) {
;     ...
;             const bool last = (t == nt - 2);
;             const char* a1 = cA + (size_t)(t + 1) * kstepA;
;             const char* a2 = last ? nA : cA + (size_t)(t + 2) * kstepA; const char* b2 = last ? nB : cB + (size_t)(t + 2) * kstep;
;             const char* a3 = a2 + kstepA; const char* b3 = b2 + kstep;
;             PG8_LDB(B0, 0, 0); PG8_LDB(B1, 0, 1); PG8_SCHED; PG8_LDA(At, 0, 0); PG8_STAGE(PG8_SA(1, 1), a1 + hsA, voffA);
;             PG8_WAIT_V(8); PG8_WAIT_L(0); PG8_BAR; PG8_MMA(0, 0, At, B0); PG8_MMA(0, 1, At, B1); PG8_BAR; PG8_SCHED;
;             PG8_LDA(At, 0, 1); PG8_STAGE(PG8_SB(0, 0), b2, voffB); PG8_STAGE(PG8_SB(0, 1), b2 + hsB, voffB); PG8_STAGE(PG8_SA(0, 0), a2, voffA);
;             PG8_WAIT_V(8); PG8_WAIT_L(0); PG8_BAR; PG8_MMA(1, 0, At, B0); PG8_MMA(1, 1, At, B1); PG8_BAR; PG8_SCHED;
.LBB0_1299:
	ds_read_b128 v[156:159], v151
	ds_read_b128 v[160:163], v151 offset:1024
	ds_read_b128 v[164:167], v151 offset:2048
	ds_read_b128 v[168:171], v151 offset:3072
	ds_read_b128 v[172:175], v152
	ds_read_b128 v[176:179], v152 offset:1024
	ds_read_b128 v[180:183], v152 offset:2048
	ds_read_b128 v[184:187], v152 offset:3072
	s_add_u32 s22, s20, 0xfffc0080
	s_addc_u32 s23, s21, -1
	s_cmp_eq_u32 s48, 12
	s_cselect_b32 s25, s11, s23
	s_cselect_b32 s24, s44, s22
	s_cselect_b32 s23, s13, s47
	s_cselect_b32 s22, s45, s46
	v_lshl_add_u64 v[220:221], s[20:21], 0, v[140:141]
	s_add_i32 m0, s19, 0xc000
	ds_read_b128 v[188:191], v153
	ds_read_b128 v[192:195], v153 offset:1024
	ds_read_b128 v[196:199], v153 offset:2048
	ds_read_b128 v[200:203], v153 offset:3072
	ds_read_b128 v[204:207], v153 offset:4096
	ds_read_b128 v[208:211], v153 offset:5120
	ds_read_b128 v[212:215], v153 offset:6144
	ds_read_b128 v[216:219], v153 offset:7168
	global_load_lds_dwordx4 v[220:221], off
	v_lshl_add_u64 v[220:221], s[20:21], 0, v[142:143]
	s_add_i32 m0, s19, 0xe000
	s_nop 0
	global_load_lds_dwordx4 v[220:221], off
	s_waitcnt vmcnt(8)
	s_waitcnt lgkmcnt(0)
	s_barrier
	s_waitcnt lgkmcnt(0)
	v_mfma_f32_16x16x32_bf16 v[118:121], v[156:159], v[188:191], v[118:121]
	v_mfma_f32_16x16x32_bf16 v[114:117], v[164:167], v[188:191], v[114:117]
	v_mfma_f32_16x16x32_bf16 v[106:109], v[156:159], v[196:199], v[106:109]
	v_mfma_f32_16x16x32_bf16 v[102:105], v[164:167], v[196:199], v[102:105]
	v_mfma_f32_16x16x32_bf16 v[94:97], v[156:159], v[204:207], v[94:97]
	v_mfma_f32_16x16x32_bf16 v[90:93], v[164:167], v[204:207], v[90:93]
	v_mfma_f32_16x16x32_bf16 v[78:81], v[156:159], v[212:215], v[78:81]
	v_mfma_f32_16x16x32_bf16 v[74:77], v[164:167], v[212:215], v[74:77]
	v_mfma_f32_16x16x32_bf16 v[118:121], v[160:163], v[192:195], v[118:121]
	v_mfma_f32_16x16x32_bf16 v[114:117], v[168:171], v[192:195], v[114:117]
	v_mfma_f32_16x16x32_bf16 v[106:109], v[160:163], v[200:203], v[106:109]
	v_mfma_f32_16x16x32_bf16 v[102:105], v[168:171], v[200:203], v[102:105]
	v_mfma_f32_16x16x32_bf16 v[94:97], v[160:163], v[208:211], v[94:97]
	v_mfma_f32_16x16x32_bf16 v[90:93], v[168:171], v[208:211], v[90:93]
	v_mfma_f32_16x16x32_bf16 v[78:81], v[160:163], v[216:219], v[78:81]
	v_mfma_f32_16x16x32_bf16 v[74:77], v[168:171], v[216:219], v[74:77]
	v_mfma_f32_16x16x32_bf16 v[126:129], v[172:175], v[188:191], v[126:129]
	v_mfma_f32_16x16x32_bf16 v[122:125], v[180:183], v[188:191], v[122:125]
	v_mfma_f32_16x16x32_bf16 v[110:113], v[172:175], v[196:199], v[110:113]
	v_mfma_f32_16x16x32_bf16 v[98:101], v[180:183], v[196:199], v[98:101]
	v_mfma_f32_16x16x32_bf16 v[86:89], v[172:175], v[204:207], v[86:89]
	v_mfma_f32_16x16x32_bf16 v[82:85], v[180:183], v[204:207], v[82:85]
	v_mfma_f32_16x16x32_bf16 v[70:73], v[172:175], v[212:215], v[70:73]
	v_mfma_f32_16x16x32_bf16 v[66:69], v[180:183], v[212:215], v[66:69]
	v_mfma_f32_16x16x32_bf16 v[126:129], v[176:179], v[192:195], v[126:129]
	v_mfma_f32_16x16x32_bf16 v[122:125], v[184:187], v[192:195], v[122:125]
	v_mfma_f32_16x16x32_bf16 v[110:113], v[176:179], v[200:203], v[110:113]
	v_mfma_f32_16x16x32_bf16 v[98:101], v[184:187], v[200:203], v[98:101]
	v_mfma_f32_16x16x32_bf16 v[86:89], v[176:179], v[208:211], v[86:89]
	v_mfma_f32_16x16x32_bf16 v[82:85], v[184:187], v[208:211], v[82:85]
	v_mfma_f32_16x16x32_bf16 v[70:73], v[176:179], v[216:219], v[70:73]
	v_mfma_f32_16x16x32_bf16 v[66:69], v[184:187], v[216:219], v[66:69]
	s_barrier
	s_add_i32 s49, s40, s26
	v_lshl_add_u64 v[220:221], s[22:23], 0, v[134:135]
	s_mov_b32 m0, s49
	ds_read_b128 v[188:191], v153 offset:16384
	ds_read_b128 v[192:195], v153 offset:17408
	ds_read_b128 v[196:199], v153 offset:18432
	ds_read_b128 v[200:203], v153 offset:19456
	ds_read_b128 v[204:207], v153 offset:20480
	ds_read_b128 v[208:211], v153 offset:21504
	ds_read_b128 v[212:215], v153 offset:22528
	ds_read_b128 v[216:219], v153 offset:23552
	global_load_lds_dwordx4 v[220:221], off
	s_add_i32 m0, s49, 0x2000
	s_add_u32 s50, s22, 0x40000
	v_lshl_add_u64 v[222:223], s[22:23], 0, v[130:131]
	s_addc_u32 s51, s23, 0
	s_add_i32 s49, s41, s26
	global_load_lds_dwordx4 v[222:223], off
	v_lshl_add_u64 v[224:225], s[50:51], 0, v[134:135]
	s_mov_b32 m0, s49
	v_lshl_add_u64 v[226:227], s[24:25], 0, v[132:133]
	global_load_lds_dwordx4 v[224:225], off
	v_lshl_add_u64 v[224:225], s[50:51], 0, v[130:131]
	s_add_i32 m0, s49, 0x2000
	s_nop 0
	global_load_lds_dwordx4 v[224:225], off
	v_lshl_add_u64 v[224:225], s[24:25], 0, v[136:137]
	s_mov_b32 m0, s19
	s_nop 0
	global_load_lds_dwordx4 v[224:225], off
	s_mov_b32 m0, s29
	s_nop 0
	global_load_lds_dwordx4 v[226:227], off
	s_waitcnt vmcnt(8)
	s_waitcnt lgkmcnt(0)
	s_barrier
; #define PG8_STAGE(bufoff, gbase, voff) do { _Pragma("unroll") for (int _i = 0; _i < 2; ++_i) \
;         __builtin_amdgcn_global_load_lds((const unsigned*)((const char*)(gbase) + (voff)[_i]), (LAS unsigned*)(lds + (bufoff) + ldsw + _i * 8192), 16, 0, 0); } while (0)
; #define PG8_LDA(dst, b, h) do { _Pragma("unroll") for (int m = 0; m < 4; ++m) _Pragma("unroll") for (int k = 0; k < 2; ++k) dst[m][k] = *(const LAS bf16x8*)(lds + PG8_SA(b, h) + aoff + m * 2048 + k * 1024); } while (0)
; #define PG8_LDB(dst, b, h) do { _Pragma("unroll") for (int n = 0; n < 2; ++n) _Pragma("unroll") for (int k = 0; k < 2; ++k) dst[n][k] = *(const LAS bf16x8*)(lds + PG8_SB(b, h) + boff + n * 2048 + k * 1024); } while (0)
; #define PG8_MMA(ai, bj, At, Bt) do { __builtin_amdgcn_s_setprio(1); _Pragma("unroll") for (int m = 0; m < 4; ++m) _Pragma("unroll") for (int n = 0; n < 2; ++n) _Pragma("unroll") for (int k = 0; k < 2; ++k) \
;         acc[ai][bj][m][n] = __builtin_amdgcn_mfma_f32_16x16x32_bf16(Bt[n][k], At[m][k], acc[ai][bj][m][n], 0, 0, 0); __builtin_amdgcn_s_setprio(0); } while (0)
; #define PG8_WAIT_V(n) asm volatile("s_waitcnt vmcnt(" #n ")" ::: "memory")
; #define PG8_WAIT_L(n) asm volatile("s_waitcnt lgkmcnt(" #n ")" ::: "memory")
; #define PG8_BAR __builtin_amdgcn_s_barrier()
; #define PG8_SCHED __builtin_amdgcn_sched_barrier(0)
; template <class Epi, bool ALIGN_EPI>
; __device__ __forceinline__ void gemm_phase(LAS unsigned char* lds, const Gemm g, const StaticOrder& S, const Epi& E) {
;     ...
;             PG8_WAIT_V(8); PG8_WAIT_L(0); PG8_BAR; PG8_MMA(1, 0, At, B0); PG8_MMA(1, 1, At, B1); PG8_BAR; PG8_SCHED;
;             PG8_LDB(B0, 1, 0); PG8_LDB(B1, 1, 1); PG8_SCHED; PG8_LDA(At, 1, 0); PG8_STAGE(PG8_SA(0, 1), a2 + hsA, voffA);
;             PG8_WAIT_V(8); PG8_WAIT_L(0); PG8_BAR; PG8_MMA(0, 0, At, B0); PG8_MMA(0, 1, At, B1); PG8_BAR; PG8_SCHED;
	s_waitcnt lgkmcnt(0)
	v_mfma_f32_16x16x32_bf16 v[62:65], v[156:159], v[188:191], v[62:65]
	v_mfma_f32_16x16x32_bf16 v[58:61], v[164:167], v[188:191], v[58:61]
	v_mfma_f32_16x16x32_bf16 v[46:49], v[156:159], v[196:199], v[46:49]
	v_mfma_f32_16x16x32_bf16 v[42:45], v[164:167], v[196:199], v[42:45]
	v_mfma_f32_16x16x32_bf16 v[30:33], v[156:159], v[204:207], v[30:33]
	v_mfma_f32_16x16x32_bf16 v[26:29], v[164:167], v[204:207], v[26:29]
	v_mfma_f32_16x16x32_bf16 v[14:17], v[156:159], v[212:215], v[14:17]
	v_mfma_f32_16x16x32_bf16 v[10:13], v[164:167], v[212:215], v[10:13]
	v_mfma_f32_16x16x32_bf16 v[62:65], v[160:163], v[192:195], v[62:65]
	v_mfma_f32_16x16x32_bf16 v[58:61], v[168:171], v[192:195], v[58:61]
	v_mfma_f32_16x16x32_bf16 v[46:49], v[160:163], v[200:203], v[46:49]
	v_mfma_f32_16x16x32_bf16 v[42:45], v[168:171], v[200:203], v[42:45]
	v_mfma_f32_16x16x32_bf16 v[30:33], v[160:163], v[208:211], v[30:33]
	v_mfma_f32_16x16x32_bf16 v[26:29], v[168:171], v[208:211], v[26:29]
	v_mfma_f32_16x16x32_bf16 v[14:17], v[160:163], v[216:219], v[14:17]
	v_mfma_f32_16x16x32_bf16 v[10:13], v[168:171], v[216:219], v[10:13]
	v_mfma_f32_16x16x32_bf16 v[54:57], v[172:175], v[188:191], v[54:57]
	v_mfma_f32_16x16x32_bf16 v[50:53], v[180:183], v[188:191], v[50:53]
	v_mfma_f32_16x16x32_bf16 v[38:41], v[172:175], v[196:199], v[38:41]
	v_mfma_f32_16x16x32_bf16 v[34:37], v[180:183], v[196:199], v[34:37]
	v_mfma_f32_16x16x32_bf16 v[22:25], v[172:175], v[204:207], v[22:25]
	v_mfma_f32_16x16x32_bf16 v[18:21], v[180:183], v[204:207], v[18:21]
	v_mfma_f32_16x16x32_bf16 v[6:9], v[172:175], v[212:215], v[6:9]
	v_mfma_f32_16x16x32_bf16 v[2:5], v[180:183], v[212:215], v[2:5]
	v_mfma_f32_16x16x32_bf16 v[54:57], v[176:179], v[192:195], v[54:57]
	v_mfma_f32_16x16x32_bf16 v[50:53], v[184:187], v[192:195], v[50:53]
	v_mfma_f32_16x16x32_bf16 v[38:41], v[176:179], v[200:203], v[38:41]
	v_mfma_f32_16x16x32_bf16 v[34:37], v[184:187], v[200:203], v[34:37]
	v_mfma_f32_16x16x32_bf16 v[22:25], v[176:179], v[208:211], v[22:25]
	v_mfma_f32_16x16x32_bf16 v[18:21], v[184:187], v[208:211], v[18:21]
	v_mfma_f32_16x16x32_bf16 v[6:9], v[176:179], v[216:219], v[6:9]
	v_mfma_f32_16x16x32_bf16 v[2:5], v[184:187], v[216:219], v[2:5]
	s_barrier
	s_add_i32 s49, 0, 0x18000
	v_add_u32_e32 v138, s49, v150
	s_add_i32 s50, 0, 0x1c000
	ds_read_b128 v[156:159], v138
	ds_read_b128 v[160:163], v138 offset:1024
	ds_read_b128 v[164:167], v138 offset:2048
	ds_read_b128 v[168:171], v138 offset:3072
	v_add_u32_e32 v138, s50, v150
	ds_read_b128 v[172:175], v138
	ds_read_b128 v[176:179], v138 offset:1024
	ds_read_b128 v[180:183], v138 offset:2048
	ds_read_b128 v[184:187], v138 offset:3072
	s_add_u32 s24, s24, 0x40000
	s_addc_u32 s25, s25, 0
	s_mov_b32 m0, s30
	v_lshl_add_u64 v[228:229], s[24:25], 0, v[136:137]
	ds_read_b128 v[188:191], v153 offset:32768
	ds_read_b128 v[192:195], v153 offset:33792
	ds_read_b128 v[196:199], v153 offset:34816
	ds_read_b128 v[200:203], v153 offset:35840
	ds_read_b128 v[204:207], v153 offset:36864
	ds_read_b128 v[208:211], v153 offset:37888
	ds_read_b128 v[212:215], v153 offset:38912
	ds_read_b128 v[216:219], v153 offset:39936
	global_load_lds_dwordx4 v[228:229], off
	v_lshl_add_u64 v[228:229], s[24:25], 0, v[132:133]
	s_mov_b32 m0, s31
	s_nop 0
	global_load_lds_dwordx4 v[228:229], off
	s_waitcnt vmcnt(8)
	s_waitcnt lgkmcnt(0)
	s_barrier
	s_waitcnt lgkmcnt(0)
	v_mfma_f32_16x16x32_bf16 v[118:121], v[156:159], v[188:191], v[118:121]
	v_mfma_f32_16x16x32_bf16 v[114:117], v[164:167], v[188:191], v[114:117]
	v_mfma_f32_16x16x32_bf16 v[106:109], v[156:159], v[196:199], v[106:109]
	v_mfma_f32_16x16x32_bf16 v[102:105], v[164:167], v[196:199], v[102:105]
	v_mfma_f32_16x16x32_bf16 v[94:97], v[156:159], v[204:207], v[94:97]
	v_mfma_f32_16x16x32_bf16 v[90:93], v[164:167], v[204:207], v[90:93]
	v_mfma_f32_16x16x32_bf16 v[78:81], v[156:159], v[212:215], v[78:81]
	v_mfma_f32_16x16x32_bf16 v[74:77], v[164:167], v[212:215], v[74:77]
	v_mfma_f32_16x16x32_bf16 v[118:121], v[160:163], v[192:195], v[118:121]
	v_mfma_f32_16x16x32_bf16 v[114:117], v[168:171], v[192:195], v[114:117]
	v_mfma_f32_16x16x32_bf16 v[106:109], v[160:163], v[200:203], v[106:109]
	v_mfma_f32_16x16x32_bf16 v[102:105], v[168:171], v[200:203], v[102:105]
	v_mfma_f32_16x16x32_bf16 v[94:97], v[160:163], v[208:211], v[94:97]
	v_mfma_f32_16x16x32_bf16 v[90:93], v[168:171], v[208:211], v[90:93]
	v_mfma_f32_16x16x32_bf16 v[78:81], v[160:163], v[216:219], v[78:81]
	v_mfma_f32_16x16x32_bf16 v[74:77], v[168:171], v[216:219], v[74:77]
	v_mfma_f32_16x16x32_bf16 v[126:129], v[172:175], v[188:191], v[126:129]
	v_mfma_f32_16x16x32_bf16 v[122:125], v[180:183], v[188:191], v[122:125]
	v_mfma_f32_16x16x32_bf16 v[110:113], v[172:175], v[196:199], v[110:113]
	v_mfma_f32_16x16x32_bf16 v[98:101], v[180:183], v[196:199], v[98:101]
	v_mfma_f32_16x16x32_bf16 v[86:89], v[172:175], v[204:207], v[86:89]
	v_mfma_f32_16x16x32_bf16 v[82:85], v[180:183], v[204:207], v[82:85]
	v_mfma_f32_16x16x32_bf16 v[70:73], v[172:175], v[212:215], v[70:73]
	v_mfma_f32_16x16x32_bf16 v[66:69], v[180:183], v[212:215], v[66:69]
	v_mfma_f32_16x16x32_bf16 v[126:129], v[176:179], v[192:195], v[126:129]
	v_mfma_f32_16x16x32_bf16 v[122:125], v[184:187], v[192:195], v[122:125]
	v_mfma_f32_16x16x32_bf16 v[110:113], v[176:179], v[200:203], v[110:113]
	v_mfma_f32_16x16x32_bf16 v[98:101], v[184:187], v[200:203], v[98:101]
	v_mfma_f32_16x16x32_bf16 v[86:89], v[176:179], v[208:211], v[86:89]
	v_mfma_f32_16x16x32_bf16 v[82:85], v[184:187], v[208:211], v[82:85]
	v_mfma_f32_16x16x32_bf16 v[70:73], v[176:179], v[216:219], v[70:73]
	v_mfma_f32_16x16x32_bf16 v[66:69], v[184:187], v[216:219], v[66:69]
	s_barrier
; #define PG8_STAGE(bufoff, gbase, voff) do { _Pragma("unroll") for (int _i = 0; _i < 2; ++_i) \
;         __builtin_amdgcn_global_load_lds((const unsigned*)((const char*)(gbase) + (voff)[_i]), (LAS unsigned*)(lds + (bufoff) + ldsw + _i * 8192), 16, 0, 0); } while (0)
; #define PG8_LDA(dst, b, h) do { _Pragma("unroll") for (int m = 0; m < 4; ++m) _Pragma("unroll") for (int k = 0; k < 2; ++k) dst[m][k] = *(const LAS bf16x8*)(lds + PG8_SA(b, h) + aoff + m * 2048 + k * 1024); } while (0)
; #define PG8_MMA(ai, bj, At, Bt) do { __builtin_amdgcn_s_setprio(1); _Pragma("unroll") for (int m = 0; m < 4; ++m) _Pragma("unroll") for (int n = 0; n < 2; ++n) _Pragma("unroll") for (int k = 0; k < 2; ++k) \
;         acc[ai][bj][m][n] = __builtin_amdgcn_mfma_f32_16x16x32_bf16(Bt[n][k], At[m][k], acc[ai][bj][m][n], 0, 0, 0); __builtin_amdgcn_s_setprio(0); } while (0)
; #define PG8_WAIT_V(n) asm volatile("s_waitcnt vmcnt(" #n ")" ::: "memory")
; #define PG8_WAIT_L(n) asm volatile("s_waitcnt lgkmcnt(" #n ")" ::: "memory")
; #define PG8_BAR __builtin_amdgcn_s_barrier()
; #define PG8_SCHED __builtin_amdgcn_sched_barrier(0)
; template <class Epi, bool ALIGN_EPI>
; __device__ __forceinline__ void gemm_phase(LAS unsigned char* lds, const Gemm g, const StaticOrder& S, const Epi& E) {
;     ...
;             PG8_LDA(At, 1, 1); PG8_STAGE(PG8_SB(1, 0), b3, voffB); PG8_STAGE(PG8_SB(1, 1), b3 + hsB, voffB); PG8_STAGE(PG8_SA(1, 0), a3, voffA);
;             PG8_WAIT_V(8); PG8_WAIT_L(0); PG8_BAR; PG8_MMA(1, 0, At, B0); PG8_MMA(1, 1, At, B1); PG8_BAR; PG8_SCHED;
;         }
	s_add_i32 s24, s49, s26
	v_lshl_add_u64 v[220:221], v[220:221], 0, s[6:7]
	s_mov_b32 m0, s24
	ds_read_b128 v[188:191], v153 offset:49152
	ds_read_b128 v[192:195], v153 offset:50176
	ds_read_b128 v[196:199], v153 offset:51200
	ds_read_b128 v[200:203], v153 offset:52224
	ds_read_b128 v[204:207], v153 offset:53248
	ds_read_b128 v[208:211], v153 offset:54272
	ds_read_b128 v[212:215], v153 offset:55296
	ds_read_b128 v[216:219], v153 offset:56320
	global_load_lds_dwordx4 v[220:221], off
	s_add_i32 m0, s24, 0x2000
	s_add_u32 s22, s22, 0x40080
	v_lshl_add_u64 v[220:221], v[222:223], 0, s[6:7]
	s_addc_u32 s23, s23, 0
	s_add_i32 s24, s50, s26
	global_load_lds_dwordx4 v[220:221], off
	v_lshl_add_u64 v[220:221], s[22:23], 0, v[134:135]
	s_mov_b32 m0, s24
	s_nop 0
	global_load_lds_dwordx4 v[220:221], off
	v_lshl_add_u64 v[220:221], s[22:23], 0, v[130:131]
	s_add_i32 m0, s24, 0x2000
	s_nop 0
	global_load_lds_dwordx4 v[220:221], off
	v_lshl_add_u64 v[220:221], v[224:225], 0, s[6:7]
	s_mov_b32 m0, s36
	s_nop 0
	global_load_lds_dwordx4 v[220:221], off
	v_lshl_add_u64 v[220:221], v[226:227], 0, s[6:7]
	s_mov_b32 m0, s37
	s_nop 0
	global_load_lds_dwordx4 v[220:221], off
	s_waitcnt vmcnt(8)
	s_waitcnt lgkmcnt(0)
	s_barrier
	s_waitcnt lgkmcnt(0)
	v_mfma_f32_16x16x32_bf16 v[62:65], v[156:159], v[188:191], v[62:65]
	v_mfma_f32_16x16x32_bf16 v[58:61], v[164:167], v[188:191], v[58:61]
	v_mfma_f32_16x16x32_bf16 v[46:49], v[156:159], v[196:199], v[46:49]
	v_mfma_f32_16x16x32_bf16 v[42:45], v[164:167], v[196:199], v[42:45]
	v_mfma_f32_16x16x32_bf16 v[30:33], v[156:159], v[204:207], v[30:33]
	v_mfma_f32_16x16x32_bf16 v[26:29], v[164:167], v[204:207], v[26:29]
	v_mfma_f32_16x16x32_bf16 v[14:17], v[156:159], v[212:215], v[14:17]
	v_mfma_f32_16x16x32_bf16 v[10:13], v[164:167], v[212:215], v[10:13]
	v_mfma_f32_16x16x32_bf16 v[62:65], v[160:163], v[192:195], v[62:65]
	v_mfma_f32_16x16x32_bf16 v[58:61], v[168:171], v[192:195], v[58:61]
	v_mfma_f32_16x16x32_bf16 v[46:49], v[160:163], v[200:203], v[46:49]
	v_mfma_f32_16x16x32_bf16 v[42:45], v[168:171], v[200:203], v[42:45]
	v_mfma_f32_16x16x32_bf16 v[30:33], v[160:163], v[208:211], v[30:33]
	v_mfma_f32_16x16x32_bf16 v[26:29], v[168:171], v[208:211], v[26:29]
	v_mfma_f32_16x16x32_bf16 v[14:17], v[160:163], v[216:219], v[14:17]
	v_mfma_f32_16x16x32_bf16 v[10:13], v[168:171], v[216:219], v[10:13]
	v_mfma_f32_16x16x32_bf16 v[54:57], v[172:175], v[188:191], v[54:57]
	v_mfma_f32_16x16x32_bf16 v[50:53], v[180:183], v[188:191], v[50:53]
	v_mfma_f32_16x16x32_bf16 v[38:41], v[172:175], v[196:199], v[38:41]
	v_mfma_f32_16x16x32_bf16 v[34:37], v[180:183], v[196:199], v[34:37]
	v_mfma_f32_16x16x32_bf16 v[22:25], v[172:175], v[204:207], v[22:25]
	v_mfma_f32_16x16x32_bf16 v[18:21], v[180:183], v[204:207], v[18:21]
	v_mfma_f32_16x16x32_bf16 v[6:9], v[172:175], v[212:215], v[6:9]
	v_mfma_f32_16x16x32_bf16 v[2:5], v[180:183], v[212:215], v[2:5]
	v_mfma_f32_16x16x32_bf16 v[54:57], v[176:179], v[192:195], v[54:57]
	v_mfma_f32_16x16x32_bf16 v[50:53], v[184:187], v[192:195], v[50:53]
	v_mfma_f32_16x16x32_bf16 v[38:41], v[176:179], v[200:203], v[38:41]
	v_mfma_f32_16x16x32_bf16 v[34:37], v[184:187], v[200:203], v[34:37]
	v_mfma_f32_16x16x32_bf16 v[22:25], v[176:179], v[208:211], v[22:25]
	v_mfma_f32_16x16x32_bf16 v[18:21], v[184:187], v[208:211], v[18:21]
	v_mfma_f32_16x16x32_bf16 v[6:9], v[176:179], v[216:219], v[6:9]
	v_mfma_f32_16x16x32_bf16 v[2:5], v[184:187], v[216:219], v[2:5]
	s_add_i32 s48, s48, 2
	s_add_u32 s20, s20, 0x100
	s_addc_u32 s21, s21, 0
	s_add_u32 s46, s46, 0x100
	s_addc_u32 s47, s47, 0
	s_cmp_gt_u32 s48, 13
	s_barrier
	s_cbranch_scc0 .LBB0_1299
	s_and_b64 vcc, exec, s[8:9]
	s_cbranch_vccz .LBB0_1302
	s_barrier

; #define PG8_STAGE(bufoff, gbase, voff) do { _Pragma("unroll") for (int _i = 0; _i < 2; ++_i) \
;         __builtin_amdgcn_global_load_lds((const unsigned*)((const char*)(gbase) + (voff)[_i]), (LAS unsigned*)(lds + (bufoff) + ldsw + _i * 8192), 16, 0, 0); } while (0)
; #define PG8_LDA(dst, b, h) do { _Pragma("unroll") for (int m = 0; m < 4; ++m) _Pragma("unroll") for (int k = 0; k < 2; ++k) dst[m][k] = *(const LAS bf16x8*)(lds + PG8_SA(b, h) + aoff + m * 2048 + k * 1024); } while (0)
; #define PG8_LDB(dst, b, h) do { _Pragma("unroll") for (int n = 0; n < 2; ++n) _Pragma("unroll") for (int k = 0; k < 2; ++k) dst[n][k] = *(const LAS bf16x8*)(lds + PG8_SB(b, h) + boff + n * 2048 + k * 1024); } while (0)
; #define PG8_MMA(ai, bj, At, Bt) do { __builtin_amdgcn_s_setprio(1); _Pragma("unroll") for (int m = 0; m < 4; ++m) _Pragma("unroll") for (int n = 0; n < 2; ++n) _Pragma("unroll") for (int k = 0; k < 2; ++k) \
;         acc[ai][bj][m][n] = __builtin_amdgcn_mfma_f32_16x16x32_bf16(Bt[n][k], At[m][k], acc[ai][bj][m][n], 0, 0, 0); __builtin_amdgcn_s_setprio(0); } while (0)
; #define PG8_WAIT_V(n) asm volatile("s_waitcnt vmcnt(" #n ")" ::: "memory")
; #define PG8_WAIT_L(n) asm volatile("s_waitcnt lgkmcnt(" #n ")" ::: "memory")
; #define PG8_BAR __builtin_amdgcn_s_barrier()
; #define PG8_SCHED __builtin_amdgcn_sched_barrier(0)
; template <class Epi, bool ALIGN_EPI>
; __device__ __forceinline__ void gemm_phase(LAS unsigned char* lds, const Gemm g, const StaticOrder& S, const Epi& E) {
;     ...
;             const bool last = (t == nt - 2);
;             const char* a1 = cA + (size_t)(t + 1) * kstepA;
;             const char* a2 = last ? nA : cA + (size_t)(t + 2) * kstepA; const char* b2 = last ? nB : cB + (size_t)(t + 2) * kstep;
;             const char* a3 = a2 + kstepA; const char* b3 = b2 + kstep;
;             PG8_LDB(B0, 0, 0); PG8_LDB(B1, 0, 1); PG8_SCHED; PG8_LDA(At, 0, 0); PG8_STAGE(PG8_SA(1, 1), a1 + hsA, voffA);
;             PG8_WAIT_V(8); PG8_WAIT_L(0); PG8_BAR; PG8_MMA(0, 0, At, B0); PG8_MMA(0, 1, At, B1); PG8_BAR; PG8_SCHED;
;             PG8_LDA(At, 0, 1); PG8_STAGE(PG8_SB(0, 0), b2, voffB); PG8_STAGE(PG8_SB(0, 1), b2 + hsB, voffB); PG8_STAGE(PG8_SA(0, 0), a2, voffA);
;             PG8_WAIT_V(8); PG8_WAIT_L(0); PG8_BAR; PG8_MMA(1, 0, At, B0); PG8_MMA(1, 1, At, B1); PG8_BAR; PG8_SCHED;
.LBB0_1405:
	ds_read_b128 v[130:133], v190
	ds_read_b128 v[134:137], v190 offset:1024
	ds_read_b128 v[138:141], v190 offset:2048
	ds_read_b128 v[142:145], v190 offset:3072
	ds_read_b128 v[146:149], v191
	ds_read_b128 v[150:153], v191 offset:1024
	ds_read_b128 v[170:173], v191 offset:2048
	ds_read_b128 v[174:177], v191 offset:3072
	s_add_u32 s18, s16, 0x4000
	s_addc_u32 s19, s17, 0
	s_cmp_eq_u32 s44, 40
	s_cselect_b32 s22, s6, s18
	s_cselect_b32 s23, s7, s19
	s_cselect_b32 s20, s14, s42
	s_cselect_b32 s21, s15, s43
	s_add_u32 s18, s22, 0x8000
	s_addc_u32 s19, s23, 0
	v_lshl_add_u64 v[186:187], s[16:17], 0, v[162:163]
	s_add_i32 m0, s25, 0xc000
	ds_read_b128 v[178:181], v192
	ds_read_b128 v[182:185], v192 offset:1024
	ds_read_b128 v[194:197], v192 offset:2048
	ds_read_b128 v[198:201], v192 offset:3072
	ds_read_b128 v[202:205], v192 offset:4096
	ds_read_b128 v[206:209], v192 offset:5120
	ds_read_b128 v[210:213], v192 offset:6144
	ds_read_b128 v[214:217], v192 offset:7168
	global_load_lds_dwordx4 v[186:187], off
	v_lshl_add_u64 v[186:187], s[16:17], 0, v[164:165]
	s_add_i32 m0, s25, 0xe000
	s_nop 0
	global_load_lds_dwordx4 v[186:187], off
	s_waitcnt vmcnt(8)
	s_waitcnt lgkmcnt(0)
	s_barrier
	s_waitcnt lgkmcnt(0)
	v_mfma_f32_16x16x32_bf16 v[126:129], v[130:133], v[178:181], v[126:129]
	v_mfma_f32_16x16x32_bf16 v[122:125], v[138:141], v[178:181], v[122:125]
	v_mfma_f32_16x16x32_bf16 v[110:113], v[130:133], v[194:197], v[110:113]
	v_mfma_f32_16x16x32_bf16 v[106:109], v[138:141], v[194:197], v[106:109]
	v_mfma_f32_16x16x32_bf16 v[94:97], v[130:133], v[202:205], v[94:97]
	v_mfma_f32_16x16x32_bf16 v[90:93], v[138:141], v[202:205], v[90:93]
	v_mfma_f32_16x16x32_bf16 v[78:81], v[130:133], v[210:213], v[78:81]
	v_mfma_f32_16x16x32_bf16 v[74:77], v[138:141], v[210:213], v[74:77]
	v_mfma_f32_16x16x32_bf16 v[126:129], v[134:137], v[182:185], v[126:129]
	v_mfma_f32_16x16x32_bf16 v[122:125], v[142:145], v[182:185], v[122:125]
	v_mfma_f32_16x16x32_bf16 v[110:113], v[134:137], v[198:201], v[110:113]
	v_mfma_f32_16x16x32_bf16 v[106:109], v[142:145], v[198:201], v[106:109]
	v_mfma_f32_16x16x32_bf16 v[94:97], v[134:137], v[206:209], v[94:97]
	v_mfma_f32_16x16x32_bf16 v[90:93], v[142:145], v[206:209], v[90:93]
	v_mfma_f32_16x16x32_bf16 v[78:81], v[134:137], v[214:217], v[78:81]
	v_mfma_f32_16x16x32_bf16 v[74:77], v[142:145], v[214:217], v[74:77]
	v_mfma_f32_16x16x32_bf16 v[118:121], v[146:149], v[178:181], v[118:121]
	v_mfma_f32_16x16x32_bf16 v[114:117], v[170:173], v[178:181], v[114:117]
	v_mfma_f32_16x16x32_bf16 v[102:105], v[146:149], v[194:197], v[102:105]
	v_mfma_f32_16x16x32_bf16 v[98:101], v[170:173], v[194:197], v[98:101]
	v_mfma_f32_16x16x32_bf16 v[86:89], v[146:149], v[202:205], v[86:89]
	v_mfma_f32_16x16x32_bf16 v[82:85], v[170:173], v[202:205], v[82:85]
	v_mfma_f32_16x16x32_bf16 v[70:73], v[146:149], v[210:213], v[70:73]
	v_mfma_f32_16x16x32_bf16 v[66:69], v[170:173], v[210:213], v[66:69]
	v_mfma_f32_16x16x32_bf16 v[118:121], v[150:153], v[182:185], v[118:121]
	v_mfma_f32_16x16x32_bf16 v[114:117], v[174:177], v[182:185], v[114:117]
	v_mfma_f32_16x16x32_bf16 v[102:105], v[150:153], v[198:201], v[102:105]
	v_mfma_f32_16x16x32_bf16 v[98:101], v[174:177], v[198:201], v[98:101]
	v_mfma_f32_16x16x32_bf16 v[86:89], v[150:153], v[206:209], v[86:89]
	v_mfma_f32_16x16x32_bf16 v[82:85], v[174:177], v[206:209], v[82:85]
	v_mfma_f32_16x16x32_bf16 v[70:73], v[150:153], v[214:217], v[70:73]
	v_mfma_f32_16x16x32_bf16 v[66:69], v[174:177], v[214:217], v[66:69]
	s_barrier
	s_add_i32 s45, s36, s24
	v_lshl_add_u64 v[186:187], s[20:21], 0, v[156:157]
	s_mov_b32 m0, s45
	ds_read_b128 v[178:181], v192 offset:16384
	ds_read_b128 v[182:185], v192 offset:17408
	ds_read_b128 v[194:197], v192 offset:18432
	ds_read_b128 v[198:201], v192 offset:19456
	ds_read_b128 v[202:205], v192 offset:20480
	ds_read_b128 v[206:209], v192 offset:21504
	ds_read_b128 v[210:213], v192 offset:22528
	ds_read_b128 v[214:217], v192 offset:23552
	global_load_lds_dwordx4 v[186:187], off
	s_add_i32 m0, s45, 0x2000
	s_add_u32 s46, s20, 0xb0000
	v_lshl_add_u64 v[218:219], s[20:21], 0, v[160:161]
	s_addc_u32 s47, s21, 0
	s_add_i32 s45, s37, s24
	global_load_lds_dwordx4 v[218:219], off
	v_lshl_add_u64 v[220:221], s[46:47], 0, v[156:157]
	s_mov_b32 m0, s45
	s_nop 0
	global_load_lds_dwordx4 v[220:221], off
	v_lshl_add_u64 v[220:221], s[46:47], 0, v[160:161]
	s_add_i32 m0, s45, 0x2000
	s_nop 0
	global_load_lds_dwordx4 v[220:221], off
	v_lshl_add_u64 v[220:221], s[22:23], 0, v[154:155]
	s_mov_b32 m0, s25
	s_nop 0
	global_load_lds_dwordx4 v[220:221], off
	v_lshl_add_u64 v[220:221], s[22:23], 0, v[158:159]
	s_mov_b32 m0, s26
	s_nop 0
	global_load_lds_dwordx4 v[220:221], off
	s_waitcnt vmcnt(8)
	s_waitcnt lgkmcnt(0)
	s_barrier
; #define PG8_STAGE(bufoff, gbase, voff) do { _Pragma("unroll") for (int _i = 0; _i < 2; ++_i) \
;         __builtin_amdgcn_global_load_lds((const unsigned*)((const char*)(gbase) + (voff)[_i]), (LAS unsigned*)(lds + (bufoff) + ldsw + _i * 8192), 16, 0, 0); } while (0)
; #define PG8_LDA(dst, b, h) do { _Pragma("unroll") for (int m = 0; m < 4; ++m) _Pragma("unroll") for (int k = 0; k < 2; ++k) dst[m][k] = *(const LAS bf16x8*)(lds + PG8_SA(b, h) + aoff + m * 2048 + k * 1024); } while (0)
; #define PG8_LDB(dst, b, h) do { _Pragma("unroll") for (int n = 0; n < 2; ++n) _Pragma("unroll") for (int k = 0; k < 2; ++k) dst[n][k] = *(const LAS bf16x8*)(lds + PG8_SB(b, h) + boff + n * 2048 + k * 1024); } while (0)
; #define PG8_MMA(ai, bj, At, Bt) do { __builtin_amdgcn_s_setprio(1); _Pragma("unroll") for (int m = 0; m < 4; ++m) _Pragma("unroll") for (int n = 0; n < 2; ++n) _Pragma("unroll") for (int k = 0; k < 2; ++k) \
;         acc[ai][bj][m][n] = __builtin_amdgcn_mfma_f32_16x16x32_bf16(Bt[n][k], At[m][k], acc[ai][bj][m][n], 0, 0, 0); __builtin_amdgcn_s_setprio(0); } while (0)
; #define PG8_WAIT_V(n) asm volatile("s_waitcnt vmcnt(" #n ")" ::: "memory")
; #define PG8_WAIT_L(n) asm volatile("s_waitcnt lgkmcnt(" #n ")" ::: "memory")
; #define PG8_BAR __builtin_amdgcn_s_barrier()
; #define PG8_SCHED __builtin_amdgcn_sched_barrier(0)
; template <class Epi, bool ALIGN_EPI>
; __device__ __forceinline__ void gemm_phase(LAS unsigned char* lds, const Gemm g, const StaticOrder& S, const Epi& E) {
;     ...
;             PG8_WAIT_V(8); PG8_WAIT_L(0); PG8_BAR; PG8_MMA(1, 0, At, B0); PG8_MMA(1, 1, At, B1); PG8_BAR; PG8_SCHED;
;             PG8_LDB(B0, 1, 0); PG8_LDB(B1, 1, 1); PG8_SCHED; PG8_LDA(At, 1, 0); PG8_STAGE(PG8_SA(0, 1), a2 + hsA, voffA);
;             PG8_WAIT_V(8); PG8_WAIT_L(0); PG8_BAR; PG8_MMA(0, 0, At, B0); PG8_MMA(0, 1, At, B1); PG8_BAR; PG8_SCHED;
	s_waitcnt lgkmcnt(0)
	v_mfma_f32_16x16x32_bf16 v[62:65], v[130:133], v[178:181], v[62:65]
	v_mfma_f32_16x16x32_bf16 v[58:61], v[138:141], v[178:181], v[58:61]
	v_mfma_f32_16x16x32_bf16 v[46:49], v[130:133], v[194:197], v[46:49]
	v_mfma_f32_16x16x32_bf16 v[42:45], v[138:141], v[194:197], v[42:45]
	v_mfma_f32_16x16x32_bf16 v[30:33], v[130:133], v[202:205], v[30:33]
	v_mfma_f32_16x16x32_bf16 v[26:29], v[138:141], v[202:205], v[26:29]
	v_mfma_f32_16x16x32_bf16 v[14:17], v[130:133], v[210:213], v[14:17]
	v_mfma_f32_16x16x32_bf16 v[10:13], v[138:141], v[210:213], v[10:13]
	v_mfma_f32_16x16x32_bf16 v[62:65], v[134:137], v[182:185], v[62:65]
	v_mfma_f32_16x16x32_bf16 v[58:61], v[142:145], v[182:185], v[58:61]
	v_mfma_f32_16x16x32_bf16 v[46:49], v[134:137], v[198:201], v[46:49]
	v_mfma_f32_16x16x32_bf16 v[42:45], v[142:145], v[198:201], v[42:45]
	v_mfma_f32_16x16x32_bf16 v[30:33], v[134:137], v[206:209], v[30:33]
	v_mfma_f32_16x16x32_bf16 v[26:29], v[142:145], v[206:209], v[26:29]
	v_mfma_f32_16x16x32_bf16 v[14:17], v[134:137], v[214:217], v[14:17]
	v_mfma_f32_16x16x32_bf16 v[10:13], v[142:145], v[214:217], v[10:13]
	v_mfma_f32_16x16x32_bf16 v[54:57], v[146:149], v[178:181], v[54:57]
	v_mfma_f32_16x16x32_bf16 v[50:53], v[170:173], v[178:181], v[50:53]
	v_mfma_f32_16x16x32_bf16 v[38:41], v[146:149], v[194:197], v[38:41]
	v_mfma_f32_16x16x32_bf16 v[34:37], v[170:173], v[194:197], v[34:37]
	v_mfma_f32_16x16x32_bf16 v[22:25], v[146:149], v[202:205], v[22:25]
	v_mfma_f32_16x16x32_bf16 v[18:21], v[170:173], v[202:205], v[18:21]
	v_mfma_f32_16x16x32_bf16 v[6:9], v[146:149], v[210:213], v[6:9]
	v_mfma_f32_16x16x32_bf16 v[2:5], v[170:173], v[210:213], v[2:5]
	v_mfma_f32_16x16x32_bf16 v[54:57], v[150:153], v[182:185], v[54:57]
	v_mfma_f32_16x16x32_bf16 v[50:53], v[174:177], v[182:185], v[50:53]
	v_mfma_f32_16x16x32_bf16 v[38:41], v[150:153], v[198:201], v[38:41]
	v_mfma_f32_16x16x32_bf16 v[34:37], v[174:177], v[198:201], v[34:37]
	v_mfma_f32_16x16x32_bf16 v[22:25], v[150:153], v[206:209], v[22:25]
	v_mfma_f32_16x16x32_bf16 v[18:21], v[174:177], v[206:209], v[18:21]
	v_mfma_f32_16x16x32_bf16 v[6:9], v[150:153], v[214:217], v[6:9]
	v_mfma_f32_16x16x32_bf16 v[2:5], v[174:177], v[214:217], v[2:5]
	s_barrier
	s_add_i32 s45, 0, 0x18000
	s_add_i32 s46, 0, 0x1c000
	v_add_u32_e32 v142, s45, v188
	v_add_u32_e32 v174, s46, v188
	ds_read_b128 v[130:133], v142
	ds_read_b128 v[134:137], v142 offset:1024
	ds_read_b128 v[138:141], v142 offset:2048
	ds_read_b128 v[142:145], v142 offset:3072
	ds_read_b128 v[146:149], v174
	ds_read_b128 v[150:153], v174 offset:1024
	ds_read_b128 v[170:173], v174 offset:2048
	ds_read_b128 v[174:177], v174 offset:3072
	s_add_u32 s22, s22, 0x4000
	s_addc_u32 s23, s23, 0
	s_mov_b32 m0, s27
	v_lshl_add_u64 v[220:221], s[22:23], 0, v[154:155]
	ds_read_b128 v[178:181], v192 offset:32768
	ds_read_b128 v[182:185], v192 offset:33792
	ds_read_b128 v[194:197], v192 offset:34816
	ds_read_b128 v[198:201], v192 offset:35840
	ds_read_b128 v[202:205], v192 offset:36864
	ds_read_b128 v[206:209], v192 offset:37888
	ds_read_b128 v[210:213], v192 offset:38912
	ds_read_b128 v[214:217], v192 offset:39936
	global_load_lds_dwordx4 v[220:221], off
	v_lshl_add_u64 v[220:221], s[22:23], 0, v[158:159]
	s_mov_b32 m0, s28
	s_nop 0
	global_load_lds_dwordx4 v[220:221], off
	s_waitcnt vmcnt(8)
	s_waitcnt lgkmcnt(0)
	s_barrier
	s_waitcnt lgkmcnt(0)
	v_mfma_f32_16x16x32_bf16 v[126:129], v[130:133], v[178:181], v[126:129]
	v_mfma_f32_16x16x32_bf16 v[122:125], v[138:141], v[178:181], v[122:125]
	v_mfma_f32_16x16x32_bf16 v[110:113], v[130:133], v[194:197], v[110:113]
	v_mfma_f32_16x16x32_bf16 v[106:109], v[138:141], v[194:197], v[106:109]
	v_mfma_f32_16x16x32_bf16 v[94:97], v[130:133], v[202:205], v[94:97]
	v_mfma_f32_16x16x32_bf16 v[90:93], v[138:141], v[202:205], v[90:93]
	v_mfma_f32_16x16x32_bf16 v[78:81], v[130:133], v[210:213], v[78:81]
	v_mfma_f32_16x16x32_bf16 v[74:77], v[138:141], v[210:213], v[74:77]
	v_mfma_f32_16x16x32_bf16 v[126:129], v[134:137], v[182:185], v[126:129]
	v_mfma_f32_16x16x32_bf16 v[122:125], v[142:145], v[182:185], v[122:125]
	v_mfma_f32_16x16x32_bf16 v[110:113], v[134:137], v[198:201], v[110:113]
	v_mfma_f32_16x16x32_bf16 v[106:109], v[142:145], v[198:201], v[106:109]
	v_mfma_f32_16x16x32_bf16 v[94:97], v[134:137], v[206:209], v[94:97]
	v_mfma_f32_16x16x32_bf16 v[90:93], v[142:145], v[206:209], v[90:93]
	v_mfma_f32_16x16x32_bf16 v[78:81], v[134:137], v[214:217], v[78:81]
	v_mfma_f32_16x16x32_bf16 v[74:77], v[142:145], v[214:217], v[74:77]
	v_mfma_f32_16x16x32_bf16 v[118:121], v[146:149], v[178:181], v[118:121]
	v_mfma_f32_16x16x32_bf16 v[114:117], v[170:173], v[178:181], v[114:117]
	v_mfma_f32_16x16x32_bf16 v[102:105], v[146:149], v[194:197], v[102:105]
	v_mfma_f32_16x16x32_bf16 v[98:101], v[170:173], v[194:197], v[98:101]
	v_mfma_f32_16x16x32_bf16 v[86:89], v[146:149], v[202:205], v[86:89]
	v_mfma_f32_16x16x32_bf16 v[82:85], v[170:173], v[202:205], v[82:85]
	v_mfma_f32_16x16x32_bf16 v[70:73], v[146:149], v[210:213], v[70:73]
	v_mfma_f32_16x16x32_bf16 v[66:69], v[170:173], v[210:213], v[66:69]
	v_mfma_f32_16x16x32_bf16 v[118:121], v[150:153], v[182:185], v[118:121]
	v_mfma_f32_16x16x32_bf16 v[114:117], v[174:177], v[182:185], v[114:117]
	v_mfma_f32_16x16x32_bf16 v[102:105], v[150:153], v[198:201], v[102:105]
	v_mfma_f32_16x16x32_bf16 v[98:101], v[174:177], v[198:201], v[98:101]
	v_mfma_f32_16x16x32_bf16 v[86:89], v[150:153], v[206:209], v[86:89]
	v_mfma_f32_16x16x32_bf16 v[82:85], v[174:177], v[206:209], v[82:85]
	v_mfma_f32_16x16x32_bf16 v[70:73], v[150:153], v[214:217], v[70:73]
	v_mfma_f32_16x16x32_bf16 v[66:69], v[174:177], v[214:217], v[66:69]
	s_barrier
; #define PG8_STAGE(bufoff, gbase, voff) do { _Pragma("unroll") for (int _i = 0; _i < 2; ++_i) \
;         __builtin_amdgcn_global_load_lds((const unsigned*)((const char*)(gbase) + (voff)[_i]), (LAS unsigned*)(lds + (bufoff) + ldsw + _i * 8192), 16, 0, 0); } while (0)
; #define PG8_LDA(dst, b, h) do { _Pragma("unroll") for (int m = 0; m < 4; ++m) _Pragma("unroll") for (int k = 0; k < 2; ++k) dst[m][k] = *(const LAS bf16x8*)(lds + PG8_SA(b, h) + aoff + m * 2048 + k * 1024); } while (0)
; #define PG8_MMA(ai, bj, At, Bt) do { __builtin_amdgcn_s_setprio(1); _Pragma("unroll") for (int m = 0; m < 4; ++m) _Pragma("unroll") for (int n = 0; n < 2; ++n) _Pragma("unroll") for (int k = 0; k < 2; ++k) \
;         acc[ai][bj][m][n] = __builtin_amdgcn_mfma_f32_16x16x32_bf16(Bt[n][k], At[m][k], acc[ai][bj][m][n], 0, 0, 0); __builtin_amdgcn_s_setprio(0); } while (0)
; #define PG8_WAIT_V(n) asm volatile("s_waitcnt vmcnt(" #n ")" ::: "memory")
; #define PG8_WAIT_L(n) asm volatile("s_waitcnt lgkmcnt(" #n ")" ::: "memory")
; #define PG8_BAR __builtin_amdgcn_s_barrier()
; #define PG8_SCHED __builtin_amdgcn_sched_barrier(0)
; template <class Epi, bool ALIGN_EPI>
; __device__ __forceinline__ void gemm_phase(LAS unsigned char* lds, const Gemm g, const StaticOrder& S, const Epi& E) {
;     ...
;             PG8_LDA(At, 1, 1); PG8_STAGE(PG8_SB(1, 0), b3, voffB); PG8_STAGE(PG8_SB(1, 1), b3 + hsB, voffB); PG8_STAGE(PG8_SA(1, 0), a3, voffA);
;             PG8_WAIT_V(8); PG8_WAIT_L(0); PG8_BAR; PG8_MMA(1, 0, At, B0); PG8_MMA(1, 1, At, B1); PG8_BAR; PG8_SCHED;
;         }
	s_add_i32 s22, s45, s24
	v_lshl_add_u64 v[186:187], v[186:187], 0, s[10:11]
	s_mov_b32 m0, s22
	ds_read_b128 v[178:181], v192 offset:49152
	ds_read_b128 v[182:185], v192 offset:50176
	ds_read_b128 v[194:197], v192 offset:51200
	ds_read_b128 v[198:201], v192 offset:52224
	ds_read_b128 v[202:205], v192 offset:53248
	ds_read_b128 v[206:209], v192 offset:54272
	ds_read_b128 v[210:213], v192 offset:55296
	ds_read_b128 v[214:217], v192 offset:56320
	global_load_lds_dwordx4 v[186:187], off
	s_add_i32 m0, s22, 0x2000
	s_add_u32 s20, s20, 0xb0080
	v_lshl_add_u64 v[186:187], v[218:219], 0, s[10:11]
	s_addc_u32 s21, s21, 0
	s_add_i32 s22, s46, s24
	global_load_lds_dwordx4 v[186:187], off
	v_lshl_add_u64 v[186:187], s[20:21], 0, v[156:157]
	s_mov_b32 m0, s22
	s_nop 0
	global_load_lds_dwordx4 v[186:187], off
	v_lshl_add_u64 v[186:187], s[20:21], 0, v[160:161]
	s_add_i32 m0, s22, 0x2000
	s_nop 0
	global_load_lds_dwordx4 v[186:187], off
	v_lshl_add_u64 v[186:187], s[18:19], 0, v[154:155]
	s_mov_b32 m0, s30
	s_nop 0
	global_load_lds_dwordx4 v[186:187], off
	v_lshl_add_u64 v[186:187], s[18:19], 0, v[158:159]
	s_mov_b32 m0, s31
	s_nop 0
	global_load_lds_dwordx4 v[186:187], off
	s_waitcnt vmcnt(8)
	s_waitcnt lgkmcnt(0)
	s_barrier
	s_waitcnt lgkmcnt(0)
	v_mfma_f32_16x16x32_bf16 v[62:65], v[130:133], v[178:181], v[62:65]
	v_mfma_f32_16x16x32_bf16 v[58:61], v[138:141], v[178:181], v[58:61]
	v_mfma_f32_16x16x32_bf16 v[46:49], v[130:133], v[194:197], v[46:49]
	v_mfma_f32_16x16x32_bf16 v[42:45], v[138:141], v[194:197], v[42:45]
	v_mfma_f32_16x16x32_bf16 v[30:33], v[130:133], v[202:205], v[30:33]
	v_mfma_f32_16x16x32_bf16 v[26:29], v[138:141], v[202:205], v[26:29]
	v_mfma_f32_16x16x32_bf16 v[14:17], v[130:133], v[210:213], v[14:17]
	v_mfma_f32_16x16x32_bf16 v[10:13], v[138:141], v[210:213], v[10:13]
	v_mfma_f32_16x16x32_bf16 v[62:65], v[134:137], v[182:185], v[62:65]
	v_mfma_f32_16x16x32_bf16 v[58:61], v[142:145], v[182:185], v[58:61]
	v_mfma_f32_16x16x32_bf16 v[46:49], v[134:137], v[198:201], v[46:49]
	v_mfma_f32_16x16x32_bf16 v[42:45], v[142:145], v[198:201], v[42:45]
	v_mfma_f32_16x16x32_bf16 v[30:33], v[134:137], v[206:209], v[30:33]
	v_mfma_f32_16x16x32_bf16 v[26:29], v[142:145], v[206:209], v[26:29]
	v_mfma_f32_16x16x32_bf16 v[14:17], v[134:137], v[214:217], v[14:17]
	v_mfma_f32_16x16x32_bf16 v[10:13], v[142:145], v[214:217], v[10:13]
	v_mfma_f32_16x16x32_bf16 v[54:57], v[146:149], v[178:181], v[54:57]
	v_mfma_f32_16x16x32_bf16 v[50:53], v[170:173], v[178:181], v[50:53]
	v_mfma_f32_16x16x32_bf16 v[38:41], v[146:149], v[194:197], v[38:41]
	v_mfma_f32_16x16x32_bf16 v[34:37], v[170:173], v[194:197], v[34:37]
	v_mfma_f32_16x16x32_bf16 v[22:25], v[146:149], v[202:205], v[22:25]
	v_mfma_f32_16x16x32_bf16 v[18:21], v[170:173], v[202:205], v[18:21]
	v_mfma_f32_16x16x32_bf16 v[6:9], v[146:149], v[210:213], v[6:9]
	v_mfma_f32_16x16x32_bf16 v[2:5], v[170:173], v[210:213], v[2:5]
	v_mfma_f32_16x16x32_bf16 v[54:57], v[150:153], v[182:185], v[54:57]
	v_mfma_f32_16x16x32_bf16 v[50:53], v[174:177], v[182:185], v[50:53]
	v_mfma_f32_16x16x32_bf16 v[38:41], v[150:153], v[198:201], v[38:41]
	v_mfma_f32_16x16x32_bf16 v[34:37], v[174:177], v[198:201], v[34:37]
	v_mfma_f32_16x16x32_bf16 v[22:25], v[150:153], v[206:209], v[22:25]
	v_mfma_f32_16x16x32_bf16 v[18:21], v[174:177], v[206:209], v[18:21]
	v_mfma_f32_16x16x32_bf16 v[6:9], v[150:153], v[214:217], v[6:9]
	v_mfma_f32_16x16x32_bf16 v[2:5], v[174:177], v[214:217], v[2:5]
	s_add_i32 s44, s44, 2
	s_add_u32 s16, s16, 0x10000
	s_addc_u32 s17, s17, 0
	s_add_u32 s42, s42, 0x100
	s_addc_u32 s43, s43, 0
	s_cmp_gt_u32 s44, 41
	s_barrier
	s_cbranch_scc0 .LBB0_1405
	s_and_b64 vcc, exec, s[12:13]
	s_cbranch_vccz .LBB0_1408
	s_barrier

; #define PG8_STAGE(bufoff, gbase, voff) do { _Pragma("unroll") for (int _i = 0; _i < 2; ++_i) \
;         __builtin_amdgcn_global_load_lds((const unsigned*)((const char*)(gbase) + (voff)[_i]), (LAS unsigned*)(lds + (bufoff) + ldsw + _i * 8192), 16, 0, 0); } while (0)
; #define PG8_LDA(dst, b, h) do { _Pragma("unroll") for (int m = 0; m < 4; ++m) _Pragma("unroll") for (int k = 0; k < 2; ++k) dst[m][k] = *(const LAS bf16x8*)(lds + PG8_SA(b, h) + aoff + m * 2048 + k * 1024); } while (0)
; #define PG8_LDB(dst, b, h) do { _Pragma("unroll") for (int n = 0; n < 2; ++n) _Pragma("unroll") for (int k = 0; k < 2; ++k) dst[n][k] = *(const LAS bf16x8*)(lds + PG8_SB(b, h) + boff + n * 2048 + k * 1024); } while (0)
; #define PG8_MMA(ai, bj, At, Bt) do { __builtin_amdgcn_s_setprio(1); _Pragma("unroll") for (int m = 0; m < 4; ++m) _Pragma("unroll") for (int n = 0; n < 2; ++n) _Pragma("unroll") for (int k = 0; k < 2; ++k) \
;         acc[ai][bj][m][n] = __builtin_amdgcn_mfma_f32_16x16x32_bf16(Bt[n][k], At[m][k], acc[ai][bj][m][n], 0, 0, 0); __builtin_amdgcn_s_setprio(0); } while (0)
; #define PG8_WAIT_V(n) asm volatile("s_waitcnt vmcnt(" #n ")" ::: "memory")
; #define PG8_WAIT_L(n) asm volatile("s_waitcnt lgkmcnt(" #n ")" ::: "memory")
; #define PG8_BAR __builtin_amdgcn_s_barrier()
; #define PG8_SCHED __builtin_amdgcn_sched_barrier(0)
; template <class Epi, bool ALIGN_EPI>
; __device__ __forceinline__ void gemm_phase(LAS unsigned char* lds, const Gemm g, const StaticOrder& S, const Epi& E) {
;     ...
;             const bool last = (t == nt - 2);
;             const char* a1 = cA + (size_t)(t + 1) * kstepA;
;             const char* a2 = last ? nA : cA + (size_t)(t + 2) * kstepA; const char* b2 = last ? nB : cB + (size_t)(t + 2) * kstep;
;             const char* a3 = a2 + kstepA; const char* b3 = b2 + kstep;
;             PG8_LDB(B0, 0, 0); PG8_LDB(B1, 0, 1); PG8_SCHED; PG8_LDA(At, 0, 0); PG8_STAGE(PG8_SA(1, 1), a1 + hsA, voffA);
;             PG8_WAIT_V(8); PG8_WAIT_L(0); PG8_BAR; PG8_MMA(0, 0, At, B0); PG8_MMA(0, 1, At, B1); PG8_BAR; PG8_SCHED;
;             PG8_LDA(At, 0, 1); PG8_STAGE(PG8_SB(0, 0), b2, voffB); PG8_STAGE(PG8_SB(0, 1), b2 + hsB, voffB); PG8_STAGE(PG8_SA(0, 0), a2, voffA);
;             PG8_WAIT_V(8); PG8_WAIT_L(0); PG8_BAR; PG8_MMA(1, 0, At, B0); PG8_MMA(1, 1, At, B1); PG8_BAR; PG8_SCHED;
.LBB0_1501:
	ds_read_b128 v[128:131], v203
	ds_read_b128 v[132:135], v203 offset:1024
	ds_read_b128 v[136:139], v203 offset:2048
	ds_read_b128 v[140:143], v203 offset:3072
	ds_read_b128 v[144:147], v204
	ds_read_b128 v[148:151], v204 offset:1024
	ds_read_b128 v[152:155], v204 offset:2048
	ds_read_b128 v[156:159], v204 offset:3072
	s_add_u32 s28, s24, 0xfffc0080
	s_addc_u32 s29, s25, -1
	s_cmp_eq_u32 s49, 12
	s_cselect_b32 s31, s19, s29
	s_cselect_b32 s30, s45, s28
	s_cselect_b32 s29, s21, s48
	s_cselect_b32 s28, s46, s47
	v_lshl_add_u64 v[216:217], s[24:25], 0, v[184:185]
	s_add_i32 m0, s9, 0xc000
	ds_read_b128 v[160:163], v205
	ds_read_b128 v[164:167], v205 offset:1024
	ds_read_b128 v[168:171], v205 offset:2048
	ds_read_b128 v[172:175], v205 offset:3072
	ds_read_b128 v[192:195], v205 offset:4096
	ds_read_b128 v[196:199], v205 offset:5120
	ds_read_b128 v[208:211], v205 offset:6144
	ds_read_b128 v[212:215], v205 offset:7168
	global_load_lds_dwordx4 v[216:217], off
	v_lshl_add_u64 v[216:217], s[24:25], 0, v[186:187]
	s_add_i32 m0, s9, 0xe000
	s_nop 0
	global_load_lds_dwordx4 v[216:217], off
	s_waitcnt vmcnt(8)
	s_waitcnt lgkmcnt(0)
	s_barrier
	s_waitcnt lgkmcnt(0)
	v_mfma_f32_16x16x32_bf16 v[124:127], v[128:131], v[160:163], v[124:127]
	v_mfma_f32_16x16x32_bf16 v[120:123], v[136:139], v[160:163], v[120:123]
	v_mfma_f32_16x16x32_bf16 v[108:111], v[128:131], v[168:171], v[108:111]
	v_mfma_f32_16x16x32_bf16 v[104:107], v[136:139], v[168:171], v[104:107]
	v_mfma_f32_16x16x32_bf16 v[92:95], v[128:131], v[192:195], v[92:95]
	v_mfma_f32_16x16x32_bf16 v[88:91], v[136:139], v[192:195], v[88:91]
	v_mfma_f32_16x16x32_bf16 v[76:79], v[128:131], v[208:211], v[76:79]
	v_mfma_f32_16x16x32_bf16 v[72:75], v[136:139], v[208:211], v[72:75]
	v_mfma_f32_16x16x32_bf16 v[124:127], v[132:135], v[164:167], v[124:127]
	v_mfma_f32_16x16x32_bf16 v[120:123], v[140:143], v[164:167], v[120:123]
	v_mfma_f32_16x16x32_bf16 v[108:111], v[132:135], v[172:175], v[108:111]
	v_mfma_f32_16x16x32_bf16 v[104:107], v[140:143], v[172:175], v[104:107]
	v_mfma_f32_16x16x32_bf16 v[92:95], v[132:135], v[196:199], v[92:95]
	v_mfma_f32_16x16x32_bf16 v[88:91], v[140:143], v[196:199], v[88:91]
	v_mfma_f32_16x16x32_bf16 v[76:79], v[132:135], v[212:215], v[76:79]
	v_mfma_f32_16x16x32_bf16 v[72:75], v[140:143], v[212:215], v[72:75]
	v_mfma_f32_16x16x32_bf16 v[116:119], v[144:147], v[160:163], v[116:119]
	v_mfma_f32_16x16x32_bf16 v[112:115], v[152:155], v[160:163], v[112:115]
	v_mfma_f32_16x16x32_bf16 v[100:103], v[144:147], v[168:171], v[100:103]
	v_mfma_f32_16x16x32_bf16 v[96:99], v[152:155], v[168:171], v[96:99]
	v_mfma_f32_16x16x32_bf16 v[84:87], v[144:147], v[192:195], v[84:87]
	v_mfma_f32_16x16x32_bf16 v[80:83], v[152:155], v[192:195], v[80:83]
	v_mfma_f32_16x16x32_bf16 v[68:71], v[144:147], v[208:211], v[68:71]
	v_mfma_f32_16x16x32_bf16 v[64:67], v[152:155], v[208:211], v[64:67]
	v_mfma_f32_16x16x32_bf16 v[116:119], v[148:151], v[164:167], v[116:119]
	v_mfma_f32_16x16x32_bf16 v[112:115], v[156:159], v[164:167], v[112:115]
	v_mfma_f32_16x16x32_bf16 v[100:103], v[148:151], v[172:175], v[100:103]
	v_mfma_f32_16x16x32_bf16 v[96:99], v[156:159], v[172:175], v[96:99]
	v_mfma_f32_16x16x32_bf16 v[84:87], v[148:151], v[196:199], v[84:87]
	v_mfma_f32_16x16x32_bf16 v[80:83], v[156:159], v[196:199], v[80:83]
	v_mfma_f32_16x16x32_bf16 v[68:71], v[148:151], v[212:215], v[68:71]
	v_mfma_f32_16x16x32_bf16 v[64:67], v[156:159], v[212:215], v[64:67]
	s_barrier
	s_add_i32 s50, s42, s34
	v_lshl_add_u64 v[216:217], s[28:29], 0, v[178:179]
	s_mov_b32 m0, s50
	ds_read_b128 v[160:163], v205 offset:16384
	ds_read_b128 v[164:167], v205 offset:17408
	ds_read_b128 v[168:171], v205 offset:18432
	ds_read_b128 v[172:175], v205 offset:19456
	ds_read_b128 v[192:195], v205 offset:20480
	ds_read_b128 v[196:199], v205 offset:21504
	ds_read_b128 v[208:211], v205 offset:22528
	ds_read_b128 v[212:215], v205 offset:23552
	global_load_lds_dwordx4 v[216:217], off
	s_add_i32 m0, s50, 0x2000
	s_add_u32 s50, s28, 0x40000
	v_lshl_add_u64 v[218:219], s[28:29], 0, v[182:183]
	s_addc_u32 s51, s29, 0
	s_add_i32 s52, s43, s34
	global_load_lds_dwordx4 v[218:219], off
	v_lshl_add_u64 v[220:221], s[50:51], 0, v[178:179]
	s_mov_b32 m0, s52
	v_lshl_add_u64 v[222:223], s[30:31], 0, v[180:181]
	global_load_lds_dwordx4 v[220:221], off
	v_lshl_add_u64 v[220:221], s[50:51], 0, v[182:183]
	s_add_i32 m0, s52, 0x2000
	s_nop 0
	global_load_lds_dwordx4 v[220:221], off
	v_lshl_add_u64 v[220:221], s[30:31], 0, v[176:177]
	s_mov_b32 m0, s9
	s_nop 0
	global_load_lds_dwordx4 v[220:221], off
	s_mov_b32 m0, s35
	s_nop 0
	global_load_lds_dwordx4 v[222:223], off
	s_waitcnt vmcnt(8)
	s_waitcnt lgkmcnt(0)
	s_barrier
; #define PG8_STAGE(bufoff, gbase, voff) do { _Pragma("unroll") for (int _i = 0; _i < 2; ++_i) \
;         __builtin_amdgcn_global_load_lds((const unsigned*)((const char*)(gbase) + (voff)[_i]), (LAS unsigned*)(lds + (bufoff) + ldsw + _i * 8192), 16, 0, 0); } while (0)
; #define PG8_LDA(dst, b, h) do { _Pragma("unroll") for (int m = 0; m < 4; ++m) _Pragma("unroll") for (int k = 0; k < 2; ++k) dst[m][k] = *(const LAS bf16x8*)(lds + PG8_SA(b, h) + aoff + m * 2048 + k * 1024); } while (0)
; #define PG8_LDB(dst, b, h) do { _Pragma("unroll") for (int n = 0; n < 2; ++n) _Pragma("unroll") for (int k = 0; k < 2; ++k) dst[n][k] = *(const LAS bf16x8*)(lds + PG8_SB(b, h) + boff + n * 2048 + k * 1024); } while (0)
; #define PG8_MMA(ai, bj, At, Bt) do { __builtin_amdgcn_s_setprio(1); _Pragma("unroll") for (int m = 0; m < 4; ++m) _Pragma("unroll") for (int n = 0; n < 2; ++n) _Pragma("unroll") for (int k = 0; k < 2; ++k) \
;         acc[ai][bj][m][n] = __builtin_amdgcn_mfma_f32_16x16x32_bf16(Bt[n][k], At[m][k], acc[ai][bj][m][n], 0, 0, 0); __builtin_amdgcn_s_setprio(0); } while (0)
; #define PG8_WAIT_V(n) asm volatile("s_waitcnt vmcnt(" #n ")" ::: "memory")
; #define PG8_WAIT_L(n) asm volatile("s_waitcnt lgkmcnt(" #n ")" ::: "memory")
; #define PG8_BAR __builtin_amdgcn_s_barrier()
; #define PG8_SCHED __builtin_amdgcn_sched_barrier(0)
; template <class Epi, bool ALIGN_EPI>
; __device__ __forceinline__ void gemm_phase(LAS unsigned char* lds, const Gemm g, const StaticOrder& S, const Epi& E) {
;     ...
;             PG8_WAIT_V(8); PG8_WAIT_L(0); PG8_BAR; PG8_MMA(1, 0, At, B0); PG8_MMA(1, 1, At, B1); PG8_BAR; PG8_SCHED;
;             PG8_LDB(B0, 1, 0); PG8_LDB(B1, 1, 1); PG8_SCHED; PG8_LDA(At, 1, 0); PG8_STAGE(PG8_SA(0, 1), a2 + hsA, voffA);
;             PG8_WAIT_V(8); PG8_WAIT_L(0); PG8_BAR; PG8_MMA(0, 0, At, B0); PG8_MMA(0, 1, At, B1); PG8_BAR; PG8_SCHED;
	s_waitcnt lgkmcnt(0)
	v_mfma_f32_16x16x32_bf16 v[60:63], v[128:131], v[160:163], v[60:63]
	v_mfma_f32_16x16x32_bf16 v[56:59], v[136:139], v[160:163], v[56:59]
	v_mfma_f32_16x16x32_bf16 v[44:47], v[128:131], v[168:171], v[44:47]
	v_mfma_f32_16x16x32_bf16 v[40:43], v[136:139], v[168:171], v[40:43]
	v_mfma_f32_16x16x32_bf16 v[28:31], v[128:131], v[192:195], v[28:31]
	v_mfma_f32_16x16x32_bf16 v[24:27], v[136:139], v[192:195], v[24:27]
	v_mfma_f32_16x16x32_bf16 v[12:15], v[128:131], v[208:211], v[12:15]
	v_mfma_f32_16x16x32_bf16 v[8:11], v[136:139], v[208:211], v[8:11]
	v_mfma_f32_16x16x32_bf16 v[60:63], v[132:135], v[164:167], v[60:63]
	v_mfma_f32_16x16x32_bf16 v[56:59], v[140:143], v[164:167], v[56:59]
	v_mfma_f32_16x16x32_bf16 v[44:47], v[132:135], v[172:175], v[44:47]
	v_mfma_f32_16x16x32_bf16 v[40:43], v[140:143], v[172:175], v[40:43]
	v_mfma_f32_16x16x32_bf16 v[28:31], v[132:135], v[196:199], v[28:31]
	v_mfma_f32_16x16x32_bf16 v[24:27], v[140:143], v[196:199], v[24:27]
	v_mfma_f32_16x16x32_bf16 v[12:15], v[132:135], v[212:215], v[12:15]
	v_mfma_f32_16x16x32_bf16 v[8:11], v[140:143], v[212:215], v[8:11]
	v_mfma_f32_16x16x32_bf16 v[52:55], v[144:147], v[160:163], v[52:55]
	v_mfma_f32_16x16x32_bf16 v[48:51], v[152:155], v[160:163], v[48:51]
	v_mfma_f32_16x16x32_bf16 v[36:39], v[144:147], v[168:171], v[36:39]
	v_mfma_f32_16x16x32_bf16 v[32:35], v[152:155], v[168:171], v[32:35]
	v_mfma_f32_16x16x32_bf16 v[20:23], v[144:147], v[192:195], v[20:23]
	v_mfma_f32_16x16x32_bf16 v[16:19], v[152:155], v[192:195], v[16:19]
	v_mfma_f32_16x16x32_bf16 v[4:7], v[144:147], v[208:211], v[4:7]
	v_mfma_f32_16x16x32_bf16 v[0:3], v[152:155], v[208:211], v[0:3]
	v_mfma_f32_16x16x32_bf16 v[52:55], v[148:151], v[164:167], v[52:55]
	v_mfma_f32_16x16x32_bf16 v[48:51], v[156:159], v[164:167], v[48:51]
	v_mfma_f32_16x16x32_bf16 v[36:39], v[148:151], v[172:175], v[36:39]
	v_mfma_f32_16x16x32_bf16 v[32:35], v[156:159], v[172:175], v[32:35]
	v_mfma_f32_16x16x32_bf16 v[20:23], v[148:151], v[196:199], v[20:23]
	v_mfma_f32_16x16x32_bf16 v[16:19], v[156:159], v[196:199], v[16:19]
	v_mfma_f32_16x16x32_bf16 v[4:7], v[148:151], v[212:215], v[4:7]
	v_mfma_f32_16x16x32_bf16 v[0:3], v[156:159], v[212:215], v[0:3]
	s_barrier
	s_add_i32 s50, 0, 0x18000
	s_add_i32 s51, 0, 0x1c000
	v_add_u32_e32 v140, s50, v201
	v_add_u32_e32 v156, s51, v201
	ds_read_b128 v[128:131], v140
	ds_read_b128 v[132:135], v140 offset:1024
	ds_read_b128 v[136:139], v140 offset:2048
	ds_read_b128 v[140:143], v140 offset:3072
	ds_read_b128 v[144:147], v156
	ds_read_b128 v[148:151], v156 offset:1024
	ds_read_b128 v[152:155], v156 offset:2048
	ds_read_b128 v[156:159], v156 offset:3072
	s_add_u32 s30, s30, 0x40000
	s_addc_u32 s31, s31, 0
	s_mov_b32 m0, s36
	v_lshl_add_u64 v[224:225], s[30:31], 0, v[176:177]
	ds_read_b128 v[160:163], v205 offset:32768
	ds_read_b128 v[164:167], v205 offset:33792
	ds_read_b128 v[168:171], v205 offset:34816
	ds_read_b128 v[172:175], v205 offset:35840
	ds_read_b128 v[192:195], v205 offset:36864
	ds_read_b128 v[196:199], v205 offset:37888
	ds_read_b128 v[208:211], v205 offset:38912
	ds_read_b128 v[212:215], v205 offset:39936
	global_load_lds_dwordx4 v[224:225], off
	v_lshl_add_u64 v[224:225], s[30:31], 0, v[180:181]
	s_mov_b32 m0, s37
	s_nop 0
	global_load_lds_dwordx4 v[224:225], off
	s_waitcnt vmcnt(8)
	s_waitcnt lgkmcnt(0)
	s_barrier
	s_waitcnt lgkmcnt(0)
	v_mfma_f32_16x16x32_bf16 v[124:127], v[128:131], v[160:163], v[124:127]
	v_mfma_f32_16x16x32_bf16 v[120:123], v[136:139], v[160:163], v[120:123]
	v_mfma_f32_16x16x32_bf16 v[108:111], v[128:131], v[168:171], v[108:111]
	v_mfma_f32_16x16x32_bf16 v[104:107], v[136:139], v[168:171], v[104:107]
	v_mfma_f32_16x16x32_bf16 v[92:95], v[128:131], v[192:195], v[92:95]
	v_mfma_f32_16x16x32_bf16 v[88:91], v[136:139], v[192:195], v[88:91]
	v_mfma_f32_16x16x32_bf16 v[76:79], v[128:131], v[208:211], v[76:79]
	v_mfma_f32_16x16x32_bf16 v[72:75], v[136:139], v[208:211], v[72:75]
	v_mfma_f32_16x16x32_bf16 v[124:127], v[132:135], v[164:167], v[124:127]
	v_mfma_f32_16x16x32_bf16 v[120:123], v[140:143], v[164:167], v[120:123]
	v_mfma_f32_16x16x32_bf16 v[108:111], v[132:135], v[172:175], v[108:111]
	v_mfma_f32_16x16x32_bf16 v[104:107], v[140:143], v[172:175], v[104:107]
	v_mfma_f32_16x16x32_bf16 v[92:95], v[132:135], v[196:199], v[92:95]
	v_mfma_f32_16x16x32_bf16 v[88:91], v[140:143], v[196:199], v[88:91]
	v_mfma_f32_16x16x32_bf16 v[76:79], v[132:135], v[212:215], v[76:79]
	v_mfma_f32_16x16x32_bf16 v[72:75], v[140:143], v[212:215], v[72:75]
	v_mfma_f32_16x16x32_bf16 v[116:119], v[144:147], v[160:163], v[116:119]
	v_mfma_f32_16x16x32_bf16 v[112:115], v[152:155], v[160:163], v[112:115]
	v_mfma_f32_16x16x32_bf16 v[100:103], v[144:147], v[168:171], v[100:103]
	v_mfma_f32_16x16x32_bf16 v[96:99], v[152:155], v[168:171], v[96:99]
	v_mfma_f32_16x16x32_bf16 v[84:87], v[144:147], v[192:195], v[84:87]
	v_mfma_f32_16x16x32_bf16 v[80:83], v[152:155], v[192:195], v[80:83]
	v_mfma_f32_16x16x32_bf16 v[68:71], v[144:147], v[208:211], v[68:71]
	v_mfma_f32_16x16x32_bf16 v[64:67], v[152:155], v[208:211], v[64:67]
	v_mfma_f32_16x16x32_bf16 v[116:119], v[148:151], v[164:167], v[116:119]
	v_mfma_f32_16x16x32_bf16 v[112:115], v[156:159], v[164:167], v[112:115]
	v_mfma_f32_16x16x32_bf16 v[100:103], v[148:151], v[172:175], v[100:103]
	v_mfma_f32_16x16x32_bf16 v[96:99], v[156:159], v[172:175], v[96:99]
	v_mfma_f32_16x16x32_bf16 v[84:87], v[148:151], v[196:199], v[84:87]
	v_mfma_f32_16x16x32_bf16 v[80:83], v[156:159], v[196:199], v[80:83]
	v_mfma_f32_16x16x32_bf16 v[68:71], v[148:151], v[212:215], v[68:71]
	v_mfma_f32_16x16x32_bf16 v[64:67], v[156:159], v[212:215], v[64:67]
	s_barrier
; #define PG8_STAGE(bufoff, gbase, voff) do { _Pragma("unroll") for (int _i = 0; _i < 2; ++_i) \
;         __builtin_amdgcn_global_load_lds((const unsigned*)((const char*)(gbase) + (voff)[_i]), (LAS unsigned*)(lds + (bufoff) + ldsw + _i * 8192), 16, 0, 0); } while (0)
; #define PG8_LDA(dst, b, h) do { _Pragma("unroll") for (int m = 0; m < 4; ++m) _Pragma("unroll") for (int k = 0; k < 2; ++k) dst[m][k] = *(const LAS bf16x8*)(lds + PG8_SA(b, h) + aoff + m * 2048 + k * 1024); } while (0)
; #define PG8_MMA(ai, bj, At, Bt) do { __builtin_amdgcn_s_setprio(1); _Pragma("unroll") for (int m = 0; m < 4; ++m) _Pragma("unroll") for (int n = 0; n < 2; ++n) _Pragma("unroll") for (int k = 0; k < 2; ++k) \
;         acc[ai][bj][m][n] = __builtin_amdgcn_mfma_f32_16x16x32_bf16(Bt[n][k], At[m][k], acc[ai][bj][m][n], 0, 0, 0); __builtin_amdgcn_s_setprio(0); } while (0)
; #define PG8_WAIT_V(n) asm volatile("s_waitcnt vmcnt(" #n ")" ::: "memory")
; #define PG8_WAIT_L(n) asm volatile("s_waitcnt lgkmcnt(" #n ")" ::: "memory")
; #define PG8_BAR __builtin_amdgcn_s_barrier()
; #define PG8_SCHED __builtin_amdgcn_sched_barrier(0)
; template <class Epi, bool ALIGN_EPI>
; __device__ __forceinline__ void gemm_phase(LAS unsigned char* lds, const Gemm g, const StaticOrder& S, const Epi& E) {
;     ...
;             PG8_LDA(At, 1, 1); PG8_STAGE(PG8_SB(1, 0), b3, voffB); PG8_STAGE(PG8_SB(1, 1), b3 + hsB, voffB); PG8_STAGE(PG8_SA(1, 0), a3, voffA);
;             PG8_WAIT_V(8); PG8_WAIT_L(0); PG8_BAR; PG8_MMA(1, 0, At, B0); PG8_MMA(1, 1, At, B1); PG8_BAR; PG8_SCHED;
;         }
	s_add_i32 s30, s50, s34
	v_lshl_add_u64 v[216:217], v[216:217], 0, s[4:5]
	s_mov_b32 m0, s30
	ds_read_b128 v[160:163], v205 offset:49152
	ds_read_b128 v[164:167], v205 offset:50176
	ds_read_b128 v[168:171], v205 offset:51200
	ds_read_b128 v[172:175], v205 offset:52224
	ds_read_b128 v[192:195], v205 offset:53248
	ds_read_b128 v[196:199], v205 offset:54272
	ds_read_b128 v[208:211], v205 offset:55296
	ds_read_b128 v[212:215], v205 offset:56320
	global_load_lds_dwordx4 v[216:217], off
	s_add_i32 m0, s30, 0x2000
	s_add_u32 s28, s28, 0x40080
	v_lshl_add_u64 v[216:217], v[218:219], 0, s[4:5]
	s_addc_u32 s29, s29, 0
	s_add_i32 s30, s51, s34
	global_load_lds_dwordx4 v[216:217], off
	v_lshl_add_u64 v[216:217], s[28:29], 0, v[178:179]
	s_mov_b32 m0, s30
	s_nop 0
	global_load_lds_dwordx4 v[216:217], off
	v_lshl_add_u64 v[216:217], s[28:29], 0, v[182:183]
	s_add_i32 m0, s30, 0x2000
	s_nop 0
	global_load_lds_dwordx4 v[216:217], off
	v_lshl_add_u64 v[216:217], v[220:221], 0, s[4:5]
	s_mov_b32 m0, s39
	s_nop 0
	global_load_lds_dwordx4 v[216:217], off
	v_lshl_add_u64 v[216:217], v[222:223], 0, s[4:5]
	s_mov_b32 m0, s40
	s_nop 0
	global_load_lds_dwordx4 v[216:217], off
	s_waitcnt vmcnt(8)
	s_waitcnt lgkmcnt(0)
	s_barrier
	s_waitcnt lgkmcnt(0)
	v_mfma_f32_16x16x32_bf16 v[60:63], v[128:131], v[160:163], v[60:63]
	v_mfma_f32_16x16x32_bf16 v[56:59], v[136:139], v[160:163], v[56:59]
	v_mfma_f32_16x16x32_bf16 v[44:47], v[128:131], v[168:171], v[44:47]
	v_mfma_f32_16x16x32_bf16 v[40:43], v[136:139], v[168:171], v[40:43]
	v_mfma_f32_16x16x32_bf16 v[28:31], v[128:131], v[192:195], v[28:31]
	v_mfma_f32_16x16x32_bf16 v[24:27], v[136:139], v[192:195], v[24:27]
	v_mfma_f32_16x16x32_bf16 v[12:15], v[128:131], v[208:211], v[12:15]
	v_mfma_f32_16x16x32_bf16 v[8:11], v[136:139], v[208:211], v[8:11]
	v_mfma_f32_16x16x32_bf16 v[60:63], v[132:135], v[164:167], v[60:63]
	v_mfma_f32_16x16x32_bf16 v[56:59], v[140:143], v[164:167], v[56:59]
	v_mfma_f32_16x16x32_bf16 v[44:47], v[132:135], v[172:175], v[44:47]
	v_mfma_f32_16x16x32_bf16 v[40:43], v[140:143], v[172:175], v[40:43]
	v_mfma_f32_16x16x32_bf16 v[28:31], v[132:135], v[196:199], v[28:31]
	v_mfma_f32_16x16x32_bf16 v[24:27], v[140:143], v[196:199], v[24:27]
	v_mfma_f32_16x16x32_bf16 v[12:15], v[132:135], v[212:215], v[12:15]
	v_mfma_f32_16x16x32_bf16 v[8:11], v[140:143], v[212:215], v[8:11]
	v_mfma_f32_16x16x32_bf16 v[52:55], v[144:147], v[160:163], v[52:55]
	v_mfma_f32_16x16x32_bf16 v[48:51], v[152:155], v[160:163], v[48:51]
	v_mfma_f32_16x16x32_bf16 v[36:39], v[144:147], v[168:171], v[36:39]
	v_mfma_f32_16x16x32_bf16 v[32:35], v[152:155], v[168:171], v[32:35]
	v_mfma_f32_16x16x32_bf16 v[20:23], v[144:147], v[192:195], v[20:23]
	v_mfma_f32_16x16x32_bf16 v[16:19], v[152:155], v[192:195], v[16:19]
	v_mfma_f32_16x16x32_bf16 v[4:7], v[144:147], v[208:211], v[4:7]
	v_mfma_f32_16x16x32_bf16 v[0:3], v[152:155], v[208:211], v[0:3]
	v_mfma_f32_16x16x32_bf16 v[52:55], v[148:151], v[164:167], v[52:55]
	v_mfma_f32_16x16x32_bf16 v[48:51], v[156:159], v[164:167], v[48:51]
	v_mfma_f32_16x16x32_bf16 v[36:39], v[148:151], v[172:175], v[36:39]
	v_mfma_f32_16x16x32_bf16 v[32:35], v[156:159], v[172:175], v[32:35]
	v_mfma_f32_16x16x32_bf16 v[20:23], v[148:151], v[196:199], v[20:23]
	v_mfma_f32_16x16x32_bf16 v[16:19], v[156:159], v[196:199], v[16:19]
	v_mfma_f32_16x16x32_bf16 v[4:7], v[148:151], v[212:215], v[4:7]
	v_mfma_f32_16x16x32_bf16 v[0:3], v[156:159], v[212:215], v[0:3]
	s_add_i32 s49, s49, 2
	s_add_u32 s24, s24, 0x100
	s_addc_u32 s25, s25, 0
	s_add_u32 s47, s47, 0x100
	s_addc_u32 s48, s48, 0
	s_cmp_gt_u32 s49, 13
	s_barrier
	s_cbranch_scc0 .LBB0_1501
	s_and_b64 vcc, exec, s[6:7]
	s_cbranch_vccz .LBB0_1504
	s_barrier
